# GEMM K-loops and scan tile loads: the address add now fills the wait state between the M0 write and the LDS-DMA load (204 s_nop removed); the two waits before each K-loop barrier merged into one s_wai
# speedup vs baseline: 1.0074x; 1.0015x over previous
.LBB0_175:
	s_ashr_i32 s57, s56, 31
	s_lshl_b64 s[52:53], s[56:57], 20
	v_readlane_b32 s66, v254, 17
	v_readlane_b32 s67, v254, 18
	s_add_u32 s66, s66, s52
	s_addc_u32 s67, s67, s53
	s_and_b64 s[52:53], s[6:7], exec
	s_cselect_b32 s11, s67, s9
	s_cselect_b32 s13, s66, s8
	s_ashr_i32 s61, s60, 31
	s_lshl_b64 s[52:53], s[60:61], 20
	v_readlane_b32 s68, v254, 21
	v_readlane_b32 s69, v254, 22
	s_add_u32 s88, s68, s52
	s_addc_u32 s89, s69, s53
	s_and_b64 s[52:53], s[6:7], exec
	s_cselect_b32 s57, s89, s15
	s_cselect_b32 s61, s88, s14
	s_add_u32 s8, s8, 0x80080
	s_addc_u32 s9, s9, 0
	s_add_u32 s68, s14, 0x100
	s_addc_u32 s69, s15, 0
	s_mov_b32 s90, -2
	s_add_u32 s14, s8, 0xfff80080
	s_addc_u32 s15, s9, -1
	s_add_i32 s91, 0, 0x10000
	s_cmp_eq_u32 s90, 28
	s_cselect_b32 s53, s11, s15
	s_cselect_b32 s52, s13, s14
	v_add_u32_e32 v14, s91, v188
	s_cselect_b32 s15, s57, s69
	s_cselect_b32 s14, s61, s68
	s_add_i32 s96, 0, 0x14000
	ds_read_b128 v[6:9], v14
	ds_read_b128 v[10:13], v14 offset:1024
	ds_read_b128 v[140:143], v14 offset:2048
	ds_read_b128 v[144:147], v14 offset:3072
	v_add_u32_e32 v14, s96, v188
	ds_read_b128 v[148:151], v14
	ds_read_b128 v[152:155], v14 offset:1024
	ds_read_b128 v[180:183], v14 offset:2048
	ds_read_b128 v[208:211], v14 offset:3072
	v_lshl_add_u64 v[14:15], s[8:9], 0, v[176:177]
	s_add_i32 m0, s40, 0xc000
	ds_read_b128 v[212:215], v206
	ds_read_b128 v[216:219], v206 offset:1024
	ds_read_b128 v[220:223], v206 offset:2048
	ds_read_b128 v[224:227], v206 offset:3072
	ds_read_b128 v[238:241], v206 offset:4096
	ds_read_b128 v[242:245], v206 offset:5120
	ds_read_b128 v[246:249], v206 offset:6144
	ds_read_b128 v[250:253], v206 offset:7168
	global_load_lds_dwordx4 v[14:15], off
	s_add_i32 m0, s40, 0xe000
	v_lshl_add_u64 v[14:15], s[8:9], 0, v[178:179]
	global_load_lds_dwordx4 v[14:15], off
	s_waitcnt vmcnt(8) lgkmcnt(0)
	s_barrier
	s_setprio 1
	v_mfma_f32_16x16x32_bf16 v[136:139], v[6:9], v[212:215], 0
	v_mfma_f32_16x16x32_bf16 v[104:107], v[140:143], v[212:215], 0
	v_mfma_f32_16x16x32_bf16 v[132:135], v[6:9], v[220:223], 0
	v_mfma_f32_16x16x32_bf16 v[100:103], v[140:143], v[220:223], 0
	v_mfma_f32_16x16x32_bf16 v[128:131], v[6:9], v[238:241], 0
	v_mfma_f32_16x16x32_bf16 v[96:99], v[140:143], v[238:241], 0
	v_mfma_f32_16x16x32_bf16 v[124:127], v[6:9], v[246:249], 0
	v_mfma_f32_16x16x32_bf16 v[92:95], v[140:143], v[246:249], 0
	v_mfma_f32_16x16x32_bf16 v[136:139], v[10:13], v[216:219], v[136:139]
	v_mfma_f32_16x16x32_bf16 v[104:107], v[144:147], v[216:219], v[104:107]
	v_mfma_f32_16x16x32_bf16 v[132:135], v[10:13], v[224:227], v[132:135]
	v_mfma_f32_16x16x32_bf16 v[100:103], v[144:147], v[224:227], v[100:103]
	v_mfma_f32_16x16x32_bf16 v[128:131], v[10:13], v[242:245], v[128:131]
	v_mfma_f32_16x16x32_bf16 v[96:99], v[144:147], v[242:245], v[96:99]
	v_mfma_f32_16x16x32_bf16 v[124:127], v[10:13], v[250:253], v[124:127]
	v_mfma_f32_16x16x32_bf16 v[92:95], v[144:147], v[250:253], v[92:95]
	s_setprio 0
	s_setprio 1
	v_mfma_f32_16x16x32_bf16 v[72:75], v[148:151], v[212:215], 0
	v_mfma_f32_16x16x32_bf16 v[40:43], v[180:183], v[212:215], 0
	v_mfma_f32_16x16x32_bf16 v[68:71], v[148:151], v[220:223], 0
	v_mfma_f32_16x16x32_bf16 v[36:39], v[180:183], v[220:223], 0
	v_mfma_f32_16x16x32_bf16 v[64:67], v[148:151], v[238:241], 0
	v_mfma_f32_16x16x32_bf16 v[32:35], v[180:183], v[238:241], 0
	v_mfma_f32_16x16x32_bf16 v[60:63], v[148:151], v[246:249], 0
	v_mfma_f32_16x16x32_bf16 v[28:31], v[180:183], v[246:249], 0
	v_mfma_f32_16x16x32_bf16 v[72:75], v[152:155], v[216:219], v[72:75]
	v_mfma_f32_16x16x32_bf16 v[40:43], v[208:211], v[216:219], v[40:43]
	v_mfma_f32_16x16x32_bf16 v[68:71], v[152:155], v[224:227], v[68:71]
	v_mfma_f32_16x16x32_bf16 v[36:39], v[208:211], v[224:227], v[36:39]
	v_mfma_f32_16x16x32_bf16 v[64:67], v[152:155], v[242:245], v[64:67]
	v_mfma_f32_16x16x32_bf16 v[32:35], v[208:211], v[242:245], v[32:35]
	v_mfma_f32_16x16x32_bf16 v[60:63], v[152:155], v[250:253], v[60:63]
	v_mfma_f32_16x16x32_bf16 v[28:31], v[208:211], v[250:253], v[28:31]
	s_setprio 0
	s_barrier
	s_add_i32 s91, s91, s33
	v_lshl_add_u64 v[156:157], s[14:15], 0, v[160:161]
	s_mov_b32 m0, s91
	ds_read_b128 v[212:215], v206 offset:16384
	ds_read_b128 v[216:219], v206 offset:17408
	ds_read_b128 v[220:223], v206 offset:18432
	ds_read_b128 v[224:227], v206 offset:19456
	ds_read_b128 v[238:241], v206 offset:20480
	ds_read_b128 v[242:245], v206 offset:21504
	ds_read_b128 v[246:249], v206 offset:22528
	ds_read_b128 v[250:253], v206 offset:23552
	global_load_lds_dwordx4 v[156:157], off
	s_add_i32 m0, s91, 0x2000
	s_add_u32 vcc_lo, s14, 0x80000
	v_lshl_add_u64 v[184:185], s[14:15], 0, v[164:165]
	s_addc_u32 vcc_hi, s15, 0
	s_add_i32 s91, s96, s33
	global_load_lds_dwordx4 v[184:185], off
	v_lshl_add_u64 v[14:15], vcc, 0, v[160:161]
	s_mov_b32 m0, s91
	v_lshl_add_u64 v[196:197], s[52:53], 0, v[158:159]
	global_load_lds_dwordx4 v[14:15], off
	v_lshl_add_u64 v[14:15], vcc, 0, v[164:165]
	s_add_i32 m0, s91, 0x2000
	v_lshl_add_u64 v[198:199], s[52:53], 0, v[162:163]
	global_load_lds_dwordx4 v[14:15], off
	s_mov_b32 m0, s40
	s_nop 0
	global_load_lds_dwordx4 v[196:197], off
	s_mov_b32 m0, s41
	s_nop 0
	global_load_lds_dwordx4 v[198:199], off
	s_waitcnt vmcnt(8) lgkmcnt(0)
	s_barrier
	s_setprio 1
	v_mfma_f32_16x16x32_bf16 v[120:123], v[6:9], v[212:215], 0
	v_mfma_f32_16x16x32_bf16 v[88:91], v[140:143], v[212:215], 0
	v_mfma_f32_16x16x32_bf16 v[116:119], v[6:9], v[220:223], 0
	v_mfma_f32_16x16x32_bf16 v[84:87], v[140:143], v[220:223], 0
	v_mfma_f32_16x16x32_bf16 v[112:115], v[6:9], v[238:241], 0
	v_mfma_f32_16x16x32_bf16 v[80:83], v[140:143], v[238:241], 0
	v_mfma_f32_16x16x32_bf16 v[6:9], v[6:9], v[246:249], 0
	v_mfma_f32_16x16x32_bf16 v[120:123], v[10:13], v[216:219], v[120:123]
	v_mfma_f32_16x16x32_bf16 v[88:91], v[144:147], v[216:219], v[88:91]
	v_mfma_f32_16x16x32_bf16 v[116:119], v[10:13], v[224:227], v[116:119]
	v_mfma_f32_16x16x32_bf16 v[84:87], v[144:147], v[224:227], v[84:87]
	v_mfma_f32_16x16x32_bf16 v[112:115], v[10:13], v[242:245], v[112:115]
	v_mfma_f32_16x16x32_bf16 v[80:83], v[144:147], v[242:245], v[80:83]
	v_mfma_f32_16x16x32_bf16 v[6:9], v[10:13], v[250:253], v[6:9]
	v_mfma_f32_16x16x32_bf16 v[10:13], v[140:143], v[246:249], 0
	v_mfma_f32_16x16x32_bf16 v[10:13], v[144:147], v[250:253], v[10:13]
	s_setprio 0
	s_setprio 1
	v_mfma_f32_16x16x32_bf16 v[56:59], v[148:151], v[212:215], 0
	v_mfma_f32_16x16x32_bf16 v[24:27], v[180:183], v[212:215], 0
	v_mfma_f32_16x16x32_bf16 v[52:55], v[148:151], v[220:223], 0
	v_mfma_f32_16x16x32_bf16 v[20:23], v[180:183], v[220:223], 0
	v_mfma_f32_16x16x32_bf16 v[48:51], v[148:151], v[238:241], 0
	v_mfma_f32_16x16x32_bf16 v[14:17], v[180:183], v[238:241], 0
	v_mfma_f32_16x16x32_bf16 v[44:47], v[148:151], v[246:249], 0
	v_mfma_f32_16x16x32_bf16 v[2:5], v[180:183], v[246:249], 0
	v_mfma_f32_16x16x32_bf16 v[56:59], v[152:155], v[216:219], v[56:59]
	v_mfma_f32_16x16x32_bf16 v[24:27], v[208:211], v[216:219], v[24:27]
	v_mfma_f32_16x16x32_bf16 v[52:55], v[152:155], v[224:227], v[52:55]
	v_mfma_f32_16x16x32_bf16 v[20:23], v[208:211], v[224:227], v[20:23]
	v_mfma_f32_16x16x32_bf16 v[48:51], v[152:155], v[242:245], v[48:51]
	v_mfma_f32_16x16x32_bf16 v[14:17], v[208:211], v[242:245], v[14:17]
	v_mfma_f32_16x16x32_bf16 v[44:47], v[152:155], v[250:253], v[44:47]
	v_mfma_f32_16x16x32_bf16 v[2:5], v[208:211], v[250:253], v[2:5]
	s_setprio 0
	s_barrier
	s_add_i32 s91, 0, 0x18000
	v_add_u32_e32 v18, s91, v188
	s_add_i32 s96, 0, 0x1c000
	ds_read_b128 v[76:79], v18
	ds_read_b128 v[108:111], v18 offset:1024
	ds_read_b128 v[140:143], v18 offset:2048
	ds_read_b128 v[144:147], v18 offset:3072
	v_add_u32_e32 v18, s96, v188
	ds_read_b128 v[148:151], v18
	ds_read_b128 v[152:155], v18 offset:1024
	ds_read_b128 v[180:183], v18 offset:2048
	ds_read_b128 v[208:211], v18 offset:3072
	s_add_u32 s52, s52, 0x80000
	s_addc_u32 s53, s53, 0
	s_mov_b32 m0, s42
	v_lshl_add_u64 v[18:19], s[52:53], 0, v[158:159]
	ds_read_b128 v[212:215], v206 offset:32768
	ds_read_b128 v[216:219], v206 offset:33792
	ds_read_b128 v[220:223], v206 offset:34816
	ds_read_b128 v[224:227], v206 offset:35840
	ds_read_b128 v[238:241], v206 offset:36864
	ds_read_b128 v[242:245], v206 offset:37888
	ds_read_b128 v[246:249], v206 offset:38912
	ds_read_b128 v[250:253], v206 offset:39936
	global_load_lds_dwordx4 v[18:19], off
	s_mov_b32 m0, s43
	v_lshl_add_u64 v[18:19], s[52:53], 0, v[162:163]
	global_load_lds_dwordx4 v[18:19], off
	s_waitcnt vmcnt(8) lgkmcnt(0)
	s_barrier
	s_setprio 1
	v_mfma_f32_16x16x32_bf16 v[136:139], v[76:79], v[212:215], v[136:139]
	v_mfma_f32_16x16x32_bf16 v[104:107], v[140:143], v[212:215], v[104:107]
	v_mfma_f32_16x16x32_bf16 v[132:135], v[76:79], v[220:223], v[132:135]
	v_mfma_f32_16x16x32_bf16 v[100:103], v[140:143], v[220:223], v[100:103]
	v_mfma_f32_16x16x32_bf16 v[128:131], v[76:79], v[238:241], v[128:131]
	v_mfma_f32_16x16x32_bf16 v[96:99], v[140:143], v[238:241], v[96:99]
	v_mfma_f32_16x16x32_bf16 v[124:127], v[76:79], v[246:249], v[124:127]
	v_mfma_f32_16x16x32_bf16 v[92:95], v[140:143], v[246:249], v[92:95]
	v_mfma_f32_16x16x32_bf16 v[136:139], v[108:111], v[216:219], v[136:139]
	v_mfma_f32_16x16x32_bf16 v[104:107], v[144:147], v[216:219], v[104:107]
	v_mfma_f32_16x16x32_bf16 v[132:135], v[108:111], v[224:227], v[132:135]
	v_mfma_f32_16x16x32_bf16 v[100:103], v[144:147], v[224:227], v[100:103]
	v_mfma_f32_16x16x32_bf16 v[128:131], v[108:111], v[242:245], v[128:131]
	v_mfma_f32_16x16x32_bf16 v[96:99], v[144:147], v[242:245], v[96:99]
	v_mfma_f32_16x16x32_bf16 v[124:127], v[108:111], v[250:253], v[124:127]
	v_mfma_f32_16x16x32_bf16 v[92:95], v[144:147], v[250:253], v[92:95]
	s_setprio 0
	s_setprio 1
	v_mfma_f32_16x16x32_bf16 v[72:75], v[148:151], v[212:215], v[72:75]
	v_mfma_f32_16x16x32_bf16 v[40:43], v[180:183], v[212:215], v[40:43]
	v_mfma_f32_16x16x32_bf16 v[68:71], v[148:151], v[220:223], v[68:71]
	v_mfma_f32_16x16x32_bf16 v[36:39], v[180:183], v[220:223], v[36:39]
	v_mfma_f32_16x16x32_bf16 v[64:67], v[148:151], v[238:241], v[64:67]
	v_mfma_f32_16x16x32_bf16 v[32:35], v[180:183], v[238:241], v[32:35]
	v_mfma_f32_16x16x32_bf16 v[60:63], v[148:151], v[246:249], v[60:63]
	v_mfma_f32_16x16x32_bf16 v[28:31], v[180:183], v[246:249], v[28:31]
	v_mfma_f32_16x16x32_bf16 v[72:75], v[152:155], v[216:219], v[72:75]
	v_mfma_f32_16x16x32_bf16 v[40:43], v[208:211], v[216:219], v[40:43]
	v_mfma_f32_16x16x32_bf16 v[68:71], v[152:155], v[224:227], v[68:71]
	v_mfma_f32_16x16x32_bf16 v[36:39], v[208:211], v[224:227], v[36:39]
	v_mfma_f32_16x16x32_bf16 v[64:67], v[152:155], v[242:245], v[64:67]
	v_mfma_f32_16x16x32_bf16 v[32:35], v[208:211], v[242:245], v[32:35]
	v_mfma_f32_16x16x32_bf16 v[60:63], v[152:155], v[250:253], v[60:63]
	v_mfma_f32_16x16x32_bf16 v[28:31], v[208:211], v[250:253], v[28:31]
	s_setprio 0
	s_barrier
	s_add_i32 s52, s91, s33
	v_lshl_add_u64 v[18:19], v[156:157], 0, s[58:59]
	s_mov_b32 m0, s52
	ds_read_b128 v[212:215], v206 offset:49152
	ds_read_b128 v[216:219], v206 offset:50176
	ds_read_b128 v[220:223], v206 offset:51200
	ds_read_b128 v[224:227], v206 offset:52224
	ds_read_b128 v[238:241], v206 offset:53248
	ds_read_b128 v[242:245], v206 offset:54272
	ds_read_b128 v[246:249], v206 offset:55296
	ds_read_b128 v[250:253], v206 offset:56320
	global_load_lds_dwordx4 v[18:19], off
	s_add_i32 m0, s52, 0x2000
	s_add_u32 s14, s14, 0x80080
	v_lshl_add_u64 v[18:19], v[184:185], 0, s[58:59]
	s_addc_u32 s15, s15, 0
	s_add_i32 s52, s96, s33
	global_load_lds_dwordx4 v[18:19], off
	s_mov_b32 m0, s52
	v_lshl_add_u64 v[18:19], s[14:15], 0, v[160:161]
	global_load_lds_dwordx4 v[18:19], off
	s_add_i32 m0, s52, 0x2000
	v_lshl_add_u64 v[18:19], s[14:15], 0, v[164:165]
	global_load_lds_dwordx4 v[18:19], off
	s_mov_b32 m0, s55
	v_lshl_add_u64 v[18:19], v[196:197], 0, s[58:59]
	global_load_lds_dwordx4 v[18:19], off
	s_mov_b32 m0, s77
	v_lshl_add_u64 v[18:19], v[198:199], 0, s[58:59]
	global_load_lds_dwordx4 v[18:19], off
	s_waitcnt vmcnt(8) lgkmcnt(0)
	s_barrier
	s_setprio 1
	v_mfma_f32_16x16x32_bf16 v[120:123], v[76:79], v[212:215], v[120:123]
	v_mfma_f32_16x16x32_bf16 v[116:119], v[76:79], v[220:223], v[116:119]
	v_mfma_f32_16x16x32_bf16 v[112:115], v[76:79], v[238:241], v[112:115]
	v_mfma_f32_16x16x32_bf16 v[6:9], v[76:79], v[246:249], v[6:9]
	v_mfma_f32_16x16x32_bf16 v[120:123], v[108:111], v[216:219], v[120:123]
	v_mfma_f32_16x16x32_bf16 v[88:91], v[140:143], v[212:215], v[88:91]
	v_mfma_f32_16x16x32_bf16 v[116:119], v[108:111], v[224:227], v[116:119]
	v_mfma_f32_16x16x32_bf16 v[84:87], v[140:143], v[220:223], v[84:87]
	v_mfma_f32_16x16x32_bf16 v[112:115], v[108:111], v[242:245], v[112:115]
	v_mfma_f32_16x16x32_bf16 v[80:83], v[140:143], v[238:241], v[80:83]
	v_mfma_f32_16x16x32_bf16 v[108:111], v[108:111], v[250:253], v[6:9]
	v_mfma_f32_16x16x32_bf16 v[6:9], v[140:143], v[246:249], v[10:13]
	v_mfma_f32_16x16x32_bf16 v[88:91], v[144:147], v[216:219], v[88:91]
	v_mfma_f32_16x16x32_bf16 v[84:87], v[144:147], v[224:227], v[84:87]
	v_mfma_f32_16x16x32_bf16 v[80:83], v[144:147], v[242:245], v[80:83]
	v_mfma_f32_16x16x32_bf16 v[76:79], v[144:147], v[250:253], v[6:9]
	s_setprio 0
	s_setprio 1
	v_mfma_f32_16x16x32_bf16 v[6:9], v[148:151], v[212:215], v[56:59]
	v_mfma_f32_16x16x32_bf16 v[56:59], v[152:155], v[216:219], v[6:9]
	v_mfma_f32_16x16x32_bf16 v[6:9], v[180:183], v[212:215], v[24:27]
	v_mfma_f32_16x16x32_bf16 v[24:27], v[208:211], v[216:219], v[6:9]
	v_mfma_f32_16x16x32_bf16 v[6:9], v[148:151], v[220:223], v[52:55]
	v_mfma_f32_16x16x32_bf16 v[52:55], v[152:155], v[224:227], v[6:9]
	v_mfma_f32_16x16x32_bf16 v[6:9], v[180:183], v[220:223], v[20:23]
	v_mfma_f32_16x16x32_bf16 v[20:23], v[208:211], v[224:227], v[6:9]
	v_mfma_f32_16x16x32_bf16 v[6:9], v[148:151], v[238:241], v[48:51]
	v_mfma_f32_16x16x32_bf16 v[48:51], v[152:155], v[242:245], v[6:9]
	v_mfma_f32_16x16x32_bf16 v[6:9], v[180:183], v[238:241], v[14:17]
	v_mfma_f32_16x16x32_bf16 v[16:19], v[208:211], v[242:245], v[6:9]
	v_mfma_f32_16x16x32_bf16 v[6:9], v[148:151], v[246:249], v[44:47]
	v_mfma_f32_16x16x32_bf16 v[2:5], v[180:183], v[246:249], v[2:5]
	v_mfma_f32_16x16x32_bf16 v[44:47], v[152:155], v[250:253], v[6:9]
	v_mfma_f32_16x16x32_bf16 v[2:5], v[208:211], v[250:253], v[2:5]
	s_setprio 0
	s_barrier
	s_add_i32 s90, s90, 2
	s_add_u32 s8, s8, 0x100
	s_addc_u32 s9, s9, 0
	s_add_u32 s68, s68, 0x100
	s_addc_u32 s69, s69, 0
	s_cmp_gt_u32 s90, 29
	s_cbranch_scc1 .Lpeel_done_0
.LBB0_176:
	s_add_u32 s14, s8, 0xfff80080
	s_addc_u32 s15, s9, -1
	s_add_i32 s91, 0, 0x10000
	s_cmp_eq_u32 s90, 28
	s_cselect_b32 s53, s11, s15
	s_cselect_b32 s52, s13, s14
	v_add_u32_e32 v14, s91, v188
	s_cselect_b32 s15, s57, s69
	s_cselect_b32 s14, s61, s68
	s_add_i32 s96, 0, 0x14000
	ds_read_b128 v[6:9], v14
	ds_read_b128 v[10:13], v14 offset:1024
	ds_read_b128 v[140:143], v14 offset:2048
	ds_read_b128 v[144:147], v14 offset:3072
	v_add_u32_e32 v14, s96, v188
	ds_read_b128 v[148:151], v14
	ds_read_b128 v[152:155], v14 offset:1024
	ds_read_b128 v[180:183], v14 offset:2048
	ds_read_b128 v[208:211], v14 offset:3072
	v_lshl_add_u64 v[14:15], s[8:9], 0, v[176:177]
	s_add_i32 m0, s40, 0xc000
	ds_read_b128 v[212:215], v206
	ds_read_b128 v[216:219], v206 offset:1024
	ds_read_b128 v[220:223], v206 offset:2048
	ds_read_b128 v[224:227], v206 offset:3072
	ds_read_b128 v[238:241], v206 offset:4096
	ds_read_b128 v[242:245], v206 offset:5120
	ds_read_b128 v[246:249], v206 offset:6144
	ds_read_b128 v[250:253], v206 offset:7168
	global_load_lds_dwordx4 v[14:15], off
	s_add_i32 m0, s40, 0xe000
	v_lshl_add_u64 v[14:15], s[8:9], 0, v[178:179]
	global_load_lds_dwordx4 v[14:15], off
	s_waitcnt vmcnt(8) lgkmcnt(0)
	s_barrier
	s_setprio 1
	v_mfma_f32_16x16x32_bf16 v[136:139], v[6:9], v[212:215], v[136:139]
	v_mfma_f32_16x16x32_bf16 v[104:107], v[140:143], v[212:215], v[104:107]
	v_mfma_f32_16x16x32_bf16 v[132:135], v[6:9], v[220:223], v[132:135]
	v_mfma_f32_16x16x32_bf16 v[100:103], v[140:143], v[220:223], v[100:103]
	v_mfma_f32_16x16x32_bf16 v[128:131], v[6:9], v[238:241], v[128:131]
	v_mfma_f32_16x16x32_bf16 v[96:99], v[140:143], v[238:241], v[96:99]
	v_mfma_f32_16x16x32_bf16 v[124:127], v[6:9], v[246:249], v[124:127]
	v_mfma_f32_16x16x32_bf16 v[92:95], v[140:143], v[246:249], v[92:95]
	v_mfma_f32_16x16x32_bf16 v[136:139], v[10:13], v[216:219], v[136:139]
	v_mfma_f32_16x16x32_bf16 v[104:107], v[144:147], v[216:219], v[104:107]
	v_mfma_f32_16x16x32_bf16 v[132:135], v[10:13], v[224:227], v[132:135]
	v_mfma_f32_16x16x32_bf16 v[100:103], v[144:147], v[224:227], v[100:103]
	v_mfma_f32_16x16x32_bf16 v[128:131], v[10:13], v[242:245], v[128:131]
	v_mfma_f32_16x16x32_bf16 v[96:99], v[144:147], v[242:245], v[96:99]
	v_mfma_f32_16x16x32_bf16 v[124:127], v[10:13], v[250:253], v[124:127]
	v_mfma_f32_16x16x32_bf16 v[92:95], v[144:147], v[250:253], v[92:95]
	s_setprio 0
	s_setprio 1
	v_mfma_f32_16x16x32_bf16 v[72:75], v[148:151], v[212:215], v[72:75]
	v_mfma_f32_16x16x32_bf16 v[40:43], v[180:183], v[212:215], v[40:43]
	v_mfma_f32_16x16x32_bf16 v[68:71], v[148:151], v[220:223], v[68:71]
	v_mfma_f32_16x16x32_bf16 v[36:39], v[180:183], v[220:223], v[36:39]
	v_mfma_f32_16x16x32_bf16 v[64:67], v[148:151], v[238:241], v[64:67]
	v_mfma_f32_16x16x32_bf16 v[32:35], v[180:183], v[238:241], v[32:35]
	v_mfma_f32_16x16x32_bf16 v[60:63], v[148:151], v[246:249], v[60:63]
	v_mfma_f32_16x16x32_bf16 v[28:31], v[180:183], v[246:249], v[28:31]
	v_mfma_f32_16x16x32_bf16 v[72:75], v[152:155], v[216:219], v[72:75]
	v_mfma_f32_16x16x32_bf16 v[40:43], v[208:211], v[216:219], v[40:43]
	v_mfma_f32_16x16x32_bf16 v[68:71], v[152:155], v[224:227], v[68:71]
	v_mfma_f32_16x16x32_bf16 v[36:39], v[208:211], v[224:227], v[36:39]
	v_mfma_f32_16x16x32_bf16 v[64:67], v[152:155], v[242:245], v[64:67]
	v_mfma_f32_16x16x32_bf16 v[32:35], v[208:211], v[242:245], v[32:35]
	v_mfma_f32_16x16x32_bf16 v[60:63], v[152:155], v[250:253], v[60:63]
	v_mfma_f32_16x16x32_bf16 v[28:31], v[208:211], v[250:253], v[28:31]
	s_setprio 0
	s_barrier
	s_add_i32 s91, s91, s33
	v_lshl_add_u64 v[156:157], s[14:15], 0, v[160:161]
	s_mov_b32 m0, s91
	ds_read_b128 v[212:215], v206 offset:16384
	ds_read_b128 v[216:219], v206 offset:17408
	ds_read_b128 v[220:223], v206 offset:18432
	ds_read_b128 v[224:227], v206 offset:19456
	ds_read_b128 v[238:241], v206 offset:20480
	ds_read_b128 v[242:245], v206 offset:21504
	ds_read_b128 v[246:249], v206 offset:22528
	ds_read_b128 v[250:253], v206 offset:23552
	global_load_lds_dwordx4 v[156:157], off
	s_add_i32 m0, s91, 0x2000
	s_add_u32 vcc_lo, s14, 0x80000
	v_lshl_add_u64 v[184:185], s[14:15], 0, v[164:165]
	s_addc_u32 vcc_hi, s15, 0
	s_add_i32 s91, s96, s33
	global_load_lds_dwordx4 v[184:185], off
	v_lshl_add_u64 v[14:15], vcc, 0, v[160:161]
	s_mov_b32 m0, s91
	v_lshl_add_u64 v[196:197], s[52:53], 0, v[158:159]
	global_load_lds_dwordx4 v[14:15], off
	v_lshl_add_u64 v[14:15], vcc, 0, v[164:165]
	s_add_i32 m0, s91, 0x2000
	v_lshl_add_u64 v[198:199], s[52:53], 0, v[162:163]
	global_load_lds_dwordx4 v[14:15], off
	s_mov_b32 m0, s40
	s_nop 0
	global_load_lds_dwordx4 v[196:197], off
	s_mov_b32 m0, s41
	s_nop 0
	global_load_lds_dwordx4 v[198:199], off
	s_waitcnt vmcnt(8) lgkmcnt(0)
	s_barrier
	s_setprio 1
	v_mfma_f32_16x16x32_bf16 v[120:123], v[6:9], v[212:215], v[120:123]
	v_mfma_f32_16x16x32_bf16 v[88:91], v[140:143], v[212:215], v[88:91]
	v_mfma_f32_16x16x32_bf16 v[116:119], v[6:9], v[220:223], v[116:119]
	v_mfma_f32_16x16x32_bf16 v[84:87], v[140:143], v[220:223], v[84:87]
	v_mfma_f32_16x16x32_bf16 v[112:115], v[6:9], v[238:241], v[112:115]
	v_mfma_f32_16x16x32_bf16 v[80:83], v[140:143], v[238:241], v[80:83]
	v_mfma_f32_16x16x32_bf16 v[6:9], v[6:9], v[246:249], v[108:111]
	v_mfma_f32_16x16x32_bf16 v[120:123], v[10:13], v[216:219], v[120:123]
	v_mfma_f32_16x16x32_bf16 v[88:91], v[144:147], v[216:219], v[88:91]
	v_mfma_f32_16x16x32_bf16 v[116:119], v[10:13], v[224:227], v[116:119]
	v_mfma_f32_16x16x32_bf16 v[84:87], v[144:147], v[224:227], v[84:87]
	v_mfma_f32_16x16x32_bf16 v[112:115], v[10:13], v[242:245], v[112:115]
	v_mfma_f32_16x16x32_bf16 v[80:83], v[144:147], v[242:245], v[80:83]
	v_mfma_f32_16x16x32_bf16 v[6:9], v[10:13], v[250:253], v[6:9]
	v_mfma_f32_16x16x32_bf16 v[10:13], v[140:143], v[246:249], v[76:79]
	v_mfma_f32_16x16x32_bf16 v[10:13], v[144:147], v[250:253], v[10:13]
	s_setprio 0
	s_setprio 1
	v_mfma_f32_16x16x32_bf16 v[56:59], v[148:151], v[212:215], v[56:59]
	v_mfma_f32_16x16x32_bf16 v[24:27], v[180:183], v[212:215], v[24:27]
	v_mfma_f32_16x16x32_bf16 v[52:55], v[148:151], v[220:223], v[52:55]
	v_mfma_f32_16x16x32_bf16 v[20:23], v[180:183], v[220:223], v[20:23]
	v_mfma_f32_16x16x32_bf16 v[48:51], v[148:151], v[238:241], v[48:51]
	v_mfma_f32_16x16x32_bf16 v[14:17], v[180:183], v[238:241], v[16:19]
	v_mfma_f32_16x16x32_bf16 v[44:47], v[148:151], v[246:249], v[44:47]
	v_mfma_f32_16x16x32_bf16 v[2:5], v[180:183], v[246:249], v[2:5]
	v_mfma_f32_16x16x32_bf16 v[56:59], v[152:155], v[216:219], v[56:59]
	v_mfma_f32_16x16x32_bf16 v[24:27], v[208:211], v[216:219], v[24:27]
	v_mfma_f32_16x16x32_bf16 v[52:55], v[152:155], v[224:227], v[52:55]
	v_mfma_f32_16x16x32_bf16 v[20:23], v[208:211], v[224:227], v[20:23]
	v_mfma_f32_16x16x32_bf16 v[48:51], v[152:155], v[242:245], v[48:51]
	v_mfma_f32_16x16x32_bf16 v[14:17], v[208:211], v[242:245], v[14:17]
	v_mfma_f32_16x16x32_bf16 v[44:47], v[152:155], v[250:253], v[44:47]
	v_mfma_f32_16x16x32_bf16 v[2:5], v[208:211], v[250:253], v[2:5]
	s_setprio 0
	s_barrier
	s_add_i32 s91, 0, 0x18000
	v_add_u32_e32 v18, s91, v188
	s_add_i32 s96, 0, 0x1c000
	ds_read_b128 v[76:79], v18
	ds_read_b128 v[108:111], v18 offset:1024
	ds_read_b128 v[140:143], v18 offset:2048
	ds_read_b128 v[144:147], v18 offset:3072
	v_add_u32_e32 v18, s96, v188
	ds_read_b128 v[148:151], v18
	ds_read_b128 v[152:155], v18 offset:1024
	ds_read_b128 v[180:183], v18 offset:2048
	ds_read_b128 v[208:211], v18 offset:3072
	s_add_u32 s52, s52, 0x80000
	s_addc_u32 s53, s53, 0
	s_mov_b32 m0, s42
	v_lshl_add_u64 v[18:19], s[52:53], 0, v[158:159]
	ds_read_b128 v[212:215], v206 offset:32768
	ds_read_b128 v[216:219], v206 offset:33792
	ds_read_b128 v[220:223], v206 offset:34816
	ds_read_b128 v[224:227], v206 offset:35840
	ds_read_b128 v[238:241], v206 offset:36864
	ds_read_b128 v[242:245], v206 offset:37888
	ds_read_b128 v[246:249], v206 offset:38912
	ds_read_b128 v[250:253], v206 offset:39936
	global_load_lds_dwordx4 v[18:19], off
	s_mov_b32 m0, s43
	v_lshl_add_u64 v[18:19], s[52:53], 0, v[162:163]
	global_load_lds_dwordx4 v[18:19], off
	s_waitcnt vmcnt(8) lgkmcnt(0)
	s_barrier
	s_setprio 1
	v_mfma_f32_16x16x32_bf16 v[136:139], v[76:79], v[212:215], v[136:139]
	v_mfma_f32_16x16x32_bf16 v[104:107], v[140:143], v[212:215], v[104:107]
	v_mfma_f32_16x16x32_bf16 v[132:135], v[76:79], v[220:223], v[132:135]
	v_mfma_f32_16x16x32_bf16 v[100:103], v[140:143], v[220:223], v[100:103]
	v_mfma_f32_16x16x32_bf16 v[128:131], v[76:79], v[238:241], v[128:131]
	v_mfma_f32_16x16x32_bf16 v[96:99], v[140:143], v[238:241], v[96:99]
	v_mfma_f32_16x16x32_bf16 v[124:127], v[76:79], v[246:249], v[124:127]
	v_mfma_f32_16x16x32_bf16 v[92:95], v[140:143], v[246:249], v[92:95]
	v_mfma_f32_16x16x32_bf16 v[136:139], v[108:111], v[216:219], v[136:139]
	v_mfma_f32_16x16x32_bf16 v[104:107], v[144:147], v[216:219], v[104:107]
	v_mfma_f32_16x16x32_bf16 v[132:135], v[108:111], v[224:227], v[132:135]
	v_mfma_f32_16x16x32_bf16 v[100:103], v[144:147], v[224:227], v[100:103]
	v_mfma_f32_16x16x32_bf16 v[128:131], v[108:111], v[242:245], v[128:131]
	v_mfma_f32_16x16x32_bf16 v[96:99], v[144:147], v[242:245], v[96:99]
	v_mfma_f32_16x16x32_bf16 v[124:127], v[108:111], v[250:253], v[124:127]
	v_mfma_f32_16x16x32_bf16 v[92:95], v[144:147], v[250:253], v[92:95]
	s_setprio 0
	s_setprio 1
	v_mfma_f32_16x16x32_bf16 v[72:75], v[148:151], v[212:215], v[72:75]
	v_mfma_f32_16x16x32_bf16 v[40:43], v[180:183], v[212:215], v[40:43]
	v_mfma_f32_16x16x32_bf16 v[68:71], v[148:151], v[220:223], v[68:71]
	v_mfma_f32_16x16x32_bf16 v[36:39], v[180:183], v[220:223], v[36:39]
	v_mfma_f32_16x16x32_bf16 v[64:67], v[148:151], v[238:241], v[64:67]
	v_mfma_f32_16x16x32_bf16 v[32:35], v[180:183], v[238:241], v[32:35]
	v_mfma_f32_16x16x32_bf16 v[60:63], v[148:151], v[246:249], v[60:63]
	v_mfma_f32_16x16x32_bf16 v[28:31], v[180:183], v[246:249], v[28:31]
	v_mfma_f32_16x16x32_bf16 v[72:75], v[152:155], v[216:219], v[72:75]
	v_mfma_f32_16x16x32_bf16 v[40:43], v[208:211], v[216:219], v[40:43]
	v_mfma_f32_16x16x32_bf16 v[68:71], v[152:155], v[224:227], v[68:71]
	v_mfma_f32_16x16x32_bf16 v[36:39], v[208:211], v[224:227], v[36:39]
	v_mfma_f32_16x16x32_bf16 v[64:67], v[152:155], v[242:245], v[64:67]
	v_mfma_f32_16x16x32_bf16 v[32:35], v[208:211], v[242:245], v[32:35]
	v_mfma_f32_16x16x32_bf16 v[60:63], v[152:155], v[250:253], v[60:63]
	v_mfma_f32_16x16x32_bf16 v[28:31], v[208:211], v[250:253], v[28:31]
	s_setprio 0
	s_barrier
	s_add_i32 s52, s91, s33
	v_lshl_add_u64 v[18:19], v[156:157], 0, s[58:59]
	s_mov_b32 m0, s52
	ds_read_b128 v[212:215], v206 offset:49152
	ds_read_b128 v[216:219], v206 offset:50176
	ds_read_b128 v[220:223], v206 offset:51200
	ds_read_b128 v[224:227], v206 offset:52224
	ds_read_b128 v[238:241], v206 offset:53248
	ds_read_b128 v[242:245], v206 offset:54272
	ds_read_b128 v[246:249], v206 offset:55296
	ds_read_b128 v[250:253], v206 offset:56320
	global_load_lds_dwordx4 v[18:19], off
	s_add_i32 m0, s52, 0x2000
	s_add_u32 s14, s14, 0x80080
	v_lshl_add_u64 v[18:19], v[184:185], 0, s[58:59]
	s_addc_u32 s15, s15, 0
	s_add_i32 s52, s96, s33
	global_load_lds_dwordx4 v[18:19], off
	s_mov_b32 m0, s52
	v_lshl_add_u64 v[18:19], s[14:15], 0, v[160:161]
	global_load_lds_dwordx4 v[18:19], off
	s_add_i32 m0, s52, 0x2000
	v_lshl_add_u64 v[18:19], s[14:15], 0, v[164:165]
	global_load_lds_dwordx4 v[18:19], off
	s_mov_b32 m0, s55
	v_lshl_add_u64 v[18:19], v[196:197], 0, s[58:59]
	global_load_lds_dwordx4 v[18:19], off
	s_mov_b32 m0, s77
	v_lshl_add_u64 v[18:19], v[198:199], 0, s[58:59]
	global_load_lds_dwordx4 v[18:19], off
	s_waitcnt vmcnt(8) lgkmcnt(0)
	s_barrier
	s_setprio 1
	v_mfma_f32_16x16x32_bf16 v[120:123], v[76:79], v[212:215], v[120:123]
	v_mfma_f32_16x16x32_bf16 v[116:119], v[76:79], v[220:223], v[116:119]
	v_mfma_f32_16x16x32_bf16 v[112:115], v[76:79], v[238:241], v[112:115]
	v_mfma_f32_16x16x32_bf16 v[6:9], v[76:79], v[246:249], v[6:9]
	v_mfma_f32_16x16x32_bf16 v[120:123], v[108:111], v[216:219], v[120:123]
	v_mfma_f32_16x16x32_bf16 v[88:91], v[140:143], v[212:215], v[88:91]
	v_mfma_f32_16x16x32_bf16 v[116:119], v[108:111], v[224:227], v[116:119]
	v_mfma_f32_16x16x32_bf16 v[84:87], v[140:143], v[220:223], v[84:87]
	v_mfma_f32_16x16x32_bf16 v[112:115], v[108:111], v[242:245], v[112:115]
	v_mfma_f32_16x16x32_bf16 v[80:83], v[140:143], v[238:241], v[80:83]
	v_mfma_f32_16x16x32_bf16 v[108:111], v[108:111], v[250:253], v[6:9]
	v_mfma_f32_16x16x32_bf16 v[6:9], v[140:143], v[246:249], v[10:13]
	v_mfma_f32_16x16x32_bf16 v[88:91], v[144:147], v[216:219], v[88:91]
	v_mfma_f32_16x16x32_bf16 v[84:87], v[144:147], v[224:227], v[84:87]
	v_mfma_f32_16x16x32_bf16 v[80:83], v[144:147], v[242:245], v[80:83]
	v_mfma_f32_16x16x32_bf16 v[76:79], v[144:147], v[250:253], v[6:9]
	s_setprio 0
	s_setprio 1
	v_mfma_f32_16x16x32_bf16 v[6:9], v[148:151], v[212:215], v[56:59]
	v_mfma_f32_16x16x32_bf16 v[56:59], v[152:155], v[216:219], v[6:9]
	v_mfma_f32_16x16x32_bf16 v[6:9], v[180:183], v[212:215], v[24:27]
	v_mfma_f32_16x16x32_bf16 v[24:27], v[208:211], v[216:219], v[6:9]
	v_mfma_f32_16x16x32_bf16 v[6:9], v[148:151], v[220:223], v[52:55]
	v_mfma_f32_16x16x32_bf16 v[52:55], v[152:155], v[224:227], v[6:9]
	v_mfma_f32_16x16x32_bf16 v[6:9], v[180:183], v[220:223], v[20:23]
	v_mfma_f32_16x16x32_bf16 v[20:23], v[208:211], v[224:227], v[6:9]
	v_mfma_f32_16x16x32_bf16 v[6:9], v[148:151], v[238:241], v[48:51]
	v_mfma_f32_16x16x32_bf16 v[48:51], v[152:155], v[242:245], v[6:9]
	v_mfma_f32_16x16x32_bf16 v[6:9], v[180:183], v[238:241], v[14:17]
	v_mfma_f32_16x16x32_bf16 v[16:19], v[208:211], v[242:245], v[6:9]
	v_mfma_f32_16x16x32_bf16 v[6:9], v[148:151], v[246:249], v[44:47]
	v_mfma_f32_16x16x32_bf16 v[2:5], v[180:183], v[246:249], v[2:5]
	v_mfma_f32_16x16x32_bf16 v[44:47], v[152:155], v[250:253], v[6:9]
	v_mfma_f32_16x16x32_bf16 v[2:5], v[208:211], v[250:253], v[2:5]
	s_setprio 0
	s_barrier
	s_add_i32 s90, s90, 2
	s_add_u32 s8, s8, 0x100
	s_addc_u32 s9, s9, 0
	s_add_u32 s68, s68, 0x100
	s_addc_u32 s69, s69, 0
	s_cmp_gt_u32 s90, 29
	s_cbranch_scc0 .LBB0_176

.LBB0_492:
	s_cmp_gt_u32 s41, 1
	s_cselect_b32 s2, 35, 1
	s_sub_i32 s8, s2, s41
	s_and_b64 s[2:3], s[4:5], exec
	s_cselect_b32 s2, s41, s8
	s_lshl_b32 s2, s2, 7
	s_ashr_i32 s3, s2, 31
	v_and_b32_e32 v155, 63, v140
	s_add_u32 s16, s38, s2
	s_addc_u32 s17, s39, s3
	v_lshlrev_b32_e32 v66, 4, v155
	s_lshl_b64 s[2:3], s[16:17], s96
	v_or_b32_e32 v67, s65, v66
	v_or_b32_e32 v70, s70, v66
	s_lshl_b64 s[2:3], s[2:3], 1
	v_and_b32_e32 v156, 15, v140
	v_lshrrev_b32_e32 v68, 8, v67
	v_lshrrev_b32_e32 v67, 6, v67
	v_lshrrev_b32_e32 v71, 8, v70
	v_lshrrev_b32_e32 v70, 6, v70
	v_or_b32_e32 v73, s71, v66
	s_add_u32 s8, s0, s2
	v_bitop3_b32 v67, v67, v156, 12 bitop3:0x6c
	v_and_b32_e32 v70, 12, v70
	v_lshrrev_b32_e32 v74, 8, v73
	v_lshrrev_b32_e32 v73, 6, v73
	s_addc_u32 s9, s55, s3
	v_lshlrev_b32_e32 v67, 4, v67
	s_add_i32 s10, s65, 0
	v_bitop3_b32 v70, v70, v156, 1 bitop3:0x36
	v_and_b32_e32 v73, 12, v73
	v_or_b32_e32 v66, s76, v66
	v_lshl_or_b32 v69, v68, s77, v67
	s_mov_b32 m0, s10
	v_lshlrev_b32_e32 v70, 4, v70
	v_bitop3_b32 v73, v73, v156, 2 bitop3:0x36
	v_lshrrev_b32_e32 v76, 8, v66
	v_lshrrev_b32_e32 v66, 6, v66
	global_load_lds_dwordx4 v69, s[8:9] nt
	v_lshl_or_b32 v72, v71, s77, v70
	s_add_i32 m0, s10, 0x400
	v_lshlrev_b32_e32 v73, 4, v73
	v_and_b32_e32 v66, 12, v66
	global_load_lds_dwordx4 v72, s[8:9] nt
	v_lshl_or_b32 v75, v74, s77, v73
	s_add_i32 m0, s10, 0x800
	v_bitop3_b32 v66, v66, v156, 3 bitop3:0x36
	global_load_lds_dwordx4 v75, s[8:9] nt
	v_lshlrev_b32_e32 v77, 4, v66
	s_add_i32 m0, s10, 0xc00
	v_lshl_or_b32 v66, v76, s77, v77
	s_add_u32 s2, s80, s2
	global_load_lds_dwordx4 v66, s[8:9] nt
	s_addc_u32 s3, s66, s3
	s_add_i32 m0, s10, 0x8000
	v_lshl_or_b32 v190, v68, 14, v67
	global_load_lds_dwordx4 v69, s[2:3] nt
	s_add_i32 m0, s10, 0x8400
	s_nop 0
	global_load_lds_dwordx4 v72, s[2:3] nt
	s_add_i32 m0, s10, 0x8800
	s_nop 0
	global_load_lds_dwordx4 v75, s[2:3] nt
	s_add_i32 m0, s10, 0x8c00
	s_nop 0
	global_load_lds_dwordx4 v66, s[2:3] nt
	s_lshl_b64 s[2:3], s[16:17], 14
	s_add_u32 s2, s67, s2
	s_addc_u32 s3, s18, s3
	s_add_i32 s8, 0, 0x10000
	s_add_i32 m0, s8, s65
	v_lshl_add_u64 v[66:67], s[2:3], 0, v[190:191]
	global_load_lds_dwordx4 v190, s[2:3] nt
	v_lshl_or_b32 v190, v71, 14, v70
	s_add_i32 m0, s8, s70
	v_lshl_add_u64 v[68:69], s[2:3], 0, v[190:191]
	global_load_lds_dwordx4 v190, s[2:3] nt
	v_lshl_or_b32 v190, v74, 14, v73
	s_add_i32 m0, s8, s71
	v_lshl_add_u64 v[70:71], s[2:3], 0, v[190:191]
	global_load_lds_dwordx4 v190, s[2:3] nt
	v_lshl_or_b32 v190, v76, 14, v77
	s_add_i32 m0, s8, s76
	v_lshl_add_u64 v[72:73], s[2:3], 0, v[190:191]
	global_load_lds_dwordx4 v190, s[2:3] nt
	s_add_i32 s2, 0, 0x18000
	v_lshl_add_u64 v[66:67], v[66:67], 0, s[50:51]
	s_add_i32 m0, s2, s65
	s_nop 0
	global_load_lds_dwordx4 v[66:67], off nt
	v_lshl_add_u64 v[66:67], v[68:69], 0, s[50:51]
	s_add_i32 m0, s2, s70
	s_nop 0
	global_load_lds_dwordx4 v[66:67], off nt
	v_lshl_add_u64 v[66:67], v[70:71], 0, s[50:51]
	s_add_i32 m0, s2, s71
	s_nop 0
	global_load_lds_dwordx4 v[66:67], off nt
	v_lshl_add_u64 v[66:67], v[72:73], 0, s[50:51]
	s_add_i32 m0, s2, s76
	s_cmp_eq_u32 s41, 33
	global_load_lds_dwordx4 v[66:67], off nt
	s_waitcnt vmcnt(8) lgkmcnt(0)
	s_barrier
	s_cselect_b64 s[2:3], -1, 0
	s_xor_b64 s[8:9], s[90:91], -1
	s_or_b64 s[2:3], s[8:9], s[2:3]
	s_and_b64 vcc, exec, s[2:3]
	s_cbranch_vccnz .LBB0_496
	s_add_i32 s8, s41, 1
	s_sub_i32 s2, 34, s41
	s_cmp_lg_u32 s41, 0
	s_cselect_b32 s9, s2, 0
	s_and_b64 s[2:3], s[4:5], exec
	s_cselect_b32 s2, s8, s9
	s_lshl_b32 s2, s2, 7
	s_add_u32 s2, s19, s2
	s_addc_u32 s3, s33, 0
	s_add_u32 s8, s2, s46
	s_addc_u32 s9, s3, 0
	s_lshl_b64 s[8:9], s[8:9], 3
	s_add_u32 s8, s8, s60
	s_addc_u32 s9, s9, s61
	s_lshl_b64 s[8:9], s[8:9], 2
	s_add_u32 s10, s82, s8
	s_addc_u32 s11, s83, s9
	s_add_u32 s8, s84, s8
	s_addc_u32 s9, s85, s9
	global_load_dword v139, v191, s[10:11]
	global_load_dword v151, v191, s[8:9]
	v_cmp_gt_i32_e32 vcc, s74, v140
	s_and_saveexec_b64 s[8:9], vcc
	s_cbranch_execz .LBB0_495
	v_ashrrev_i32_e32 v141, 31, v140
	v_lshl_add_u64 v[66:67], s[2:3], 0, v[140:141]
	v_lshl_add_u64 v[66:67], v[66:67], 3, s[60:61]
	v_readlane_b32 s2, v254, 48
	v_lshlrev_b64 v[66:67], 2, v[66:67]
	v_readlane_b32 s3, v254, 49
	s_nop 1
	v_lshl_add_u64 v[68:69], s[2:3], 0, v[66:67]
	global_load_dword v150, v[68:69], off
	v_lshl_add_u64 v[68:69], s[82:83], 0, v[66:67]
	v_lshl_add_u64 v[66:67], s[84:85], 0, v[66:67]
	global_load_dword v152, v[68:69], off
	global_load_dword v153, v[66:67], off

.LBB0_671:
	s_ashr_i32 s11, s10, 31
	s_lshl_b64 s[12:13], s[10:11], 20
	v_readlane_b32 s14, v254, 17
	v_readlane_b32 s15, v254, 18
	s_add_u32 s12, s14, s12
	s_addc_u32 s13, s15, s13
	s_and_b64 s[14:15], s[4:5], exec
	s_cselect_b32 s11, s13, s23
	s_cselect_b32 s18, s12, s22
	s_ashr_i32 s9, s8, 31
	s_lshl_b64 s[14:15], s[8:9], 20
	v_readlane_b32 s26, v254, 44
	v_readlane_b32 s27, v254, 45
	s_add_u32 s14, s26, s14
	s_addc_u32 s15, s27, s15
	s_and_b64 s[26:27], s[4:5], exec
	s_cselect_b32 s9, s15, s25
	s_cselect_b32 s19, s14, s24
	s_add_u32 s22, s22, 0x80080
	s_addc_u32 s23, s23, 0
	s_add_u32 s21, s24, 0x100
	s_addc_u32 s33, s25, 0
	s_mov_b32 s40, -2
	v_readlane_b32 s41, v255, 49
	s_nop 3
	s_cmp_eq_u32 s41, 2
	v_writelane_b32 v255, 2, 49
	s_cbranch_scc0 .Ltrip0_strict_1
	s_add_u32 s24, s22, 0xfff80080
	s_addc_u32 s25, s23, -1
	s_add_i32 s41, 0, 0x10000
	s_cmp_eq_u32 s40, 28
	s_cselect_b32 s27, s11, s25
	s_cselect_b32 s26, s18, s24
	s_cselect_b32 s25, s9, s33
	s_cselect_b32 s24, s19, s21
	s_add_i32 s46, 0, 0x14000
	v_add_u32_e32 v142, s41, v214
	v_add_u32_e32 v158, s46, v214
	ds_read_b128 v[130:133], v142
	ds_read_b128 v[134:137], v142 offset:1024
	ds_read_b128 v[138:141], v142 offset:2048
	ds_read_b128 v[142:145], v142 offset:3072
	ds_read_b128 v[146:149], v158
	ds_read_b128 v[150:153], v158 offset:1024
	ds_read_b128 v[154:157], v158 offset:2048
	ds_read_b128 v[158:161], v158 offset:3072
	v_lshl_add_u64 v[212:213], s[22:23], 0, v[182:183]
	s_add_i32 m0, s17, 0xc000
	ds_read_b128 v[162:165], v216
	ds_read_b128 v[166:169], v216 offset:1024
	ds_read_b128 v[170:173], v216 offset:2048
	ds_read_b128 v[186:189], v216 offset:3072
	ds_read_b128 v[196:199], v216 offset:4096
	ds_read_b128 v[200:203], v216 offset:5120
	ds_read_b128 v[204:207], v216 offset:6144
	ds_read_b128 v[208:211], v216 offset:7168
	global_load_lds_dwordx4 v[212:213], off
	s_add_i32 m0, s17, 0xe000
	v_lshl_add_u64 v[212:213], s[22:23], 0, v[184:185]
	global_load_lds_dwordx4 v[212:213], off
	s_waitcnt vmcnt(24) lgkmcnt(0)
	s_barrier
	s_setprio 1
	v_mfma_f32_16x16x32_bf16 v[126:129], v[130:133], v[162:165], 0
	v_mfma_f32_16x16x32_bf16 v[122:125], v[138:141], v[162:165], 0
	v_mfma_f32_16x16x32_bf16 v[110:113], v[130:133], v[170:173], 0
	v_mfma_f32_16x16x32_bf16 v[106:109], v[138:141], v[170:173], 0
	v_mfma_f32_16x16x32_bf16 v[94:97], v[130:133], v[196:199], 0
	v_mfma_f32_16x16x32_bf16 v[90:93], v[138:141], v[196:199], 0
	v_mfma_f32_16x16x32_bf16 v[78:81], v[130:133], v[204:207], 0
	v_mfma_f32_16x16x32_bf16 v[74:77], v[138:141], v[204:207], 0
	v_mfma_f32_16x16x32_bf16 v[126:129], v[134:137], v[166:169], v[126:129]
	v_mfma_f32_16x16x32_bf16 v[122:125], v[142:145], v[166:169], v[122:125]
	v_mfma_f32_16x16x32_bf16 v[110:113], v[134:137], v[186:189], v[110:113]
	v_mfma_f32_16x16x32_bf16 v[106:109], v[142:145], v[186:189], v[106:109]
	v_mfma_f32_16x16x32_bf16 v[94:97], v[134:137], v[200:203], v[94:97]
	v_mfma_f32_16x16x32_bf16 v[90:93], v[142:145], v[200:203], v[90:93]
	v_mfma_f32_16x16x32_bf16 v[78:81], v[134:137], v[208:211], v[78:81]
	v_mfma_f32_16x16x32_bf16 v[74:77], v[142:145], v[208:211], v[74:77]
	s_setprio 0
	s_setprio 1
	v_mfma_f32_16x16x32_bf16 v[118:121], v[146:149], v[162:165], 0
	v_mfma_f32_16x16x32_bf16 v[114:117], v[154:157], v[162:165], 0
	v_mfma_f32_16x16x32_bf16 v[102:105], v[146:149], v[170:173], 0
	v_mfma_f32_16x16x32_bf16 v[98:101], v[154:157], v[170:173], 0
	v_mfma_f32_16x16x32_bf16 v[86:89], v[146:149], v[196:199], 0
	v_mfma_f32_16x16x32_bf16 v[82:85], v[154:157], v[196:199], 0
	v_mfma_f32_16x16x32_bf16 v[70:73], v[146:149], v[204:207], 0
	v_mfma_f32_16x16x32_bf16 v[66:69], v[154:157], v[204:207], 0
	v_mfma_f32_16x16x32_bf16 v[118:121], v[150:153], v[166:169], v[118:121]
	v_mfma_f32_16x16x32_bf16 v[114:117], v[158:161], v[166:169], v[114:117]
	v_mfma_f32_16x16x32_bf16 v[102:105], v[150:153], v[186:189], v[102:105]
	v_mfma_f32_16x16x32_bf16 v[98:101], v[158:161], v[186:189], v[98:101]
	v_mfma_f32_16x16x32_bf16 v[86:89], v[150:153], v[200:203], v[86:89]
	v_mfma_f32_16x16x32_bf16 v[82:85], v[158:161], v[200:203], v[82:85]
	v_mfma_f32_16x16x32_bf16 v[70:73], v[150:153], v[208:211], v[70:73]
	v_mfma_f32_16x16x32_bf16 v[66:69], v[158:161], v[208:211], v[66:69]
	s_setprio 0
	s_barrier
	s_add_i32 s41, s41, s29
	v_lshl_add_u64 v[212:213], s[24:25], 0, v[178:179]
	s_mov_b32 m0, s41
	ds_read_b128 v[162:165], v216 offset:16384
	ds_read_b128 v[166:169], v216 offset:17408
	ds_read_b128 v[170:173], v216 offset:18432
	ds_read_b128 v[186:189], v216 offset:19456
	ds_read_b128 v[196:199], v216 offset:20480
	ds_read_b128 v[200:203], v216 offset:21504
	ds_read_b128 v[204:207], v216 offset:22528
	ds_read_b128 v[208:211], v216 offset:23552
	global_load_lds_dwordx4 v[212:213], off
	s_add_i32 m0, s41, 0x2000
	s_add_u32 s42, s24, 0x80000
	v_lshl_add_u64 v[218:219], s[24:25], 0, v[174:175]
	s_addc_u32 s43, s25, 0
	s_add_i32 s41, s46, s29
	global_load_lds_dwordx4 v[218:219], off
	v_lshl_add_u64 v[220:221], s[42:43], 0, v[178:179]
	s_mov_b32 m0, s41
	v_lshl_add_u64 v[222:223], s[26:27], 0, v[176:177]
	global_load_lds_dwordx4 v[220:221], off
	s_add_i32 m0, s41, 0x2000
	v_lshl_add_u64 v[220:221], s[42:43], 0, v[174:175]
	global_load_lds_dwordx4 v[220:221], off
	s_mov_b32 m0, s17
	v_lshl_add_u64 v[220:221], s[26:27], 0, v[180:181]
	global_load_lds_dwordx4 v[220:221], off
	s_mov_b32 m0, s31
	s_nop 0
	global_load_lds_dwordx4 v[222:223], off
	s_waitcnt vmcnt(24) lgkmcnt(0)
	s_barrier
	s_setprio 1
	v_mfma_f32_16x16x32_bf16 v[62:65], v[130:133], v[162:165], 0
	v_mfma_f32_16x16x32_bf16 v[58:61], v[138:141], v[162:165], 0
	v_mfma_f32_16x16x32_bf16 v[46:49], v[130:133], v[170:173], 0
	v_mfma_f32_16x16x32_bf16 v[42:45], v[138:141], v[170:173], 0
	v_mfma_f32_16x16x32_bf16 v[30:33], v[130:133], v[196:199], 0
	v_mfma_f32_16x16x32_bf16 v[26:29], v[138:141], v[196:199], 0
	v_mfma_f32_16x16x32_bf16 v[14:17], v[130:133], v[204:207], 0
	v_mfma_f32_16x16x32_bf16 v[10:13], v[138:141], v[204:207], 0
	v_mfma_f32_16x16x32_bf16 v[62:65], v[134:137], v[166:169], v[62:65]
	v_mfma_f32_16x16x32_bf16 v[58:61], v[142:145], v[166:169], v[58:61]
	v_mfma_f32_16x16x32_bf16 v[46:49], v[134:137], v[186:189], v[46:49]
	v_mfma_f32_16x16x32_bf16 v[42:45], v[142:145], v[186:189], v[42:45]
	v_mfma_f32_16x16x32_bf16 v[30:33], v[134:137], v[200:203], v[30:33]
	v_mfma_f32_16x16x32_bf16 v[26:29], v[142:145], v[200:203], v[26:29]
	v_mfma_f32_16x16x32_bf16 v[14:17], v[134:137], v[208:211], v[14:17]
	v_mfma_f32_16x16x32_bf16 v[10:13], v[142:145], v[208:211], v[10:13]
	s_setprio 0
	s_setprio 1
	v_mfma_f32_16x16x32_bf16 v[54:57], v[146:149], v[162:165], 0
	v_mfma_f32_16x16x32_bf16 v[50:53], v[154:157], v[162:165], 0
	v_mfma_f32_16x16x32_bf16 v[38:41], v[146:149], v[170:173], 0
	v_mfma_f32_16x16x32_bf16 v[34:37], v[154:157], v[170:173], 0
	v_mfma_f32_16x16x32_bf16 v[22:25], v[146:149], v[196:199], 0
	v_mfma_f32_16x16x32_bf16 v[18:21], v[154:157], v[196:199], 0
	v_mfma_f32_16x16x32_bf16 v[6:9], v[146:149], v[204:207], 0
	v_mfma_f32_16x16x32_bf16 v[2:5], v[154:157], v[204:207], 0
	v_mfma_f32_16x16x32_bf16 v[54:57], v[150:153], v[166:169], v[54:57]
	v_mfma_f32_16x16x32_bf16 v[50:53], v[158:161], v[166:169], v[50:53]
	v_mfma_f32_16x16x32_bf16 v[38:41], v[150:153], v[186:189], v[38:41]
	v_mfma_f32_16x16x32_bf16 v[34:37], v[158:161], v[186:189], v[34:37]
	v_mfma_f32_16x16x32_bf16 v[22:25], v[150:153], v[200:203], v[22:25]
	v_mfma_f32_16x16x32_bf16 v[18:21], v[158:161], v[200:203], v[18:21]
	v_mfma_f32_16x16x32_bf16 v[6:9], v[150:153], v[208:211], v[6:9]
	v_mfma_f32_16x16x32_bf16 v[2:5], v[158:161], v[208:211], v[2:5]
	s_setprio 0
	s_barrier
	s_add_i32 s41, 0, 0x18000
	s_add_i32 s42, 0, 0x1c000
	v_add_u32_e32 v142, s41, v214
	v_add_u32_e32 v158, s42, v214
	ds_read_b128 v[130:133], v142
	ds_read_b128 v[134:137], v142 offset:1024
	ds_read_b128 v[138:141], v142 offset:2048
	ds_read_b128 v[142:145], v142 offset:3072
	ds_read_b128 v[146:149], v158
	ds_read_b128 v[150:153], v158 offset:1024
	ds_read_b128 v[154:157], v158 offset:2048
	ds_read_b128 v[158:161], v158 offset:3072
	s_add_u32 s26, s26, 0x80000
	s_addc_u32 s27, s27, 0
	s_mov_b32 m0, s34
	v_lshl_add_u64 v[224:225], s[26:27], 0, v[180:181]
	ds_read_b128 v[162:165], v216 offset:32768
	ds_read_b128 v[166:169], v216 offset:33792
	ds_read_b128 v[170:173], v216 offset:34816
	ds_read_b128 v[186:189], v216 offset:35840
	ds_read_b128 v[196:199], v216 offset:36864
	ds_read_b128 v[200:203], v216 offset:37888
	ds_read_b128 v[204:207], v216 offset:38912
	ds_read_b128 v[208:211], v216 offset:39936
	global_load_lds_dwordx4 v[224:225], off
	s_mov_b32 m0, s35
	v_lshl_add_u64 v[224:225], s[26:27], 0, v[176:177]
	global_load_lds_dwordx4 v[224:225], off
	s_waitcnt vmcnt(8) lgkmcnt(0)
	s_barrier
	s_setprio 1
	v_mfma_f32_16x16x32_bf16 v[126:129], v[130:133], v[162:165], v[126:129]
	v_mfma_f32_16x16x32_bf16 v[122:125], v[138:141], v[162:165], v[122:125]
	v_mfma_f32_16x16x32_bf16 v[110:113], v[130:133], v[170:173], v[110:113]
	v_mfma_f32_16x16x32_bf16 v[106:109], v[138:141], v[170:173], v[106:109]
	v_mfma_f32_16x16x32_bf16 v[94:97], v[130:133], v[196:199], v[94:97]
	v_mfma_f32_16x16x32_bf16 v[90:93], v[138:141], v[196:199], v[90:93]
	v_mfma_f32_16x16x32_bf16 v[78:81], v[130:133], v[204:207], v[78:81]
	v_mfma_f32_16x16x32_bf16 v[74:77], v[138:141], v[204:207], v[74:77]
	v_mfma_f32_16x16x32_bf16 v[126:129], v[134:137], v[166:169], v[126:129]
	v_mfma_f32_16x16x32_bf16 v[122:125], v[142:145], v[166:169], v[122:125]
	v_mfma_f32_16x16x32_bf16 v[110:113], v[134:137], v[186:189], v[110:113]
	v_mfma_f32_16x16x32_bf16 v[106:109], v[142:145], v[186:189], v[106:109]
	v_mfma_f32_16x16x32_bf16 v[94:97], v[134:137], v[200:203], v[94:97]
	v_mfma_f32_16x16x32_bf16 v[90:93], v[142:145], v[200:203], v[90:93]
	v_mfma_f32_16x16x32_bf16 v[78:81], v[134:137], v[208:211], v[78:81]
	v_mfma_f32_16x16x32_bf16 v[74:77], v[142:145], v[208:211], v[74:77]
	s_setprio 0
	s_setprio 1
	v_mfma_f32_16x16x32_bf16 v[118:121], v[146:149], v[162:165], v[118:121]
	v_mfma_f32_16x16x32_bf16 v[114:117], v[154:157], v[162:165], v[114:117]
	v_mfma_f32_16x16x32_bf16 v[102:105], v[146:149], v[170:173], v[102:105]
	v_mfma_f32_16x16x32_bf16 v[98:101], v[154:157], v[170:173], v[98:101]
	v_mfma_f32_16x16x32_bf16 v[86:89], v[146:149], v[196:199], v[86:89]
	v_mfma_f32_16x16x32_bf16 v[82:85], v[154:157], v[196:199], v[82:85]
	v_mfma_f32_16x16x32_bf16 v[70:73], v[146:149], v[204:207], v[70:73]
	v_mfma_f32_16x16x32_bf16 v[66:69], v[154:157], v[204:207], v[66:69]
	v_mfma_f32_16x16x32_bf16 v[118:121], v[150:153], v[166:169], v[118:121]
	v_mfma_f32_16x16x32_bf16 v[114:117], v[158:161], v[166:169], v[114:117]
	v_mfma_f32_16x16x32_bf16 v[102:105], v[150:153], v[186:189], v[102:105]
	v_mfma_f32_16x16x32_bf16 v[98:101], v[158:161], v[186:189], v[98:101]
	v_mfma_f32_16x16x32_bf16 v[86:89], v[150:153], v[200:203], v[86:89]
	v_mfma_f32_16x16x32_bf16 v[82:85], v[158:161], v[200:203], v[82:85]
	v_mfma_f32_16x16x32_bf16 v[70:73], v[150:153], v[208:211], v[70:73]
	v_mfma_f32_16x16x32_bf16 v[66:69], v[158:161], v[208:211], v[66:69]
	s_setprio 0
	s_barrier
	s_add_i32 s26, s41, s29
	v_lshl_add_u64 v[212:213], v[212:213], 0, s[58:59]
	s_mov_b32 m0, s26
	ds_read_b128 v[162:165], v216 offset:49152
	ds_read_b128 v[166:169], v216 offset:50176
	ds_read_b128 v[170:173], v216 offset:51200
	ds_read_b128 v[186:189], v216 offset:52224
	ds_read_b128 v[196:199], v216 offset:53248
	ds_read_b128 v[200:203], v216 offset:54272
	ds_read_b128 v[204:207], v216 offset:55296
	ds_read_b128 v[208:211], v216 offset:56320
	global_load_lds_dwordx4 v[212:213], off
	s_add_i32 m0, s26, 0x2000
	s_add_u32 s24, s24, 0x80080
	v_lshl_add_u64 v[212:213], v[218:219], 0, s[58:59]
	s_addc_u32 s25, s25, 0
	s_add_i32 s26, s42, s29
	global_load_lds_dwordx4 v[212:213], off
	s_mov_b32 m0, s26
	v_lshl_add_u64 v[212:213], s[24:25], 0, v[178:179]
	global_load_lds_dwordx4 v[212:213], off
	s_add_i32 m0, s26, 0x2000
	v_lshl_add_u64 v[212:213], s[24:25], 0, v[174:175]
	global_load_lds_dwordx4 v[212:213], off
	s_mov_b32 m0, s38
	v_lshl_add_u64 v[212:213], v[220:221], 0, s[58:59]
	global_load_lds_dwordx4 v[212:213], off
	s_mov_b32 m0, s39
	v_lshl_add_u64 v[212:213], v[222:223], 0, s[58:59]
	global_load_lds_dwordx4 v[212:213], off
	s_waitcnt vmcnt(8) lgkmcnt(0)
	s_barrier
	s_setprio 1
	v_mfma_f32_16x16x32_bf16 v[62:65], v[130:133], v[162:165], v[62:65]
	v_mfma_f32_16x16x32_bf16 v[58:61], v[138:141], v[162:165], v[58:61]
	v_mfma_f32_16x16x32_bf16 v[46:49], v[130:133], v[170:173], v[46:49]
	v_mfma_f32_16x16x32_bf16 v[42:45], v[138:141], v[170:173], v[42:45]
	v_mfma_f32_16x16x32_bf16 v[30:33], v[130:133], v[196:199], v[30:33]
	v_mfma_f32_16x16x32_bf16 v[26:29], v[138:141], v[196:199], v[26:29]
	v_mfma_f32_16x16x32_bf16 v[14:17], v[130:133], v[204:207], v[14:17]
	v_mfma_f32_16x16x32_bf16 v[10:13], v[138:141], v[204:207], v[10:13]
	v_mfma_f32_16x16x32_bf16 v[62:65], v[134:137], v[166:169], v[62:65]
	v_mfma_f32_16x16x32_bf16 v[58:61], v[142:145], v[166:169], v[58:61]
	v_mfma_f32_16x16x32_bf16 v[46:49], v[134:137], v[186:189], v[46:49]
	v_mfma_f32_16x16x32_bf16 v[42:45], v[142:145], v[186:189], v[42:45]
	v_mfma_f32_16x16x32_bf16 v[30:33], v[134:137], v[200:203], v[30:33]
	v_mfma_f32_16x16x32_bf16 v[26:29], v[142:145], v[200:203], v[26:29]
	v_mfma_f32_16x16x32_bf16 v[14:17], v[134:137], v[208:211], v[14:17]
	v_mfma_f32_16x16x32_bf16 v[10:13], v[142:145], v[208:211], v[10:13]
	s_setprio 0
	s_setprio 1
	v_mfma_f32_16x16x32_bf16 v[54:57], v[146:149], v[162:165], v[54:57]
	v_mfma_f32_16x16x32_bf16 v[50:53], v[154:157], v[162:165], v[50:53]
	v_mfma_f32_16x16x32_bf16 v[38:41], v[146:149], v[170:173], v[38:41]
	v_mfma_f32_16x16x32_bf16 v[34:37], v[154:157], v[170:173], v[34:37]
	v_mfma_f32_16x16x32_bf16 v[22:25], v[146:149], v[196:199], v[22:25]
	v_mfma_f32_16x16x32_bf16 v[18:21], v[154:157], v[196:199], v[18:21]
	v_mfma_f32_16x16x32_bf16 v[6:9], v[146:149], v[204:207], v[6:9]
	v_mfma_f32_16x16x32_bf16 v[2:5], v[154:157], v[204:207], v[2:5]
	v_mfma_f32_16x16x32_bf16 v[54:57], v[150:153], v[166:169], v[54:57]
	v_mfma_f32_16x16x32_bf16 v[50:53], v[158:161], v[166:169], v[50:53]
	v_mfma_f32_16x16x32_bf16 v[38:41], v[150:153], v[186:189], v[38:41]
	v_mfma_f32_16x16x32_bf16 v[34:37], v[158:161], v[186:189], v[34:37]
	v_mfma_f32_16x16x32_bf16 v[22:25], v[150:153], v[200:203], v[22:25]
	v_mfma_f32_16x16x32_bf16 v[18:21], v[158:161], v[200:203], v[18:21]
	v_mfma_f32_16x16x32_bf16 v[6:9], v[150:153], v[208:211], v[6:9]
	v_mfma_f32_16x16x32_bf16 v[2:5], v[158:161], v[208:211], v[2:5]
	s_setprio 0
	s_barrier
	s_add_i32 s40, s40, 2
	s_add_u32 s22, s22, 0x100
	s_addc_u32 s23, s23, 0
	s_add_u32 s21, s21, 0x100
	s_addc_u32 s33, s33, 0
	s_cmp_gt_u32 s40, 29
	s_cbranch_scc1 .Lpeel_done_1
	s_branch .LBB0_672
.Ltrip0_strict_1:
	s_add_u32 s24, s22, 0xfff80080
	s_addc_u32 s25, s23, -1
	s_add_i32 s41, 0, 0x10000
	s_cmp_eq_u32 s40, 28
	s_cselect_b32 s27, s11, s25
	s_cselect_b32 s26, s18, s24
	s_cselect_b32 s25, s9, s33
	s_cselect_b32 s24, s19, s21
	s_add_i32 s46, 0, 0x14000
	v_add_u32_e32 v142, s41, v214
	v_add_u32_e32 v158, s46, v214
	ds_read_b128 v[130:133], v142
	ds_read_b128 v[134:137], v142 offset:1024
	ds_read_b128 v[138:141], v142 offset:2048
	ds_read_b128 v[142:145], v142 offset:3072
	ds_read_b128 v[146:149], v158
	ds_read_b128 v[150:153], v158 offset:1024
	ds_read_b128 v[154:157], v158 offset:2048
	ds_read_b128 v[158:161], v158 offset:3072
	v_lshl_add_u64 v[212:213], s[22:23], 0, v[182:183]
	s_add_i32 m0, s17, 0xc000
	ds_read_b128 v[162:165], v216
	ds_read_b128 v[166:169], v216 offset:1024
	ds_read_b128 v[170:173], v216 offset:2048
	ds_read_b128 v[186:189], v216 offset:3072
	ds_read_b128 v[196:199], v216 offset:4096
	ds_read_b128 v[200:203], v216 offset:5120
	ds_read_b128 v[204:207], v216 offset:6144
	ds_read_b128 v[208:211], v216 offset:7168
	global_load_lds_dwordx4 v[212:213], off
	s_add_i32 m0, s17, 0xe000
	v_lshl_add_u64 v[212:213], s[22:23], 0, v[184:185]
	global_load_lds_dwordx4 v[212:213], off
	s_waitcnt vmcnt(8) lgkmcnt(0)
	s_barrier
	s_setprio 1
	v_mfma_f32_16x16x32_bf16 v[126:129], v[130:133], v[162:165], 0
	v_mfma_f32_16x16x32_bf16 v[122:125], v[138:141], v[162:165], 0
	v_mfma_f32_16x16x32_bf16 v[110:113], v[130:133], v[170:173], 0
	v_mfma_f32_16x16x32_bf16 v[106:109], v[138:141], v[170:173], 0
	v_mfma_f32_16x16x32_bf16 v[94:97], v[130:133], v[196:199], 0
	v_mfma_f32_16x16x32_bf16 v[90:93], v[138:141], v[196:199], 0
	v_mfma_f32_16x16x32_bf16 v[78:81], v[130:133], v[204:207], 0
	v_mfma_f32_16x16x32_bf16 v[74:77], v[138:141], v[204:207], 0
	v_mfma_f32_16x16x32_bf16 v[126:129], v[134:137], v[166:169], v[126:129]
	v_mfma_f32_16x16x32_bf16 v[122:125], v[142:145], v[166:169], v[122:125]
	v_mfma_f32_16x16x32_bf16 v[110:113], v[134:137], v[186:189], v[110:113]
	v_mfma_f32_16x16x32_bf16 v[106:109], v[142:145], v[186:189], v[106:109]
	v_mfma_f32_16x16x32_bf16 v[94:97], v[134:137], v[200:203], v[94:97]
	v_mfma_f32_16x16x32_bf16 v[90:93], v[142:145], v[200:203], v[90:93]
	v_mfma_f32_16x16x32_bf16 v[78:81], v[134:137], v[208:211], v[78:81]
	v_mfma_f32_16x16x32_bf16 v[74:77], v[142:145], v[208:211], v[74:77]
	s_setprio 0
	s_setprio 1
	v_mfma_f32_16x16x32_bf16 v[118:121], v[146:149], v[162:165], 0
	v_mfma_f32_16x16x32_bf16 v[114:117], v[154:157], v[162:165], 0
	v_mfma_f32_16x16x32_bf16 v[102:105], v[146:149], v[170:173], 0
	v_mfma_f32_16x16x32_bf16 v[98:101], v[154:157], v[170:173], 0
	v_mfma_f32_16x16x32_bf16 v[86:89], v[146:149], v[196:199], 0
	v_mfma_f32_16x16x32_bf16 v[82:85], v[154:157], v[196:199], 0
	v_mfma_f32_16x16x32_bf16 v[70:73], v[146:149], v[204:207], 0
	v_mfma_f32_16x16x32_bf16 v[66:69], v[154:157], v[204:207], 0
	v_mfma_f32_16x16x32_bf16 v[118:121], v[150:153], v[166:169], v[118:121]
	v_mfma_f32_16x16x32_bf16 v[114:117], v[158:161], v[166:169], v[114:117]
	v_mfma_f32_16x16x32_bf16 v[102:105], v[150:153], v[186:189], v[102:105]
	v_mfma_f32_16x16x32_bf16 v[98:101], v[158:161], v[186:189], v[98:101]
	v_mfma_f32_16x16x32_bf16 v[86:89], v[150:153], v[200:203], v[86:89]
	v_mfma_f32_16x16x32_bf16 v[82:85], v[158:161], v[200:203], v[82:85]
	v_mfma_f32_16x16x32_bf16 v[70:73], v[150:153], v[208:211], v[70:73]
	v_mfma_f32_16x16x32_bf16 v[66:69], v[158:161], v[208:211], v[66:69]
	s_setprio 0
	s_barrier
	s_add_i32 s41, s41, s29
	v_lshl_add_u64 v[212:213], s[24:25], 0, v[178:179]
	s_mov_b32 m0, s41
	ds_read_b128 v[162:165], v216 offset:16384
	ds_read_b128 v[166:169], v216 offset:17408
	ds_read_b128 v[170:173], v216 offset:18432
	ds_read_b128 v[186:189], v216 offset:19456
	ds_read_b128 v[196:199], v216 offset:20480
	ds_read_b128 v[200:203], v216 offset:21504
	ds_read_b128 v[204:207], v216 offset:22528
	ds_read_b128 v[208:211], v216 offset:23552
	global_load_lds_dwordx4 v[212:213], off
	s_add_i32 m0, s41, 0x2000
	s_add_u32 s42, s24, 0x80000
	v_lshl_add_u64 v[218:219], s[24:25], 0, v[174:175]
	s_addc_u32 s43, s25, 0
	s_add_i32 s41, s46, s29
	global_load_lds_dwordx4 v[218:219], off
	v_lshl_add_u64 v[220:221], s[42:43], 0, v[178:179]
	s_mov_b32 m0, s41
	v_lshl_add_u64 v[222:223], s[26:27], 0, v[176:177]
	global_load_lds_dwordx4 v[220:221], off
	s_add_i32 m0, s41, 0x2000
	v_lshl_add_u64 v[220:221], s[42:43], 0, v[174:175]
	global_load_lds_dwordx4 v[220:221], off
	s_mov_b32 m0, s17
	v_lshl_add_u64 v[220:221], s[26:27], 0, v[180:181]
	global_load_lds_dwordx4 v[220:221], off
	s_mov_b32 m0, s31
	s_nop 0
	global_load_lds_dwordx4 v[222:223], off
	s_waitcnt vmcnt(8) lgkmcnt(0)
	s_barrier
	s_setprio 1
	v_mfma_f32_16x16x32_bf16 v[62:65], v[130:133], v[162:165], 0
	v_mfma_f32_16x16x32_bf16 v[58:61], v[138:141], v[162:165], 0
	v_mfma_f32_16x16x32_bf16 v[46:49], v[130:133], v[170:173], 0
	v_mfma_f32_16x16x32_bf16 v[42:45], v[138:141], v[170:173], 0
	v_mfma_f32_16x16x32_bf16 v[30:33], v[130:133], v[196:199], 0
	v_mfma_f32_16x16x32_bf16 v[26:29], v[138:141], v[196:199], 0
	v_mfma_f32_16x16x32_bf16 v[14:17], v[130:133], v[204:207], 0
	v_mfma_f32_16x16x32_bf16 v[10:13], v[138:141], v[204:207], 0
	v_mfma_f32_16x16x32_bf16 v[62:65], v[134:137], v[166:169], v[62:65]
	v_mfma_f32_16x16x32_bf16 v[58:61], v[142:145], v[166:169], v[58:61]
	v_mfma_f32_16x16x32_bf16 v[46:49], v[134:137], v[186:189], v[46:49]
	v_mfma_f32_16x16x32_bf16 v[42:45], v[142:145], v[186:189], v[42:45]
	v_mfma_f32_16x16x32_bf16 v[30:33], v[134:137], v[200:203], v[30:33]
	v_mfma_f32_16x16x32_bf16 v[26:29], v[142:145], v[200:203], v[26:29]
	v_mfma_f32_16x16x32_bf16 v[14:17], v[134:137], v[208:211], v[14:17]
	v_mfma_f32_16x16x32_bf16 v[10:13], v[142:145], v[208:211], v[10:13]
	s_setprio 0
	s_setprio 1
	v_mfma_f32_16x16x32_bf16 v[54:57], v[146:149], v[162:165], 0
	v_mfma_f32_16x16x32_bf16 v[50:53], v[154:157], v[162:165], 0
	v_mfma_f32_16x16x32_bf16 v[38:41], v[146:149], v[170:173], 0
	v_mfma_f32_16x16x32_bf16 v[34:37], v[154:157], v[170:173], 0
	v_mfma_f32_16x16x32_bf16 v[22:25], v[146:149], v[196:199], 0
	v_mfma_f32_16x16x32_bf16 v[18:21], v[154:157], v[196:199], 0
	v_mfma_f32_16x16x32_bf16 v[6:9], v[146:149], v[204:207], 0
	v_mfma_f32_16x16x32_bf16 v[2:5], v[154:157], v[204:207], 0
	v_mfma_f32_16x16x32_bf16 v[54:57], v[150:153], v[166:169], v[54:57]
	v_mfma_f32_16x16x32_bf16 v[50:53], v[158:161], v[166:169], v[50:53]
	v_mfma_f32_16x16x32_bf16 v[38:41], v[150:153], v[186:189], v[38:41]
	v_mfma_f32_16x16x32_bf16 v[34:37], v[158:161], v[186:189], v[34:37]
	v_mfma_f32_16x16x32_bf16 v[22:25], v[150:153], v[200:203], v[22:25]
	v_mfma_f32_16x16x32_bf16 v[18:21], v[158:161], v[200:203], v[18:21]
	v_mfma_f32_16x16x32_bf16 v[6:9], v[150:153], v[208:211], v[6:9]
	v_mfma_f32_16x16x32_bf16 v[2:5], v[158:161], v[208:211], v[2:5]
	s_setprio 0
	s_barrier
	s_add_i32 s41, 0, 0x18000
	s_add_i32 s42, 0, 0x1c000
	v_add_u32_e32 v142, s41, v214
	v_add_u32_e32 v158, s42, v214
	ds_read_b128 v[130:133], v142
	ds_read_b128 v[134:137], v142 offset:1024
	ds_read_b128 v[138:141], v142 offset:2048
	ds_read_b128 v[142:145], v142 offset:3072
	ds_read_b128 v[146:149], v158
	ds_read_b128 v[150:153], v158 offset:1024
	ds_read_b128 v[154:157], v158 offset:2048
	ds_read_b128 v[158:161], v158 offset:3072
	s_add_u32 s26, s26, 0x80000
	s_addc_u32 s27, s27, 0
	s_mov_b32 m0, s34
	v_lshl_add_u64 v[224:225], s[26:27], 0, v[180:181]
	ds_read_b128 v[162:165], v216 offset:32768
	ds_read_b128 v[166:169], v216 offset:33792
	ds_read_b128 v[170:173], v216 offset:34816
	ds_read_b128 v[186:189], v216 offset:35840
	ds_read_b128 v[196:199], v216 offset:36864
	ds_read_b128 v[200:203], v216 offset:37888
	ds_read_b128 v[204:207], v216 offset:38912
	ds_read_b128 v[208:211], v216 offset:39936
	global_load_lds_dwordx4 v[224:225], off
	s_mov_b32 m0, s35
	v_lshl_add_u64 v[224:225], s[26:27], 0, v[176:177]
	global_load_lds_dwordx4 v[224:225], off
	s_waitcnt vmcnt(8) lgkmcnt(0)
	s_barrier
	s_setprio 1
	v_mfma_f32_16x16x32_bf16 v[126:129], v[130:133], v[162:165], v[126:129]
	v_mfma_f32_16x16x32_bf16 v[122:125], v[138:141], v[162:165], v[122:125]
	v_mfma_f32_16x16x32_bf16 v[110:113], v[130:133], v[170:173], v[110:113]
	v_mfma_f32_16x16x32_bf16 v[106:109], v[138:141], v[170:173], v[106:109]
	v_mfma_f32_16x16x32_bf16 v[94:97], v[130:133], v[196:199], v[94:97]
	v_mfma_f32_16x16x32_bf16 v[90:93], v[138:141], v[196:199], v[90:93]
	v_mfma_f32_16x16x32_bf16 v[78:81], v[130:133], v[204:207], v[78:81]
	v_mfma_f32_16x16x32_bf16 v[74:77], v[138:141], v[204:207], v[74:77]
	v_mfma_f32_16x16x32_bf16 v[126:129], v[134:137], v[166:169], v[126:129]
	v_mfma_f32_16x16x32_bf16 v[122:125], v[142:145], v[166:169], v[122:125]
	v_mfma_f32_16x16x32_bf16 v[110:113], v[134:137], v[186:189], v[110:113]
	v_mfma_f32_16x16x32_bf16 v[106:109], v[142:145], v[186:189], v[106:109]
	v_mfma_f32_16x16x32_bf16 v[94:97], v[134:137], v[200:203], v[94:97]
	v_mfma_f32_16x16x32_bf16 v[90:93], v[142:145], v[200:203], v[90:93]
	v_mfma_f32_16x16x32_bf16 v[78:81], v[134:137], v[208:211], v[78:81]
	v_mfma_f32_16x16x32_bf16 v[74:77], v[142:145], v[208:211], v[74:77]
	s_setprio 0
	s_setprio 1
	v_mfma_f32_16x16x32_bf16 v[118:121], v[146:149], v[162:165], v[118:121]
	v_mfma_f32_16x16x32_bf16 v[114:117], v[154:157], v[162:165], v[114:117]
	v_mfma_f32_16x16x32_bf16 v[102:105], v[146:149], v[170:173], v[102:105]
	v_mfma_f32_16x16x32_bf16 v[98:101], v[154:157], v[170:173], v[98:101]
	v_mfma_f32_16x16x32_bf16 v[86:89], v[146:149], v[196:199], v[86:89]
	v_mfma_f32_16x16x32_bf16 v[82:85], v[154:157], v[196:199], v[82:85]
	v_mfma_f32_16x16x32_bf16 v[70:73], v[146:149], v[204:207], v[70:73]
	v_mfma_f32_16x16x32_bf16 v[66:69], v[154:157], v[204:207], v[66:69]
	v_mfma_f32_16x16x32_bf16 v[118:121], v[150:153], v[166:169], v[118:121]
	v_mfma_f32_16x16x32_bf16 v[114:117], v[158:161], v[166:169], v[114:117]
	v_mfma_f32_16x16x32_bf16 v[102:105], v[150:153], v[186:189], v[102:105]
	v_mfma_f32_16x16x32_bf16 v[98:101], v[158:161], v[186:189], v[98:101]
	v_mfma_f32_16x16x32_bf16 v[86:89], v[150:153], v[200:203], v[86:89]
	v_mfma_f32_16x16x32_bf16 v[82:85], v[158:161], v[200:203], v[82:85]
	v_mfma_f32_16x16x32_bf16 v[70:73], v[150:153], v[208:211], v[70:73]
	v_mfma_f32_16x16x32_bf16 v[66:69], v[158:161], v[208:211], v[66:69]
	s_setprio 0
	s_barrier
	s_add_i32 s26, s41, s29
	v_lshl_add_u64 v[212:213], v[212:213], 0, s[58:59]
	s_mov_b32 m0, s26
	ds_read_b128 v[162:165], v216 offset:49152
	ds_read_b128 v[166:169], v216 offset:50176
	ds_read_b128 v[170:173], v216 offset:51200
	ds_read_b128 v[186:189], v216 offset:52224
	ds_read_b128 v[196:199], v216 offset:53248
	ds_read_b128 v[200:203], v216 offset:54272
	ds_read_b128 v[204:207], v216 offset:55296
	ds_read_b128 v[208:211], v216 offset:56320
	global_load_lds_dwordx4 v[212:213], off
	s_add_i32 m0, s26, 0x2000
	s_add_u32 s24, s24, 0x80080
	v_lshl_add_u64 v[212:213], v[218:219], 0, s[58:59]
	s_addc_u32 s25, s25, 0
	s_add_i32 s26, s42, s29
	global_load_lds_dwordx4 v[212:213], off
	s_mov_b32 m0, s26
	v_lshl_add_u64 v[212:213], s[24:25], 0, v[178:179]
	global_load_lds_dwordx4 v[212:213], off
	s_add_i32 m0, s26, 0x2000
	v_lshl_add_u64 v[212:213], s[24:25], 0, v[174:175]
	global_load_lds_dwordx4 v[212:213], off
	s_mov_b32 m0, s38
	v_lshl_add_u64 v[212:213], v[220:221], 0, s[58:59]
	global_load_lds_dwordx4 v[212:213], off
	s_mov_b32 m0, s39
	v_lshl_add_u64 v[212:213], v[222:223], 0, s[58:59]
	global_load_lds_dwordx4 v[212:213], off
	s_waitcnt vmcnt(8) lgkmcnt(0)
	s_barrier
	s_setprio 1
	v_mfma_f32_16x16x32_bf16 v[62:65], v[130:133], v[162:165], v[62:65]
	v_mfma_f32_16x16x32_bf16 v[58:61], v[138:141], v[162:165], v[58:61]
	v_mfma_f32_16x16x32_bf16 v[46:49], v[130:133], v[170:173], v[46:49]
	v_mfma_f32_16x16x32_bf16 v[42:45], v[138:141], v[170:173], v[42:45]
	v_mfma_f32_16x16x32_bf16 v[30:33], v[130:133], v[196:199], v[30:33]
	v_mfma_f32_16x16x32_bf16 v[26:29], v[138:141], v[196:199], v[26:29]
	v_mfma_f32_16x16x32_bf16 v[14:17], v[130:133], v[204:207], v[14:17]
	v_mfma_f32_16x16x32_bf16 v[10:13], v[138:141], v[204:207], v[10:13]
	v_mfma_f32_16x16x32_bf16 v[62:65], v[134:137], v[166:169], v[62:65]
	v_mfma_f32_16x16x32_bf16 v[58:61], v[142:145], v[166:169], v[58:61]
	v_mfma_f32_16x16x32_bf16 v[46:49], v[134:137], v[186:189], v[46:49]
	v_mfma_f32_16x16x32_bf16 v[42:45], v[142:145], v[186:189], v[42:45]
	v_mfma_f32_16x16x32_bf16 v[30:33], v[134:137], v[200:203], v[30:33]
	v_mfma_f32_16x16x32_bf16 v[26:29], v[142:145], v[200:203], v[26:29]
	v_mfma_f32_16x16x32_bf16 v[14:17], v[134:137], v[208:211], v[14:17]
	v_mfma_f32_16x16x32_bf16 v[10:13], v[142:145], v[208:211], v[10:13]
	s_setprio 0
	s_setprio 1
	v_mfma_f32_16x16x32_bf16 v[54:57], v[146:149], v[162:165], v[54:57]
	v_mfma_f32_16x16x32_bf16 v[50:53], v[154:157], v[162:165], v[50:53]
	v_mfma_f32_16x16x32_bf16 v[38:41], v[146:149], v[170:173], v[38:41]
	v_mfma_f32_16x16x32_bf16 v[34:37], v[154:157], v[170:173], v[34:37]
	v_mfma_f32_16x16x32_bf16 v[22:25], v[146:149], v[196:199], v[22:25]
	v_mfma_f32_16x16x32_bf16 v[18:21], v[154:157], v[196:199], v[18:21]
	v_mfma_f32_16x16x32_bf16 v[6:9], v[146:149], v[204:207], v[6:9]
	v_mfma_f32_16x16x32_bf16 v[2:5], v[154:157], v[204:207], v[2:5]
	v_mfma_f32_16x16x32_bf16 v[54:57], v[150:153], v[166:169], v[54:57]
	v_mfma_f32_16x16x32_bf16 v[50:53], v[158:161], v[166:169], v[50:53]
	v_mfma_f32_16x16x32_bf16 v[38:41], v[150:153], v[186:189], v[38:41]
	v_mfma_f32_16x16x32_bf16 v[34:37], v[158:161], v[186:189], v[34:37]
	v_mfma_f32_16x16x32_bf16 v[22:25], v[150:153], v[200:203], v[22:25]
	v_mfma_f32_16x16x32_bf16 v[18:21], v[158:161], v[200:203], v[18:21]
	v_mfma_f32_16x16x32_bf16 v[6:9], v[150:153], v[208:211], v[6:9]
	v_mfma_f32_16x16x32_bf16 v[2:5], v[158:161], v[208:211], v[2:5]
	s_setprio 0
	s_barrier
	s_add_i32 s40, s40, 2
	s_add_u32 s22, s22, 0x100
	s_addc_u32 s23, s23, 0
	s_add_u32 s21, s21, 0x100
	s_addc_u32 s33, s33, 0
	s_cmp_gt_u32 s40, 29
	s_cbranch_scc1 .Lpeel_done_1
.LBB0_672:
	s_add_u32 s24, s22, 0xfff80080
	s_addc_u32 s25, s23, -1
	s_add_i32 s41, 0, 0x10000
	s_cmp_eq_u32 s40, 28
	s_cselect_b32 s27, s11, s25
	s_cselect_b32 s26, s18, s24
	s_cselect_b32 s25, s9, s33
	s_cselect_b32 s24, s19, s21
	s_add_i32 s46, 0, 0x14000
	v_add_u32_e32 v142, s41, v214
	v_add_u32_e32 v158, s46, v214
	ds_read_b128 v[130:133], v142
	ds_read_b128 v[134:137], v142 offset:1024
	ds_read_b128 v[138:141], v142 offset:2048
	ds_read_b128 v[142:145], v142 offset:3072
	ds_read_b128 v[146:149], v158
	ds_read_b128 v[150:153], v158 offset:1024
	ds_read_b128 v[154:157], v158 offset:2048
	ds_read_b128 v[158:161], v158 offset:3072
	v_lshl_add_u64 v[212:213], s[22:23], 0, v[182:183]
	s_add_i32 m0, s17, 0xc000
	ds_read_b128 v[162:165], v216
	ds_read_b128 v[166:169], v216 offset:1024
	ds_read_b128 v[170:173], v216 offset:2048
	ds_read_b128 v[186:189], v216 offset:3072
	ds_read_b128 v[196:199], v216 offset:4096
	ds_read_b128 v[200:203], v216 offset:5120
	ds_read_b128 v[204:207], v216 offset:6144
	ds_read_b128 v[208:211], v216 offset:7168
	global_load_lds_dwordx4 v[212:213], off
	s_add_i32 m0, s17, 0xe000
	v_lshl_add_u64 v[212:213], s[22:23], 0, v[184:185]
	global_load_lds_dwordx4 v[212:213], off
	s_waitcnt vmcnt(8) lgkmcnt(0)
	s_barrier
	s_setprio 1
	v_mfma_f32_16x16x32_bf16 v[126:129], v[130:133], v[162:165], v[126:129]
	v_mfma_f32_16x16x32_bf16 v[122:125], v[138:141], v[162:165], v[122:125]
	v_mfma_f32_16x16x32_bf16 v[110:113], v[130:133], v[170:173], v[110:113]
	v_mfma_f32_16x16x32_bf16 v[106:109], v[138:141], v[170:173], v[106:109]
	v_mfma_f32_16x16x32_bf16 v[94:97], v[130:133], v[196:199], v[94:97]
	v_mfma_f32_16x16x32_bf16 v[90:93], v[138:141], v[196:199], v[90:93]
	v_mfma_f32_16x16x32_bf16 v[78:81], v[130:133], v[204:207], v[78:81]
	v_mfma_f32_16x16x32_bf16 v[74:77], v[138:141], v[204:207], v[74:77]
	v_mfma_f32_16x16x32_bf16 v[126:129], v[134:137], v[166:169], v[126:129]
	v_mfma_f32_16x16x32_bf16 v[122:125], v[142:145], v[166:169], v[122:125]
	v_mfma_f32_16x16x32_bf16 v[110:113], v[134:137], v[186:189], v[110:113]
	v_mfma_f32_16x16x32_bf16 v[106:109], v[142:145], v[186:189], v[106:109]
	v_mfma_f32_16x16x32_bf16 v[94:97], v[134:137], v[200:203], v[94:97]
	v_mfma_f32_16x16x32_bf16 v[90:93], v[142:145], v[200:203], v[90:93]
	v_mfma_f32_16x16x32_bf16 v[78:81], v[134:137], v[208:211], v[78:81]
	v_mfma_f32_16x16x32_bf16 v[74:77], v[142:145], v[208:211], v[74:77]
	s_setprio 0
	s_setprio 1
	v_mfma_f32_16x16x32_bf16 v[118:121], v[146:149], v[162:165], v[118:121]
	v_mfma_f32_16x16x32_bf16 v[114:117], v[154:157], v[162:165], v[114:117]
	v_mfma_f32_16x16x32_bf16 v[102:105], v[146:149], v[170:173], v[102:105]
	v_mfma_f32_16x16x32_bf16 v[98:101], v[154:157], v[170:173], v[98:101]
	v_mfma_f32_16x16x32_bf16 v[86:89], v[146:149], v[196:199], v[86:89]
	v_mfma_f32_16x16x32_bf16 v[82:85], v[154:157], v[196:199], v[82:85]
	v_mfma_f32_16x16x32_bf16 v[70:73], v[146:149], v[204:207], v[70:73]
	v_mfma_f32_16x16x32_bf16 v[66:69], v[154:157], v[204:207], v[66:69]
	v_mfma_f32_16x16x32_bf16 v[118:121], v[150:153], v[166:169], v[118:121]
	v_mfma_f32_16x16x32_bf16 v[114:117], v[158:161], v[166:169], v[114:117]
	v_mfma_f32_16x16x32_bf16 v[102:105], v[150:153], v[186:189], v[102:105]
	v_mfma_f32_16x16x32_bf16 v[98:101], v[158:161], v[186:189], v[98:101]
	v_mfma_f32_16x16x32_bf16 v[86:89], v[150:153], v[200:203], v[86:89]
	v_mfma_f32_16x16x32_bf16 v[82:85], v[158:161], v[200:203], v[82:85]
	v_mfma_f32_16x16x32_bf16 v[70:73], v[150:153], v[208:211], v[70:73]
	v_mfma_f32_16x16x32_bf16 v[66:69], v[158:161], v[208:211], v[66:69]
	s_setprio 0
	s_barrier
	s_add_i32 s41, s41, s29
	v_lshl_add_u64 v[212:213], s[24:25], 0, v[178:179]
	s_mov_b32 m0, s41
	ds_read_b128 v[162:165], v216 offset:16384
	ds_read_b128 v[166:169], v216 offset:17408
	ds_read_b128 v[170:173], v216 offset:18432
	ds_read_b128 v[186:189], v216 offset:19456
	ds_read_b128 v[196:199], v216 offset:20480
	ds_read_b128 v[200:203], v216 offset:21504
	ds_read_b128 v[204:207], v216 offset:22528
	ds_read_b128 v[208:211], v216 offset:23552
	global_load_lds_dwordx4 v[212:213], off
	s_add_i32 m0, s41, 0x2000
	s_add_u32 s42, s24, 0x80000
	v_lshl_add_u64 v[218:219], s[24:25], 0, v[174:175]
	s_addc_u32 s43, s25, 0
	s_add_i32 s41, s46, s29
	global_load_lds_dwordx4 v[218:219], off
	v_lshl_add_u64 v[220:221], s[42:43], 0, v[178:179]
	s_mov_b32 m0, s41
	v_lshl_add_u64 v[222:223], s[26:27], 0, v[176:177]
	global_load_lds_dwordx4 v[220:221], off
	s_add_i32 m0, s41, 0x2000
	v_lshl_add_u64 v[220:221], s[42:43], 0, v[174:175]
	global_load_lds_dwordx4 v[220:221], off
	s_mov_b32 m0, s17
	v_lshl_add_u64 v[220:221], s[26:27], 0, v[180:181]
	global_load_lds_dwordx4 v[220:221], off
	s_mov_b32 m0, s31
	s_nop 0
	global_load_lds_dwordx4 v[222:223], off
	s_waitcnt vmcnt(8) lgkmcnt(0)
	s_barrier
	s_setprio 1
	v_mfma_f32_16x16x32_bf16 v[62:65], v[130:133], v[162:165], v[62:65]
	v_mfma_f32_16x16x32_bf16 v[58:61], v[138:141], v[162:165], v[58:61]
	v_mfma_f32_16x16x32_bf16 v[46:49], v[130:133], v[170:173], v[46:49]
	v_mfma_f32_16x16x32_bf16 v[42:45], v[138:141], v[170:173], v[42:45]
	v_mfma_f32_16x16x32_bf16 v[30:33], v[130:133], v[196:199], v[30:33]
	v_mfma_f32_16x16x32_bf16 v[26:29], v[138:141], v[196:199], v[26:29]
	v_mfma_f32_16x16x32_bf16 v[14:17], v[130:133], v[204:207], v[14:17]
	v_mfma_f32_16x16x32_bf16 v[10:13], v[138:141], v[204:207], v[10:13]
	v_mfma_f32_16x16x32_bf16 v[62:65], v[134:137], v[166:169], v[62:65]
	v_mfma_f32_16x16x32_bf16 v[58:61], v[142:145], v[166:169], v[58:61]
	v_mfma_f32_16x16x32_bf16 v[46:49], v[134:137], v[186:189], v[46:49]
	v_mfma_f32_16x16x32_bf16 v[42:45], v[142:145], v[186:189], v[42:45]
	v_mfma_f32_16x16x32_bf16 v[30:33], v[134:137], v[200:203], v[30:33]
	v_mfma_f32_16x16x32_bf16 v[26:29], v[142:145], v[200:203], v[26:29]
	v_mfma_f32_16x16x32_bf16 v[14:17], v[134:137], v[208:211], v[14:17]
	v_mfma_f32_16x16x32_bf16 v[10:13], v[142:145], v[208:211], v[10:13]
	s_setprio 0
	s_setprio 1
	v_mfma_f32_16x16x32_bf16 v[54:57], v[146:149], v[162:165], v[54:57]
	v_mfma_f32_16x16x32_bf16 v[50:53], v[154:157], v[162:165], v[50:53]
	v_mfma_f32_16x16x32_bf16 v[38:41], v[146:149], v[170:173], v[38:41]
	v_mfma_f32_16x16x32_bf16 v[34:37], v[154:157], v[170:173], v[34:37]
	v_mfma_f32_16x16x32_bf16 v[22:25], v[146:149], v[196:199], v[22:25]
	v_mfma_f32_16x16x32_bf16 v[18:21], v[154:157], v[196:199], v[18:21]
	v_mfma_f32_16x16x32_bf16 v[6:9], v[146:149], v[204:207], v[6:9]
	v_mfma_f32_16x16x32_bf16 v[2:5], v[154:157], v[204:207], v[2:5]
	v_mfma_f32_16x16x32_bf16 v[54:57], v[150:153], v[166:169], v[54:57]
	v_mfma_f32_16x16x32_bf16 v[50:53], v[158:161], v[166:169], v[50:53]
	v_mfma_f32_16x16x32_bf16 v[38:41], v[150:153], v[186:189], v[38:41]
	v_mfma_f32_16x16x32_bf16 v[34:37], v[158:161], v[186:189], v[34:37]
	v_mfma_f32_16x16x32_bf16 v[22:25], v[150:153], v[200:203], v[22:25]
	v_mfma_f32_16x16x32_bf16 v[18:21], v[158:161], v[200:203], v[18:21]
	v_mfma_f32_16x16x32_bf16 v[6:9], v[150:153], v[208:211], v[6:9]
	v_mfma_f32_16x16x32_bf16 v[2:5], v[158:161], v[208:211], v[2:5]
	s_setprio 0
	s_barrier
	s_add_i32 s41, 0, 0x18000
	s_add_i32 s42, 0, 0x1c000
	v_add_u32_e32 v142, s41, v214
	v_add_u32_e32 v158, s42, v214
	ds_read_b128 v[130:133], v142
	ds_read_b128 v[134:137], v142 offset:1024
	ds_read_b128 v[138:141], v142 offset:2048
	ds_read_b128 v[142:145], v142 offset:3072
	ds_read_b128 v[146:149], v158
	ds_read_b128 v[150:153], v158 offset:1024
	ds_read_b128 v[154:157], v158 offset:2048
	ds_read_b128 v[158:161], v158 offset:3072
	s_add_u32 s26, s26, 0x80000
	s_addc_u32 s27, s27, 0
	s_mov_b32 m0, s34
	v_lshl_add_u64 v[224:225], s[26:27], 0, v[180:181]
	ds_read_b128 v[162:165], v216 offset:32768
	ds_read_b128 v[166:169], v216 offset:33792
	ds_read_b128 v[170:173], v216 offset:34816
	ds_read_b128 v[186:189], v216 offset:35840
	ds_read_b128 v[196:199], v216 offset:36864
	ds_read_b128 v[200:203], v216 offset:37888
	ds_read_b128 v[204:207], v216 offset:38912
	ds_read_b128 v[208:211], v216 offset:39936
	global_load_lds_dwordx4 v[224:225], off
	s_mov_b32 m0, s35
	v_lshl_add_u64 v[224:225], s[26:27], 0, v[176:177]
	global_load_lds_dwordx4 v[224:225], off
	s_waitcnt vmcnt(8) lgkmcnt(0)
	s_barrier
	s_setprio 1
	v_mfma_f32_16x16x32_bf16 v[126:129], v[130:133], v[162:165], v[126:129]
	v_mfma_f32_16x16x32_bf16 v[122:125], v[138:141], v[162:165], v[122:125]
	v_mfma_f32_16x16x32_bf16 v[110:113], v[130:133], v[170:173], v[110:113]
	v_mfma_f32_16x16x32_bf16 v[106:109], v[138:141], v[170:173], v[106:109]
	v_mfma_f32_16x16x32_bf16 v[94:97], v[130:133], v[196:199], v[94:97]
	v_mfma_f32_16x16x32_bf16 v[90:93], v[138:141], v[196:199], v[90:93]
	v_mfma_f32_16x16x32_bf16 v[78:81], v[130:133], v[204:207], v[78:81]
	v_mfma_f32_16x16x32_bf16 v[74:77], v[138:141], v[204:207], v[74:77]
	v_mfma_f32_16x16x32_bf16 v[126:129], v[134:137], v[166:169], v[126:129]
	v_mfma_f32_16x16x32_bf16 v[122:125], v[142:145], v[166:169], v[122:125]
	v_mfma_f32_16x16x32_bf16 v[110:113], v[134:137], v[186:189], v[110:113]
	v_mfma_f32_16x16x32_bf16 v[106:109], v[142:145], v[186:189], v[106:109]
	v_mfma_f32_16x16x32_bf16 v[94:97], v[134:137], v[200:203], v[94:97]
	v_mfma_f32_16x16x32_bf16 v[90:93], v[142:145], v[200:203], v[90:93]
	v_mfma_f32_16x16x32_bf16 v[78:81], v[134:137], v[208:211], v[78:81]
	v_mfma_f32_16x16x32_bf16 v[74:77], v[142:145], v[208:211], v[74:77]
	s_setprio 0
	s_setprio 1
	v_mfma_f32_16x16x32_bf16 v[118:121], v[146:149], v[162:165], v[118:121]
	v_mfma_f32_16x16x32_bf16 v[114:117], v[154:157], v[162:165], v[114:117]
	v_mfma_f32_16x16x32_bf16 v[102:105], v[146:149], v[170:173], v[102:105]
	v_mfma_f32_16x16x32_bf16 v[98:101], v[154:157], v[170:173], v[98:101]
	v_mfma_f32_16x16x32_bf16 v[86:89], v[146:149], v[196:199], v[86:89]
	v_mfma_f32_16x16x32_bf16 v[82:85], v[154:157], v[196:199], v[82:85]
	v_mfma_f32_16x16x32_bf16 v[70:73], v[146:149], v[204:207], v[70:73]
	v_mfma_f32_16x16x32_bf16 v[66:69], v[154:157], v[204:207], v[66:69]
	v_mfma_f32_16x16x32_bf16 v[118:121], v[150:153], v[166:169], v[118:121]
	v_mfma_f32_16x16x32_bf16 v[114:117], v[158:161], v[166:169], v[114:117]
	v_mfma_f32_16x16x32_bf16 v[102:105], v[150:153], v[186:189], v[102:105]
	v_mfma_f32_16x16x32_bf16 v[98:101], v[158:161], v[186:189], v[98:101]
	v_mfma_f32_16x16x32_bf16 v[86:89], v[150:153], v[200:203], v[86:89]
	v_mfma_f32_16x16x32_bf16 v[82:85], v[158:161], v[200:203], v[82:85]
	v_mfma_f32_16x16x32_bf16 v[70:73], v[150:153], v[208:211], v[70:73]
	v_mfma_f32_16x16x32_bf16 v[66:69], v[158:161], v[208:211], v[66:69]
	s_setprio 0
	s_barrier
	s_add_i32 s26, s41, s29
	v_lshl_add_u64 v[212:213], v[212:213], 0, s[58:59]
	s_mov_b32 m0, s26
	ds_read_b128 v[162:165], v216 offset:49152
	ds_read_b128 v[166:169], v216 offset:50176
	ds_read_b128 v[170:173], v216 offset:51200
	ds_read_b128 v[186:189], v216 offset:52224
	ds_read_b128 v[196:199], v216 offset:53248
	ds_read_b128 v[200:203], v216 offset:54272
	ds_read_b128 v[204:207], v216 offset:55296
	ds_read_b128 v[208:211], v216 offset:56320
	global_load_lds_dwordx4 v[212:213], off
	s_add_i32 m0, s26, 0x2000
	s_add_u32 s24, s24, 0x80080
	v_lshl_add_u64 v[212:213], v[218:219], 0, s[58:59]
	s_addc_u32 s25, s25, 0
	s_add_i32 s26, s42, s29
	global_load_lds_dwordx4 v[212:213], off
	s_mov_b32 m0, s26
	v_lshl_add_u64 v[212:213], s[24:25], 0, v[178:179]
	global_load_lds_dwordx4 v[212:213], off
	s_add_i32 m0, s26, 0x2000
	v_lshl_add_u64 v[212:213], s[24:25], 0, v[174:175]
	global_load_lds_dwordx4 v[212:213], off
	s_mov_b32 m0, s38
	v_lshl_add_u64 v[212:213], v[220:221], 0, s[58:59]
	global_load_lds_dwordx4 v[212:213], off
	s_mov_b32 m0, s39
	v_lshl_add_u64 v[212:213], v[222:223], 0, s[58:59]
	global_load_lds_dwordx4 v[212:213], off
	s_waitcnt vmcnt(8) lgkmcnt(0)
	s_barrier
	s_setprio 1
	v_mfma_f32_16x16x32_bf16 v[62:65], v[130:133], v[162:165], v[62:65]
	v_mfma_f32_16x16x32_bf16 v[58:61], v[138:141], v[162:165], v[58:61]
	v_mfma_f32_16x16x32_bf16 v[46:49], v[130:133], v[170:173], v[46:49]
	v_mfma_f32_16x16x32_bf16 v[42:45], v[138:141], v[170:173], v[42:45]
	v_mfma_f32_16x16x32_bf16 v[30:33], v[130:133], v[196:199], v[30:33]
	v_mfma_f32_16x16x32_bf16 v[26:29], v[138:141], v[196:199], v[26:29]
	v_mfma_f32_16x16x32_bf16 v[14:17], v[130:133], v[204:207], v[14:17]
	v_mfma_f32_16x16x32_bf16 v[10:13], v[138:141], v[204:207], v[10:13]
	v_mfma_f32_16x16x32_bf16 v[62:65], v[134:137], v[166:169], v[62:65]
	v_mfma_f32_16x16x32_bf16 v[58:61], v[142:145], v[166:169], v[58:61]
	v_mfma_f32_16x16x32_bf16 v[46:49], v[134:137], v[186:189], v[46:49]
	v_mfma_f32_16x16x32_bf16 v[42:45], v[142:145], v[186:189], v[42:45]
	v_mfma_f32_16x16x32_bf16 v[30:33], v[134:137], v[200:203], v[30:33]
	v_mfma_f32_16x16x32_bf16 v[26:29], v[142:145], v[200:203], v[26:29]
	v_mfma_f32_16x16x32_bf16 v[14:17], v[134:137], v[208:211], v[14:17]
	v_mfma_f32_16x16x32_bf16 v[10:13], v[142:145], v[208:211], v[10:13]
	s_setprio 0
	s_setprio 1
	v_mfma_f32_16x16x32_bf16 v[54:57], v[146:149], v[162:165], v[54:57]
	v_mfma_f32_16x16x32_bf16 v[50:53], v[154:157], v[162:165], v[50:53]
	v_mfma_f32_16x16x32_bf16 v[38:41], v[146:149], v[170:173], v[38:41]
	v_mfma_f32_16x16x32_bf16 v[34:37], v[154:157], v[170:173], v[34:37]
	v_mfma_f32_16x16x32_bf16 v[22:25], v[146:149], v[196:199], v[22:25]
	v_mfma_f32_16x16x32_bf16 v[18:21], v[154:157], v[196:199], v[18:21]
	v_mfma_f32_16x16x32_bf16 v[6:9], v[146:149], v[204:207], v[6:9]
	v_mfma_f32_16x16x32_bf16 v[2:5], v[154:157], v[204:207], v[2:5]
	v_mfma_f32_16x16x32_bf16 v[54:57], v[150:153], v[166:169], v[54:57]
	v_mfma_f32_16x16x32_bf16 v[50:53], v[158:161], v[166:169], v[50:53]
	v_mfma_f32_16x16x32_bf16 v[38:41], v[150:153], v[186:189], v[38:41]
	v_mfma_f32_16x16x32_bf16 v[34:37], v[158:161], v[186:189], v[34:37]
	v_mfma_f32_16x16x32_bf16 v[22:25], v[150:153], v[200:203], v[22:25]
	v_mfma_f32_16x16x32_bf16 v[18:21], v[158:161], v[200:203], v[18:21]
	v_mfma_f32_16x16x32_bf16 v[6:9], v[150:153], v[208:211], v[6:9]
	v_mfma_f32_16x16x32_bf16 v[2:5], v[158:161], v[208:211], v[2:5]
	s_setprio 0
	s_barrier
	s_add_i32 s40, s40, 2
	s_add_u32 s22, s22, 0x100
	s_addc_u32 s23, s23, 0
	s_add_u32 s21, s21, 0x100
	s_addc_u32 s33, s33, 0
	s_cmp_gt_u32 s40, 29
	s_cbranch_scc0 .LBB0_672

.LBB0_747:
	s_ashr_i32 s9, s8, 31
	s_lshl_b64 s[10:11], s[8:9], 20
	s_add_u32 s10, s69, s10
	s_addc_u32 s11, s77, s11
	s_and_b64 s[12:13], s[4:5], exec
	s_cselect_b32 s9, s11, s17
	s_cselect_b32 s31, s10, s16
	s_ashr_i32 s7, s6, 31
	s_lshl_b64 s[12:13], s[6:7], 20
	v_readlane_b32 s22, v254, 42
	v_readlane_b32 s23, v254, 43
	s_add_u32 s12, s22, s12
	s_addc_u32 s13, s23, s13
	s_and_b64 s[22:23], s[4:5], exec
	s_cselect_b32 s7, s13, s21
	s_cselect_b32 s33, s12, s20
	s_add_u32 s16, s16, 0x80080
	s_addc_u32 s17, s17, 0
	s_add_u32 s34, s20, 0x100
	s_addc_u32 s35, s21, 0
	s_mov_b32 s36, -2
	v_readlane_b32 s37, v255, 49
	s_nop 3
	s_cmp_eq_u32 s37, 3
	v_writelane_b32 v255, 3, 49
	s_cbranch_scc0 .Ltrip0_strict_2
	s_add_u32 s20, s16, 0xfff80080
	s_addc_u32 s21, s17, -1
	s_add_i32 s37, 0, 0x10000
	s_cmp_eq_u32 s36, 28
	s_cselect_b32 s23, s9, s21
	s_cselect_b32 s22, s31, s20
	s_cselect_b32 s21, s7, s35
	s_cselect_b32 s20, s33, s34
	s_add_i32 s40, 0, 0x14000
	v_add_u32_e32 v142, s37, v238
	v_add_u32_e32 v158, s40, v238
	ds_read_b128 v[130:133], v142
	ds_read_b128 v[134:137], v142 offset:1024
	ds_read_b128 v[138:141], v142 offset:2048
	ds_read_b128 v[142:145], v142 offset:3072
	ds_read_b128 v[146:149], v158
	ds_read_b128 v[150:153], v158 offset:1024
	ds_read_b128 v[154:157], v158 offset:2048
	ds_read_b128 v[158:161], v158 offset:3072
	v_lshl_add_u64 v[210:211], s[16:17], 0, v[206:207]
	s_add_i32 m0, s25, 0xc000
	ds_read_b128 v[162:165], v240
	ds_read_b128 v[166:169], v240 offset:1024
	ds_read_b128 v[170:173], v240 offset:2048
	ds_read_b128 v[174:177], v240 offset:3072
	ds_read_b128 v[178:181], v240 offset:4096
	ds_read_b128 v[182:185], v240 offset:5120
	ds_read_b128 v[186:189], v240 offset:6144
	ds_read_b128 v[196:199], v240 offset:7168
	global_load_lds_dwordx4 v[210:211], off
	s_add_i32 m0, s25, 0xe000
	v_lshl_add_u64 v[210:211], s[16:17], 0, v[208:209]
	global_load_lds_dwordx4 v[210:211], off
	s_waitcnt vmcnt(24) lgkmcnt(0)
	s_barrier
	s_setprio 1
	v_mfma_f32_16x16x32_bf16 v[126:129], v[130:133], v[162:165], 0
	v_mfma_f32_16x16x32_bf16 v[122:125], v[138:141], v[162:165], 0
	v_mfma_f32_16x16x32_bf16 v[110:113], v[130:133], v[170:173], 0
	v_mfma_f32_16x16x32_bf16 v[106:109], v[138:141], v[170:173], 0
	v_mfma_f32_16x16x32_bf16 v[98:101], v[130:133], v[178:181], 0
	v_mfma_f32_16x16x32_bf16 v[90:93], v[138:141], v[178:181], 0
	v_mfma_f32_16x16x32_bf16 v[82:85], v[130:133], v[186:189], 0
	v_mfma_f32_16x16x32_bf16 v[74:77], v[138:141], v[186:189], 0
	v_mfma_f32_16x16x32_bf16 v[126:129], v[134:137], v[166:169], v[126:129]
	v_mfma_f32_16x16x32_bf16 v[122:125], v[142:145], v[166:169], v[122:125]
	v_mfma_f32_16x16x32_bf16 v[110:113], v[134:137], v[174:177], v[110:113]
	v_mfma_f32_16x16x32_bf16 v[106:109], v[142:145], v[174:177], v[106:109]
	v_mfma_f32_16x16x32_bf16 v[98:101], v[134:137], v[182:185], v[98:101]
	v_mfma_f32_16x16x32_bf16 v[90:93], v[142:145], v[182:185], v[90:93]
	v_mfma_f32_16x16x32_bf16 v[82:85], v[134:137], v[196:199], v[82:85]
	v_mfma_f32_16x16x32_bf16 v[74:77], v[142:145], v[196:199], v[74:77]
	s_setprio 0
	s_setprio 1
	v_mfma_f32_16x16x32_bf16 v[118:121], v[146:149], v[162:165], 0
	v_mfma_f32_16x16x32_bf16 v[114:117], v[154:157], v[162:165], 0
	v_mfma_f32_16x16x32_bf16 v[102:105], v[146:149], v[170:173], 0
	v_mfma_f32_16x16x32_bf16 v[94:97], v[154:157], v[170:173], 0
	v_mfma_f32_16x16x32_bf16 v[86:89], v[146:149], v[178:181], 0
	v_mfma_f32_16x16x32_bf16 v[78:81], v[154:157], v[178:181], 0
	v_mfma_f32_16x16x32_bf16 v[70:73], v[146:149], v[186:189], 0
	v_mfma_f32_16x16x32_bf16 v[66:69], v[154:157], v[186:189], 0
	v_mfma_f32_16x16x32_bf16 v[118:121], v[150:153], v[166:169], v[118:121]
	v_mfma_f32_16x16x32_bf16 v[114:117], v[158:161], v[166:169], v[114:117]
	v_mfma_f32_16x16x32_bf16 v[102:105], v[150:153], v[174:177], v[102:105]
	v_mfma_f32_16x16x32_bf16 v[94:97], v[158:161], v[174:177], v[94:97]
	v_mfma_f32_16x16x32_bf16 v[86:89], v[150:153], v[182:185], v[86:89]
	v_mfma_f32_16x16x32_bf16 v[78:81], v[158:161], v[182:185], v[78:81]
	v_mfma_f32_16x16x32_bf16 v[70:73], v[150:153], v[196:199], v[70:73]
	v_mfma_f32_16x16x32_bf16 v[66:69], v[158:161], v[196:199], v[66:69]
	s_setprio 0
	s_barrier
	s_add_i32 s37, s37, s24
	v_lshl_add_u64 v[210:211], s[20:21], 0, v[190:191]
	s_mov_b32 m0, s37
	ds_read_b128 v[162:165], v240 offset:16384
	ds_read_b128 v[166:169], v240 offset:17408
	ds_read_b128 v[170:173], v240 offset:18432
	ds_read_b128 v[174:177], v240 offset:19456
	ds_read_b128 v[178:181], v240 offset:20480
	ds_read_b128 v[182:185], v240 offset:21504
	ds_read_b128 v[186:189], v240 offset:22528
	ds_read_b128 v[196:199], v240 offset:23552
	global_load_lds_dwordx4 v[210:211], off
	s_add_i32 m0, s37, 0x2000
	s_add_u32 s38, s20, 0x80000
	v_lshl_add_u64 v[212:213], s[20:21], 0, v[204:205]
	s_addc_u32 s39, s21, 0
	s_add_i32 s37, s40, s24
	global_load_lds_dwordx4 v[212:213], off
	v_lshl_add_u64 v[214:215], s[38:39], 0, v[190:191]
	s_mov_b32 m0, s37
	v_lshl_add_u64 v[216:217], s[22:23], 0, v[202:203]
	global_load_lds_dwordx4 v[214:215], off
	s_add_i32 m0, s37, 0x2000
	v_lshl_add_u64 v[214:215], s[38:39], 0, v[204:205]
	global_load_lds_dwordx4 v[214:215], off
	s_mov_b32 m0, s25
	v_lshl_add_u64 v[214:215], s[22:23], 0, v[200:201]
	global_load_lds_dwordx4 v[214:215], off
	s_mov_b32 m0, s26
	s_nop 0
	global_load_lds_dwordx4 v[216:217], off
	s_waitcnt vmcnt(24) lgkmcnt(0)
	s_barrier
	s_setprio 1
	v_mfma_f32_16x16x32_bf16 v[62:65], v[130:133], v[162:165], 0
	v_mfma_f32_16x16x32_bf16 v[58:61], v[138:141], v[162:165], 0
	v_mfma_f32_16x16x32_bf16 v[50:53], v[130:133], v[170:173], 0
	v_mfma_f32_16x16x32_bf16 v[42:45], v[138:141], v[170:173], 0
	v_mfma_f32_16x16x32_bf16 v[34:37], v[130:133], v[178:181], 0
	v_mfma_f32_16x16x32_bf16 v[26:29], v[138:141], v[178:181], 0
	v_mfma_f32_16x16x32_bf16 v[18:21], v[130:133], v[186:189], 0
	v_mfma_f32_16x16x32_bf16 v[10:13], v[138:141], v[186:189], 0
	v_mfma_f32_16x16x32_bf16 v[62:65], v[134:137], v[166:169], v[62:65]
	v_mfma_f32_16x16x32_bf16 v[58:61], v[142:145], v[166:169], v[58:61]
	v_mfma_f32_16x16x32_bf16 v[50:53], v[134:137], v[174:177], v[50:53]
	v_mfma_f32_16x16x32_bf16 v[42:45], v[142:145], v[174:177], v[42:45]
	v_mfma_f32_16x16x32_bf16 v[34:37], v[134:137], v[182:185], v[34:37]
	v_mfma_f32_16x16x32_bf16 v[26:29], v[142:145], v[182:185], v[26:29]
	v_mfma_f32_16x16x32_bf16 v[18:21], v[134:137], v[196:199], v[18:21]
	v_mfma_f32_16x16x32_bf16 v[10:13], v[142:145], v[196:199], v[10:13]
	s_setprio 0
	s_setprio 1
	v_mfma_f32_16x16x32_bf16 v[54:57], v[146:149], v[162:165], 0
	v_mfma_f32_16x16x32_bf16 v[46:49], v[154:157], v[162:165], 0
	v_mfma_f32_16x16x32_bf16 v[38:41], v[146:149], v[170:173], 0
	v_mfma_f32_16x16x32_bf16 v[30:33], v[154:157], v[170:173], 0
	v_mfma_f32_16x16x32_bf16 v[22:25], v[146:149], v[178:181], 0
	v_mfma_f32_16x16x32_bf16 v[14:17], v[154:157], v[178:181], 0
	v_mfma_f32_16x16x32_bf16 v[6:9], v[146:149], v[186:189], 0
	v_mfma_f32_16x16x32_bf16 v[2:5], v[154:157], v[186:189], 0
	v_mfma_f32_16x16x32_bf16 v[54:57], v[150:153], v[166:169], v[54:57]
	v_mfma_f32_16x16x32_bf16 v[46:49], v[158:161], v[166:169], v[46:49]
	v_mfma_f32_16x16x32_bf16 v[38:41], v[150:153], v[174:177], v[38:41]
	v_mfma_f32_16x16x32_bf16 v[30:33], v[158:161], v[174:177], v[30:33]
	v_mfma_f32_16x16x32_bf16 v[22:25], v[150:153], v[182:185], v[22:25]
	v_mfma_f32_16x16x32_bf16 v[14:17], v[158:161], v[182:185], v[14:17]
	v_mfma_f32_16x16x32_bf16 v[6:9], v[150:153], v[196:199], v[6:9]
	v_mfma_f32_16x16x32_bf16 v[2:5], v[158:161], v[196:199], v[2:5]
	s_setprio 0
	s_barrier
	s_add_i32 s37, 0, 0x18000
	s_add_i32 s38, 0, 0x1c000
	v_add_u32_e32 v142, s37, v238
	v_add_u32_e32 v158, s38, v238
	ds_read_b128 v[130:133], v142
	ds_read_b128 v[134:137], v142 offset:1024
	ds_read_b128 v[138:141], v142 offset:2048
	ds_read_b128 v[142:145], v142 offset:3072
	ds_read_b128 v[146:149], v158
	ds_read_b128 v[150:153], v158 offset:1024
	ds_read_b128 v[154:157], v158 offset:2048
	ds_read_b128 v[158:161], v158 offset:3072
	s_add_u32 s22, s22, 0x80000
	s_addc_u32 s23, s23, 0
	s_mov_b32 m0, s27
	v_lshl_add_u64 v[218:219], s[22:23], 0, v[200:201]
	ds_read_b128 v[162:165], v240 offset:32768
	ds_read_b128 v[166:169], v240 offset:33792
	ds_read_b128 v[170:173], v240 offset:34816
	ds_read_b128 v[174:177], v240 offset:35840
	ds_read_b128 v[178:181], v240 offset:36864
	ds_read_b128 v[182:185], v240 offset:37888
	ds_read_b128 v[186:189], v240 offset:38912
	ds_read_b128 v[196:199], v240 offset:39936
	global_load_lds_dwordx4 v[218:219], off
	s_mov_b32 m0, s28
	v_lshl_add_u64 v[218:219], s[22:23], 0, v[202:203]
	global_load_lds_dwordx4 v[218:219], off
	s_waitcnt vmcnt(8) lgkmcnt(0)
	s_barrier
	s_setprio 1
	v_mfma_f32_16x16x32_bf16 v[126:129], v[130:133], v[162:165], v[126:129]
	v_mfma_f32_16x16x32_bf16 v[122:125], v[138:141], v[162:165], v[122:125]
	v_mfma_f32_16x16x32_bf16 v[110:113], v[130:133], v[170:173], v[110:113]
	v_mfma_f32_16x16x32_bf16 v[106:109], v[138:141], v[170:173], v[106:109]
	v_mfma_f32_16x16x32_bf16 v[98:101], v[130:133], v[178:181], v[98:101]
	v_mfma_f32_16x16x32_bf16 v[90:93], v[138:141], v[178:181], v[90:93]
	v_mfma_f32_16x16x32_bf16 v[82:85], v[130:133], v[186:189], v[82:85]
	v_mfma_f32_16x16x32_bf16 v[74:77], v[138:141], v[186:189], v[74:77]
	v_mfma_f32_16x16x32_bf16 v[126:129], v[134:137], v[166:169], v[126:129]
	v_mfma_f32_16x16x32_bf16 v[122:125], v[142:145], v[166:169], v[122:125]
	v_mfma_f32_16x16x32_bf16 v[110:113], v[134:137], v[174:177], v[110:113]
	v_mfma_f32_16x16x32_bf16 v[106:109], v[142:145], v[174:177], v[106:109]
	v_mfma_f32_16x16x32_bf16 v[98:101], v[134:137], v[182:185], v[98:101]
	v_mfma_f32_16x16x32_bf16 v[90:93], v[142:145], v[182:185], v[90:93]
	v_mfma_f32_16x16x32_bf16 v[82:85], v[134:137], v[196:199], v[82:85]
	v_mfma_f32_16x16x32_bf16 v[74:77], v[142:145], v[196:199], v[74:77]
	s_setprio 0
	s_setprio 1
	v_mfma_f32_16x16x32_bf16 v[118:121], v[146:149], v[162:165], v[118:121]
	v_mfma_f32_16x16x32_bf16 v[114:117], v[154:157], v[162:165], v[114:117]
	v_mfma_f32_16x16x32_bf16 v[102:105], v[146:149], v[170:173], v[102:105]
	v_mfma_f32_16x16x32_bf16 v[94:97], v[154:157], v[170:173], v[94:97]
	v_mfma_f32_16x16x32_bf16 v[86:89], v[146:149], v[178:181], v[86:89]
	v_mfma_f32_16x16x32_bf16 v[78:81], v[154:157], v[178:181], v[78:81]
	v_mfma_f32_16x16x32_bf16 v[70:73], v[146:149], v[186:189], v[70:73]
	v_mfma_f32_16x16x32_bf16 v[66:69], v[154:157], v[186:189], v[66:69]
	v_mfma_f32_16x16x32_bf16 v[118:121], v[150:153], v[166:169], v[118:121]
	v_mfma_f32_16x16x32_bf16 v[114:117], v[158:161], v[166:169], v[114:117]
	v_mfma_f32_16x16x32_bf16 v[102:105], v[150:153], v[174:177], v[102:105]
	v_mfma_f32_16x16x32_bf16 v[94:97], v[158:161], v[174:177], v[94:97]
	v_mfma_f32_16x16x32_bf16 v[86:89], v[150:153], v[182:185], v[86:89]
	v_mfma_f32_16x16x32_bf16 v[78:81], v[158:161], v[182:185], v[78:81]
	v_mfma_f32_16x16x32_bf16 v[70:73], v[150:153], v[196:199], v[70:73]
	v_mfma_f32_16x16x32_bf16 v[66:69], v[158:161], v[196:199], v[66:69]
	s_setprio 0
	s_barrier
	s_add_i32 s22, s37, s24
	v_lshl_add_u64 v[210:211], v[210:211], 0, s[58:59]
	s_mov_b32 m0, s22
	ds_read_b128 v[162:165], v240 offset:49152
	ds_read_b128 v[166:169], v240 offset:50176
	ds_read_b128 v[170:173], v240 offset:51200
	ds_read_b128 v[174:177], v240 offset:52224
	ds_read_b128 v[178:181], v240 offset:53248
	ds_read_b128 v[182:185], v240 offset:54272
	ds_read_b128 v[186:189], v240 offset:55296
	ds_read_b128 v[196:199], v240 offset:56320
	global_load_lds_dwordx4 v[210:211], off
	s_add_i32 m0, s22, 0x2000
	s_add_u32 s20, s20, 0x80080
	v_lshl_add_u64 v[210:211], v[212:213], 0, s[58:59]
	s_addc_u32 s21, s21, 0
	s_add_i32 s22, s38, s24
	global_load_lds_dwordx4 v[210:211], off
	s_mov_b32 m0, s22
	v_lshl_add_u64 v[210:211], s[20:21], 0, v[190:191]
	global_load_lds_dwordx4 v[210:211], off
	s_add_i32 m0, s22, 0x2000
	v_lshl_add_u64 v[210:211], s[20:21], 0, v[204:205]
	global_load_lds_dwordx4 v[210:211], off
	s_mov_b32 m0, s29
	v_lshl_add_u64 v[210:211], v[214:215], 0, s[58:59]
	global_load_lds_dwordx4 v[210:211], off
	s_mov_b32 m0, s30
	v_lshl_add_u64 v[210:211], v[216:217], 0, s[58:59]
	global_load_lds_dwordx4 v[210:211], off
	s_waitcnt vmcnt(8) lgkmcnt(0)
	s_barrier
	s_setprio 1
	v_mfma_f32_16x16x32_bf16 v[62:65], v[130:133], v[162:165], v[62:65]
	v_mfma_f32_16x16x32_bf16 v[58:61], v[138:141], v[162:165], v[58:61]
	v_mfma_f32_16x16x32_bf16 v[50:53], v[130:133], v[170:173], v[50:53]
	v_mfma_f32_16x16x32_bf16 v[42:45], v[138:141], v[170:173], v[42:45]
	v_mfma_f32_16x16x32_bf16 v[34:37], v[130:133], v[178:181], v[34:37]
	v_mfma_f32_16x16x32_bf16 v[26:29], v[138:141], v[178:181], v[26:29]
	v_mfma_f32_16x16x32_bf16 v[18:21], v[130:133], v[186:189], v[18:21]
	v_mfma_f32_16x16x32_bf16 v[10:13], v[138:141], v[186:189], v[10:13]
	v_mfma_f32_16x16x32_bf16 v[62:65], v[134:137], v[166:169], v[62:65]
	v_mfma_f32_16x16x32_bf16 v[58:61], v[142:145], v[166:169], v[58:61]
	v_mfma_f32_16x16x32_bf16 v[50:53], v[134:137], v[174:177], v[50:53]
	v_mfma_f32_16x16x32_bf16 v[42:45], v[142:145], v[174:177], v[42:45]
	v_mfma_f32_16x16x32_bf16 v[34:37], v[134:137], v[182:185], v[34:37]
	v_mfma_f32_16x16x32_bf16 v[26:29], v[142:145], v[182:185], v[26:29]
	v_mfma_f32_16x16x32_bf16 v[18:21], v[134:137], v[196:199], v[18:21]
	v_mfma_f32_16x16x32_bf16 v[10:13], v[142:145], v[196:199], v[10:13]
	s_setprio 0
	s_setprio 1
	v_mfma_f32_16x16x32_bf16 v[54:57], v[146:149], v[162:165], v[54:57]
	v_mfma_f32_16x16x32_bf16 v[46:49], v[154:157], v[162:165], v[46:49]
	v_mfma_f32_16x16x32_bf16 v[38:41], v[146:149], v[170:173], v[38:41]
	v_mfma_f32_16x16x32_bf16 v[30:33], v[154:157], v[170:173], v[30:33]
	v_mfma_f32_16x16x32_bf16 v[22:25], v[146:149], v[178:181], v[22:25]
	v_mfma_f32_16x16x32_bf16 v[14:17], v[154:157], v[178:181], v[14:17]
	v_mfma_f32_16x16x32_bf16 v[6:9], v[146:149], v[186:189], v[6:9]
	v_mfma_f32_16x16x32_bf16 v[2:5], v[154:157], v[186:189], v[2:5]
	v_mfma_f32_16x16x32_bf16 v[54:57], v[150:153], v[166:169], v[54:57]
	v_mfma_f32_16x16x32_bf16 v[46:49], v[158:161], v[166:169], v[46:49]
	v_mfma_f32_16x16x32_bf16 v[38:41], v[150:153], v[174:177], v[38:41]
	v_mfma_f32_16x16x32_bf16 v[30:33], v[158:161], v[174:177], v[30:33]
	v_mfma_f32_16x16x32_bf16 v[22:25], v[150:153], v[182:185], v[22:25]
	v_mfma_f32_16x16x32_bf16 v[14:17], v[158:161], v[182:185], v[14:17]
	v_mfma_f32_16x16x32_bf16 v[6:9], v[150:153], v[196:199], v[6:9]
	v_mfma_f32_16x16x32_bf16 v[2:5], v[158:161], v[196:199], v[2:5]
	s_setprio 0
	s_barrier
	s_add_i32 s36, s36, 2
	s_add_u32 s16, s16, 0x100
	s_addc_u32 s17, s17, 0
	s_add_u32 s34, s34, 0x100
	s_addc_u32 s35, s35, 0
	s_cmp_gt_u32 s36, 29
	s_cbranch_scc1 .Lpeel_done_2
	s_branch .LBB0_748
.Ltrip0_strict_2:
	s_add_u32 s20, s16, 0xfff80080
	s_addc_u32 s21, s17, -1
	s_add_i32 s37, 0, 0x10000
	s_cmp_eq_u32 s36, 28
	s_cselect_b32 s23, s9, s21
	s_cselect_b32 s22, s31, s20
	s_cselect_b32 s21, s7, s35
	s_cselect_b32 s20, s33, s34
	s_add_i32 s40, 0, 0x14000
	v_add_u32_e32 v142, s37, v238
	v_add_u32_e32 v158, s40, v238
	ds_read_b128 v[130:133], v142
	ds_read_b128 v[134:137], v142 offset:1024
	ds_read_b128 v[138:141], v142 offset:2048
	ds_read_b128 v[142:145], v142 offset:3072
	ds_read_b128 v[146:149], v158
	ds_read_b128 v[150:153], v158 offset:1024
	ds_read_b128 v[154:157], v158 offset:2048
	ds_read_b128 v[158:161], v158 offset:3072
	v_lshl_add_u64 v[210:211], s[16:17], 0, v[206:207]
	s_add_i32 m0, s25, 0xc000
	ds_read_b128 v[162:165], v240
	ds_read_b128 v[166:169], v240 offset:1024
	ds_read_b128 v[170:173], v240 offset:2048
	ds_read_b128 v[174:177], v240 offset:3072
	ds_read_b128 v[178:181], v240 offset:4096
	ds_read_b128 v[182:185], v240 offset:5120
	ds_read_b128 v[186:189], v240 offset:6144
	ds_read_b128 v[196:199], v240 offset:7168
	global_load_lds_dwordx4 v[210:211], off
	s_add_i32 m0, s25, 0xe000
	v_lshl_add_u64 v[210:211], s[16:17], 0, v[208:209]
	global_load_lds_dwordx4 v[210:211], off
	s_waitcnt vmcnt(8) lgkmcnt(0)
	s_barrier
	s_setprio 1
	v_mfma_f32_16x16x32_bf16 v[126:129], v[130:133], v[162:165], 0
	v_mfma_f32_16x16x32_bf16 v[122:125], v[138:141], v[162:165], 0
	v_mfma_f32_16x16x32_bf16 v[110:113], v[130:133], v[170:173], 0
	v_mfma_f32_16x16x32_bf16 v[106:109], v[138:141], v[170:173], 0
	v_mfma_f32_16x16x32_bf16 v[98:101], v[130:133], v[178:181], 0
	v_mfma_f32_16x16x32_bf16 v[90:93], v[138:141], v[178:181], 0
	v_mfma_f32_16x16x32_bf16 v[82:85], v[130:133], v[186:189], 0
	v_mfma_f32_16x16x32_bf16 v[74:77], v[138:141], v[186:189], 0
	v_mfma_f32_16x16x32_bf16 v[126:129], v[134:137], v[166:169], v[126:129]
	v_mfma_f32_16x16x32_bf16 v[122:125], v[142:145], v[166:169], v[122:125]
	v_mfma_f32_16x16x32_bf16 v[110:113], v[134:137], v[174:177], v[110:113]
	v_mfma_f32_16x16x32_bf16 v[106:109], v[142:145], v[174:177], v[106:109]
	v_mfma_f32_16x16x32_bf16 v[98:101], v[134:137], v[182:185], v[98:101]
	v_mfma_f32_16x16x32_bf16 v[90:93], v[142:145], v[182:185], v[90:93]
	v_mfma_f32_16x16x32_bf16 v[82:85], v[134:137], v[196:199], v[82:85]
	v_mfma_f32_16x16x32_bf16 v[74:77], v[142:145], v[196:199], v[74:77]
	s_setprio 0
	s_setprio 1
	v_mfma_f32_16x16x32_bf16 v[118:121], v[146:149], v[162:165], 0
	v_mfma_f32_16x16x32_bf16 v[114:117], v[154:157], v[162:165], 0
	v_mfma_f32_16x16x32_bf16 v[102:105], v[146:149], v[170:173], 0
	v_mfma_f32_16x16x32_bf16 v[94:97], v[154:157], v[170:173], 0
	v_mfma_f32_16x16x32_bf16 v[86:89], v[146:149], v[178:181], 0
	v_mfma_f32_16x16x32_bf16 v[78:81], v[154:157], v[178:181], 0
	v_mfma_f32_16x16x32_bf16 v[70:73], v[146:149], v[186:189], 0
	v_mfma_f32_16x16x32_bf16 v[66:69], v[154:157], v[186:189], 0
	v_mfma_f32_16x16x32_bf16 v[118:121], v[150:153], v[166:169], v[118:121]
	v_mfma_f32_16x16x32_bf16 v[114:117], v[158:161], v[166:169], v[114:117]
	v_mfma_f32_16x16x32_bf16 v[102:105], v[150:153], v[174:177], v[102:105]
	v_mfma_f32_16x16x32_bf16 v[94:97], v[158:161], v[174:177], v[94:97]
	v_mfma_f32_16x16x32_bf16 v[86:89], v[150:153], v[182:185], v[86:89]
	v_mfma_f32_16x16x32_bf16 v[78:81], v[158:161], v[182:185], v[78:81]
	v_mfma_f32_16x16x32_bf16 v[70:73], v[150:153], v[196:199], v[70:73]
	v_mfma_f32_16x16x32_bf16 v[66:69], v[158:161], v[196:199], v[66:69]
	s_setprio 0
	s_barrier
	s_add_i32 s37, s37, s24
	v_lshl_add_u64 v[210:211], s[20:21], 0, v[190:191]
	s_mov_b32 m0, s37
	ds_read_b128 v[162:165], v240 offset:16384
	ds_read_b128 v[166:169], v240 offset:17408
	ds_read_b128 v[170:173], v240 offset:18432
	ds_read_b128 v[174:177], v240 offset:19456
	ds_read_b128 v[178:181], v240 offset:20480
	ds_read_b128 v[182:185], v240 offset:21504
	ds_read_b128 v[186:189], v240 offset:22528
	ds_read_b128 v[196:199], v240 offset:23552
	global_load_lds_dwordx4 v[210:211], off
	s_add_i32 m0, s37, 0x2000
	s_add_u32 s38, s20, 0x80000
	v_lshl_add_u64 v[212:213], s[20:21], 0, v[204:205]
	s_addc_u32 s39, s21, 0
	s_add_i32 s37, s40, s24
	global_load_lds_dwordx4 v[212:213], off
	v_lshl_add_u64 v[214:215], s[38:39], 0, v[190:191]
	s_mov_b32 m0, s37
	v_lshl_add_u64 v[216:217], s[22:23], 0, v[202:203]
	global_load_lds_dwordx4 v[214:215], off
	s_add_i32 m0, s37, 0x2000
	v_lshl_add_u64 v[214:215], s[38:39], 0, v[204:205]
	global_load_lds_dwordx4 v[214:215], off
	s_mov_b32 m0, s25
	v_lshl_add_u64 v[214:215], s[22:23], 0, v[200:201]
	global_load_lds_dwordx4 v[214:215], off
	s_mov_b32 m0, s26
	s_nop 0
	global_load_lds_dwordx4 v[216:217], off
	s_waitcnt vmcnt(8) lgkmcnt(0)
	s_barrier
	s_setprio 1
	v_mfma_f32_16x16x32_bf16 v[62:65], v[130:133], v[162:165], 0
	v_mfma_f32_16x16x32_bf16 v[58:61], v[138:141], v[162:165], 0
	v_mfma_f32_16x16x32_bf16 v[50:53], v[130:133], v[170:173], 0
	v_mfma_f32_16x16x32_bf16 v[42:45], v[138:141], v[170:173], 0
	v_mfma_f32_16x16x32_bf16 v[34:37], v[130:133], v[178:181], 0
	v_mfma_f32_16x16x32_bf16 v[26:29], v[138:141], v[178:181], 0
	v_mfma_f32_16x16x32_bf16 v[18:21], v[130:133], v[186:189], 0
	v_mfma_f32_16x16x32_bf16 v[10:13], v[138:141], v[186:189], 0
	v_mfma_f32_16x16x32_bf16 v[62:65], v[134:137], v[166:169], v[62:65]
	v_mfma_f32_16x16x32_bf16 v[58:61], v[142:145], v[166:169], v[58:61]
	v_mfma_f32_16x16x32_bf16 v[50:53], v[134:137], v[174:177], v[50:53]
	v_mfma_f32_16x16x32_bf16 v[42:45], v[142:145], v[174:177], v[42:45]
	v_mfma_f32_16x16x32_bf16 v[34:37], v[134:137], v[182:185], v[34:37]
	v_mfma_f32_16x16x32_bf16 v[26:29], v[142:145], v[182:185], v[26:29]
	v_mfma_f32_16x16x32_bf16 v[18:21], v[134:137], v[196:199], v[18:21]
	v_mfma_f32_16x16x32_bf16 v[10:13], v[142:145], v[196:199], v[10:13]
	s_setprio 0
	s_setprio 1
	v_mfma_f32_16x16x32_bf16 v[54:57], v[146:149], v[162:165], 0
	v_mfma_f32_16x16x32_bf16 v[46:49], v[154:157], v[162:165], 0
	v_mfma_f32_16x16x32_bf16 v[38:41], v[146:149], v[170:173], 0
	v_mfma_f32_16x16x32_bf16 v[30:33], v[154:157], v[170:173], 0
	v_mfma_f32_16x16x32_bf16 v[22:25], v[146:149], v[178:181], 0
	v_mfma_f32_16x16x32_bf16 v[14:17], v[154:157], v[178:181], 0
	v_mfma_f32_16x16x32_bf16 v[6:9], v[146:149], v[186:189], 0
	v_mfma_f32_16x16x32_bf16 v[2:5], v[154:157], v[186:189], 0
	v_mfma_f32_16x16x32_bf16 v[54:57], v[150:153], v[166:169], v[54:57]
	v_mfma_f32_16x16x32_bf16 v[46:49], v[158:161], v[166:169], v[46:49]
	v_mfma_f32_16x16x32_bf16 v[38:41], v[150:153], v[174:177], v[38:41]
	v_mfma_f32_16x16x32_bf16 v[30:33], v[158:161], v[174:177], v[30:33]
	v_mfma_f32_16x16x32_bf16 v[22:25], v[150:153], v[182:185], v[22:25]
	v_mfma_f32_16x16x32_bf16 v[14:17], v[158:161], v[182:185], v[14:17]
	v_mfma_f32_16x16x32_bf16 v[6:9], v[150:153], v[196:199], v[6:9]
	v_mfma_f32_16x16x32_bf16 v[2:5], v[158:161], v[196:199], v[2:5]
	s_setprio 0
	s_barrier
	s_add_i32 s37, 0, 0x18000
	s_add_i32 s38, 0, 0x1c000
	v_add_u32_e32 v142, s37, v238
	v_add_u32_e32 v158, s38, v238
	ds_read_b128 v[130:133], v142
	ds_read_b128 v[134:137], v142 offset:1024
	ds_read_b128 v[138:141], v142 offset:2048
	ds_read_b128 v[142:145], v142 offset:3072
	ds_read_b128 v[146:149], v158
	ds_read_b128 v[150:153], v158 offset:1024
	ds_read_b128 v[154:157], v158 offset:2048
	ds_read_b128 v[158:161], v158 offset:3072
	s_add_u32 s22, s22, 0x80000
	s_addc_u32 s23, s23, 0
	s_mov_b32 m0, s27
	v_lshl_add_u64 v[218:219], s[22:23], 0, v[200:201]
	ds_read_b128 v[162:165], v240 offset:32768
	ds_read_b128 v[166:169], v240 offset:33792
	ds_read_b128 v[170:173], v240 offset:34816
	ds_read_b128 v[174:177], v240 offset:35840
	ds_read_b128 v[178:181], v240 offset:36864
	ds_read_b128 v[182:185], v240 offset:37888
	ds_read_b128 v[186:189], v240 offset:38912
	ds_read_b128 v[196:199], v240 offset:39936
	global_load_lds_dwordx4 v[218:219], off
	s_mov_b32 m0, s28
	v_lshl_add_u64 v[218:219], s[22:23], 0, v[202:203]
	global_load_lds_dwordx4 v[218:219], off
	s_waitcnt vmcnt(8) lgkmcnt(0)
	s_barrier
	s_setprio 1
	v_mfma_f32_16x16x32_bf16 v[126:129], v[130:133], v[162:165], v[126:129]
	v_mfma_f32_16x16x32_bf16 v[122:125], v[138:141], v[162:165], v[122:125]
	v_mfma_f32_16x16x32_bf16 v[110:113], v[130:133], v[170:173], v[110:113]
	v_mfma_f32_16x16x32_bf16 v[106:109], v[138:141], v[170:173], v[106:109]
	v_mfma_f32_16x16x32_bf16 v[98:101], v[130:133], v[178:181], v[98:101]
	v_mfma_f32_16x16x32_bf16 v[90:93], v[138:141], v[178:181], v[90:93]
	v_mfma_f32_16x16x32_bf16 v[82:85], v[130:133], v[186:189], v[82:85]
	v_mfma_f32_16x16x32_bf16 v[74:77], v[138:141], v[186:189], v[74:77]
	v_mfma_f32_16x16x32_bf16 v[126:129], v[134:137], v[166:169], v[126:129]
	v_mfma_f32_16x16x32_bf16 v[122:125], v[142:145], v[166:169], v[122:125]
	v_mfma_f32_16x16x32_bf16 v[110:113], v[134:137], v[174:177], v[110:113]
	v_mfma_f32_16x16x32_bf16 v[106:109], v[142:145], v[174:177], v[106:109]
	v_mfma_f32_16x16x32_bf16 v[98:101], v[134:137], v[182:185], v[98:101]
	v_mfma_f32_16x16x32_bf16 v[90:93], v[142:145], v[182:185], v[90:93]
	v_mfma_f32_16x16x32_bf16 v[82:85], v[134:137], v[196:199], v[82:85]
	v_mfma_f32_16x16x32_bf16 v[74:77], v[142:145], v[196:199], v[74:77]
	s_setprio 0
	s_setprio 1
	v_mfma_f32_16x16x32_bf16 v[118:121], v[146:149], v[162:165], v[118:121]
	v_mfma_f32_16x16x32_bf16 v[114:117], v[154:157], v[162:165], v[114:117]
	v_mfma_f32_16x16x32_bf16 v[102:105], v[146:149], v[170:173], v[102:105]
	v_mfma_f32_16x16x32_bf16 v[94:97], v[154:157], v[170:173], v[94:97]
	v_mfma_f32_16x16x32_bf16 v[86:89], v[146:149], v[178:181], v[86:89]
	v_mfma_f32_16x16x32_bf16 v[78:81], v[154:157], v[178:181], v[78:81]
	v_mfma_f32_16x16x32_bf16 v[70:73], v[146:149], v[186:189], v[70:73]
	v_mfma_f32_16x16x32_bf16 v[66:69], v[154:157], v[186:189], v[66:69]
	v_mfma_f32_16x16x32_bf16 v[118:121], v[150:153], v[166:169], v[118:121]
	v_mfma_f32_16x16x32_bf16 v[114:117], v[158:161], v[166:169], v[114:117]
	v_mfma_f32_16x16x32_bf16 v[102:105], v[150:153], v[174:177], v[102:105]
	v_mfma_f32_16x16x32_bf16 v[94:97], v[158:161], v[174:177], v[94:97]
	v_mfma_f32_16x16x32_bf16 v[86:89], v[150:153], v[182:185], v[86:89]
	v_mfma_f32_16x16x32_bf16 v[78:81], v[158:161], v[182:185], v[78:81]
	v_mfma_f32_16x16x32_bf16 v[70:73], v[150:153], v[196:199], v[70:73]
	v_mfma_f32_16x16x32_bf16 v[66:69], v[158:161], v[196:199], v[66:69]
	s_setprio 0
	s_barrier
	s_add_i32 s22, s37, s24
	v_lshl_add_u64 v[210:211], v[210:211], 0, s[58:59]
	s_mov_b32 m0, s22
	ds_read_b128 v[162:165], v240 offset:49152
	ds_read_b128 v[166:169], v240 offset:50176
	ds_read_b128 v[170:173], v240 offset:51200
	ds_read_b128 v[174:177], v240 offset:52224
	ds_read_b128 v[178:181], v240 offset:53248
	ds_read_b128 v[182:185], v240 offset:54272
	ds_read_b128 v[186:189], v240 offset:55296
	ds_read_b128 v[196:199], v240 offset:56320
	global_load_lds_dwordx4 v[210:211], off
	s_add_i32 m0, s22, 0x2000
	s_add_u32 s20, s20, 0x80080
	v_lshl_add_u64 v[210:211], v[212:213], 0, s[58:59]
	s_addc_u32 s21, s21, 0
	s_add_i32 s22, s38, s24
	global_load_lds_dwordx4 v[210:211], off
	s_mov_b32 m0, s22
	v_lshl_add_u64 v[210:211], s[20:21], 0, v[190:191]
	global_load_lds_dwordx4 v[210:211], off
	s_add_i32 m0, s22, 0x2000
	v_lshl_add_u64 v[210:211], s[20:21], 0, v[204:205]
	global_load_lds_dwordx4 v[210:211], off
	s_mov_b32 m0, s29
	v_lshl_add_u64 v[210:211], v[214:215], 0, s[58:59]
	global_load_lds_dwordx4 v[210:211], off
	s_mov_b32 m0, s30
	v_lshl_add_u64 v[210:211], v[216:217], 0, s[58:59]
	global_load_lds_dwordx4 v[210:211], off
	s_waitcnt vmcnt(8) lgkmcnt(0)
	s_barrier
	s_setprio 1
	v_mfma_f32_16x16x32_bf16 v[62:65], v[130:133], v[162:165], v[62:65]
	v_mfma_f32_16x16x32_bf16 v[58:61], v[138:141], v[162:165], v[58:61]
	v_mfma_f32_16x16x32_bf16 v[50:53], v[130:133], v[170:173], v[50:53]
	v_mfma_f32_16x16x32_bf16 v[42:45], v[138:141], v[170:173], v[42:45]
	v_mfma_f32_16x16x32_bf16 v[34:37], v[130:133], v[178:181], v[34:37]
	v_mfma_f32_16x16x32_bf16 v[26:29], v[138:141], v[178:181], v[26:29]
	v_mfma_f32_16x16x32_bf16 v[18:21], v[130:133], v[186:189], v[18:21]
	v_mfma_f32_16x16x32_bf16 v[10:13], v[138:141], v[186:189], v[10:13]
	v_mfma_f32_16x16x32_bf16 v[62:65], v[134:137], v[166:169], v[62:65]
	v_mfma_f32_16x16x32_bf16 v[58:61], v[142:145], v[166:169], v[58:61]
	v_mfma_f32_16x16x32_bf16 v[50:53], v[134:137], v[174:177], v[50:53]
	v_mfma_f32_16x16x32_bf16 v[42:45], v[142:145], v[174:177], v[42:45]
	v_mfma_f32_16x16x32_bf16 v[34:37], v[134:137], v[182:185], v[34:37]
	v_mfma_f32_16x16x32_bf16 v[26:29], v[142:145], v[182:185], v[26:29]
	v_mfma_f32_16x16x32_bf16 v[18:21], v[134:137], v[196:199], v[18:21]
	v_mfma_f32_16x16x32_bf16 v[10:13], v[142:145], v[196:199], v[10:13]
	s_setprio 0
	s_setprio 1
	v_mfma_f32_16x16x32_bf16 v[54:57], v[146:149], v[162:165], v[54:57]
	v_mfma_f32_16x16x32_bf16 v[46:49], v[154:157], v[162:165], v[46:49]
	v_mfma_f32_16x16x32_bf16 v[38:41], v[146:149], v[170:173], v[38:41]
	v_mfma_f32_16x16x32_bf16 v[30:33], v[154:157], v[170:173], v[30:33]
	v_mfma_f32_16x16x32_bf16 v[22:25], v[146:149], v[178:181], v[22:25]
	v_mfma_f32_16x16x32_bf16 v[14:17], v[154:157], v[178:181], v[14:17]
	v_mfma_f32_16x16x32_bf16 v[6:9], v[146:149], v[186:189], v[6:9]
	v_mfma_f32_16x16x32_bf16 v[2:5], v[154:157], v[186:189], v[2:5]
	v_mfma_f32_16x16x32_bf16 v[54:57], v[150:153], v[166:169], v[54:57]
	v_mfma_f32_16x16x32_bf16 v[46:49], v[158:161], v[166:169], v[46:49]
	v_mfma_f32_16x16x32_bf16 v[38:41], v[150:153], v[174:177], v[38:41]
	v_mfma_f32_16x16x32_bf16 v[30:33], v[158:161], v[174:177], v[30:33]
	v_mfma_f32_16x16x32_bf16 v[22:25], v[150:153], v[182:185], v[22:25]
	v_mfma_f32_16x16x32_bf16 v[14:17], v[158:161], v[182:185], v[14:17]
	v_mfma_f32_16x16x32_bf16 v[6:9], v[150:153], v[196:199], v[6:9]
	v_mfma_f32_16x16x32_bf16 v[2:5], v[158:161], v[196:199], v[2:5]
	s_setprio 0
	s_barrier
	s_add_i32 s36, s36, 2
	s_add_u32 s16, s16, 0x100
	s_addc_u32 s17, s17, 0
	s_add_u32 s34, s34, 0x100
	s_addc_u32 s35, s35, 0
	s_cmp_gt_u32 s36, 29
	s_cbranch_scc1 .Lpeel_done_2
.LBB0_748:
	s_add_u32 s20, s16, 0xfff80080
	s_addc_u32 s21, s17, -1
	s_add_i32 s37, 0, 0x10000
	s_cmp_eq_u32 s36, 28
	s_cselect_b32 s23, s9, s21
	s_cselect_b32 s22, s31, s20
	s_cselect_b32 s21, s7, s35
	s_cselect_b32 s20, s33, s34
	s_add_i32 s40, 0, 0x14000
	v_add_u32_e32 v142, s37, v238
	v_add_u32_e32 v158, s40, v238
	ds_read_b128 v[130:133], v142
	ds_read_b128 v[134:137], v142 offset:1024
	ds_read_b128 v[138:141], v142 offset:2048
	ds_read_b128 v[142:145], v142 offset:3072
	ds_read_b128 v[146:149], v158
	ds_read_b128 v[150:153], v158 offset:1024
	ds_read_b128 v[154:157], v158 offset:2048
	ds_read_b128 v[158:161], v158 offset:3072
	v_lshl_add_u64 v[210:211], s[16:17], 0, v[206:207]
	s_add_i32 m0, s25, 0xc000
	ds_read_b128 v[162:165], v240
	ds_read_b128 v[166:169], v240 offset:1024
	ds_read_b128 v[170:173], v240 offset:2048
	ds_read_b128 v[174:177], v240 offset:3072
	ds_read_b128 v[178:181], v240 offset:4096
	ds_read_b128 v[182:185], v240 offset:5120
	ds_read_b128 v[186:189], v240 offset:6144
	ds_read_b128 v[196:199], v240 offset:7168
	global_load_lds_dwordx4 v[210:211], off
	s_add_i32 m0, s25, 0xe000
	v_lshl_add_u64 v[210:211], s[16:17], 0, v[208:209]
	global_load_lds_dwordx4 v[210:211], off
	s_waitcnt vmcnt(8) lgkmcnt(0)
	s_barrier
	s_setprio 1
	v_mfma_f32_16x16x32_bf16 v[126:129], v[130:133], v[162:165], v[126:129]
	v_mfma_f32_16x16x32_bf16 v[122:125], v[138:141], v[162:165], v[122:125]
	v_mfma_f32_16x16x32_bf16 v[110:113], v[130:133], v[170:173], v[110:113]
	v_mfma_f32_16x16x32_bf16 v[106:109], v[138:141], v[170:173], v[106:109]
	v_mfma_f32_16x16x32_bf16 v[98:101], v[130:133], v[178:181], v[98:101]
	v_mfma_f32_16x16x32_bf16 v[90:93], v[138:141], v[178:181], v[90:93]
	v_mfma_f32_16x16x32_bf16 v[82:85], v[130:133], v[186:189], v[82:85]
	v_mfma_f32_16x16x32_bf16 v[74:77], v[138:141], v[186:189], v[74:77]
	v_mfma_f32_16x16x32_bf16 v[126:129], v[134:137], v[166:169], v[126:129]
	v_mfma_f32_16x16x32_bf16 v[122:125], v[142:145], v[166:169], v[122:125]
	v_mfma_f32_16x16x32_bf16 v[110:113], v[134:137], v[174:177], v[110:113]
	v_mfma_f32_16x16x32_bf16 v[106:109], v[142:145], v[174:177], v[106:109]
	v_mfma_f32_16x16x32_bf16 v[98:101], v[134:137], v[182:185], v[98:101]
	v_mfma_f32_16x16x32_bf16 v[90:93], v[142:145], v[182:185], v[90:93]
	v_mfma_f32_16x16x32_bf16 v[82:85], v[134:137], v[196:199], v[82:85]
	v_mfma_f32_16x16x32_bf16 v[74:77], v[142:145], v[196:199], v[74:77]
	s_setprio 0
	s_setprio 1
	v_mfma_f32_16x16x32_bf16 v[118:121], v[146:149], v[162:165], v[118:121]
	v_mfma_f32_16x16x32_bf16 v[114:117], v[154:157], v[162:165], v[114:117]
	v_mfma_f32_16x16x32_bf16 v[102:105], v[146:149], v[170:173], v[102:105]
	v_mfma_f32_16x16x32_bf16 v[94:97], v[154:157], v[170:173], v[94:97]
	v_mfma_f32_16x16x32_bf16 v[86:89], v[146:149], v[178:181], v[86:89]
	v_mfma_f32_16x16x32_bf16 v[78:81], v[154:157], v[178:181], v[78:81]
	v_mfma_f32_16x16x32_bf16 v[70:73], v[146:149], v[186:189], v[70:73]
	v_mfma_f32_16x16x32_bf16 v[66:69], v[154:157], v[186:189], v[66:69]
	v_mfma_f32_16x16x32_bf16 v[118:121], v[150:153], v[166:169], v[118:121]
	v_mfma_f32_16x16x32_bf16 v[114:117], v[158:161], v[166:169], v[114:117]
	v_mfma_f32_16x16x32_bf16 v[102:105], v[150:153], v[174:177], v[102:105]
	v_mfma_f32_16x16x32_bf16 v[94:97], v[158:161], v[174:177], v[94:97]
	v_mfma_f32_16x16x32_bf16 v[86:89], v[150:153], v[182:185], v[86:89]
	v_mfma_f32_16x16x32_bf16 v[78:81], v[158:161], v[182:185], v[78:81]
	v_mfma_f32_16x16x32_bf16 v[70:73], v[150:153], v[196:199], v[70:73]
	v_mfma_f32_16x16x32_bf16 v[66:69], v[158:161], v[196:199], v[66:69]
	s_setprio 0
	s_barrier
	s_add_i32 s37, s37, s24
	v_lshl_add_u64 v[210:211], s[20:21], 0, v[190:191]
	s_mov_b32 m0, s37
	ds_read_b128 v[162:165], v240 offset:16384
	ds_read_b128 v[166:169], v240 offset:17408
	ds_read_b128 v[170:173], v240 offset:18432
	ds_read_b128 v[174:177], v240 offset:19456
	ds_read_b128 v[178:181], v240 offset:20480
	ds_read_b128 v[182:185], v240 offset:21504
	ds_read_b128 v[186:189], v240 offset:22528
	ds_read_b128 v[196:199], v240 offset:23552
	global_load_lds_dwordx4 v[210:211], off
	s_add_i32 m0, s37, 0x2000
	s_add_u32 s38, s20, 0x80000
	v_lshl_add_u64 v[212:213], s[20:21], 0, v[204:205]
	s_addc_u32 s39, s21, 0
	s_add_i32 s37, s40, s24
	global_load_lds_dwordx4 v[212:213], off
	v_lshl_add_u64 v[214:215], s[38:39], 0, v[190:191]
	s_mov_b32 m0, s37
	v_lshl_add_u64 v[216:217], s[22:23], 0, v[202:203]
	global_load_lds_dwordx4 v[214:215], off
	s_add_i32 m0, s37, 0x2000
	v_lshl_add_u64 v[214:215], s[38:39], 0, v[204:205]
	global_load_lds_dwordx4 v[214:215], off
	s_mov_b32 m0, s25
	v_lshl_add_u64 v[214:215], s[22:23], 0, v[200:201]
	global_load_lds_dwordx4 v[214:215], off
	s_mov_b32 m0, s26
	s_nop 0
	global_load_lds_dwordx4 v[216:217], off
	s_waitcnt vmcnt(8) lgkmcnt(0)
	s_barrier
	s_setprio 1
	v_mfma_f32_16x16x32_bf16 v[62:65], v[130:133], v[162:165], v[62:65]
	v_mfma_f32_16x16x32_bf16 v[58:61], v[138:141], v[162:165], v[58:61]
	v_mfma_f32_16x16x32_bf16 v[50:53], v[130:133], v[170:173], v[50:53]
	v_mfma_f32_16x16x32_bf16 v[42:45], v[138:141], v[170:173], v[42:45]
	v_mfma_f32_16x16x32_bf16 v[34:37], v[130:133], v[178:181], v[34:37]
	v_mfma_f32_16x16x32_bf16 v[26:29], v[138:141], v[178:181], v[26:29]
	v_mfma_f32_16x16x32_bf16 v[18:21], v[130:133], v[186:189], v[18:21]
	v_mfma_f32_16x16x32_bf16 v[10:13], v[138:141], v[186:189], v[10:13]
	v_mfma_f32_16x16x32_bf16 v[62:65], v[134:137], v[166:169], v[62:65]
	v_mfma_f32_16x16x32_bf16 v[58:61], v[142:145], v[166:169], v[58:61]
	v_mfma_f32_16x16x32_bf16 v[50:53], v[134:137], v[174:177], v[50:53]
	v_mfma_f32_16x16x32_bf16 v[42:45], v[142:145], v[174:177], v[42:45]
	v_mfma_f32_16x16x32_bf16 v[34:37], v[134:137], v[182:185], v[34:37]
	v_mfma_f32_16x16x32_bf16 v[26:29], v[142:145], v[182:185], v[26:29]
	v_mfma_f32_16x16x32_bf16 v[18:21], v[134:137], v[196:199], v[18:21]
	v_mfma_f32_16x16x32_bf16 v[10:13], v[142:145], v[196:199], v[10:13]
	s_setprio 0
	s_setprio 1
	v_mfma_f32_16x16x32_bf16 v[54:57], v[146:149], v[162:165], v[54:57]
	v_mfma_f32_16x16x32_bf16 v[46:49], v[154:157], v[162:165], v[46:49]
	v_mfma_f32_16x16x32_bf16 v[38:41], v[146:149], v[170:173], v[38:41]
	v_mfma_f32_16x16x32_bf16 v[30:33], v[154:157], v[170:173], v[30:33]
	v_mfma_f32_16x16x32_bf16 v[22:25], v[146:149], v[178:181], v[22:25]
	v_mfma_f32_16x16x32_bf16 v[14:17], v[154:157], v[178:181], v[14:17]
	v_mfma_f32_16x16x32_bf16 v[6:9], v[146:149], v[186:189], v[6:9]
	v_mfma_f32_16x16x32_bf16 v[2:5], v[154:157], v[186:189], v[2:5]
	v_mfma_f32_16x16x32_bf16 v[54:57], v[150:153], v[166:169], v[54:57]
	v_mfma_f32_16x16x32_bf16 v[46:49], v[158:161], v[166:169], v[46:49]
	v_mfma_f32_16x16x32_bf16 v[38:41], v[150:153], v[174:177], v[38:41]
	v_mfma_f32_16x16x32_bf16 v[30:33], v[158:161], v[174:177], v[30:33]
	v_mfma_f32_16x16x32_bf16 v[22:25], v[150:153], v[182:185], v[22:25]
	v_mfma_f32_16x16x32_bf16 v[14:17], v[158:161], v[182:185], v[14:17]
	v_mfma_f32_16x16x32_bf16 v[6:9], v[150:153], v[196:199], v[6:9]
	v_mfma_f32_16x16x32_bf16 v[2:5], v[158:161], v[196:199], v[2:5]
	s_setprio 0
	s_barrier
	s_add_i32 s37, 0, 0x18000
	s_add_i32 s38, 0, 0x1c000
	v_add_u32_e32 v142, s37, v238
	v_add_u32_e32 v158, s38, v238
	ds_read_b128 v[130:133], v142
	ds_read_b128 v[134:137], v142 offset:1024
	ds_read_b128 v[138:141], v142 offset:2048
	ds_read_b128 v[142:145], v142 offset:3072
	ds_read_b128 v[146:149], v158
	ds_read_b128 v[150:153], v158 offset:1024
	ds_read_b128 v[154:157], v158 offset:2048
	ds_read_b128 v[158:161], v158 offset:3072
	s_add_u32 s22, s22, 0x80000
	s_addc_u32 s23, s23, 0
	s_mov_b32 m0, s27
	v_lshl_add_u64 v[218:219], s[22:23], 0, v[200:201]
	ds_read_b128 v[162:165], v240 offset:32768
	ds_read_b128 v[166:169], v240 offset:33792
	ds_read_b128 v[170:173], v240 offset:34816
	ds_read_b128 v[174:177], v240 offset:35840
	ds_read_b128 v[178:181], v240 offset:36864
	ds_read_b128 v[182:185], v240 offset:37888
	ds_read_b128 v[186:189], v240 offset:38912
	ds_read_b128 v[196:199], v240 offset:39936
	global_load_lds_dwordx4 v[218:219], off
	s_mov_b32 m0, s28
	v_lshl_add_u64 v[218:219], s[22:23], 0, v[202:203]
	global_load_lds_dwordx4 v[218:219], off
	s_waitcnt vmcnt(8) lgkmcnt(0)
	s_barrier
	s_setprio 1
	v_mfma_f32_16x16x32_bf16 v[126:129], v[130:133], v[162:165], v[126:129]
	v_mfma_f32_16x16x32_bf16 v[122:125], v[138:141], v[162:165], v[122:125]
	v_mfma_f32_16x16x32_bf16 v[110:113], v[130:133], v[170:173], v[110:113]
	v_mfma_f32_16x16x32_bf16 v[106:109], v[138:141], v[170:173], v[106:109]
	v_mfma_f32_16x16x32_bf16 v[98:101], v[130:133], v[178:181], v[98:101]
	v_mfma_f32_16x16x32_bf16 v[90:93], v[138:141], v[178:181], v[90:93]
	v_mfma_f32_16x16x32_bf16 v[82:85], v[130:133], v[186:189], v[82:85]
	v_mfma_f32_16x16x32_bf16 v[74:77], v[138:141], v[186:189], v[74:77]
	v_mfma_f32_16x16x32_bf16 v[126:129], v[134:137], v[166:169], v[126:129]
	v_mfma_f32_16x16x32_bf16 v[122:125], v[142:145], v[166:169], v[122:125]
	v_mfma_f32_16x16x32_bf16 v[110:113], v[134:137], v[174:177], v[110:113]
	v_mfma_f32_16x16x32_bf16 v[106:109], v[142:145], v[174:177], v[106:109]
	v_mfma_f32_16x16x32_bf16 v[98:101], v[134:137], v[182:185], v[98:101]
	v_mfma_f32_16x16x32_bf16 v[90:93], v[142:145], v[182:185], v[90:93]
	v_mfma_f32_16x16x32_bf16 v[82:85], v[134:137], v[196:199], v[82:85]
	v_mfma_f32_16x16x32_bf16 v[74:77], v[142:145], v[196:199], v[74:77]
	s_setprio 0
	s_setprio 1
	v_mfma_f32_16x16x32_bf16 v[118:121], v[146:149], v[162:165], v[118:121]
	v_mfma_f32_16x16x32_bf16 v[114:117], v[154:157], v[162:165], v[114:117]
	v_mfma_f32_16x16x32_bf16 v[102:105], v[146:149], v[170:173], v[102:105]
	v_mfma_f32_16x16x32_bf16 v[94:97], v[154:157], v[170:173], v[94:97]
	v_mfma_f32_16x16x32_bf16 v[86:89], v[146:149], v[178:181], v[86:89]
	v_mfma_f32_16x16x32_bf16 v[78:81], v[154:157], v[178:181], v[78:81]
	v_mfma_f32_16x16x32_bf16 v[70:73], v[146:149], v[186:189], v[70:73]
	v_mfma_f32_16x16x32_bf16 v[66:69], v[154:157], v[186:189], v[66:69]
	v_mfma_f32_16x16x32_bf16 v[118:121], v[150:153], v[166:169], v[118:121]
	v_mfma_f32_16x16x32_bf16 v[114:117], v[158:161], v[166:169], v[114:117]
	v_mfma_f32_16x16x32_bf16 v[102:105], v[150:153], v[174:177], v[102:105]
	v_mfma_f32_16x16x32_bf16 v[94:97], v[158:161], v[174:177], v[94:97]
	v_mfma_f32_16x16x32_bf16 v[86:89], v[150:153], v[182:185], v[86:89]
	v_mfma_f32_16x16x32_bf16 v[78:81], v[158:161], v[182:185], v[78:81]
	v_mfma_f32_16x16x32_bf16 v[70:73], v[150:153], v[196:199], v[70:73]
	v_mfma_f32_16x16x32_bf16 v[66:69], v[158:161], v[196:199], v[66:69]
	s_setprio 0
	s_barrier
	s_add_i32 s22, s37, s24
	v_lshl_add_u64 v[210:211], v[210:211], 0, s[58:59]
	s_mov_b32 m0, s22
	ds_read_b128 v[162:165], v240 offset:49152
	ds_read_b128 v[166:169], v240 offset:50176
	ds_read_b128 v[170:173], v240 offset:51200
	ds_read_b128 v[174:177], v240 offset:52224
	ds_read_b128 v[178:181], v240 offset:53248
	ds_read_b128 v[182:185], v240 offset:54272
	ds_read_b128 v[186:189], v240 offset:55296
	ds_read_b128 v[196:199], v240 offset:56320
	global_load_lds_dwordx4 v[210:211], off
	s_add_i32 m0, s22, 0x2000
	s_add_u32 s20, s20, 0x80080
	v_lshl_add_u64 v[210:211], v[212:213], 0, s[58:59]
	s_addc_u32 s21, s21, 0
	s_add_i32 s22, s38, s24
	global_load_lds_dwordx4 v[210:211], off
	s_mov_b32 m0, s22
	v_lshl_add_u64 v[210:211], s[20:21], 0, v[190:191]
	global_load_lds_dwordx4 v[210:211], off
	s_add_i32 m0, s22, 0x2000
	v_lshl_add_u64 v[210:211], s[20:21], 0, v[204:205]
	global_load_lds_dwordx4 v[210:211], off
	s_mov_b32 m0, s29
	v_lshl_add_u64 v[210:211], v[214:215], 0, s[58:59]
	global_load_lds_dwordx4 v[210:211], off
	s_mov_b32 m0, s30
	v_lshl_add_u64 v[210:211], v[216:217], 0, s[58:59]
	global_load_lds_dwordx4 v[210:211], off
	s_waitcnt vmcnt(8) lgkmcnt(0)
	s_barrier
	s_setprio 1
	v_mfma_f32_16x16x32_bf16 v[62:65], v[130:133], v[162:165], v[62:65]
	v_mfma_f32_16x16x32_bf16 v[58:61], v[138:141], v[162:165], v[58:61]
	v_mfma_f32_16x16x32_bf16 v[50:53], v[130:133], v[170:173], v[50:53]
	v_mfma_f32_16x16x32_bf16 v[42:45], v[138:141], v[170:173], v[42:45]
	v_mfma_f32_16x16x32_bf16 v[34:37], v[130:133], v[178:181], v[34:37]
	v_mfma_f32_16x16x32_bf16 v[26:29], v[138:141], v[178:181], v[26:29]
	v_mfma_f32_16x16x32_bf16 v[18:21], v[130:133], v[186:189], v[18:21]
	v_mfma_f32_16x16x32_bf16 v[10:13], v[138:141], v[186:189], v[10:13]
	v_mfma_f32_16x16x32_bf16 v[62:65], v[134:137], v[166:169], v[62:65]
	v_mfma_f32_16x16x32_bf16 v[58:61], v[142:145], v[166:169], v[58:61]
	v_mfma_f32_16x16x32_bf16 v[50:53], v[134:137], v[174:177], v[50:53]
	v_mfma_f32_16x16x32_bf16 v[42:45], v[142:145], v[174:177], v[42:45]
	v_mfma_f32_16x16x32_bf16 v[34:37], v[134:137], v[182:185], v[34:37]
	v_mfma_f32_16x16x32_bf16 v[26:29], v[142:145], v[182:185], v[26:29]
	v_mfma_f32_16x16x32_bf16 v[18:21], v[134:137], v[196:199], v[18:21]
	v_mfma_f32_16x16x32_bf16 v[10:13], v[142:145], v[196:199], v[10:13]
	s_setprio 0
	s_setprio 1
	v_mfma_f32_16x16x32_bf16 v[54:57], v[146:149], v[162:165], v[54:57]
	v_mfma_f32_16x16x32_bf16 v[46:49], v[154:157], v[162:165], v[46:49]
	v_mfma_f32_16x16x32_bf16 v[38:41], v[146:149], v[170:173], v[38:41]
	v_mfma_f32_16x16x32_bf16 v[30:33], v[154:157], v[170:173], v[30:33]
	v_mfma_f32_16x16x32_bf16 v[22:25], v[146:149], v[178:181], v[22:25]
	v_mfma_f32_16x16x32_bf16 v[14:17], v[154:157], v[178:181], v[14:17]
	v_mfma_f32_16x16x32_bf16 v[6:9], v[146:149], v[186:189], v[6:9]
	v_mfma_f32_16x16x32_bf16 v[2:5], v[154:157], v[186:189], v[2:5]
	v_mfma_f32_16x16x32_bf16 v[54:57], v[150:153], v[166:169], v[54:57]
	v_mfma_f32_16x16x32_bf16 v[46:49], v[158:161], v[166:169], v[46:49]
	v_mfma_f32_16x16x32_bf16 v[38:41], v[150:153], v[174:177], v[38:41]
	v_mfma_f32_16x16x32_bf16 v[30:33], v[158:161], v[174:177], v[30:33]
	v_mfma_f32_16x16x32_bf16 v[22:25], v[150:153], v[182:185], v[22:25]
	v_mfma_f32_16x16x32_bf16 v[14:17], v[158:161], v[182:185], v[14:17]
	v_mfma_f32_16x16x32_bf16 v[6:9], v[150:153], v[196:199], v[6:9]
	v_mfma_f32_16x16x32_bf16 v[2:5], v[158:161], v[196:199], v[2:5]
	s_setprio 0
	s_barrier
	s_add_i32 s36, s36, 2
	s_add_u32 s16, s16, 0x100
	s_addc_u32 s17, s17, 0
	s_add_u32 s34, s34, 0x100
	s_addc_u32 s35, s35, 0
	s_cmp_gt_u32 s36, 29
	s_cbranch_scc0 .LBB0_748

.LBB0_771:
	s_ashr_i32 s17, s16, 31
	s_lshl_b64 s[20:21], s[16:17], 20
	v_readlane_b32 s0, v254, 60
	s_add_u32 s20, s0, s20
	v_readlane_b32 s0, v254, 61
	s_addc_u32 s21, s0, s21
	s_and_b64 s[22:23], s[6:7], exec
	s_cselect_b32 s17, s21, s27
	s_cselect_b32 s40, s20, s26
	s_ashr_i32 s15, s14, 31
	s_lshl_b64 s[22:23], s[14:15], 20
	v_readlane_b32 s0, v254, 40
	v_readlane_b32 s1, v254, 41
	s_add_u32 s22, s0, s22
	s_addc_u32 s23, s1, s23
	s_and_b64 s[30:31], s[6:7], exec
	s_cselect_b32 s15, s23, s29
	s_cselect_b32 s41, s22, s28
	s_add_u32 s26, s26, 0x80080
	s_addc_u32 s27, s27, 0
	s_add_u32 s42, s28, 0x100
	s_addc_u32 s43, s29, 0
	s_mov_b32 s46, -2
	v_readlane_b32 s47, v255, 49
	s_nop 3
	s_cmp_eq_u32 s47, 4
	v_writelane_b32 v255, 4, 49
	s_cbranch_scc0 .Ltrip0_strict_3
	s_add_u32 s28, s26, 0xfff80080
	s_addc_u32 s29, s27, -1
	s_add_i32 s47, 0, 0x10000
	s_cmp_eq_u32 s46, 28
	s_cselect_b32 s31, s17, s29
	s_cselect_b32 s30, s40, s28
	s_cselect_b32 s29, s15, s43
	s_cselect_b32 s28, s41, s42
	s_add_i32 s55, 0, 0x14000
	v_add_u32_e32 v142, s47, v220
	v_add_u32_e32 v158, s55, v220
	ds_read_b128 v[130:133], v142
	ds_read_b128 v[134:137], v142 offset:1024
	ds_read_b128 v[138:141], v142 offset:2048
	ds_read_b128 v[142:145], v142 offset:3072
	ds_read_b128 v[146:149], v158
	ds_read_b128 v[150:153], v158 offset:1024
	ds_read_b128 v[154:157], v158 offset:2048
	ds_read_b128 v[158:161], v158 offset:3072
	v_lshl_add_u64 v[210:211], s[26:27], 0, v[202:203]
	s_add_i32 m0, s34, 0xc000
	ds_read_b128 v[162:165], v222
	ds_read_b128 v[166:169], v222 offset:1024
	ds_read_b128 v[170:173], v222 offset:2048
	ds_read_b128 v[174:177], v222 offset:3072
	ds_read_b128 v[178:181], v222 offset:4096
	ds_read_b128 v[182:185], v222 offset:5120
	ds_read_b128 v[196:199], v222 offset:6144
	ds_read_b128 v[206:209], v222 offset:7168
	global_load_lds_dwordx4 v[210:211], off
	s_add_i32 m0, s34, 0xe000
	v_lshl_add_u64 v[210:211], s[26:27], 0, v[204:205]
	global_load_lds_dwordx4 v[210:211], off
	s_waitcnt vmcnt(24) lgkmcnt(0)
	s_barrier
	s_setprio 1
	v_mfma_f32_16x16x32_bf16 v[126:129], v[130:133], v[162:165], 0
	v_mfma_f32_16x16x32_bf16 v[122:125], v[138:141], v[162:165], 0
	v_mfma_f32_16x16x32_bf16 v[110:113], v[130:133], v[170:173], 0
	v_mfma_f32_16x16x32_bf16 v[106:109], v[138:141], v[170:173], 0
	v_mfma_f32_16x16x32_bf16 v[94:97], v[130:133], v[178:181], 0
	v_mfma_f32_16x16x32_bf16 v[90:93], v[138:141], v[178:181], 0
	v_mfma_f32_16x16x32_bf16 v[78:81], v[130:133], v[196:199], 0
	v_mfma_f32_16x16x32_bf16 v[74:77], v[138:141], v[196:199], 0
	v_mfma_f32_16x16x32_bf16 v[126:129], v[134:137], v[166:169], v[126:129]
	v_mfma_f32_16x16x32_bf16 v[122:125], v[142:145], v[166:169], v[122:125]
	v_mfma_f32_16x16x32_bf16 v[110:113], v[134:137], v[174:177], v[110:113]
	v_mfma_f32_16x16x32_bf16 v[106:109], v[142:145], v[174:177], v[106:109]
	v_mfma_f32_16x16x32_bf16 v[94:97], v[134:137], v[182:185], v[94:97]
	v_mfma_f32_16x16x32_bf16 v[90:93], v[142:145], v[182:185], v[90:93]
	v_mfma_f32_16x16x32_bf16 v[78:81], v[134:137], v[206:209], v[78:81]
	v_mfma_f32_16x16x32_bf16 v[74:77], v[142:145], v[206:209], v[74:77]
	s_setprio 0
	s_setprio 1
	v_mfma_f32_16x16x32_bf16 v[118:121], v[146:149], v[162:165], 0
	v_mfma_f32_16x16x32_bf16 v[114:117], v[154:157], v[162:165], 0
	v_mfma_f32_16x16x32_bf16 v[102:105], v[146:149], v[170:173], 0
	v_mfma_f32_16x16x32_bf16 v[98:101], v[154:157], v[170:173], 0
	v_mfma_f32_16x16x32_bf16 v[86:89], v[146:149], v[178:181], 0
	v_mfma_f32_16x16x32_bf16 v[82:85], v[154:157], v[178:181], 0
	v_mfma_f32_16x16x32_bf16 v[70:73], v[146:149], v[196:199], 0
	v_mfma_f32_16x16x32_bf16 v[66:69], v[154:157], v[196:199], 0
	v_mfma_f32_16x16x32_bf16 v[118:121], v[150:153], v[166:169], v[118:121]
	v_mfma_f32_16x16x32_bf16 v[114:117], v[158:161], v[166:169], v[114:117]
	v_mfma_f32_16x16x32_bf16 v[102:105], v[150:153], v[174:177], v[102:105]
	v_mfma_f32_16x16x32_bf16 v[98:101], v[158:161], v[174:177], v[98:101]
	v_mfma_f32_16x16x32_bf16 v[86:89], v[150:153], v[182:185], v[86:89]
	v_mfma_f32_16x16x32_bf16 v[82:85], v[158:161], v[182:185], v[82:85]
	v_mfma_f32_16x16x32_bf16 v[70:73], v[150:153], v[206:209], v[70:73]
	v_mfma_f32_16x16x32_bf16 v[66:69], v[158:161], v[206:209], v[66:69]
	s_setprio 0
	s_barrier
	s_add_i32 s47, s47, s33
	v_lshl_add_u64 v[210:211], s[28:29], 0, v[190:191]
	s_mov_b32 m0, s47
	ds_read_b128 v[162:165], v222 offset:16384
	ds_read_b128 v[166:169], v222 offset:17408
	ds_read_b128 v[170:173], v222 offset:18432
	ds_read_b128 v[174:177], v222 offset:19456
	ds_read_b128 v[178:181], v222 offset:20480
	ds_read_b128 v[182:185], v222 offset:21504
	ds_read_b128 v[196:199], v222 offset:22528
	ds_read_b128 v[206:209], v222 offset:23552
	global_load_lds_dwordx4 v[210:211], off
	s_add_i32 m0, s47, 0x2000
	s_add_u32 s52, s28, 0x80000
	v_lshl_add_u64 v[212:213], s[28:29], 0, v[200:201]
	s_addc_u32 s53, s29, 0
	s_add_i32 s47, s55, s33
	global_load_lds_dwordx4 v[212:213], off
	v_lshl_add_u64 v[214:215], s[52:53], 0, v[190:191]
	s_mov_b32 m0, s47
	v_lshl_add_u64 v[216:217], s[30:31], 0, v[188:189]
	global_load_lds_dwordx4 v[214:215], off
	s_add_i32 m0, s47, 0x2000
	v_lshl_add_u64 v[214:215], s[52:53], 0, v[200:201]
	global_load_lds_dwordx4 v[214:215], off
	s_mov_b32 m0, s34
	v_lshl_add_u64 v[214:215], s[30:31], 0, v[186:187]
	global_load_lds_dwordx4 v[214:215], off
	s_mov_b32 m0, s35
	s_nop 0
	global_load_lds_dwordx4 v[216:217], off
	s_waitcnt vmcnt(24) lgkmcnt(0)
	s_barrier
	s_setprio 1
	v_mfma_f32_16x16x32_bf16 v[62:65], v[130:133], v[162:165], 0
	v_mfma_f32_16x16x32_bf16 v[58:61], v[138:141], v[162:165], 0
	v_mfma_f32_16x16x32_bf16 v[46:49], v[130:133], v[170:173], 0
	v_mfma_f32_16x16x32_bf16 v[42:45], v[138:141], v[170:173], 0
	v_mfma_f32_16x16x32_bf16 v[30:33], v[130:133], v[178:181], 0
	v_mfma_f32_16x16x32_bf16 v[26:29], v[138:141], v[178:181], 0
	v_mfma_f32_16x16x32_bf16 v[14:17], v[130:133], v[196:199], 0
	v_mfma_f32_16x16x32_bf16 v[10:13], v[138:141], v[196:199], 0
	v_mfma_f32_16x16x32_bf16 v[62:65], v[134:137], v[166:169], v[62:65]
	v_mfma_f32_16x16x32_bf16 v[58:61], v[142:145], v[166:169], v[58:61]
	v_mfma_f32_16x16x32_bf16 v[46:49], v[134:137], v[174:177], v[46:49]
	v_mfma_f32_16x16x32_bf16 v[42:45], v[142:145], v[174:177], v[42:45]
	v_mfma_f32_16x16x32_bf16 v[30:33], v[134:137], v[182:185], v[30:33]
	v_mfma_f32_16x16x32_bf16 v[26:29], v[142:145], v[182:185], v[26:29]
	v_mfma_f32_16x16x32_bf16 v[14:17], v[134:137], v[206:209], v[14:17]
	v_mfma_f32_16x16x32_bf16 v[10:13], v[142:145], v[206:209], v[10:13]
	s_setprio 0
	s_setprio 1
	v_mfma_f32_16x16x32_bf16 v[54:57], v[146:149], v[162:165], 0
	v_mfma_f32_16x16x32_bf16 v[50:53], v[154:157], v[162:165], 0
	v_mfma_f32_16x16x32_bf16 v[38:41], v[146:149], v[170:173], 0
	v_mfma_f32_16x16x32_bf16 v[34:37], v[154:157], v[170:173], 0
	v_mfma_f32_16x16x32_bf16 v[22:25], v[146:149], v[178:181], 0
	v_mfma_f32_16x16x32_bf16 v[18:21], v[154:157], v[178:181], 0
	v_mfma_f32_16x16x32_bf16 v[6:9], v[146:149], v[196:199], 0
	v_mfma_f32_16x16x32_bf16 v[2:5], v[154:157], v[196:199], 0
	v_mfma_f32_16x16x32_bf16 v[54:57], v[150:153], v[166:169], v[54:57]
	v_mfma_f32_16x16x32_bf16 v[50:53], v[158:161], v[166:169], v[50:53]
	v_mfma_f32_16x16x32_bf16 v[38:41], v[150:153], v[174:177], v[38:41]
	v_mfma_f32_16x16x32_bf16 v[34:37], v[158:161], v[174:177], v[34:37]
	v_mfma_f32_16x16x32_bf16 v[22:25], v[150:153], v[182:185], v[22:25]
	v_mfma_f32_16x16x32_bf16 v[18:21], v[158:161], v[182:185], v[18:21]
	v_mfma_f32_16x16x32_bf16 v[6:9], v[150:153], v[206:209], v[6:9]
	v_mfma_f32_16x16x32_bf16 v[2:5], v[158:161], v[206:209], v[2:5]
	s_setprio 0
	s_barrier
	s_add_i32 s47, 0, 0x18000
	s_add_i32 s52, 0, 0x1c000
	v_add_u32_e32 v142, s47, v220
	v_add_u32_e32 v158, s52, v220
	ds_read_b128 v[130:133], v142
	ds_read_b128 v[134:137], v142 offset:1024
	ds_read_b128 v[138:141], v142 offset:2048
	ds_read_b128 v[142:145], v142 offset:3072
	ds_read_b128 v[146:149], v158
	ds_read_b128 v[150:153], v158 offset:1024
	ds_read_b128 v[154:157], v158 offset:2048
	ds_read_b128 v[158:161], v158 offset:3072
	s_add_u32 s30, s30, 0x80000
	s_addc_u32 s31, s31, 0
	s_mov_b32 m0, s36
	v_lshl_add_u64 v[218:219], s[30:31], 0, v[186:187]
	ds_read_b128 v[162:165], v222 offset:32768
	ds_read_b128 v[166:169], v222 offset:33792
	ds_read_b128 v[170:173], v222 offset:34816
	ds_read_b128 v[174:177], v222 offset:35840
	ds_read_b128 v[178:181], v222 offset:36864
	ds_read_b128 v[182:185], v222 offset:37888
	ds_read_b128 v[196:199], v222 offset:38912
	ds_read_b128 v[206:209], v222 offset:39936
	global_load_lds_dwordx4 v[218:219], off
	s_mov_b32 m0, s37
	v_lshl_add_u64 v[218:219], s[30:31], 0, v[188:189]
	global_load_lds_dwordx4 v[218:219], off
	s_waitcnt vmcnt(8) lgkmcnt(0)
	s_barrier
	s_setprio 1
	v_mfma_f32_16x16x32_bf16 v[126:129], v[130:133], v[162:165], v[126:129]
	v_mfma_f32_16x16x32_bf16 v[122:125], v[138:141], v[162:165], v[122:125]
	v_mfma_f32_16x16x32_bf16 v[110:113], v[130:133], v[170:173], v[110:113]
	v_mfma_f32_16x16x32_bf16 v[106:109], v[138:141], v[170:173], v[106:109]
	v_mfma_f32_16x16x32_bf16 v[94:97], v[130:133], v[178:181], v[94:97]
	v_mfma_f32_16x16x32_bf16 v[90:93], v[138:141], v[178:181], v[90:93]
	v_mfma_f32_16x16x32_bf16 v[78:81], v[130:133], v[196:199], v[78:81]
	v_mfma_f32_16x16x32_bf16 v[74:77], v[138:141], v[196:199], v[74:77]
	v_mfma_f32_16x16x32_bf16 v[126:129], v[134:137], v[166:169], v[126:129]
	v_mfma_f32_16x16x32_bf16 v[122:125], v[142:145], v[166:169], v[122:125]
	v_mfma_f32_16x16x32_bf16 v[110:113], v[134:137], v[174:177], v[110:113]
	v_mfma_f32_16x16x32_bf16 v[106:109], v[142:145], v[174:177], v[106:109]
	v_mfma_f32_16x16x32_bf16 v[94:97], v[134:137], v[182:185], v[94:97]
	v_mfma_f32_16x16x32_bf16 v[90:93], v[142:145], v[182:185], v[90:93]
	v_mfma_f32_16x16x32_bf16 v[78:81], v[134:137], v[206:209], v[78:81]
	v_mfma_f32_16x16x32_bf16 v[74:77], v[142:145], v[206:209], v[74:77]
	s_setprio 0
	s_setprio 1
	v_mfma_f32_16x16x32_bf16 v[118:121], v[146:149], v[162:165], v[118:121]
	v_mfma_f32_16x16x32_bf16 v[114:117], v[154:157], v[162:165], v[114:117]
	v_mfma_f32_16x16x32_bf16 v[102:105], v[146:149], v[170:173], v[102:105]
	v_mfma_f32_16x16x32_bf16 v[98:101], v[154:157], v[170:173], v[98:101]
	v_mfma_f32_16x16x32_bf16 v[86:89], v[146:149], v[178:181], v[86:89]
	v_mfma_f32_16x16x32_bf16 v[82:85], v[154:157], v[178:181], v[82:85]
	v_mfma_f32_16x16x32_bf16 v[70:73], v[146:149], v[196:199], v[70:73]
	v_mfma_f32_16x16x32_bf16 v[66:69], v[154:157], v[196:199], v[66:69]
	v_mfma_f32_16x16x32_bf16 v[118:121], v[150:153], v[166:169], v[118:121]
	v_mfma_f32_16x16x32_bf16 v[114:117], v[158:161], v[166:169], v[114:117]
	v_mfma_f32_16x16x32_bf16 v[102:105], v[150:153], v[174:177], v[102:105]
	v_mfma_f32_16x16x32_bf16 v[98:101], v[158:161], v[174:177], v[98:101]
	v_mfma_f32_16x16x32_bf16 v[86:89], v[150:153], v[182:185], v[86:89]
	v_mfma_f32_16x16x32_bf16 v[82:85], v[158:161], v[182:185], v[82:85]
	v_mfma_f32_16x16x32_bf16 v[70:73], v[150:153], v[206:209], v[70:73]
	v_mfma_f32_16x16x32_bf16 v[66:69], v[158:161], v[206:209], v[66:69]
	s_setprio 0
	s_barrier
	s_add_i32 s30, s47, s33
	v_lshl_add_u64 v[210:211], v[210:211], 0, s[58:59]
	s_mov_b32 m0, s30
	ds_read_b128 v[162:165], v222 offset:49152
	ds_read_b128 v[166:169], v222 offset:50176
	ds_read_b128 v[170:173], v222 offset:51200
	ds_read_b128 v[174:177], v222 offset:52224
	ds_read_b128 v[178:181], v222 offset:53248
	ds_read_b128 v[182:185], v222 offset:54272
	ds_read_b128 v[196:199], v222 offset:55296
	ds_read_b128 v[206:209], v222 offset:56320
	global_load_lds_dwordx4 v[210:211], off
	s_add_i32 m0, s30, 0x2000
	s_add_u32 s28, s28, 0x80080
	v_lshl_add_u64 v[210:211], v[212:213], 0, s[58:59]
	s_addc_u32 s29, s29, 0
	s_add_i32 s30, s52, s33
	global_load_lds_dwordx4 v[210:211], off
	s_mov_b32 m0, s30
	v_lshl_add_u64 v[210:211], s[28:29], 0, v[190:191]
	global_load_lds_dwordx4 v[210:211], off
	s_add_i32 m0, s30, 0x2000
	v_lshl_add_u64 v[210:211], s[28:29], 0, v[200:201]
	global_load_lds_dwordx4 v[210:211], off
	s_mov_b32 m0, s38
	v_lshl_add_u64 v[210:211], v[214:215], 0, s[58:59]
	global_load_lds_dwordx4 v[210:211], off
	s_mov_b32 m0, s39
	v_lshl_add_u64 v[210:211], v[216:217], 0, s[58:59]
	global_load_lds_dwordx4 v[210:211], off
	s_waitcnt vmcnt(8) lgkmcnt(0)
	s_barrier
	s_setprio 1
	v_mfma_f32_16x16x32_bf16 v[62:65], v[130:133], v[162:165], v[62:65]
	v_mfma_f32_16x16x32_bf16 v[58:61], v[138:141], v[162:165], v[58:61]
	v_mfma_f32_16x16x32_bf16 v[46:49], v[130:133], v[170:173], v[46:49]
	v_mfma_f32_16x16x32_bf16 v[42:45], v[138:141], v[170:173], v[42:45]
	v_mfma_f32_16x16x32_bf16 v[30:33], v[130:133], v[178:181], v[30:33]
	v_mfma_f32_16x16x32_bf16 v[26:29], v[138:141], v[178:181], v[26:29]
	v_mfma_f32_16x16x32_bf16 v[14:17], v[130:133], v[196:199], v[14:17]
	v_mfma_f32_16x16x32_bf16 v[10:13], v[138:141], v[196:199], v[10:13]
	v_mfma_f32_16x16x32_bf16 v[62:65], v[134:137], v[166:169], v[62:65]
	v_mfma_f32_16x16x32_bf16 v[58:61], v[142:145], v[166:169], v[58:61]
	v_mfma_f32_16x16x32_bf16 v[46:49], v[134:137], v[174:177], v[46:49]
	v_mfma_f32_16x16x32_bf16 v[42:45], v[142:145], v[174:177], v[42:45]
	v_mfma_f32_16x16x32_bf16 v[30:33], v[134:137], v[182:185], v[30:33]
	v_mfma_f32_16x16x32_bf16 v[26:29], v[142:145], v[182:185], v[26:29]
	v_mfma_f32_16x16x32_bf16 v[14:17], v[134:137], v[206:209], v[14:17]
	v_mfma_f32_16x16x32_bf16 v[10:13], v[142:145], v[206:209], v[10:13]
	s_setprio 0
	s_setprio 1
	v_mfma_f32_16x16x32_bf16 v[54:57], v[146:149], v[162:165], v[54:57]
	v_mfma_f32_16x16x32_bf16 v[50:53], v[154:157], v[162:165], v[50:53]
	v_mfma_f32_16x16x32_bf16 v[38:41], v[146:149], v[170:173], v[38:41]
	v_mfma_f32_16x16x32_bf16 v[34:37], v[154:157], v[170:173], v[34:37]
	v_mfma_f32_16x16x32_bf16 v[22:25], v[146:149], v[178:181], v[22:25]
	v_mfma_f32_16x16x32_bf16 v[18:21], v[154:157], v[178:181], v[18:21]
	v_mfma_f32_16x16x32_bf16 v[6:9], v[146:149], v[196:199], v[6:9]
	v_mfma_f32_16x16x32_bf16 v[2:5], v[154:157], v[196:199], v[2:5]
	v_mfma_f32_16x16x32_bf16 v[54:57], v[150:153], v[166:169], v[54:57]
	v_mfma_f32_16x16x32_bf16 v[50:53], v[158:161], v[166:169], v[50:53]
	v_mfma_f32_16x16x32_bf16 v[38:41], v[150:153], v[174:177], v[38:41]
	v_mfma_f32_16x16x32_bf16 v[34:37], v[158:161], v[174:177], v[34:37]
	v_mfma_f32_16x16x32_bf16 v[22:25], v[150:153], v[182:185], v[22:25]
	v_mfma_f32_16x16x32_bf16 v[18:21], v[158:161], v[182:185], v[18:21]
	v_mfma_f32_16x16x32_bf16 v[6:9], v[150:153], v[206:209], v[6:9]
	v_mfma_f32_16x16x32_bf16 v[2:5], v[158:161], v[206:209], v[2:5]
	s_setprio 0
	s_barrier
	s_add_i32 s46, s46, 2
	s_add_u32 s26, s26, 0x100
	s_addc_u32 s27, s27, 0
	s_add_u32 s42, s42, 0x100
	s_addc_u32 s43, s43, 0
	s_cmp_gt_u32 s46, 29
	s_cbranch_scc1 .Lpeel_done_3
	s_branch .LBB0_772
.Ltrip0_strict_3:
	s_add_u32 s28, s26, 0xfff80080
	s_addc_u32 s29, s27, -1
	s_add_i32 s47, 0, 0x10000
	s_cmp_eq_u32 s46, 28
	s_cselect_b32 s31, s17, s29
	s_cselect_b32 s30, s40, s28
	s_cselect_b32 s29, s15, s43
	s_cselect_b32 s28, s41, s42
	s_add_i32 s55, 0, 0x14000
	v_add_u32_e32 v142, s47, v220
	v_add_u32_e32 v158, s55, v220
	ds_read_b128 v[130:133], v142
	ds_read_b128 v[134:137], v142 offset:1024
	ds_read_b128 v[138:141], v142 offset:2048
	ds_read_b128 v[142:145], v142 offset:3072
	ds_read_b128 v[146:149], v158
	ds_read_b128 v[150:153], v158 offset:1024
	ds_read_b128 v[154:157], v158 offset:2048
	ds_read_b128 v[158:161], v158 offset:3072
	v_lshl_add_u64 v[210:211], s[26:27], 0, v[202:203]
	s_add_i32 m0, s34, 0xc000
	ds_read_b128 v[162:165], v222
	ds_read_b128 v[166:169], v222 offset:1024
	ds_read_b128 v[170:173], v222 offset:2048
	ds_read_b128 v[174:177], v222 offset:3072
	ds_read_b128 v[178:181], v222 offset:4096
	ds_read_b128 v[182:185], v222 offset:5120
	ds_read_b128 v[196:199], v222 offset:6144
	ds_read_b128 v[206:209], v222 offset:7168
	global_load_lds_dwordx4 v[210:211], off
	s_add_i32 m0, s34, 0xe000
	v_lshl_add_u64 v[210:211], s[26:27], 0, v[204:205]
	global_load_lds_dwordx4 v[210:211], off
	s_waitcnt vmcnt(8) lgkmcnt(0)
	s_barrier
	s_setprio 1
	v_mfma_f32_16x16x32_bf16 v[126:129], v[130:133], v[162:165], 0
	v_mfma_f32_16x16x32_bf16 v[122:125], v[138:141], v[162:165], 0
	v_mfma_f32_16x16x32_bf16 v[110:113], v[130:133], v[170:173], 0
	v_mfma_f32_16x16x32_bf16 v[106:109], v[138:141], v[170:173], 0
	v_mfma_f32_16x16x32_bf16 v[94:97], v[130:133], v[178:181], 0
	v_mfma_f32_16x16x32_bf16 v[90:93], v[138:141], v[178:181], 0
	v_mfma_f32_16x16x32_bf16 v[78:81], v[130:133], v[196:199], 0
	v_mfma_f32_16x16x32_bf16 v[74:77], v[138:141], v[196:199], 0
	v_mfma_f32_16x16x32_bf16 v[126:129], v[134:137], v[166:169], v[126:129]
	v_mfma_f32_16x16x32_bf16 v[122:125], v[142:145], v[166:169], v[122:125]
	v_mfma_f32_16x16x32_bf16 v[110:113], v[134:137], v[174:177], v[110:113]
	v_mfma_f32_16x16x32_bf16 v[106:109], v[142:145], v[174:177], v[106:109]
	v_mfma_f32_16x16x32_bf16 v[94:97], v[134:137], v[182:185], v[94:97]
	v_mfma_f32_16x16x32_bf16 v[90:93], v[142:145], v[182:185], v[90:93]
	v_mfma_f32_16x16x32_bf16 v[78:81], v[134:137], v[206:209], v[78:81]
	v_mfma_f32_16x16x32_bf16 v[74:77], v[142:145], v[206:209], v[74:77]
	s_setprio 0
	s_setprio 1
	v_mfma_f32_16x16x32_bf16 v[118:121], v[146:149], v[162:165], 0
	v_mfma_f32_16x16x32_bf16 v[114:117], v[154:157], v[162:165], 0
	v_mfma_f32_16x16x32_bf16 v[102:105], v[146:149], v[170:173], 0
	v_mfma_f32_16x16x32_bf16 v[98:101], v[154:157], v[170:173], 0
	v_mfma_f32_16x16x32_bf16 v[86:89], v[146:149], v[178:181], 0
	v_mfma_f32_16x16x32_bf16 v[82:85], v[154:157], v[178:181], 0
	v_mfma_f32_16x16x32_bf16 v[70:73], v[146:149], v[196:199], 0
	v_mfma_f32_16x16x32_bf16 v[66:69], v[154:157], v[196:199], 0
	v_mfma_f32_16x16x32_bf16 v[118:121], v[150:153], v[166:169], v[118:121]
	v_mfma_f32_16x16x32_bf16 v[114:117], v[158:161], v[166:169], v[114:117]
	v_mfma_f32_16x16x32_bf16 v[102:105], v[150:153], v[174:177], v[102:105]
	v_mfma_f32_16x16x32_bf16 v[98:101], v[158:161], v[174:177], v[98:101]
	v_mfma_f32_16x16x32_bf16 v[86:89], v[150:153], v[182:185], v[86:89]
	v_mfma_f32_16x16x32_bf16 v[82:85], v[158:161], v[182:185], v[82:85]
	v_mfma_f32_16x16x32_bf16 v[70:73], v[150:153], v[206:209], v[70:73]
	v_mfma_f32_16x16x32_bf16 v[66:69], v[158:161], v[206:209], v[66:69]
	s_setprio 0
	s_barrier
	s_add_i32 s47, s47, s33
	v_lshl_add_u64 v[210:211], s[28:29], 0, v[190:191]
	s_mov_b32 m0, s47
	ds_read_b128 v[162:165], v222 offset:16384
	ds_read_b128 v[166:169], v222 offset:17408
	ds_read_b128 v[170:173], v222 offset:18432
	ds_read_b128 v[174:177], v222 offset:19456
	ds_read_b128 v[178:181], v222 offset:20480
	ds_read_b128 v[182:185], v222 offset:21504
	ds_read_b128 v[196:199], v222 offset:22528
	ds_read_b128 v[206:209], v222 offset:23552
	global_load_lds_dwordx4 v[210:211], off
	s_add_i32 m0, s47, 0x2000
	s_add_u32 s52, s28, 0x80000
	v_lshl_add_u64 v[212:213], s[28:29], 0, v[200:201]
	s_addc_u32 s53, s29, 0
	s_add_i32 s47, s55, s33
	global_load_lds_dwordx4 v[212:213], off
	v_lshl_add_u64 v[214:215], s[52:53], 0, v[190:191]
	s_mov_b32 m0, s47
	v_lshl_add_u64 v[216:217], s[30:31], 0, v[188:189]
	global_load_lds_dwordx4 v[214:215], off
	s_add_i32 m0, s47, 0x2000
	v_lshl_add_u64 v[214:215], s[52:53], 0, v[200:201]
	global_load_lds_dwordx4 v[214:215], off
	s_mov_b32 m0, s34
	v_lshl_add_u64 v[214:215], s[30:31], 0, v[186:187]
	global_load_lds_dwordx4 v[214:215], off
	s_mov_b32 m0, s35
	s_nop 0
	global_load_lds_dwordx4 v[216:217], off
	s_waitcnt vmcnt(8) lgkmcnt(0)
	s_barrier
	s_setprio 1
	v_mfma_f32_16x16x32_bf16 v[62:65], v[130:133], v[162:165], 0
	v_mfma_f32_16x16x32_bf16 v[58:61], v[138:141], v[162:165], 0
	v_mfma_f32_16x16x32_bf16 v[46:49], v[130:133], v[170:173], 0
	v_mfma_f32_16x16x32_bf16 v[42:45], v[138:141], v[170:173], 0
	v_mfma_f32_16x16x32_bf16 v[30:33], v[130:133], v[178:181], 0
	v_mfma_f32_16x16x32_bf16 v[26:29], v[138:141], v[178:181], 0
	v_mfma_f32_16x16x32_bf16 v[14:17], v[130:133], v[196:199], 0
	v_mfma_f32_16x16x32_bf16 v[10:13], v[138:141], v[196:199], 0
	v_mfma_f32_16x16x32_bf16 v[62:65], v[134:137], v[166:169], v[62:65]
	v_mfma_f32_16x16x32_bf16 v[58:61], v[142:145], v[166:169], v[58:61]
	v_mfma_f32_16x16x32_bf16 v[46:49], v[134:137], v[174:177], v[46:49]
	v_mfma_f32_16x16x32_bf16 v[42:45], v[142:145], v[174:177], v[42:45]
	v_mfma_f32_16x16x32_bf16 v[30:33], v[134:137], v[182:185], v[30:33]
	v_mfma_f32_16x16x32_bf16 v[26:29], v[142:145], v[182:185], v[26:29]
	v_mfma_f32_16x16x32_bf16 v[14:17], v[134:137], v[206:209], v[14:17]
	v_mfma_f32_16x16x32_bf16 v[10:13], v[142:145], v[206:209], v[10:13]
	s_setprio 0
	s_setprio 1
	v_mfma_f32_16x16x32_bf16 v[54:57], v[146:149], v[162:165], 0
	v_mfma_f32_16x16x32_bf16 v[50:53], v[154:157], v[162:165], 0
	v_mfma_f32_16x16x32_bf16 v[38:41], v[146:149], v[170:173], 0
	v_mfma_f32_16x16x32_bf16 v[34:37], v[154:157], v[170:173], 0
	v_mfma_f32_16x16x32_bf16 v[22:25], v[146:149], v[178:181], 0
	v_mfma_f32_16x16x32_bf16 v[18:21], v[154:157], v[178:181], 0
	v_mfma_f32_16x16x32_bf16 v[6:9], v[146:149], v[196:199], 0
	v_mfma_f32_16x16x32_bf16 v[2:5], v[154:157], v[196:199], 0
	v_mfma_f32_16x16x32_bf16 v[54:57], v[150:153], v[166:169], v[54:57]
	v_mfma_f32_16x16x32_bf16 v[50:53], v[158:161], v[166:169], v[50:53]
	v_mfma_f32_16x16x32_bf16 v[38:41], v[150:153], v[174:177], v[38:41]
	v_mfma_f32_16x16x32_bf16 v[34:37], v[158:161], v[174:177], v[34:37]
	v_mfma_f32_16x16x32_bf16 v[22:25], v[150:153], v[182:185], v[22:25]
	v_mfma_f32_16x16x32_bf16 v[18:21], v[158:161], v[182:185], v[18:21]
	v_mfma_f32_16x16x32_bf16 v[6:9], v[150:153], v[206:209], v[6:9]
	v_mfma_f32_16x16x32_bf16 v[2:5], v[158:161], v[206:209], v[2:5]
	s_setprio 0
	s_barrier
	s_add_i32 s47, 0, 0x18000
	s_add_i32 s52, 0, 0x1c000
	v_add_u32_e32 v142, s47, v220
	v_add_u32_e32 v158, s52, v220
	ds_read_b128 v[130:133], v142
	ds_read_b128 v[134:137], v142 offset:1024
	ds_read_b128 v[138:141], v142 offset:2048
	ds_read_b128 v[142:145], v142 offset:3072
	ds_read_b128 v[146:149], v158
	ds_read_b128 v[150:153], v158 offset:1024
	ds_read_b128 v[154:157], v158 offset:2048
	ds_read_b128 v[158:161], v158 offset:3072
	s_add_u32 s30, s30, 0x80000
	s_addc_u32 s31, s31, 0
	s_mov_b32 m0, s36
	v_lshl_add_u64 v[218:219], s[30:31], 0, v[186:187]
	ds_read_b128 v[162:165], v222 offset:32768
	ds_read_b128 v[166:169], v222 offset:33792
	ds_read_b128 v[170:173], v222 offset:34816
	ds_read_b128 v[174:177], v222 offset:35840
	ds_read_b128 v[178:181], v222 offset:36864
	ds_read_b128 v[182:185], v222 offset:37888
	ds_read_b128 v[196:199], v222 offset:38912
	ds_read_b128 v[206:209], v222 offset:39936
	global_load_lds_dwordx4 v[218:219], off
	s_mov_b32 m0, s37
	v_lshl_add_u64 v[218:219], s[30:31], 0, v[188:189]
	global_load_lds_dwordx4 v[218:219], off
	s_waitcnt vmcnt(8) lgkmcnt(0)
	s_barrier
	s_setprio 1
	v_mfma_f32_16x16x32_bf16 v[126:129], v[130:133], v[162:165], v[126:129]
	v_mfma_f32_16x16x32_bf16 v[122:125], v[138:141], v[162:165], v[122:125]
	v_mfma_f32_16x16x32_bf16 v[110:113], v[130:133], v[170:173], v[110:113]
	v_mfma_f32_16x16x32_bf16 v[106:109], v[138:141], v[170:173], v[106:109]
	v_mfma_f32_16x16x32_bf16 v[94:97], v[130:133], v[178:181], v[94:97]
	v_mfma_f32_16x16x32_bf16 v[90:93], v[138:141], v[178:181], v[90:93]
	v_mfma_f32_16x16x32_bf16 v[78:81], v[130:133], v[196:199], v[78:81]
	v_mfma_f32_16x16x32_bf16 v[74:77], v[138:141], v[196:199], v[74:77]
	v_mfma_f32_16x16x32_bf16 v[126:129], v[134:137], v[166:169], v[126:129]
	v_mfma_f32_16x16x32_bf16 v[122:125], v[142:145], v[166:169], v[122:125]
	v_mfma_f32_16x16x32_bf16 v[110:113], v[134:137], v[174:177], v[110:113]
	v_mfma_f32_16x16x32_bf16 v[106:109], v[142:145], v[174:177], v[106:109]
	v_mfma_f32_16x16x32_bf16 v[94:97], v[134:137], v[182:185], v[94:97]
	v_mfma_f32_16x16x32_bf16 v[90:93], v[142:145], v[182:185], v[90:93]
	v_mfma_f32_16x16x32_bf16 v[78:81], v[134:137], v[206:209], v[78:81]
	v_mfma_f32_16x16x32_bf16 v[74:77], v[142:145], v[206:209], v[74:77]
	s_setprio 0
	s_setprio 1
	v_mfma_f32_16x16x32_bf16 v[118:121], v[146:149], v[162:165], v[118:121]
	v_mfma_f32_16x16x32_bf16 v[114:117], v[154:157], v[162:165], v[114:117]
	v_mfma_f32_16x16x32_bf16 v[102:105], v[146:149], v[170:173], v[102:105]
	v_mfma_f32_16x16x32_bf16 v[98:101], v[154:157], v[170:173], v[98:101]
	v_mfma_f32_16x16x32_bf16 v[86:89], v[146:149], v[178:181], v[86:89]
	v_mfma_f32_16x16x32_bf16 v[82:85], v[154:157], v[178:181], v[82:85]
	v_mfma_f32_16x16x32_bf16 v[70:73], v[146:149], v[196:199], v[70:73]
	v_mfma_f32_16x16x32_bf16 v[66:69], v[154:157], v[196:199], v[66:69]
	v_mfma_f32_16x16x32_bf16 v[118:121], v[150:153], v[166:169], v[118:121]
	v_mfma_f32_16x16x32_bf16 v[114:117], v[158:161], v[166:169], v[114:117]
	v_mfma_f32_16x16x32_bf16 v[102:105], v[150:153], v[174:177], v[102:105]
	v_mfma_f32_16x16x32_bf16 v[98:101], v[158:161], v[174:177], v[98:101]
	v_mfma_f32_16x16x32_bf16 v[86:89], v[150:153], v[182:185], v[86:89]
	v_mfma_f32_16x16x32_bf16 v[82:85], v[158:161], v[182:185], v[82:85]
	v_mfma_f32_16x16x32_bf16 v[70:73], v[150:153], v[206:209], v[70:73]
	v_mfma_f32_16x16x32_bf16 v[66:69], v[158:161], v[206:209], v[66:69]
	s_setprio 0
	s_barrier
	s_add_i32 s30, s47, s33
	v_lshl_add_u64 v[210:211], v[210:211], 0, s[58:59]
	s_mov_b32 m0, s30
	ds_read_b128 v[162:165], v222 offset:49152
	ds_read_b128 v[166:169], v222 offset:50176
	ds_read_b128 v[170:173], v222 offset:51200
	ds_read_b128 v[174:177], v222 offset:52224
	ds_read_b128 v[178:181], v222 offset:53248
	ds_read_b128 v[182:185], v222 offset:54272
	ds_read_b128 v[196:199], v222 offset:55296
	ds_read_b128 v[206:209], v222 offset:56320
	global_load_lds_dwordx4 v[210:211], off
	s_add_i32 m0, s30, 0x2000
	s_add_u32 s28, s28, 0x80080
	v_lshl_add_u64 v[210:211], v[212:213], 0, s[58:59]
	s_addc_u32 s29, s29, 0
	s_add_i32 s30, s52, s33
	global_load_lds_dwordx4 v[210:211], off
	s_mov_b32 m0, s30
	v_lshl_add_u64 v[210:211], s[28:29], 0, v[190:191]
	global_load_lds_dwordx4 v[210:211], off
	s_add_i32 m0, s30, 0x2000
	v_lshl_add_u64 v[210:211], s[28:29], 0, v[200:201]
	global_load_lds_dwordx4 v[210:211], off
	s_mov_b32 m0, s38
	v_lshl_add_u64 v[210:211], v[214:215], 0, s[58:59]
	global_load_lds_dwordx4 v[210:211], off
	s_mov_b32 m0, s39
	v_lshl_add_u64 v[210:211], v[216:217], 0, s[58:59]
	global_load_lds_dwordx4 v[210:211], off
	s_waitcnt vmcnt(8) lgkmcnt(0)
	s_barrier
	s_setprio 1
	v_mfma_f32_16x16x32_bf16 v[62:65], v[130:133], v[162:165], v[62:65]
	v_mfma_f32_16x16x32_bf16 v[58:61], v[138:141], v[162:165], v[58:61]
	v_mfma_f32_16x16x32_bf16 v[46:49], v[130:133], v[170:173], v[46:49]
	v_mfma_f32_16x16x32_bf16 v[42:45], v[138:141], v[170:173], v[42:45]
	v_mfma_f32_16x16x32_bf16 v[30:33], v[130:133], v[178:181], v[30:33]
	v_mfma_f32_16x16x32_bf16 v[26:29], v[138:141], v[178:181], v[26:29]
	v_mfma_f32_16x16x32_bf16 v[14:17], v[130:133], v[196:199], v[14:17]
	v_mfma_f32_16x16x32_bf16 v[10:13], v[138:141], v[196:199], v[10:13]
	v_mfma_f32_16x16x32_bf16 v[62:65], v[134:137], v[166:169], v[62:65]
	v_mfma_f32_16x16x32_bf16 v[58:61], v[142:145], v[166:169], v[58:61]
	v_mfma_f32_16x16x32_bf16 v[46:49], v[134:137], v[174:177], v[46:49]
	v_mfma_f32_16x16x32_bf16 v[42:45], v[142:145], v[174:177], v[42:45]
	v_mfma_f32_16x16x32_bf16 v[30:33], v[134:137], v[182:185], v[30:33]
	v_mfma_f32_16x16x32_bf16 v[26:29], v[142:145], v[182:185], v[26:29]
	v_mfma_f32_16x16x32_bf16 v[14:17], v[134:137], v[206:209], v[14:17]
	v_mfma_f32_16x16x32_bf16 v[10:13], v[142:145], v[206:209], v[10:13]
	s_setprio 0
	s_setprio 1
	v_mfma_f32_16x16x32_bf16 v[54:57], v[146:149], v[162:165], v[54:57]
	v_mfma_f32_16x16x32_bf16 v[50:53], v[154:157], v[162:165], v[50:53]
	v_mfma_f32_16x16x32_bf16 v[38:41], v[146:149], v[170:173], v[38:41]
	v_mfma_f32_16x16x32_bf16 v[34:37], v[154:157], v[170:173], v[34:37]
	v_mfma_f32_16x16x32_bf16 v[22:25], v[146:149], v[178:181], v[22:25]
	v_mfma_f32_16x16x32_bf16 v[18:21], v[154:157], v[178:181], v[18:21]
	v_mfma_f32_16x16x32_bf16 v[6:9], v[146:149], v[196:199], v[6:9]
	v_mfma_f32_16x16x32_bf16 v[2:5], v[154:157], v[196:199], v[2:5]
	v_mfma_f32_16x16x32_bf16 v[54:57], v[150:153], v[166:169], v[54:57]
	v_mfma_f32_16x16x32_bf16 v[50:53], v[158:161], v[166:169], v[50:53]
	v_mfma_f32_16x16x32_bf16 v[38:41], v[150:153], v[174:177], v[38:41]
	v_mfma_f32_16x16x32_bf16 v[34:37], v[158:161], v[174:177], v[34:37]
	v_mfma_f32_16x16x32_bf16 v[22:25], v[150:153], v[182:185], v[22:25]
	v_mfma_f32_16x16x32_bf16 v[18:21], v[158:161], v[182:185], v[18:21]
	v_mfma_f32_16x16x32_bf16 v[6:9], v[150:153], v[206:209], v[6:9]
	v_mfma_f32_16x16x32_bf16 v[2:5], v[158:161], v[206:209], v[2:5]
	s_setprio 0
	s_barrier
	s_add_i32 s46, s46, 2
	s_add_u32 s26, s26, 0x100
	s_addc_u32 s27, s27, 0
	s_add_u32 s42, s42, 0x100
	s_addc_u32 s43, s43, 0
	s_cmp_gt_u32 s46, 29
	s_cbranch_scc1 .Lpeel_done_3
.LBB0_772:
	s_add_u32 s28, s26, 0xfff80080
	s_addc_u32 s29, s27, -1
	s_add_i32 s47, 0, 0x10000
	s_cmp_eq_u32 s46, 28
	s_cselect_b32 s31, s17, s29
	s_cselect_b32 s30, s40, s28
	s_cselect_b32 s29, s15, s43
	s_cselect_b32 s28, s41, s42
	s_add_i32 s55, 0, 0x14000
	v_add_u32_e32 v142, s47, v220
	v_add_u32_e32 v158, s55, v220
	ds_read_b128 v[130:133], v142
	ds_read_b128 v[134:137], v142 offset:1024
	ds_read_b128 v[138:141], v142 offset:2048
	ds_read_b128 v[142:145], v142 offset:3072
	ds_read_b128 v[146:149], v158
	ds_read_b128 v[150:153], v158 offset:1024
	ds_read_b128 v[154:157], v158 offset:2048
	ds_read_b128 v[158:161], v158 offset:3072
	v_lshl_add_u64 v[210:211], s[26:27], 0, v[202:203]
	s_add_i32 m0, s34, 0xc000
	ds_read_b128 v[162:165], v222
	ds_read_b128 v[166:169], v222 offset:1024
	ds_read_b128 v[170:173], v222 offset:2048
	ds_read_b128 v[174:177], v222 offset:3072
	ds_read_b128 v[178:181], v222 offset:4096
	ds_read_b128 v[182:185], v222 offset:5120
	ds_read_b128 v[196:199], v222 offset:6144
	ds_read_b128 v[206:209], v222 offset:7168
	global_load_lds_dwordx4 v[210:211], off
	s_add_i32 m0, s34, 0xe000
	v_lshl_add_u64 v[210:211], s[26:27], 0, v[204:205]
	global_load_lds_dwordx4 v[210:211], off
	s_waitcnt vmcnt(8) lgkmcnt(0)
	s_barrier
	s_setprio 1
	v_mfma_f32_16x16x32_bf16 v[126:129], v[130:133], v[162:165], v[126:129]
	v_mfma_f32_16x16x32_bf16 v[122:125], v[138:141], v[162:165], v[122:125]
	v_mfma_f32_16x16x32_bf16 v[110:113], v[130:133], v[170:173], v[110:113]
	v_mfma_f32_16x16x32_bf16 v[106:109], v[138:141], v[170:173], v[106:109]
	v_mfma_f32_16x16x32_bf16 v[94:97], v[130:133], v[178:181], v[94:97]
	v_mfma_f32_16x16x32_bf16 v[90:93], v[138:141], v[178:181], v[90:93]
	v_mfma_f32_16x16x32_bf16 v[78:81], v[130:133], v[196:199], v[78:81]
	v_mfma_f32_16x16x32_bf16 v[74:77], v[138:141], v[196:199], v[74:77]
	v_mfma_f32_16x16x32_bf16 v[126:129], v[134:137], v[166:169], v[126:129]
	v_mfma_f32_16x16x32_bf16 v[122:125], v[142:145], v[166:169], v[122:125]
	v_mfma_f32_16x16x32_bf16 v[110:113], v[134:137], v[174:177], v[110:113]
	v_mfma_f32_16x16x32_bf16 v[106:109], v[142:145], v[174:177], v[106:109]
	v_mfma_f32_16x16x32_bf16 v[94:97], v[134:137], v[182:185], v[94:97]
	v_mfma_f32_16x16x32_bf16 v[90:93], v[142:145], v[182:185], v[90:93]
	v_mfma_f32_16x16x32_bf16 v[78:81], v[134:137], v[206:209], v[78:81]
	v_mfma_f32_16x16x32_bf16 v[74:77], v[142:145], v[206:209], v[74:77]
	s_setprio 0
	s_setprio 1
	v_mfma_f32_16x16x32_bf16 v[118:121], v[146:149], v[162:165], v[118:121]
	v_mfma_f32_16x16x32_bf16 v[114:117], v[154:157], v[162:165], v[114:117]
	v_mfma_f32_16x16x32_bf16 v[102:105], v[146:149], v[170:173], v[102:105]
	v_mfma_f32_16x16x32_bf16 v[98:101], v[154:157], v[170:173], v[98:101]
	v_mfma_f32_16x16x32_bf16 v[86:89], v[146:149], v[178:181], v[86:89]
	v_mfma_f32_16x16x32_bf16 v[82:85], v[154:157], v[178:181], v[82:85]
	v_mfma_f32_16x16x32_bf16 v[70:73], v[146:149], v[196:199], v[70:73]
	v_mfma_f32_16x16x32_bf16 v[66:69], v[154:157], v[196:199], v[66:69]
	v_mfma_f32_16x16x32_bf16 v[118:121], v[150:153], v[166:169], v[118:121]
	v_mfma_f32_16x16x32_bf16 v[114:117], v[158:161], v[166:169], v[114:117]
	v_mfma_f32_16x16x32_bf16 v[102:105], v[150:153], v[174:177], v[102:105]
	v_mfma_f32_16x16x32_bf16 v[98:101], v[158:161], v[174:177], v[98:101]
	v_mfma_f32_16x16x32_bf16 v[86:89], v[150:153], v[182:185], v[86:89]
	v_mfma_f32_16x16x32_bf16 v[82:85], v[158:161], v[182:185], v[82:85]
	v_mfma_f32_16x16x32_bf16 v[70:73], v[150:153], v[206:209], v[70:73]
	v_mfma_f32_16x16x32_bf16 v[66:69], v[158:161], v[206:209], v[66:69]
	s_setprio 0
	s_barrier
	s_add_i32 s47, s47, s33
	v_lshl_add_u64 v[210:211], s[28:29], 0, v[190:191]
	s_mov_b32 m0, s47
	ds_read_b128 v[162:165], v222 offset:16384
	ds_read_b128 v[166:169], v222 offset:17408
	ds_read_b128 v[170:173], v222 offset:18432
	ds_read_b128 v[174:177], v222 offset:19456
	ds_read_b128 v[178:181], v222 offset:20480
	ds_read_b128 v[182:185], v222 offset:21504
	ds_read_b128 v[196:199], v222 offset:22528
	ds_read_b128 v[206:209], v222 offset:23552
	global_load_lds_dwordx4 v[210:211], off
	s_add_i32 m0, s47, 0x2000
	s_add_u32 s52, s28, 0x80000
	v_lshl_add_u64 v[212:213], s[28:29], 0, v[200:201]
	s_addc_u32 s53, s29, 0
	s_add_i32 s47, s55, s33
	global_load_lds_dwordx4 v[212:213], off
	v_lshl_add_u64 v[214:215], s[52:53], 0, v[190:191]
	s_mov_b32 m0, s47
	v_lshl_add_u64 v[216:217], s[30:31], 0, v[188:189]
	global_load_lds_dwordx4 v[214:215], off
	s_add_i32 m0, s47, 0x2000
	v_lshl_add_u64 v[214:215], s[52:53], 0, v[200:201]
	global_load_lds_dwordx4 v[214:215], off
	s_mov_b32 m0, s34
	v_lshl_add_u64 v[214:215], s[30:31], 0, v[186:187]
	global_load_lds_dwordx4 v[214:215], off
	s_mov_b32 m0, s35
	s_nop 0
	global_load_lds_dwordx4 v[216:217], off
	s_waitcnt vmcnt(8) lgkmcnt(0)
	s_barrier
	s_setprio 1
	v_mfma_f32_16x16x32_bf16 v[62:65], v[130:133], v[162:165], v[62:65]
	v_mfma_f32_16x16x32_bf16 v[58:61], v[138:141], v[162:165], v[58:61]
	v_mfma_f32_16x16x32_bf16 v[46:49], v[130:133], v[170:173], v[46:49]
	v_mfma_f32_16x16x32_bf16 v[42:45], v[138:141], v[170:173], v[42:45]
	v_mfma_f32_16x16x32_bf16 v[30:33], v[130:133], v[178:181], v[30:33]
	v_mfma_f32_16x16x32_bf16 v[26:29], v[138:141], v[178:181], v[26:29]
	v_mfma_f32_16x16x32_bf16 v[14:17], v[130:133], v[196:199], v[14:17]
	v_mfma_f32_16x16x32_bf16 v[10:13], v[138:141], v[196:199], v[10:13]
	v_mfma_f32_16x16x32_bf16 v[62:65], v[134:137], v[166:169], v[62:65]
	v_mfma_f32_16x16x32_bf16 v[58:61], v[142:145], v[166:169], v[58:61]
	v_mfma_f32_16x16x32_bf16 v[46:49], v[134:137], v[174:177], v[46:49]
	v_mfma_f32_16x16x32_bf16 v[42:45], v[142:145], v[174:177], v[42:45]
	v_mfma_f32_16x16x32_bf16 v[30:33], v[134:137], v[182:185], v[30:33]
	v_mfma_f32_16x16x32_bf16 v[26:29], v[142:145], v[182:185], v[26:29]
	v_mfma_f32_16x16x32_bf16 v[14:17], v[134:137], v[206:209], v[14:17]
	v_mfma_f32_16x16x32_bf16 v[10:13], v[142:145], v[206:209], v[10:13]
	s_setprio 0
	s_setprio 1
	v_mfma_f32_16x16x32_bf16 v[54:57], v[146:149], v[162:165], v[54:57]
	v_mfma_f32_16x16x32_bf16 v[50:53], v[154:157], v[162:165], v[50:53]
	v_mfma_f32_16x16x32_bf16 v[38:41], v[146:149], v[170:173], v[38:41]
	v_mfma_f32_16x16x32_bf16 v[34:37], v[154:157], v[170:173], v[34:37]
	v_mfma_f32_16x16x32_bf16 v[22:25], v[146:149], v[178:181], v[22:25]
	v_mfma_f32_16x16x32_bf16 v[18:21], v[154:157], v[178:181], v[18:21]
	v_mfma_f32_16x16x32_bf16 v[6:9], v[146:149], v[196:199], v[6:9]
	v_mfma_f32_16x16x32_bf16 v[2:5], v[154:157], v[196:199], v[2:5]
	v_mfma_f32_16x16x32_bf16 v[54:57], v[150:153], v[166:169], v[54:57]
	v_mfma_f32_16x16x32_bf16 v[50:53], v[158:161], v[166:169], v[50:53]
	v_mfma_f32_16x16x32_bf16 v[38:41], v[150:153], v[174:177], v[38:41]
	v_mfma_f32_16x16x32_bf16 v[34:37], v[158:161], v[174:177], v[34:37]
	v_mfma_f32_16x16x32_bf16 v[22:25], v[150:153], v[182:185], v[22:25]
	v_mfma_f32_16x16x32_bf16 v[18:21], v[158:161], v[182:185], v[18:21]
	v_mfma_f32_16x16x32_bf16 v[6:9], v[150:153], v[206:209], v[6:9]
	v_mfma_f32_16x16x32_bf16 v[2:5], v[158:161], v[206:209], v[2:5]
	s_setprio 0
	s_barrier
	s_add_i32 s47, 0, 0x18000
	s_add_i32 s52, 0, 0x1c000
	v_add_u32_e32 v142, s47, v220
	v_add_u32_e32 v158, s52, v220
	ds_read_b128 v[130:133], v142
	ds_read_b128 v[134:137], v142 offset:1024
	ds_read_b128 v[138:141], v142 offset:2048
	ds_read_b128 v[142:145], v142 offset:3072
	ds_read_b128 v[146:149], v158
	ds_read_b128 v[150:153], v158 offset:1024
	ds_read_b128 v[154:157], v158 offset:2048
	ds_read_b128 v[158:161], v158 offset:3072
	s_add_u32 s30, s30, 0x80000
	s_addc_u32 s31, s31, 0
	s_mov_b32 m0, s36
	v_lshl_add_u64 v[218:219], s[30:31], 0, v[186:187]
	ds_read_b128 v[162:165], v222 offset:32768
	ds_read_b128 v[166:169], v222 offset:33792
	ds_read_b128 v[170:173], v222 offset:34816
	ds_read_b128 v[174:177], v222 offset:35840
	ds_read_b128 v[178:181], v222 offset:36864
	ds_read_b128 v[182:185], v222 offset:37888
	ds_read_b128 v[196:199], v222 offset:38912
	ds_read_b128 v[206:209], v222 offset:39936
	global_load_lds_dwordx4 v[218:219], off
	s_mov_b32 m0, s37
	v_lshl_add_u64 v[218:219], s[30:31], 0, v[188:189]
	global_load_lds_dwordx4 v[218:219], off
	s_waitcnt vmcnt(8) lgkmcnt(0)
	s_barrier
	s_setprio 1
	v_mfma_f32_16x16x32_bf16 v[126:129], v[130:133], v[162:165], v[126:129]
	v_mfma_f32_16x16x32_bf16 v[122:125], v[138:141], v[162:165], v[122:125]
	v_mfma_f32_16x16x32_bf16 v[110:113], v[130:133], v[170:173], v[110:113]
	v_mfma_f32_16x16x32_bf16 v[106:109], v[138:141], v[170:173], v[106:109]
	v_mfma_f32_16x16x32_bf16 v[94:97], v[130:133], v[178:181], v[94:97]
	v_mfma_f32_16x16x32_bf16 v[90:93], v[138:141], v[178:181], v[90:93]
	v_mfma_f32_16x16x32_bf16 v[78:81], v[130:133], v[196:199], v[78:81]
	v_mfma_f32_16x16x32_bf16 v[74:77], v[138:141], v[196:199], v[74:77]
	v_mfma_f32_16x16x32_bf16 v[126:129], v[134:137], v[166:169], v[126:129]
	v_mfma_f32_16x16x32_bf16 v[122:125], v[142:145], v[166:169], v[122:125]
	v_mfma_f32_16x16x32_bf16 v[110:113], v[134:137], v[174:177], v[110:113]
	v_mfma_f32_16x16x32_bf16 v[106:109], v[142:145], v[174:177], v[106:109]
	v_mfma_f32_16x16x32_bf16 v[94:97], v[134:137], v[182:185], v[94:97]
	v_mfma_f32_16x16x32_bf16 v[90:93], v[142:145], v[182:185], v[90:93]
	v_mfma_f32_16x16x32_bf16 v[78:81], v[134:137], v[206:209], v[78:81]
	v_mfma_f32_16x16x32_bf16 v[74:77], v[142:145], v[206:209], v[74:77]
	s_setprio 0
	s_setprio 1
	v_mfma_f32_16x16x32_bf16 v[118:121], v[146:149], v[162:165], v[118:121]
	v_mfma_f32_16x16x32_bf16 v[114:117], v[154:157], v[162:165], v[114:117]
	v_mfma_f32_16x16x32_bf16 v[102:105], v[146:149], v[170:173], v[102:105]
	v_mfma_f32_16x16x32_bf16 v[98:101], v[154:157], v[170:173], v[98:101]
	v_mfma_f32_16x16x32_bf16 v[86:89], v[146:149], v[178:181], v[86:89]
	v_mfma_f32_16x16x32_bf16 v[82:85], v[154:157], v[178:181], v[82:85]
	v_mfma_f32_16x16x32_bf16 v[70:73], v[146:149], v[196:199], v[70:73]
	v_mfma_f32_16x16x32_bf16 v[66:69], v[154:157], v[196:199], v[66:69]
	v_mfma_f32_16x16x32_bf16 v[118:121], v[150:153], v[166:169], v[118:121]
	v_mfma_f32_16x16x32_bf16 v[114:117], v[158:161], v[166:169], v[114:117]
	v_mfma_f32_16x16x32_bf16 v[102:105], v[150:153], v[174:177], v[102:105]
	v_mfma_f32_16x16x32_bf16 v[98:101], v[158:161], v[174:177], v[98:101]
	v_mfma_f32_16x16x32_bf16 v[86:89], v[150:153], v[182:185], v[86:89]
	v_mfma_f32_16x16x32_bf16 v[82:85], v[158:161], v[182:185], v[82:85]
	v_mfma_f32_16x16x32_bf16 v[70:73], v[150:153], v[206:209], v[70:73]
	v_mfma_f32_16x16x32_bf16 v[66:69], v[158:161], v[206:209], v[66:69]
	s_setprio 0
	s_barrier
	s_add_i32 s30, s47, s33
	v_lshl_add_u64 v[210:211], v[210:211], 0, s[58:59]
	s_mov_b32 m0, s30
	ds_read_b128 v[162:165], v222 offset:49152
	ds_read_b128 v[166:169], v222 offset:50176
	ds_read_b128 v[170:173], v222 offset:51200
	ds_read_b128 v[174:177], v222 offset:52224
	ds_read_b128 v[178:181], v222 offset:53248
	ds_read_b128 v[182:185], v222 offset:54272
	ds_read_b128 v[196:199], v222 offset:55296
	ds_read_b128 v[206:209], v222 offset:56320
	global_load_lds_dwordx4 v[210:211], off
	s_add_i32 m0, s30, 0x2000
	s_add_u32 s28, s28, 0x80080
	v_lshl_add_u64 v[210:211], v[212:213], 0, s[58:59]
	s_addc_u32 s29, s29, 0
	s_add_i32 s30, s52, s33
	global_load_lds_dwordx4 v[210:211], off
	s_mov_b32 m0, s30
	v_lshl_add_u64 v[210:211], s[28:29], 0, v[190:191]
	global_load_lds_dwordx4 v[210:211], off
	s_add_i32 m0, s30, 0x2000
	v_lshl_add_u64 v[210:211], s[28:29], 0, v[200:201]
	global_load_lds_dwordx4 v[210:211], off
	s_mov_b32 m0, s38
	v_lshl_add_u64 v[210:211], v[214:215], 0, s[58:59]
	global_load_lds_dwordx4 v[210:211], off
	s_mov_b32 m0, s39
	v_lshl_add_u64 v[210:211], v[216:217], 0, s[58:59]
	global_load_lds_dwordx4 v[210:211], off
	s_waitcnt vmcnt(8) lgkmcnt(0)
	s_barrier
	s_setprio 1
	v_mfma_f32_16x16x32_bf16 v[62:65], v[130:133], v[162:165], v[62:65]
	v_mfma_f32_16x16x32_bf16 v[58:61], v[138:141], v[162:165], v[58:61]
	v_mfma_f32_16x16x32_bf16 v[46:49], v[130:133], v[170:173], v[46:49]
	v_mfma_f32_16x16x32_bf16 v[42:45], v[138:141], v[170:173], v[42:45]
	v_mfma_f32_16x16x32_bf16 v[30:33], v[130:133], v[178:181], v[30:33]
	v_mfma_f32_16x16x32_bf16 v[26:29], v[138:141], v[178:181], v[26:29]
	v_mfma_f32_16x16x32_bf16 v[14:17], v[130:133], v[196:199], v[14:17]
	v_mfma_f32_16x16x32_bf16 v[10:13], v[138:141], v[196:199], v[10:13]
	v_mfma_f32_16x16x32_bf16 v[62:65], v[134:137], v[166:169], v[62:65]
	v_mfma_f32_16x16x32_bf16 v[58:61], v[142:145], v[166:169], v[58:61]
	v_mfma_f32_16x16x32_bf16 v[46:49], v[134:137], v[174:177], v[46:49]
	v_mfma_f32_16x16x32_bf16 v[42:45], v[142:145], v[174:177], v[42:45]
	v_mfma_f32_16x16x32_bf16 v[30:33], v[134:137], v[182:185], v[30:33]
	v_mfma_f32_16x16x32_bf16 v[26:29], v[142:145], v[182:185], v[26:29]
	v_mfma_f32_16x16x32_bf16 v[14:17], v[134:137], v[206:209], v[14:17]
	v_mfma_f32_16x16x32_bf16 v[10:13], v[142:145], v[206:209], v[10:13]
	s_setprio 0
	s_setprio 1
	v_mfma_f32_16x16x32_bf16 v[54:57], v[146:149], v[162:165], v[54:57]
	v_mfma_f32_16x16x32_bf16 v[50:53], v[154:157], v[162:165], v[50:53]
	v_mfma_f32_16x16x32_bf16 v[38:41], v[146:149], v[170:173], v[38:41]
	v_mfma_f32_16x16x32_bf16 v[34:37], v[154:157], v[170:173], v[34:37]
	v_mfma_f32_16x16x32_bf16 v[22:25], v[146:149], v[178:181], v[22:25]
	v_mfma_f32_16x16x32_bf16 v[18:21], v[154:157], v[178:181], v[18:21]
	v_mfma_f32_16x16x32_bf16 v[6:9], v[146:149], v[196:199], v[6:9]
	v_mfma_f32_16x16x32_bf16 v[2:5], v[154:157], v[196:199], v[2:5]
	v_mfma_f32_16x16x32_bf16 v[54:57], v[150:153], v[166:169], v[54:57]
	v_mfma_f32_16x16x32_bf16 v[50:53], v[158:161], v[166:169], v[50:53]
	v_mfma_f32_16x16x32_bf16 v[38:41], v[150:153], v[174:177], v[38:41]
	v_mfma_f32_16x16x32_bf16 v[34:37], v[158:161], v[174:177], v[34:37]
	v_mfma_f32_16x16x32_bf16 v[22:25], v[150:153], v[182:185], v[22:25]
	v_mfma_f32_16x16x32_bf16 v[18:21], v[158:161], v[182:185], v[18:21]
	v_mfma_f32_16x16x32_bf16 v[6:9], v[150:153], v[206:209], v[6:9]
	v_mfma_f32_16x16x32_bf16 v[2:5], v[158:161], v[206:209], v[2:5]
	s_setprio 0
	s_barrier
	s_add_i32 s46, s46, 2
	s_add_u32 s26, s26, 0x100
	s_addc_u32 s27, s27, 0
	s_add_u32 s42, s42, 0x100
	s_addc_u32 s43, s43, 0
	s_cmp_gt_u32 s46, 29
	s_cbranch_scc0 .LBB0_772

.LBB0_799:
	s_ashr_i32 s11, s10, 31
	s_lshl_b64 s[14:15], s[10:11], 20
	s_add_u32 s14, s69, s14
	s_addc_u32 s15, s77, s15
	s_and_b64 s[16:17], s[12:13], exec
	s_cselect_b32 s11, s15, s25
	s_cselect_b32 s21, s14, s24
	s_ashr_i32 s9, s8, 31
	s_lshl_b64 s[16:17], s[8:9], 20
	v_readlane_b32 s0, v254, 42
	v_readlane_b32 s1, v254, 43
	s_add_u32 s16, s0, s16
	s_addc_u32 s17, s1, s17
	s_and_b64 s[28:29], s[12:13], exec
	s_cselect_b32 s9, s17, s27
	s_cselect_b32 s47, s16, s26
	s_add_u32 s24, s24, 0x80080
	s_addc_u32 s25, s25, 0
	s_add_u32 s52, s26, 0x100
	s_addc_u32 s53, s27, 0
	s_mov_b32 s55, -2
	v_readlane_b32 s56, v255, 49
	s_nop 3
	s_cmp_eq_u32 s56, 5
	v_writelane_b32 v255, 5, 49
	s_cbranch_scc0 .Ltrip0_strict_4
	s_add_u32 s26, s24, 0xfff80080
	s_addc_u32 s27, s25, -1
	s_add_i32 s56, 0, 0x10000
	s_cmp_eq_u32 s55, 28
	s_cselect_b32 s29, s11, s27
	s_cselect_b32 s28, s21, s26
	s_cselect_b32 s27, s9, s53
	s_cselect_b32 s26, s47, s52
	s_add_i32 s60, 0, 0x14000
	v_add_u32_e32 v142, s56, v238
	v_add_u32_e32 v158, s60, v238
	ds_read_b128 v[130:133], v142
	ds_read_b128 v[134:137], v142 offset:1024
	ds_read_b128 v[138:141], v142 offset:2048
	ds_read_b128 v[142:145], v142 offset:3072
	ds_read_b128 v[146:149], v158
	ds_read_b128 v[150:153], v158 offset:1024
	ds_read_b128 v[154:157], v158 offset:2048
	ds_read_b128 v[158:161], v158 offset:3072
	v_lshl_add_u64 v[210:211], s[24:25], 0, v[206:207]
	s_add_i32 m0, s23, 0xc000
	ds_read_b128 v[162:165], v240
	ds_read_b128 v[166:169], v240 offset:1024
	ds_read_b128 v[170:173], v240 offset:2048
	ds_read_b128 v[174:177], v240 offset:3072
	ds_read_b128 v[178:181], v240 offset:4096
	ds_read_b128 v[182:185], v240 offset:5120
	ds_read_b128 v[186:189], v240 offset:6144
	ds_read_b128 v[196:199], v240 offset:7168
	global_load_lds_dwordx4 v[210:211], off
	s_add_i32 m0, s23, 0xe000
	v_lshl_add_u64 v[210:211], s[24:25], 0, v[208:209]
	global_load_lds_dwordx4 v[210:211], off
	s_waitcnt vmcnt(24) lgkmcnt(0)
	s_barrier
	s_setprio 1
	v_mfma_f32_16x16x32_bf16 v[126:129], v[130:133], v[162:165], 0
	v_mfma_f32_16x16x32_bf16 v[122:125], v[138:141], v[162:165], 0
	v_mfma_f32_16x16x32_bf16 v[110:113], v[130:133], v[170:173], 0
	v_mfma_f32_16x16x32_bf16 v[106:109], v[138:141], v[170:173], 0
	v_mfma_f32_16x16x32_bf16 v[98:101], v[130:133], v[178:181], 0
	v_mfma_f32_16x16x32_bf16 v[90:93], v[138:141], v[178:181], 0
	v_mfma_f32_16x16x32_bf16 v[82:85], v[130:133], v[186:189], 0
	v_mfma_f32_16x16x32_bf16 v[74:77], v[138:141], v[186:189], 0
	v_mfma_f32_16x16x32_bf16 v[126:129], v[134:137], v[166:169], v[126:129]
	v_mfma_f32_16x16x32_bf16 v[122:125], v[142:145], v[166:169], v[122:125]
	v_mfma_f32_16x16x32_bf16 v[110:113], v[134:137], v[174:177], v[110:113]
	v_mfma_f32_16x16x32_bf16 v[106:109], v[142:145], v[174:177], v[106:109]
	v_mfma_f32_16x16x32_bf16 v[98:101], v[134:137], v[182:185], v[98:101]
	v_mfma_f32_16x16x32_bf16 v[90:93], v[142:145], v[182:185], v[90:93]
	v_mfma_f32_16x16x32_bf16 v[82:85], v[134:137], v[196:199], v[82:85]
	v_mfma_f32_16x16x32_bf16 v[74:77], v[142:145], v[196:199], v[74:77]
	s_setprio 0
	s_setprio 1
	v_mfma_f32_16x16x32_bf16 v[118:121], v[146:149], v[162:165], 0
	v_mfma_f32_16x16x32_bf16 v[114:117], v[154:157], v[162:165], 0
	v_mfma_f32_16x16x32_bf16 v[102:105], v[146:149], v[170:173], 0
	v_mfma_f32_16x16x32_bf16 v[94:97], v[154:157], v[170:173], 0
	v_mfma_f32_16x16x32_bf16 v[86:89], v[146:149], v[178:181], 0
	v_mfma_f32_16x16x32_bf16 v[78:81], v[154:157], v[178:181], 0
	v_mfma_f32_16x16x32_bf16 v[70:73], v[146:149], v[186:189], 0
	v_mfma_f32_16x16x32_bf16 v[66:69], v[154:157], v[186:189], 0
	v_mfma_f32_16x16x32_bf16 v[118:121], v[150:153], v[166:169], v[118:121]
	v_mfma_f32_16x16x32_bf16 v[114:117], v[158:161], v[166:169], v[114:117]
	v_mfma_f32_16x16x32_bf16 v[102:105], v[150:153], v[174:177], v[102:105]
	v_mfma_f32_16x16x32_bf16 v[94:97], v[158:161], v[174:177], v[94:97]
	v_mfma_f32_16x16x32_bf16 v[86:89], v[150:153], v[182:185], v[86:89]
	v_mfma_f32_16x16x32_bf16 v[78:81], v[158:161], v[182:185], v[78:81]
	v_mfma_f32_16x16x32_bf16 v[70:73], v[150:153], v[196:199], v[70:73]
	v_mfma_f32_16x16x32_bf16 v[66:69], v[158:161], v[196:199], v[66:69]
	s_setprio 0
	s_barrier
	s_add_i32 s56, s56, s34
	v_lshl_add_u64 v[210:211], s[26:27], 0, v[190:191]
	s_mov_b32 m0, s56
	ds_read_b128 v[162:165], v240 offset:16384
	ds_read_b128 v[166:169], v240 offset:17408
	ds_read_b128 v[170:173], v240 offset:18432
	ds_read_b128 v[174:177], v240 offset:19456
	ds_read_b128 v[178:181], v240 offset:20480
	ds_read_b128 v[182:185], v240 offset:21504
	ds_read_b128 v[186:189], v240 offset:22528
	ds_read_b128 v[196:199], v240 offset:23552
	global_load_lds_dwordx4 v[210:211], off
	s_add_i32 m0, s56, 0x2000
	s_add_u32 s56, s26, 0x80000
	v_lshl_add_u64 v[212:213], s[26:27], 0, v[204:205]
	s_addc_u32 s57, s27, 0
	s_add_i32 s60, s60, s34
	global_load_lds_dwordx4 v[212:213], off
	v_lshl_add_u64 v[214:215], s[56:57], 0, v[190:191]
	s_mov_b32 m0, s60
	v_lshl_add_u64 v[216:217], s[28:29], 0, v[202:203]
	global_load_lds_dwordx4 v[214:215], off
	s_add_i32 m0, s60, 0x2000
	v_lshl_add_u64 v[214:215], s[56:57], 0, v[204:205]
	global_load_lds_dwordx4 v[214:215], off
	s_mov_b32 m0, s23
	v_lshl_add_u64 v[214:215], s[28:29], 0, v[200:201]
	global_load_lds_dwordx4 v[214:215], off
	s_mov_b32 m0, s35
	s_nop 0
	global_load_lds_dwordx4 v[216:217], off
	s_waitcnt vmcnt(24) lgkmcnt(0)
	s_barrier
	s_setprio 1
	v_mfma_f32_16x16x32_bf16 v[62:65], v[130:133], v[162:165], 0
	v_mfma_f32_16x16x32_bf16 v[58:61], v[138:141], v[162:165], 0
	v_mfma_f32_16x16x32_bf16 v[50:53], v[130:133], v[170:173], 0
	v_mfma_f32_16x16x32_bf16 v[42:45], v[138:141], v[170:173], 0
	v_mfma_f32_16x16x32_bf16 v[34:37], v[130:133], v[178:181], 0
	v_mfma_f32_16x16x32_bf16 v[26:29], v[138:141], v[178:181], 0
	v_mfma_f32_16x16x32_bf16 v[18:21], v[130:133], v[186:189], 0
	v_mfma_f32_16x16x32_bf16 v[10:13], v[138:141], v[186:189], 0
	v_mfma_f32_16x16x32_bf16 v[62:65], v[134:137], v[166:169], v[62:65]
	v_mfma_f32_16x16x32_bf16 v[58:61], v[142:145], v[166:169], v[58:61]
	v_mfma_f32_16x16x32_bf16 v[50:53], v[134:137], v[174:177], v[50:53]
	v_mfma_f32_16x16x32_bf16 v[42:45], v[142:145], v[174:177], v[42:45]
	v_mfma_f32_16x16x32_bf16 v[34:37], v[134:137], v[182:185], v[34:37]
	v_mfma_f32_16x16x32_bf16 v[26:29], v[142:145], v[182:185], v[26:29]
	v_mfma_f32_16x16x32_bf16 v[18:21], v[134:137], v[196:199], v[18:21]
	v_mfma_f32_16x16x32_bf16 v[10:13], v[142:145], v[196:199], v[10:13]
	s_setprio 0
	s_setprio 1
	v_mfma_f32_16x16x32_bf16 v[54:57], v[146:149], v[162:165], 0
	v_mfma_f32_16x16x32_bf16 v[46:49], v[154:157], v[162:165], 0
	v_mfma_f32_16x16x32_bf16 v[38:41], v[146:149], v[170:173], 0
	v_mfma_f32_16x16x32_bf16 v[30:33], v[154:157], v[170:173], 0
	v_mfma_f32_16x16x32_bf16 v[22:25], v[146:149], v[178:181], 0
	v_mfma_f32_16x16x32_bf16 v[14:17], v[154:157], v[178:181], 0
	v_mfma_f32_16x16x32_bf16 v[6:9], v[146:149], v[186:189], 0
	v_mfma_f32_16x16x32_bf16 v[2:5], v[154:157], v[186:189], 0
	v_mfma_f32_16x16x32_bf16 v[54:57], v[150:153], v[166:169], v[54:57]
	v_mfma_f32_16x16x32_bf16 v[46:49], v[158:161], v[166:169], v[46:49]
	v_mfma_f32_16x16x32_bf16 v[38:41], v[150:153], v[174:177], v[38:41]
	v_mfma_f32_16x16x32_bf16 v[30:33], v[158:161], v[174:177], v[30:33]
	v_mfma_f32_16x16x32_bf16 v[22:25], v[150:153], v[182:185], v[22:25]
	v_mfma_f32_16x16x32_bf16 v[14:17], v[158:161], v[182:185], v[14:17]
	v_mfma_f32_16x16x32_bf16 v[6:9], v[150:153], v[196:199], v[6:9]
	v_mfma_f32_16x16x32_bf16 v[2:5], v[158:161], v[196:199], v[2:5]
	s_setprio 0
	s_barrier
	s_add_i32 s56, 0, 0x18000
	s_add_i32 s57, 0, 0x1c000
	v_add_u32_e32 v142, s56, v238
	v_add_u32_e32 v158, s57, v238
	ds_read_b128 v[130:133], v142
	ds_read_b128 v[134:137], v142 offset:1024
	ds_read_b128 v[138:141], v142 offset:2048
	ds_read_b128 v[142:145], v142 offset:3072
	ds_read_b128 v[146:149], v158
	ds_read_b128 v[150:153], v158 offset:1024
	ds_read_b128 v[154:157], v158 offset:2048
	ds_read_b128 v[158:161], v158 offset:3072
	s_add_u32 s28, s28, 0x80000
	s_addc_u32 s29, s29, 0
	s_mov_b32 m0, s41
	v_lshl_add_u64 v[218:219], s[28:29], 0, v[200:201]
	ds_read_b128 v[162:165], v240 offset:32768
	ds_read_b128 v[166:169], v240 offset:33792
	ds_read_b128 v[170:173], v240 offset:34816
	ds_read_b128 v[174:177], v240 offset:35840
	ds_read_b128 v[178:181], v240 offset:36864
	ds_read_b128 v[182:185], v240 offset:37888
	ds_read_b128 v[186:189], v240 offset:38912
	ds_read_b128 v[196:199], v240 offset:39936
	global_load_lds_dwordx4 v[218:219], off
	s_mov_b32 m0, s42
	v_lshl_add_u64 v[218:219], s[28:29], 0, v[202:203]
	global_load_lds_dwordx4 v[218:219], off
	s_waitcnt vmcnt(8) lgkmcnt(0)
	s_barrier
	s_setprio 1
	v_mfma_f32_16x16x32_bf16 v[126:129], v[130:133], v[162:165], v[126:129]
	v_mfma_f32_16x16x32_bf16 v[122:125], v[138:141], v[162:165], v[122:125]
	v_mfma_f32_16x16x32_bf16 v[110:113], v[130:133], v[170:173], v[110:113]
	v_mfma_f32_16x16x32_bf16 v[106:109], v[138:141], v[170:173], v[106:109]
	v_mfma_f32_16x16x32_bf16 v[98:101], v[130:133], v[178:181], v[98:101]
	v_mfma_f32_16x16x32_bf16 v[90:93], v[138:141], v[178:181], v[90:93]
	v_mfma_f32_16x16x32_bf16 v[82:85], v[130:133], v[186:189], v[82:85]
	v_mfma_f32_16x16x32_bf16 v[74:77], v[138:141], v[186:189], v[74:77]
	v_mfma_f32_16x16x32_bf16 v[126:129], v[134:137], v[166:169], v[126:129]
	v_mfma_f32_16x16x32_bf16 v[122:125], v[142:145], v[166:169], v[122:125]
	v_mfma_f32_16x16x32_bf16 v[110:113], v[134:137], v[174:177], v[110:113]
	v_mfma_f32_16x16x32_bf16 v[106:109], v[142:145], v[174:177], v[106:109]
	v_mfma_f32_16x16x32_bf16 v[98:101], v[134:137], v[182:185], v[98:101]
	v_mfma_f32_16x16x32_bf16 v[90:93], v[142:145], v[182:185], v[90:93]
	v_mfma_f32_16x16x32_bf16 v[82:85], v[134:137], v[196:199], v[82:85]
	v_mfma_f32_16x16x32_bf16 v[74:77], v[142:145], v[196:199], v[74:77]
	s_setprio 0
	s_setprio 1
	v_mfma_f32_16x16x32_bf16 v[118:121], v[146:149], v[162:165], v[118:121]
	v_mfma_f32_16x16x32_bf16 v[114:117], v[154:157], v[162:165], v[114:117]
	v_mfma_f32_16x16x32_bf16 v[102:105], v[146:149], v[170:173], v[102:105]
	v_mfma_f32_16x16x32_bf16 v[94:97], v[154:157], v[170:173], v[94:97]
	v_mfma_f32_16x16x32_bf16 v[86:89], v[146:149], v[178:181], v[86:89]
	v_mfma_f32_16x16x32_bf16 v[78:81], v[154:157], v[178:181], v[78:81]
	v_mfma_f32_16x16x32_bf16 v[70:73], v[146:149], v[186:189], v[70:73]
	v_mfma_f32_16x16x32_bf16 v[66:69], v[154:157], v[186:189], v[66:69]
	v_mfma_f32_16x16x32_bf16 v[118:121], v[150:153], v[166:169], v[118:121]
	v_mfma_f32_16x16x32_bf16 v[114:117], v[158:161], v[166:169], v[114:117]
	v_mfma_f32_16x16x32_bf16 v[102:105], v[150:153], v[174:177], v[102:105]
	v_mfma_f32_16x16x32_bf16 v[94:97], v[158:161], v[174:177], v[94:97]
	v_mfma_f32_16x16x32_bf16 v[86:89], v[150:153], v[182:185], v[86:89]
	v_mfma_f32_16x16x32_bf16 v[78:81], v[158:161], v[182:185], v[78:81]
	v_mfma_f32_16x16x32_bf16 v[70:73], v[150:153], v[196:199], v[70:73]
	v_mfma_f32_16x16x32_bf16 v[66:69], v[158:161], v[196:199], v[66:69]
	s_setprio 0
	s_barrier
	s_add_i32 s28, s56, s34
	v_lshl_add_u64 v[210:211], v[210:211], 0, s[58:59]
	s_mov_b32 m0, s28
	ds_read_b128 v[162:165], v240 offset:49152
	ds_read_b128 v[166:169], v240 offset:50176
	ds_read_b128 v[170:173], v240 offset:51200
	ds_read_b128 v[174:177], v240 offset:52224
	ds_read_b128 v[178:181], v240 offset:53248
	ds_read_b128 v[182:185], v240 offset:54272
	ds_read_b128 v[186:189], v240 offset:55296
	ds_read_b128 v[196:199], v240 offset:56320
	global_load_lds_dwordx4 v[210:211], off
	s_add_i32 m0, s28, 0x2000
	s_add_u32 s26, s26, 0x80080
	v_lshl_add_u64 v[210:211], v[212:213], 0, s[58:59]
	s_addc_u32 s27, s27, 0
	s_add_i32 s28, s57, s34
	global_load_lds_dwordx4 v[210:211], off
	s_mov_b32 m0, s28
	v_lshl_add_u64 v[210:211], s[26:27], 0, v[190:191]
	global_load_lds_dwordx4 v[210:211], off
	s_add_i32 m0, s28, 0x2000
	v_lshl_add_u64 v[210:211], s[26:27], 0, v[204:205]
	global_load_lds_dwordx4 v[210:211], off
	s_mov_b32 m0, s43
	v_lshl_add_u64 v[210:211], v[214:215], 0, s[58:59]
	global_load_lds_dwordx4 v[210:211], off
	s_mov_b32 m0, s46
	v_lshl_add_u64 v[210:211], v[216:217], 0, s[58:59]
	global_load_lds_dwordx4 v[210:211], off
	s_waitcnt vmcnt(8) lgkmcnt(0)
	s_barrier
	s_setprio 1
	v_mfma_f32_16x16x32_bf16 v[62:65], v[130:133], v[162:165], v[62:65]
	v_mfma_f32_16x16x32_bf16 v[58:61], v[138:141], v[162:165], v[58:61]
	v_mfma_f32_16x16x32_bf16 v[50:53], v[130:133], v[170:173], v[50:53]
	v_mfma_f32_16x16x32_bf16 v[42:45], v[138:141], v[170:173], v[42:45]
	v_mfma_f32_16x16x32_bf16 v[34:37], v[130:133], v[178:181], v[34:37]
	v_mfma_f32_16x16x32_bf16 v[26:29], v[138:141], v[178:181], v[26:29]
	v_mfma_f32_16x16x32_bf16 v[18:21], v[130:133], v[186:189], v[18:21]
	v_mfma_f32_16x16x32_bf16 v[10:13], v[138:141], v[186:189], v[10:13]
	v_mfma_f32_16x16x32_bf16 v[62:65], v[134:137], v[166:169], v[62:65]
	v_mfma_f32_16x16x32_bf16 v[58:61], v[142:145], v[166:169], v[58:61]
	v_mfma_f32_16x16x32_bf16 v[50:53], v[134:137], v[174:177], v[50:53]
	v_mfma_f32_16x16x32_bf16 v[42:45], v[142:145], v[174:177], v[42:45]
	v_mfma_f32_16x16x32_bf16 v[34:37], v[134:137], v[182:185], v[34:37]
	v_mfma_f32_16x16x32_bf16 v[26:29], v[142:145], v[182:185], v[26:29]
	v_mfma_f32_16x16x32_bf16 v[18:21], v[134:137], v[196:199], v[18:21]
	v_mfma_f32_16x16x32_bf16 v[10:13], v[142:145], v[196:199], v[10:13]
	s_setprio 0
	s_setprio 1
	v_mfma_f32_16x16x32_bf16 v[54:57], v[146:149], v[162:165], v[54:57]
	v_mfma_f32_16x16x32_bf16 v[46:49], v[154:157], v[162:165], v[46:49]
	v_mfma_f32_16x16x32_bf16 v[38:41], v[146:149], v[170:173], v[38:41]
	v_mfma_f32_16x16x32_bf16 v[30:33], v[154:157], v[170:173], v[30:33]
	v_mfma_f32_16x16x32_bf16 v[22:25], v[146:149], v[178:181], v[22:25]
	v_mfma_f32_16x16x32_bf16 v[14:17], v[154:157], v[178:181], v[14:17]
	v_mfma_f32_16x16x32_bf16 v[6:9], v[146:149], v[186:189], v[6:9]
	v_mfma_f32_16x16x32_bf16 v[2:5], v[154:157], v[186:189], v[2:5]
	v_mfma_f32_16x16x32_bf16 v[54:57], v[150:153], v[166:169], v[54:57]
	v_mfma_f32_16x16x32_bf16 v[46:49], v[158:161], v[166:169], v[46:49]
	v_mfma_f32_16x16x32_bf16 v[38:41], v[150:153], v[174:177], v[38:41]
	v_mfma_f32_16x16x32_bf16 v[30:33], v[158:161], v[174:177], v[30:33]
	v_mfma_f32_16x16x32_bf16 v[22:25], v[150:153], v[182:185], v[22:25]
	v_mfma_f32_16x16x32_bf16 v[14:17], v[158:161], v[182:185], v[14:17]
	v_mfma_f32_16x16x32_bf16 v[6:9], v[150:153], v[196:199], v[6:9]
	v_mfma_f32_16x16x32_bf16 v[2:5], v[158:161], v[196:199], v[2:5]
	s_setprio 0
	s_barrier
	s_add_i32 s55, s55, 2
	s_add_u32 s24, s24, 0x100
	s_addc_u32 s25, s25, 0
	s_add_u32 s52, s52, 0x100
	s_addc_u32 s53, s53, 0
	s_cmp_gt_u32 s55, 29
	s_cbranch_scc1 .Lpeel_done_4
	s_branch .LBB0_800
.Ltrip0_strict_4:
	s_add_u32 s26, s24, 0xfff80080
	s_addc_u32 s27, s25, -1
	s_add_i32 s56, 0, 0x10000
	s_cmp_eq_u32 s55, 28
	s_cselect_b32 s29, s11, s27
	s_cselect_b32 s28, s21, s26
	s_cselect_b32 s27, s9, s53
	s_cselect_b32 s26, s47, s52
	s_add_i32 s60, 0, 0x14000
	v_add_u32_e32 v142, s56, v238
	v_add_u32_e32 v158, s60, v238
	ds_read_b128 v[130:133], v142
	ds_read_b128 v[134:137], v142 offset:1024
	ds_read_b128 v[138:141], v142 offset:2048
	ds_read_b128 v[142:145], v142 offset:3072
	ds_read_b128 v[146:149], v158
	ds_read_b128 v[150:153], v158 offset:1024
	ds_read_b128 v[154:157], v158 offset:2048
	ds_read_b128 v[158:161], v158 offset:3072
	v_lshl_add_u64 v[210:211], s[24:25], 0, v[206:207]
	s_add_i32 m0, s23, 0xc000
	ds_read_b128 v[162:165], v240
	ds_read_b128 v[166:169], v240 offset:1024
	ds_read_b128 v[170:173], v240 offset:2048
	ds_read_b128 v[174:177], v240 offset:3072
	ds_read_b128 v[178:181], v240 offset:4096
	ds_read_b128 v[182:185], v240 offset:5120
	ds_read_b128 v[186:189], v240 offset:6144
	ds_read_b128 v[196:199], v240 offset:7168
	global_load_lds_dwordx4 v[210:211], off
	s_add_i32 m0, s23, 0xe000
	v_lshl_add_u64 v[210:211], s[24:25], 0, v[208:209]
	global_load_lds_dwordx4 v[210:211], off
	s_waitcnt vmcnt(8) lgkmcnt(0)
	s_barrier
	s_setprio 1
	v_mfma_f32_16x16x32_bf16 v[126:129], v[130:133], v[162:165], 0
	v_mfma_f32_16x16x32_bf16 v[122:125], v[138:141], v[162:165], 0
	v_mfma_f32_16x16x32_bf16 v[110:113], v[130:133], v[170:173], 0
	v_mfma_f32_16x16x32_bf16 v[106:109], v[138:141], v[170:173], 0
	v_mfma_f32_16x16x32_bf16 v[98:101], v[130:133], v[178:181], 0
	v_mfma_f32_16x16x32_bf16 v[90:93], v[138:141], v[178:181], 0
	v_mfma_f32_16x16x32_bf16 v[82:85], v[130:133], v[186:189], 0
	v_mfma_f32_16x16x32_bf16 v[74:77], v[138:141], v[186:189], 0
	v_mfma_f32_16x16x32_bf16 v[126:129], v[134:137], v[166:169], v[126:129]
	v_mfma_f32_16x16x32_bf16 v[122:125], v[142:145], v[166:169], v[122:125]
	v_mfma_f32_16x16x32_bf16 v[110:113], v[134:137], v[174:177], v[110:113]
	v_mfma_f32_16x16x32_bf16 v[106:109], v[142:145], v[174:177], v[106:109]
	v_mfma_f32_16x16x32_bf16 v[98:101], v[134:137], v[182:185], v[98:101]
	v_mfma_f32_16x16x32_bf16 v[90:93], v[142:145], v[182:185], v[90:93]
	v_mfma_f32_16x16x32_bf16 v[82:85], v[134:137], v[196:199], v[82:85]
	v_mfma_f32_16x16x32_bf16 v[74:77], v[142:145], v[196:199], v[74:77]
	s_setprio 0
	s_setprio 1
	v_mfma_f32_16x16x32_bf16 v[118:121], v[146:149], v[162:165], 0
	v_mfma_f32_16x16x32_bf16 v[114:117], v[154:157], v[162:165], 0
	v_mfma_f32_16x16x32_bf16 v[102:105], v[146:149], v[170:173], 0
	v_mfma_f32_16x16x32_bf16 v[94:97], v[154:157], v[170:173], 0
	v_mfma_f32_16x16x32_bf16 v[86:89], v[146:149], v[178:181], 0
	v_mfma_f32_16x16x32_bf16 v[78:81], v[154:157], v[178:181], 0
	v_mfma_f32_16x16x32_bf16 v[70:73], v[146:149], v[186:189], 0
	v_mfma_f32_16x16x32_bf16 v[66:69], v[154:157], v[186:189], 0
	v_mfma_f32_16x16x32_bf16 v[118:121], v[150:153], v[166:169], v[118:121]
	v_mfma_f32_16x16x32_bf16 v[114:117], v[158:161], v[166:169], v[114:117]
	v_mfma_f32_16x16x32_bf16 v[102:105], v[150:153], v[174:177], v[102:105]
	v_mfma_f32_16x16x32_bf16 v[94:97], v[158:161], v[174:177], v[94:97]
	v_mfma_f32_16x16x32_bf16 v[86:89], v[150:153], v[182:185], v[86:89]
	v_mfma_f32_16x16x32_bf16 v[78:81], v[158:161], v[182:185], v[78:81]
	v_mfma_f32_16x16x32_bf16 v[70:73], v[150:153], v[196:199], v[70:73]
	v_mfma_f32_16x16x32_bf16 v[66:69], v[158:161], v[196:199], v[66:69]
	s_setprio 0
	s_barrier
	s_add_i32 s56, s56, s34
	v_lshl_add_u64 v[210:211], s[26:27], 0, v[190:191]
	s_mov_b32 m0, s56
	ds_read_b128 v[162:165], v240 offset:16384
	ds_read_b128 v[166:169], v240 offset:17408
	ds_read_b128 v[170:173], v240 offset:18432
	ds_read_b128 v[174:177], v240 offset:19456
	ds_read_b128 v[178:181], v240 offset:20480
	ds_read_b128 v[182:185], v240 offset:21504
	ds_read_b128 v[186:189], v240 offset:22528
	ds_read_b128 v[196:199], v240 offset:23552
	global_load_lds_dwordx4 v[210:211], off
	s_add_i32 m0, s56, 0x2000
	s_add_u32 s56, s26, 0x80000
	v_lshl_add_u64 v[212:213], s[26:27], 0, v[204:205]
	s_addc_u32 s57, s27, 0
	s_add_i32 s60, s60, s34
	global_load_lds_dwordx4 v[212:213], off
	v_lshl_add_u64 v[214:215], s[56:57], 0, v[190:191]
	s_mov_b32 m0, s60
	v_lshl_add_u64 v[216:217], s[28:29], 0, v[202:203]
	global_load_lds_dwordx4 v[214:215], off
	s_add_i32 m0, s60, 0x2000
	v_lshl_add_u64 v[214:215], s[56:57], 0, v[204:205]
	global_load_lds_dwordx4 v[214:215], off
	s_mov_b32 m0, s23
	v_lshl_add_u64 v[214:215], s[28:29], 0, v[200:201]
	global_load_lds_dwordx4 v[214:215], off
	s_mov_b32 m0, s35
	s_nop 0
	global_load_lds_dwordx4 v[216:217], off
	s_waitcnt vmcnt(8) lgkmcnt(0)
	s_barrier
	s_setprio 1
	v_mfma_f32_16x16x32_bf16 v[62:65], v[130:133], v[162:165], 0
	v_mfma_f32_16x16x32_bf16 v[58:61], v[138:141], v[162:165], 0
	v_mfma_f32_16x16x32_bf16 v[50:53], v[130:133], v[170:173], 0
	v_mfma_f32_16x16x32_bf16 v[42:45], v[138:141], v[170:173], 0
	v_mfma_f32_16x16x32_bf16 v[34:37], v[130:133], v[178:181], 0
	v_mfma_f32_16x16x32_bf16 v[26:29], v[138:141], v[178:181], 0
	v_mfma_f32_16x16x32_bf16 v[18:21], v[130:133], v[186:189], 0
	v_mfma_f32_16x16x32_bf16 v[10:13], v[138:141], v[186:189], 0
	v_mfma_f32_16x16x32_bf16 v[62:65], v[134:137], v[166:169], v[62:65]
	v_mfma_f32_16x16x32_bf16 v[58:61], v[142:145], v[166:169], v[58:61]
	v_mfma_f32_16x16x32_bf16 v[50:53], v[134:137], v[174:177], v[50:53]
	v_mfma_f32_16x16x32_bf16 v[42:45], v[142:145], v[174:177], v[42:45]
	v_mfma_f32_16x16x32_bf16 v[34:37], v[134:137], v[182:185], v[34:37]
	v_mfma_f32_16x16x32_bf16 v[26:29], v[142:145], v[182:185], v[26:29]
	v_mfma_f32_16x16x32_bf16 v[18:21], v[134:137], v[196:199], v[18:21]
	v_mfma_f32_16x16x32_bf16 v[10:13], v[142:145], v[196:199], v[10:13]
	s_setprio 0
	s_setprio 1
	v_mfma_f32_16x16x32_bf16 v[54:57], v[146:149], v[162:165], 0
	v_mfma_f32_16x16x32_bf16 v[46:49], v[154:157], v[162:165], 0
	v_mfma_f32_16x16x32_bf16 v[38:41], v[146:149], v[170:173], 0
	v_mfma_f32_16x16x32_bf16 v[30:33], v[154:157], v[170:173], 0
	v_mfma_f32_16x16x32_bf16 v[22:25], v[146:149], v[178:181], 0
	v_mfma_f32_16x16x32_bf16 v[14:17], v[154:157], v[178:181], 0
	v_mfma_f32_16x16x32_bf16 v[6:9], v[146:149], v[186:189], 0
	v_mfma_f32_16x16x32_bf16 v[2:5], v[154:157], v[186:189], 0
	v_mfma_f32_16x16x32_bf16 v[54:57], v[150:153], v[166:169], v[54:57]
	v_mfma_f32_16x16x32_bf16 v[46:49], v[158:161], v[166:169], v[46:49]
	v_mfma_f32_16x16x32_bf16 v[38:41], v[150:153], v[174:177], v[38:41]
	v_mfma_f32_16x16x32_bf16 v[30:33], v[158:161], v[174:177], v[30:33]
	v_mfma_f32_16x16x32_bf16 v[22:25], v[150:153], v[182:185], v[22:25]
	v_mfma_f32_16x16x32_bf16 v[14:17], v[158:161], v[182:185], v[14:17]
	v_mfma_f32_16x16x32_bf16 v[6:9], v[150:153], v[196:199], v[6:9]
	v_mfma_f32_16x16x32_bf16 v[2:5], v[158:161], v[196:199], v[2:5]
	s_setprio 0
	s_barrier
	s_add_i32 s56, 0, 0x18000
	s_add_i32 s57, 0, 0x1c000
	v_add_u32_e32 v142, s56, v238
	v_add_u32_e32 v158, s57, v238
	ds_read_b128 v[130:133], v142
	ds_read_b128 v[134:137], v142 offset:1024
	ds_read_b128 v[138:141], v142 offset:2048
	ds_read_b128 v[142:145], v142 offset:3072
	ds_read_b128 v[146:149], v158
	ds_read_b128 v[150:153], v158 offset:1024
	ds_read_b128 v[154:157], v158 offset:2048
	ds_read_b128 v[158:161], v158 offset:3072
	s_add_u32 s28, s28, 0x80000
	s_addc_u32 s29, s29, 0
	s_mov_b32 m0, s41
	v_lshl_add_u64 v[218:219], s[28:29], 0, v[200:201]
	ds_read_b128 v[162:165], v240 offset:32768
	ds_read_b128 v[166:169], v240 offset:33792
	ds_read_b128 v[170:173], v240 offset:34816
	ds_read_b128 v[174:177], v240 offset:35840
	ds_read_b128 v[178:181], v240 offset:36864
	ds_read_b128 v[182:185], v240 offset:37888
	ds_read_b128 v[186:189], v240 offset:38912
	ds_read_b128 v[196:199], v240 offset:39936
	global_load_lds_dwordx4 v[218:219], off
	s_mov_b32 m0, s42
	v_lshl_add_u64 v[218:219], s[28:29], 0, v[202:203]
	global_load_lds_dwordx4 v[218:219], off
	s_waitcnt vmcnt(8) lgkmcnt(0)
	s_barrier
	s_setprio 1
	v_mfma_f32_16x16x32_bf16 v[126:129], v[130:133], v[162:165], v[126:129]
	v_mfma_f32_16x16x32_bf16 v[122:125], v[138:141], v[162:165], v[122:125]
	v_mfma_f32_16x16x32_bf16 v[110:113], v[130:133], v[170:173], v[110:113]
	v_mfma_f32_16x16x32_bf16 v[106:109], v[138:141], v[170:173], v[106:109]
	v_mfma_f32_16x16x32_bf16 v[98:101], v[130:133], v[178:181], v[98:101]
	v_mfma_f32_16x16x32_bf16 v[90:93], v[138:141], v[178:181], v[90:93]
	v_mfma_f32_16x16x32_bf16 v[82:85], v[130:133], v[186:189], v[82:85]
	v_mfma_f32_16x16x32_bf16 v[74:77], v[138:141], v[186:189], v[74:77]
	v_mfma_f32_16x16x32_bf16 v[126:129], v[134:137], v[166:169], v[126:129]
	v_mfma_f32_16x16x32_bf16 v[122:125], v[142:145], v[166:169], v[122:125]
	v_mfma_f32_16x16x32_bf16 v[110:113], v[134:137], v[174:177], v[110:113]
	v_mfma_f32_16x16x32_bf16 v[106:109], v[142:145], v[174:177], v[106:109]
	v_mfma_f32_16x16x32_bf16 v[98:101], v[134:137], v[182:185], v[98:101]
	v_mfma_f32_16x16x32_bf16 v[90:93], v[142:145], v[182:185], v[90:93]
	v_mfma_f32_16x16x32_bf16 v[82:85], v[134:137], v[196:199], v[82:85]
	v_mfma_f32_16x16x32_bf16 v[74:77], v[142:145], v[196:199], v[74:77]
	s_setprio 0
	s_setprio 1
	v_mfma_f32_16x16x32_bf16 v[118:121], v[146:149], v[162:165], v[118:121]
	v_mfma_f32_16x16x32_bf16 v[114:117], v[154:157], v[162:165], v[114:117]
	v_mfma_f32_16x16x32_bf16 v[102:105], v[146:149], v[170:173], v[102:105]
	v_mfma_f32_16x16x32_bf16 v[94:97], v[154:157], v[170:173], v[94:97]
	v_mfma_f32_16x16x32_bf16 v[86:89], v[146:149], v[178:181], v[86:89]
	v_mfma_f32_16x16x32_bf16 v[78:81], v[154:157], v[178:181], v[78:81]
	v_mfma_f32_16x16x32_bf16 v[70:73], v[146:149], v[186:189], v[70:73]
	v_mfma_f32_16x16x32_bf16 v[66:69], v[154:157], v[186:189], v[66:69]
	v_mfma_f32_16x16x32_bf16 v[118:121], v[150:153], v[166:169], v[118:121]
	v_mfma_f32_16x16x32_bf16 v[114:117], v[158:161], v[166:169], v[114:117]
	v_mfma_f32_16x16x32_bf16 v[102:105], v[150:153], v[174:177], v[102:105]
	v_mfma_f32_16x16x32_bf16 v[94:97], v[158:161], v[174:177], v[94:97]
	v_mfma_f32_16x16x32_bf16 v[86:89], v[150:153], v[182:185], v[86:89]
	v_mfma_f32_16x16x32_bf16 v[78:81], v[158:161], v[182:185], v[78:81]
	v_mfma_f32_16x16x32_bf16 v[70:73], v[150:153], v[196:199], v[70:73]
	v_mfma_f32_16x16x32_bf16 v[66:69], v[158:161], v[196:199], v[66:69]
	s_setprio 0
	s_barrier
	s_add_i32 s28, s56, s34
	v_lshl_add_u64 v[210:211], v[210:211], 0, s[58:59]
	s_mov_b32 m0, s28
	ds_read_b128 v[162:165], v240 offset:49152
	ds_read_b128 v[166:169], v240 offset:50176
	ds_read_b128 v[170:173], v240 offset:51200
	ds_read_b128 v[174:177], v240 offset:52224
	ds_read_b128 v[178:181], v240 offset:53248
	ds_read_b128 v[182:185], v240 offset:54272
	ds_read_b128 v[186:189], v240 offset:55296
	ds_read_b128 v[196:199], v240 offset:56320
	global_load_lds_dwordx4 v[210:211], off
	s_add_i32 m0, s28, 0x2000
	s_add_u32 s26, s26, 0x80080
	v_lshl_add_u64 v[210:211], v[212:213], 0, s[58:59]
	s_addc_u32 s27, s27, 0
	s_add_i32 s28, s57, s34
	global_load_lds_dwordx4 v[210:211], off
	s_mov_b32 m0, s28
	v_lshl_add_u64 v[210:211], s[26:27], 0, v[190:191]
	global_load_lds_dwordx4 v[210:211], off
	s_add_i32 m0, s28, 0x2000
	v_lshl_add_u64 v[210:211], s[26:27], 0, v[204:205]
	global_load_lds_dwordx4 v[210:211], off
	s_mov_b32 m0, s43
	v_lshl_add_u64 v[210:211], v[214:215], 0, s[58:59]
	global_load_lds_dwordx4 v[210:211], off
	s_mov_b32 m0, s46
	v_lshl_add_u64 v[210:211], v[216:217], 0, s[58:59]
	global_load_lds_dwordx4 v[210:211], off
	s_waitcnt vmcnt(8) lgkmcnt(0)
	s_barrier
	s_setprio 1
	v_mfma_f32_16x16x32_bf16 v[62:65], v[130:133], v[162:165], v[62:65]
	v_mfma_f32_16x16x32_bf16 v[58:61], v[138:141], v[162:165], v[58:61]
	v_mfma_f32_16x16x32_bf16 v[50:53], v[130:133], v[170:173], v[50:53]
	v_mfma_f32_16x16x32_bf16 v[42:45], v[138:141], v[170:173], v[42:45]
	v_mfma_f32_16x16x32_bf16 v[34:37], v[130:133], v[178:181], v[34:37]
	v_mfma_f32_16x16x32_bf16 v[26:29], v[138:141], v[178:181], v[26:29]
	v_mfma_f32_16x16x32_bf16 v[18:21], v[130:133], v[186:189], v[18:21]
	v_mfma_f32_16x16x32_bf16 v[10:13], v[138:141], v[186:189], v[10:13]
	v_mfma_f32_16x16x32_bf16 v[62:65], v[134:137], v[166:169], v[62:65]
	v_mfma_f32_16x16x32_bf16 v[58:61], v[142:145], v[166:169], v[58:61]
	v_mfma_f32_16x16x32_bf16 v[50:53], v[134:137], v[174:177], v[50:53]
	v_mfma_f32_16x16x32_bf16 v[42:45], v[142:145], v[174:177], v[42:45]
	v_mfma_f32_16x16x32_bf16 v[34:37], v[134:137], v[182:185], v[34:37]
	v_mfma_f32_16x16x32_bf16 v[26:29], v[142:145], v[182:185], v[26:29]
	v_mfma_f32_16x16x32_bf16 v[18:21], v[134:137], v[196:199], v[18:21]
	v_mfma_f32_16x16x32_bf16 v[10:13], v[142:145], v[196:199], v[10:13]
	s_setprio 0
	s_setprio 1
	v_mfma_f32_16x16x32_bf16 v[54:57], v[146:149], v[162:165], v[54:57]
	v_mfma_f32_16x16x32_bf16 v[46:49], v[154:157], v[162:165], v[46:49]
	v_mfma_f32_16x16x32_bf16 v[38:41], v[146:149], v[170:173], v[38:41]
	v_mfma_f32_16x16x32_bf16 v[30:33], v[154:157], v[170:173], v[30:33]
	v_mfma_f32_16x16x32_bf16 v[22:25], v[146:149], v[178:181], v[22:25]
	v_mfma_f32_16x16x32_bf16 v[14:17], v[154:157], v[178:181], v[14:17]
	v_mfma_f32_16x16x32_bf16 v[6:9], v[146:149], v[186:189], v[6:9]
	v_mfma_f32_16x16x32_bf16 v[2:5], v[154:157], v[186:189], v[2:5]
	v_mfma_f32_16x16x32_bf16 v[54:57], v[150:153], v[166:169], v[54:57]
	v_mfma_f32_16x16x32_bf16 v[46:49], v[158:161], v[166:169], v[46:49]
	v_mfma_f32_16x16x32_bf16 v[38:41], v[150:153], v[174:177], v[38:41]
	v_mfma_f32_16x16x32_bf16 v[30:33], v[158:161], v[174:177], v[30:33]
	v_mfma_f32_16x16x32_bf16 v[22:25], v[150:153], v[182:185], v[22:25]
	v_mfma_f32_16x16x32_bf16 v[14:17], v[158:161], v[182:185], v[14:17]
	v_mfma_f32_16x16x32_bf16 v[6:9], v[150:153], v[196:199], v[6:9]
	v_mfma_f32_16x16x32_bf16 v[2:5], v[158:161], v[196:199], v[2:5]
	s_setprio 0
	s_barrier
	s_add_i32 s55, s55, 2
	s_add_u32 s24, s24, 0x100
	s_addc_u32 s25, s25, 0
	s_add_u32 s52, s52, 0x100
	s_addc_u32 s53, s53, 0
	s_cmp_gt_u32 s55, 29
	s_cbranch_scc1 .Lpeel_done_4
.LBB0_800:
	s_add_u32 s26, s24, 0xfff80080
	s_addc_u32 s27, s25, -1
	s_add_i32 s56, 0, 0x10000
	s_cmp_eq_u32 s55, 28
	s_cselect_b32 s29, s11, s27
	s_cselect_b32 s28, s21, s26
	s_cselect_b32 s27, s9, s53
	s_cselect_b32 s26, s47, s52
	s_add_i32 s60, 0, 0x14000
	v_add_u32_e32 v142, s56, v238
	v_add_u32_e32 v158, s60, v238
	ds_read_b128 v[130:133], v142
	ds_read_b128 v[134:137], v142 offset:1024
	ds_read_b128 v[138:141], v142 offset:2048
	ds_read_b128 v[142:145], v142 offset:3072
	ds_read_b128 v[146:149], v158
	ds_read_b128 v[150:153], v158 offset:1024
	ds_read_b128 v[154:157], v158 offset:2048
	ds_read_b128 v[158:161], v158 offset:3072
	v_lshl_add_u64 v[210:211], s[24:25], 0, v[206:207]
	s_add_i32 m0, s23, 0xc000
	ds_read_b128 v[162:165], v240
	ds_read_b128 v[166:169], v240 offset:1024
	ds_read_b128 v[170:173], v240 offset:2048
	ds_read_b128 v[174:177], v240 offset:3072
	ds_read_b128 v[178:181], v240 offset:4096
	ds_read_b128 v[182:185], v240 offset:5120
	ds_read_b128 v[186:189], v240 offset:6144
	ds_read_b128 v[196:199], v240 offset:7168
	global_load_lds_dwordx4 v[210:211], off
	s_add_i32 m0, s23, 0xe000
	v_lshl_add_u64 v[210:211], s[24:25], 0, v[208:209]
	global_load_lds_dwordx4 v[210:211], off
	s_waitcnt vmcnt(8) lgkmcnt(0)
	s_barrier
	s_setprio 1
	v_mfma_f32_16x16x32_bf16 v[126:129], v[130:133], v[162:165], v[126:129]
	v_mfma_f32_16x16x32_bf16 v[122:125], v[138:141], v[162:165], v[122:125]
	v_mfma_f32_16x16x32_bf16 v[110:113], v[130:133], v[170:173], v[110:113]
	v_mfma_f32_16x16x32_bf16 v[106:109], v[138:141], v[170:173], v[106:109]
	v_mfma_f32_16x16x32_bf16 v[98:101], v[130:133], v[178:181], v[98:101]
	v_mfma_f32_16x16x32_bf16 v[90:93], v[138:141], v[178:181], v[90:93]
	v_mfma_f32_16x16x32_bf16 v[82:85], v[130:133], v[186:189], v[82:85]
	v_mfma_f32_16x16x32_bf16 v[74:77], v[138:141], v[186:189], v[74:77]
	v_mfma_f32_16x16x32_bf16 v[126:129], v[134:137], v[166:169], v[126:129]
	v_mfma_f32_16x16x32_bf16 v[122:125], v[142:145], v[166:169], v[122:125]
	v_mfma_f32_16x16x32_bf16 v[110:113], v[134:137], v[174:177], v[110:113]
	v_mfma_f32_16x16x32_bf16 v[106:109], v[142:145], v[174:177], v[106:109]
	v_mfma_f32_16x16x32_bf16 v[98:101], v[134:137], v[182:185], v[98:101]
	v_mfma_f32_16x16x32_bf16 v[90:93], v[142:145], v[182:185], v[90:93]
	v_mfma_f32_16x16x32_bf16 v[82:85], v[134:137], v[196:199], v[82:85]
	v_mfma_f32_16x16x32_bf16 v[74:77], v[142:145], v[196:199], v[74:77]
	s_setprio 0
	s_setprio 1
	v_mfma_f32_16x16x32_bf16 v[118:121], v[146:149], v[162:165], v[118:121]
	v_mfma_f32_16x16x32_bf16 v[114:117], v[154:157], v[162:165], v[114:117]
	v_mfma_f32_16x16x32_bf16 v[102:105], v[146:149], v[170:173], v[102:105]
	v_mfma_f32_16x16x32_bf16 v[94:97], v[154:157], v[170:173], v[94:97]
	v_mfma_f32_16x16x32_bf16 v[86:89], v[146:149], v[178:181], v[86:89]
	v_mfma_f32_16x16x32_bf16 v[78:81], v[154:157], v[178:181], v[78:81]
	v_mfma_f32_16x16x32_bf16 v[70:73], v[146:149], v[186:189], v[70:73]
	v_mfma_f32_16x16x32_bf16 v[66:69], v[154:157], v[186:189], v[66:69]
	v_mfma_f32_16x16x32_bf16 v[118:121], v[150:153], v[166:169], v[118:121]
	v_mfma_f32_16x16x32_bf16 v[114:117], v[158:161], v[166:169], v[114:117]
	v_mfma_f32_16x16x32_bf16 v[102:105], v[150:153], v[174:177], v[102:105]
	v_mfma_f32_16x16x32_bf16 v[94:97], v[158:161], v[174:177], v[94:97]
	v_mfma_f32_16x16x32_bf16 v[86:89], v[150:153], v[182:185], v[86:89]
	v_mfma_f32_16x16x32_bf16 v[78:81], v[158:161], v[182:185], v[78:81]
	v_mfma_f32_16x16x32_bf16 v[70:73], v[150:153], v[196:199], v[70:73]
	v_mfma_f32_16x16x32_bf16 v[66:69], v[158:161], v[196:199], v[66:69]
	s_setprio 0
	s_barrier
	s_add_i32 s56, s56, s34
	v_lshl_add_u64 v[210:211], s[26:27], 0, v[190:191]
	s_mov_b32 m0, s56
	ds_read_b128 v[162:165], v240 offset:16384
	ds_read_b128 v[166:169], v240 offset:17408
	ds_read_b128 v[170:173], v240 offset:18432
	ds_read_b128 v[174:177], v240 offset:19456
	ds_read_b128 v[178:181], v240 offset:20480
	ds_read_b128 v[182:185], v240 offset:21504
	ds_read_b128 v[186:189], v240 offset:22528
	ds_read_b128 v[196:199], v240 offset:23552
	global_load_lds_dwordx4 v[210:211], off
	s_add_i32 m0, s56, 0x2000
	s_add_u32 s56, s26, 0x80000
	v_lshl_add_u64 v[212:213], s[26:27], 0, v[204:205]
	s_addc_u32 s57, s27, 0
	s_add_i32 s60, s60, s34
	global_load_lds_dwordx4 v[212:213], off
	v_lshl_add_u64 v[214:215], s[56:57], 0, v[190:191]
	s_mov_b32 m0, s60
	v_lshl_add_u64 v[216:217], s[28:29], 0, v[202:203]
	global_load_lds_dwordx4 v[214:215], off
	s_add_i32 m0, s60, 0x2000
	v_lshl_add_u64 v[214:215], s[56:57], 0, v[204:205]
	global_load_lds_dwordx4 v[214:215], off
	s_mov_b32 m0, s23
	v_lshl_add_u64 v[214:215], s[28:29], 0, v[200:201]
	global_load_lds_dwordx4 v[214:215], off
	s_mov_b32 m0, s35
	s_nop 0
	global_load_lds_dwordx4 v[216:217], off
	s_waitcnt vmcnt(8) lgkmcnt(0)
	s_barrier
	s_setprio 1
	v_mfma_f32_16x16x32_bf16 v[62:65], v[130:133], v[162:165], v[62:65]
	v_mfma_f32_16x16x32_bf16 v[58:61], v[138:141], v[162:165], v[58:61]
	v_mfma_f32_16x16x32_bf16 v[50:53], v[130:133], v[170:173], v[50:53]
	v_mfma_f32_16x16x32_bf16 v[42:45], v[138:141], v[170:173], v[42:45]
	v_mfma_f32_16x16x32_bf16 v[34:37], v[130:133], v[178:181], v[34:37]
	v_mfma_f32_16x16x32_bf16 v[26:29], v[138:141], v[178:181], v[26:29]
	v_mfma_f32_16x16x32_bf16 v[18:21], v[130:133], v[186:189], v[18:21]
	v_mfma_f32_16x16x32_bf16 v[10:13], v[138:141], v[186:189], v[10:13]
	v_mfma_f32_16x16x32_bf16 v[62:65], v[134:137], v[166:169], v[62:65]
	v_mfma_f32_16x16x32_bf16 v[58:61], v[142:145], v[166:169], v[58:61]
	v_mfma_f32_16x16x32_bf16 v[50:53], v[134:137], v[174:177], v[50:53]
	v_mfma_f32_16x16x32_bf16 v[42:45], v[142:145], v[174:177], v[42:45]
	v_mfma_f32_16x16x32_bf16 v[34:37], v[134:137], v[182:185], v[34:37]
	v_mfma_f32_16x16x32_bf16 v[26:29], v[142:145], v[182:185], v[26:29]
	v_mfma_f32_16x16x32_bf16 v[18:21], v[134:137], v[196:199], v[18:21]
	v_mfma_f32_16x16x32_bf16 v[10:13], v[142:145], v[196:199], v[10:13]
	s_setprio 0
	s_setprio 1
	v_mfma_f32_16x16x32_bf16 v[54:57], v[146:149], v[162:165], v[54:57]
	v_mfma_f32_16x16x32_bf16 v[46:49], v[154:157], v[162:165], v[46:49]
	v_mfma_f32_16x16x32_bf16 v[38:41], v[146:149], v[170:173], v[38:41]
	v_mfma_f32_16x16x32_bf16 v[30:33], v[154:157], v[170:173], v[30:33]
	v_mfma_f32_16x16x32_bf16 v[22:25], v[146:149], v[178:181], v[22:25]
	v_mfma_f32_16x16x32_bf16 v[14:17], v[154:157], v[178:181], v[14:17]
	v_mfma_f32_16x16x32_bf16 v[6:9], v[146:149], v[186:189], v[6:9]
	v_mfma_f32_16x16x32_bf16 v[2:5], v[154:157], v[186:189], v[2:5]
	v_mfma_f32_16x16x32_bf16 v[54:57], v[150:153], v[166:169], v[54:57]
	v_mfma_f32_16x16x32_bf16 v[46:49], v[158:161], v[166:169], v[46:49]
	v_mfma_f32_16x16x32_bf16 v[38:41], v[150:153], v[174:177], v[38:41]
	v_mfma_f32_16x16x32_bf16 v[30:33], v[158:161], v[174:177], v[30:33]
	v_mfma_f32_16x16x32_bf16 v[22:25], v[150:153], v[182:185], v[22:25]
	v_mfma_f32_16x16x32_bf16 v[14:17], v[158:161], v[182:185], v[14:17]
	v_mfma_f32_16x16x32_bf16 v[6:9], v[150:153], v[196:199], v[6:9]
	v_mfma_f32_16x16x32_bf16 v[2:5], v[158:161], v[196:199], v[2:5]
	s_setprio 0
	s_barrier
	s_add_i32 s56, 0, 0x18000
	s_add_i32 s57, 0, 0x1c000
	v_add_u32_e32 v142, s56, v238
	v_add_u32_e32 v158, s57, v238
	ds_read_b128 v[130:133], v142
	ds_read_b128 v[134:137], v142 offset:1024
	ds_read_b128 v[138:141], v142 offset:2048
	ds_read_b128 v[142:145], v142 offset:3072
	ds_read_b128 v[146:149], v158
	ds_read_b128 v[150:153], v158 offset:1024
	ds_read_b128 v[154:157], v158 offset:2048
	ds_read_b128 v[158:161], v158 offset:3072
	s_add_u32 s28, s28, 0x80000
	s_addc_u32 s29, s29, 0
	s_mov_b32 m0, s41
	v_lshl_add_u64 v[218:219], s[28:29], 0, v[200:201]
	ds_read_b128 v[162:165], v240 offset:32768
	ds_read_b128 v[166:169], v240 offset:33792
	ds_read_b128 v[170:173], v240 offset:34816
	ds_read_b128 v[174:177], v240 offset:35840
	ds_read_b128 v[178:181], v240 offset:36864
	ds_read_b128 v[182:185], v240 offset:37888
	ds_read_b128 v[186:189], v240 offset:38912
	ds_read_b128 v[196:199], v240 offset:39936
	global_load_lds_dwordx4 v[218:219], off
	s_mov_b32 m0, s42
	v_lshl_add_u64 v[218:219], s[28:29], 0, v[202:203]
	global_load_lds_dwordx4 v[218:219], off
	s_waitcnt vmcnt(8) lgkmcnt(0)
	s_barrier
	s_setprio 1
	v_mfma_f32_16x16x32_bf16 v[126:129], v[130:133], v[162:165], v[126:129]
	v_mfma_f32_16x16x32_bf16 v[122:125], v[138:141], v[162:165], v[122:125]
	v_mfma_f32_16x16x32_bf16 v[110:113], v[130:133], v[170:173], v[110:113]
	v_mfma_f32_16x16x32_bf16 v[106:109], v[138:141], v[170:173], v[106:109]
	v_mfma_f32_16x16x32_bf16 v[98:101], v[130:133], v[178:181], v[98:101]
	v_mfma_f32_16x16x32_bf16 v[90:93], v[138:141], v[178:181], v[90:93]
	v_mfma_f32_16x16x32_bf16 v[82:85], v[130:133], v[186:189], v[82:85]
	v_mfma_f32_16x16x32_bf16 v[74:77], v[138:141], v[186:189], v[74:77]
	v_mfma_f32_16x16x32_bf16 v[126:129], v[134:137], v[166:169], v[126:129]
	v_mfma_f32_16x16x32_bf16 v[122:125], v[142:145], v[166:169], v[122:125]
	v_mfma_f32_16x16x32_bf16 v[110:113], v[134:137], v[174:177], v[110:113]
	v_mfma_f32_16x16x32_bf16 v[106:109], v[142:145], v[174:177], v[106:109]
	v_mfma_f32_16x16x32_bf16 v[98:101], v[134:137], v[182:185], v[98:101]
	v_mfma_f32_16x16x32_bf16 v[90:93], v[142:145], v[182:185], v[90:93]
	v_mfma_f32_16x16x32_bf16 v[82:85], v[134:137], v[196:199], v[82:85]
	v_mfma_f32_16x16x32_bf16 v[74:77], v[142:145], v[196:199], v[74:77]
	s_setprio 0
	s_setprio 1
	v_mfma_f32_16x16x32_bf16 v[118:121], v[146:149], v[162:165], v[118:121]
	v_mfma_f32_16x16x32_bf16 v[114:117], v[154:157], v[162:165], v[114:117]
	v_mfma_f32_16x16x32_bf16 v[102:105], v[146:149], v[170:173], v[102:105]
	v_mfma_f32_16x16x32_bf16 v[94:97], v[154:157], v[170:173], v[94:97]
	v_mfma_f32_16x16x32_bf16 v[86:89], v[146:149], v[178:181], v[86:89]
	v_mfma_f32_16x16x32_bf16 v[78:81], v[154:157], v[178:181], v[78:81]
	v_mfma_f32_16x16x32_bf16 v[70:73], v[146:149], v[186:189], v[70:73]
	v_mfma_f32_16x16x32_bf16 v[66:69], v[154:157], v[186:189], v[66:69]
	v_mfma_f32_16x16x32_bf16 v[118:121], v[150:153], v[166:169], v[118:121]
	v_mfma_f32_16x16x32_bf16 v[114:117], v[158:161], v[166:169], v[114:117]
	v_mfma_f32_16x16x32_bf16 v[102:105], v[150:153], v[174:177], v[102:105]
	v_mfma_f32_16x16x32_bf16 v[94:97], v[158:161], v[174:177], v[94:97]
	v_mfma_f32_16x16x32_bf16 v[86:89], v[150:153], v[182:185], v[86:89]
	v_mfma_f32_16x16x32_bf16 v[78:81], v[158:161], v[182:185], v[78:81]
	v_mfma_f32_16x16x32_bf16 v[70:73], v[150:153], v[196:199], v[70:73]
	v_mfma_f32_16x16x32_bf16 v[66:69], v[158:161], v[196:199], v[66:69]
	s_setprio 0
	s_barrier
	s_add_i32 s28, s56, s34
	v_lshl_add_u64 v[210:211], v[210:211], 0, s[58:59]
	s_mov_b32 m0, s28
	ds_read_b128 v[162:165], v240 offset:49152
	ds_read_b128 v[166:169], v240 offset:50176
	ds_read_b128 v[170:173], v240 offset:51200
	ds_read_b128 v[174:177], v240 offset:52224
	ds_read_b128 v[178:181], v240 offset:53248
	ds_read_b128 v[182:185], v240 offset:54272
	ds_read_b128 v[186:189], v240 offset:55296
	ds_read_b128 v[196:199], v240 offset:56320
	global_load_lds_dwordx4 v[210:211], off
	s_add_i32 m0, s28, 0x2000
	s_add_u32 s26, s26, 0x80080
	v_lshl_add_u64 v[210:211], v[212:213], 0, s[58:59]
	s_addc_u32 s27, s27, 0
	s_add_i32 s28, s57, s34
	global_load_lds_dwordx4 v[210:211], off
	s_mov_b32 m0, s28
	v_lshl_add_u64 v[210:211], s[26:27], 0, v[190:191]
	global_load_lds_dwordx4 v[210:211], off
	s_add_i32 m0, s28, 0x2000
	v_lshl_add_u64 v[210:211], s[26:27], 0, v[204:205]
	global_load_lds_dwordx4 v[210:211], off
	s_mov_b32 m0, s43
	v_lshl_add_u64 v[210:211], v[214:215], 0, s[58:59]
	global_load_lds_dwordx4 v[210:211], off
	s_mov_b32 m0, s46
	v_lshl_add_u64 v[210:211], v[216:217], 0, s[58:59]
	global_load_lds_dwordx4 v[210:211], off
	s_waitcnt vmcnt(8) lgkmcnt(0)
	s_barrier
	s_setprio 1
	v_mfma_f32_16x16x32_bf16 v[62:65], v[130:133], v[162:165], v[62:65]
	v_mfma_f32_16x16x32_bf16 v[58:61], v[138:141], v[162:165], v[58:61]
	v_mfma_f32_16x16x32_bf16 v[50:53], v[130:133], v[170:173], v[50:53]
	v_mfma_f32_16x16x32_bf16 v[42:45], v[138:141], v[170:173], v[42:45]
	v_mfma_f32_16x16x32_bf16 v[34:37], v[130:133], v[178:181], v[34:37]
	v_mfma_f32_16x16x32_bf16 v[26:29], v[138:141], v[178:181], v[26:29]
	v_mfma_f32_16x16x32_bf16 v[18:21], v[130:133], v[186:189], v[18:21]
	v_mfma_f32_16x16x32_bf16 v[10:13], v[138:141], v[186:189], v[10:13]
	v_mfma_f32_16x16x32_bf16 v[62:65], v[134:137], v[166:169], v[62:65]
	v_mfma_f32_16x16x32_bf16 v[58:61], v[142:145], v[166:169], v[58:61]
	v_mfma_f32_16x16x32_bf16 v[50:53], v[134:137], v[174:177], v[50:53]
	v_mfma_f32_16x16x32_bf16 v[42:45], v[142:145], v[174:177], v[42:45]
	v_mfma_f32_16x16x32_bf16 v[34:37], v[134:137], v[182:185], v[34:37]
	v_mfma_f32_16x16x32_bf16 v[26:29], v[142:145], v[182:185], v[26:29]
	v_mfma_f32_16x16x32_bf16 v[18:21], v[134:137], v[196:199], v[18:21]
	v_mfma_f32_16x16x32_bf16 v[10:13], v[142:145], v[196:199], v[10:13]
	s_setprio 0
	s_setprio 1
	v_mfma_f32_16x16x32_bf16 v[54:57], v[146:149], v[162:165], v[54:57]
	v_mfma_f32_16x16x32_bf16 v[46:49], v[154:157], v[162:165], v[46:49]
	v_mfma_f32_16x16x32_bf16 v[38:41], v[146:149], v[170:173], v[38:41]
	v_mfma_f32_16x16x32_bf16 v[30:33], v[154:157], v[170:173], v[30:33]
	v_mfma_f32_16x16x32_bf16 v[22:25], v[146:149], v[178:181], v[22:25]
	v_mfma_f32_16x16x32_bf16 v[14:17], v[154:157], v[178:181], v[14:17]
	v_mfma_f32_16x16x32_bf16 v[6:9], v[146:149], v[186:189], v[6:9]
	v_mfma_f32_16x16x32_bf16 v[2:5], v[154:157], v[186:189], v[2:5]
	v_mfma_f32_16x16x32_bf16 v[54:57], v[150:153], v[166:169], v[54:57]
	v_mfma_f32_16x16x32_bf16 v[46:49], v[158:161], v[166:169], v[46:49]
	v_mfma_f32_16x16x32_bf16 v[38:41], v[150:153], v[174:177], v[38:41]
	v_mfma_f32_16x16x32_bf16 v[30:33], v[158:161], v[174:177], v[30:33]
	v_mfma_f32_16x16x32_bf16 v[22:25], v[150:153], v[182:185], v[22:25]
	v_mfma_f32_16x16x32_bf16 v[14:17], v[158:161], v[182:185], v[14:17]
	v_mfma_f32_16x16x32_bf16 v[6:9], v[150:153], v[196:199], v[6:9]
	v_mfma_f32_16x16x32_bf16 v[2:5], v[158:161], v[196:199], v[2:5]
	s_setprio 0
	s_barrier
	s_add_i32 s55, s55, 2
	s_add_u32 s24, s24, 0x100
	s_addc_u32 s25, s25, 0
	s_add_u32 s52, s52, 0x100
	s_addc_u32 s53, s53, 0
	s_cmp_gt_u32 s55, 29
	s_cbranch_scc0 .LBB0_800

.LBB0_822:
	s_ashr_i32 s17, s16, 31
	s_lshl_b64 s[22:23], s[16:17], 20
	v_readlane_b32 s0, v254, 60
	s_add_u32 s22, s0, s22
	v_readlane_b32 s0, v254, 61
	s_addc_u32 s23, s0, s23
	s_and_b64 s[24:25], s[20:21], exec
	s_cselect_b32 s17, s23, s31
	s_cselect_b32 s27, s22, s30
	s_ashr_i32 s15, s14, 31
	s_lshl_b64 s[24:25], s[14:15], 20
	v_readlane_b32 s0, v254, 40
	v_readlane_b32 s1, v254, 41
	s_add_u32 s24, s0, s24
	s_addc_u32 s25, s1, s25
	s_and_b64 s[52:53], s[20:21], exec
	s_cselect_b32 s15, s25, s35
	s_cselect_b32 s29, s24, s34
	s_add_u32 s30, s30, 0x80080
	s_addc_u32 s31, s31, 0
	s_add_u32 s81, s34, 0x100
	s_addc_u32 s88, s35, 0
	s_mov_b32 s89, -2
	v_readlane_b32 s90, v255, 49
	s_nop 3
	s_cmp_eq_u32 s90, 6
	v_writelane_b32 v255, 6, 49
	s_cbranch_scc0 .Ltrip0_strict_5
	s_add_u32 s34, s30, 0xfff80080
	s_addc_u32 s35, s31, -1
	s_add_i32 s90, 0, 0x10000
	s_cmp_eq_u32 s89, 28
	s_cselect_b32 s53, s17, s35
	s_cselect_b32 s52, s27, s34
	s_cselect_b32 s35, s15, s88
	s_cselect_b32 s34, s29, s81
	s_add_i32 s96, 0, 0x14000
	v_add_u32_e32 v142, s90, v220
	v_add_u32_e32 v158, s96, v220
	ds_read_b128 v[130:133], v142
	ds_read_b128 v[134:137], v142 offset:1024
	ds_read_b128 v[138:141], v142 offset:2048
	ds_read_b128 v[142:145], v142 offset:3072
	ds_read_b128 v[146:149], v158
	ds_read_b128 v[150:153], v158 offset:1024
	ds_read_b128 v[154:157], v158 offset:2048
	ds_read_b128 v[158:161], v158 offset:3072
	v_lshl_add_u64 v[210:211], s[30:31], 0, v[202:203]
	s_add_i32 m0, s55, 0xc000
	ds_read_b128 v[162:165], v222
	ds_read_b128 v[166:169], v222 offset:1024
	ds_read_b128 v[170:173], v222 offset:2048
	ds_read_b128 v[174:177], v222 offset:3072
	ds_read_b128 v[178:181], v222 offset:4096
	ds_read_b128 v[182:185], v222 offset:5120
	ds_read_b128 v[196:199], v222 offset:6144
	ds_read_b128 v[206:209], v222 offset:7168
	global_load_lds_dwordx4 v[210:211], off
	s_add_i32 m0, s55, 0xe000
	v_lshl_add_u64 v[210:211], s[30:31], 0, v[204:205]
	global_load_lds_dwordx4 v[210:211], off
	s_waitcnt vmcnt(24) lgkmcnt(0)
	s_barrier
	s_setprio 1
	v_mfma_f32_16x16x32_bf16 v[126:129], v[130:133], v[162:165], 0
	v_mfma_f32_16x16x32_bf16 v[122:125], v[138:141], v[162:165], 0
	v_mfma_f32_16x16x32_bf16 v[110:113], v[130:133], v[170:173], 0
	v_mfma_f32_16x16x32_bf16 v[106:109], v[138:141], v[170:173], 0
	v_mfma_f32_16x16x32_bf16 v[94:97], v[130:133], v[178:181], 0
	v_mfma_f32_16x16x32_bf16 v[90:93], v[138:141], v[178:181], 0
	v_mfma_f32_16x16x32_bf16 v[78:81], v[130:133], v[196:199], 0
	v_mfma_f32_16x16x32_bf16 v[74:77], v[138:141], v[196:199], 0
	v_mfma_f32_16x16x32_bf16 v[126:129], v[134:137], v[166:169], v[126:129]
	v_mfma_f32_16x16x32_bf16 v[122:125], v[142:145], v[166:169], v[122:125]
	v_mfma_f32_16x16x32_bf16 v[110:113], v[134:137], v[174:177], v[110:113]
	v_mfma_f32_16x16x32_bf16 v[106:109], v[142:145], v[174:177], v[106:109]
	v_mfma_f32_16x16x32_bf16 v[94:97], v[134:137], v[182:185], v[94:97]
	v_mfma_f32_16x16x32_bf16 v[90:93], v[142:145], v[182:185], v[90:93]
	v_mfma_f32_16x16x32_bf16 v[78:81], v[134:137], v[206:209], v[78:81]
	v_mfma_f32_16x16x32_bf16 v[74:77], v[142:145], v[206:209], v[74:77]
	s_setprio 0
	s_setprio 1
	v_mfma_f32_16x16x32_bf16 v[118:121], v[146:149], v[162:165], 0
	v_mfma_f32_16x16x32_bf16 v[114:117], v[154:157], v[162:165], 0
	v_mfma_f32_16x16x32_bf16 v[102:105], v[146:149], v[170:173], 0
	v_mfma_f32_16x16x32_bf16 v[98:101], v[154:157], v[170:173], 0
	v_mfma_f32_16x16x32_bf16 v[86:89], v[146:149], v[178:181], 0
	v_mfma_f32_16x16x32_bf16 v[82:85], v[154:157], v[178:181], 0
	v_mfma_f32_16x16x32_bf16 v[70:73], v[146:149], v[196:199], 0
	v_mfma_f32_16x16x32_bf16 v[66:69], v[154:157], v[196:199], 0
	v_mfma_f32_16x16x32_bf16 v[118:121], v[150:153], v[166:169], v[118:121]
	v_mfma_f32_16x16x32_bf16 v[114:117], v[158:161], v[166:169], v[114:117]
	v_mfma_f32_16x16x32_bf16 v[102:105], v[150:153], v[174:177], v[102:105]
	v_mfma_f32_16x16x32_bf16 v[98:101], v[158:161], v[174:177], v[98:101]
	v_mfma_f32_16x16x32_bf16 v[86:89], v[150:153], v[182:185], v[86:89]
	v_mfma_f32_16x16x32_bf16 v[82:85], v[158:161], v[182:185], v[82:85]
	v_mfma_f32_16x16x32_bf16 v[70:73], v[150:153], v[206:209], v[70:73]
	v_mfma_f32_16x16x32_bf16 v[66:69], v[158:161], v[206:209], v[66:69]
	s_setprio 0
	s_barrier
	s_add_i32 s90, s90, s47
	v_lshl_add_u64 v[210:211], s[34:35], 0, v[190:191]
	s_mov_b32 m0, s90
	ds_read_b128 v[162:165], v222 offset:16384
	ds_read_b128 v[166:169], v222 offset:17408
	ds_read_b128 v[170:173], v222 offset:18432
	ds_read_b128 v[174:177], v222 offset:19456
	ds_read_b128 v[178:181], v222 offset:20480
	ds_read_b128 v[182:185], v222 offset:21504
	ds_read_b128 v[196:199], v222 offset:22528
	ds_read_b128 v[206:209], v222 offset:23552
	global_load_lds_dwordx4 v[210:211], off
	s_add_i32 m0, s90, 0x2000
	s_add_u32 s90, s34, 0x80000
	v_lshl_add_u64 v[212:213], s[34:35], 0, v[200:201]
	s_addc_u32 s91, s35, 0
	s_add_i32 s96, s96, s47
	global_load_lds_dwordx4 v[212:213], off
	v_lshl_add_u64 v[214:215], s[90:91], 0, v[190:191]
	s_mov_b32 m0, s96
	v_lshl_add_u64 v[216:217], s[52:53], 0, v[188:189]
	global_load_lds_dwordx4 v[214:215], off
	s_add_i32 m0, s96, 0x2000
	v_lshl_add_u64 v[214:215], s[90:91], 0, v[200:201]
	global_load_lds_dwordx4 v[214:215], off
	s_mov_b32 m0, s55
	v_lshl_add_u64 v[214:215], s[52:53], 0, v[186:187]
	global_load_lds_dwordx4 v[214:215], off
	s_mov_b32 m0, s56
	s_nop 0
	global_load_lds_dwordx4 v[216:217], off
	s_waitcnt vmcnt(24) lgkmcnt(0)
	s_barrier
	s_setprio 1
	v_mfma_f32_16x16x32_bf16 v[62:65], v[130:133], v[162:165], 0
	v_mfma_f32_16x16x32_bf16 v[58:61], v[138:141], v[162:165], 0
	v_mfma_f32_16x16x32_bf16 v[46:49], v[130:133], v[170:173], 0
	v_mfma_f32_16x16x32_bf16 v[42:45], v[138:141], v[170:173], 0
	v_mfma_f32_16x16x32_bf16 v[30:33], v[130:133], v[178:181], 0
	v_mfma_f32_16x16x32_bf16 v[26:29], v[138:141], v[178:181], 0
	v_mfma_f32_16x16x32_bf16 v[14:17], v[130:133], v[196:199], 0
	v_mfma_f32_16x16x32_bf16 v[10:13], v[138:141], v[196:199], 0
	v_mfma_f32_16x16x32_bf16 v[62:65], v[134:137], v[166:169], v[62:65]
	v_mfma_f32_16x16x32_bf16 v[58:61], v[142:145], v[166:169], v[58:61]
	v_mfma_f32_16x16x32_bf16 v[46:49], v[134:137], v[174:177], v[46:49]
	v_mfma_f32_16x16x32_bf16 v[42:45], v[142:145], v[174:177], v[42:45]
	v_mfma_f32_16x16x32_bf16 v[30:33], v[134:137], v[182:185], v[30:33]
	v_mfma_f32_16x16x32_bf16 v[26:29], v[142:145], v[182:185], v[26:29]
	v_mfma_f32_16x16x32_bf16 v[14:17], v[134:137], v[206:209], v[14:17]
	v_mfma_f32_16x16x32_bf16 v[10:13], v[142:145], v[206:209], v[10:13]
	s_setprio 0
	s_setprio 1
	v_mfma_f32_16x16x32_bf16 v[54:57], v[146:149], v[162:165], 0
	v_mfma_f32_16x16x32_bf16 v[50:53], v[154:157], v[162:165], 0
	v_mfma_f32_16x16x32_bf16 v[38:41], v[146:149], v[170:173], 0
	v_mfma_f32_16x16x32_bf16 v[34:37], v[154:157], v[170:173], 0
	v_mfma_f32_16x16x32_bf16 v[22:25], v[146:149], v[178:181], 0
	v_mfma_f32_16x16x32_bf16 v[18:21], v[154:157], v[178:181], 0
	v_mfma_f32_16x16x32_bf16 v[6:9], v[146:149], v[196:199], 0
	v_mfma_f32_16x16x32_bf16 v[2:5], v[154:157], v[196:199], 0
	v_mfma_f32_16x16x32_bf16 v[54:57], v[150:153], v[166:169], v[54:57]
	v_mfma_f32_16x16x32_bf16 v[50:53], v[158:161], v[166:169], v[50:53]
	v_mfma_f32_16x16x32_bf16 v[38:41], v[150:153], v[174:177], v[38:41]
	v_mfma_f32_16x16x32_bf16 v[34:37], v[158:161], v[174:177], v[34:37]
	v_mfma_f32_16x16x32_bf16 v[22:25], v[150:153], v[182:185], v[22:25]
	v_mfma_f32_16x16x32_bf16 v[18:21], v[158:161], v[182:185], v[18:21]
	v_mfma_f32_16x16x32_bf16 v[6:9], v[150:153], v[206:209], v[6:9]
	v_mfma_f32_16x16x32_bf16 v[2:5], v[158:161], v[206:209], v[2:5]
	s_setprio 0
	s_barrier
	s_add_i32 s90, 0, 0x18000
	s_add_i32 s91, 0, 0x1c000
	v_add_u32_e32 v142, s90, v220
	v_add_u32_e32 v158, s91, v220
	ds_read_b128 v[130:133], v142
	ds_read_b128 v[134:137], v142 offset:1024
	ds_read_b128 v[138:141], v142 offset:2048
	ds_read_b128 v[142:145], v142 offset:3072
	ds_read_b128 v[146:149], v158
	ds_read_b128 v[150:153], v158 offset:1024
	ds_read_b128 v[154:157], v158 offset:2048
	ds_read_b128 v[158:161], v158 offset:3072
	s_add_u32 s52, s52, 0x80000
	s_addc_u32 s53, s53, 0
	s_mov_b32 m0, s57
	v_lshl_add_u64 v[218:219], s[52:53], 0, v[186:187]
	ds_read_b128 v[162:165], v222 offset:32768
	ds_read_b128 v[166:169], v222 offset:33792
	ds_read_b128 v[170:173], v222 offset:34816
	ds_read_b128 v[174:177], v222 offset:35840
	ds_read_b128 v[178:181], v222 offset:36864
	ds_read_b128 v[182:185], v222 offset:37888
	ds_read_b128 v[196:199], v222 offset:38912
	ds_read_b128 v[206:209], v222 offset:39936
	global_load_lds_dwordx4 v[218:219], off
	s_mov_b32 m0, s60
	v_lshl_add_u64 v[218:219], s[52:53], 0, v[188:189]
	global_load_lds_dwordx4 v[218:219], off
	s_waitcnt vmcnt(8) lgkmcnt(0)
	s_barrier
	s_setprio 1
	v_mfma_f32_16x16x32_bf16 v[126:129], v[130:133], v[162:165], v[126:129]
	v_mfma_f32_16x16x32_bf16 v[122:125], v[138:141], v[162:165], v[122:125]
	v_mfma_f32_16x16x32_bf16 v[110:113], v[130:133], v[170:173], v[110:113]
	v_mfma_f32_16x16x32_bf16 v[106:109], v[138:141], v[170:173], v[106:109]
	v_mfma_f32_16x16x32_bf16 v[94:97], v[130:133], v[178:181], v[94:97]
	v_mfma_f32_16x16x32_bf16 v[90:93], v[138:141], v[178:181], v[90:93]
	v_mfma_f32_16x16x32_bf16 v[78:81], v[130:133], v[196:199], v[78:81]
	v_mfma_f32_16x16x32_bf16 v[74:77], v[138:141], v[196:199], v[74:77]
	v_mfma_f32_16x16x32_bf16 v[126:129], v[134:137], v[166:169], v[126:129]
	v_mfma_f32_16x16x32_bf16 v[122:125], v[142:145], v[166:169], v[122:125]
	v_mfma_f32_16x16x32_bf16 v[110:113], v[134:137], v[174:177], v[110:113]
	v_mfma_f32_16x16x32_bf16 v[106:109], v[142:145], v[174:177], v[106:109]
	v_mfma_f32_16x16x32_bf16 v[94:97], v[134:137], v[182:185], v[94:97]
	v_mfma_f32_16x16x32_bf16 v[90:93], v[142:145], v[182:185], v[90:93]
	v_mfma_f32_16x16x32_bf16 v[78:81], v[134:137], v[206:209], v[78:81]
	v_mfma_f32_16x16x32_bf16 v[74:77], v[142:145], v[206:209], v[74:77]
	s_setprio 0
	s_setprio 1
	v_mfma_f32_16x16x32_bf16 v[118:121], v[146:149], v[162:165], v[118:121]
	v_mfma_f32_16x16x32_bf16 v[114:117], v[154:157], v[162:165], v[114:117]
	v_mfma_f32_16x16x32_bf16 v[102:105], v[146:149], v[170:173], v[102:105]
	v_mfma_f32_16x16x32_bf16 v[98:101], v[154:157], v[170:173], v[98:101]
	v_mfma_f32_16x16x32_bf16 v[86:89], v[146:149], v[178:181], v[86:89]
	v_mfma_f32_16x16x32_bf16 v[82:85], v[154:157], v[178:181], v[82:85]
	v_mfma_f32_16x16x32_bf16 v[70:73], v[146:149], v[196:199], v[70:73]
	v_mfma_f32_16x16x32_bf16 v[66:69], v[154:157], v[196:199], v[66:69]
	v_mfma_f32_16x16x32_bf16 v[118:121], v[150:153], v[166:169], v[118:121]
	v_mfma_f32_16x16x32_bf16 v[114:117], v[158:161], v[166:169], v[114:117]
	v_mfma_f32_16x16x32_bf16 v[102:105], v[150:153], v[174:177], v[102:105]
	v_mfma_f32_16x16x32_bf16 v[98:101], v[158:161], v[174:177], v[98:101]
	v_mfma_f32_16x16x32_bf16 v[86:89], v[150:153], v[182:185], v[86:89]
	v_mfma_f32_16x16x32_bf16 v[82:85], v[158:161], v[182:185], v[82:85]
	v_mfma_f32_16x16x32_bf16 v[70:73], v[150:153], v[206:209], v[70:73]
	v_mfma_f32_16x16x32_bf16 v[66:69], v[158:161], v[206:209], v[66:69]
	s_setprio 0
	s_barrier
	s_add_i32 s52, s90, s47
	v_lshl_add_u64 v[210:211], v[210:211], 0, s[58:59]
	s_mov_b32 m0, s52
	ds_read_b128 v[162:165], v222 offset:49152
	ds_read_b128 v[166:169], v222 offset:50176
	ds_read_b128 v[170:173], v222 offset:51200
	ds_read_b128 v[174:177], v222 offset:52224
	ds_read_b128 v[178:181], v222 offset:53248
	ds_read_b128 v[182:185], v222 offset:54272
	ds_read_b128 v[196:199], v222 offset:55296
	ds_read_b128 v[206:209], v222 offset:56320
	global_load_lds_dwordx4 v[210:211], off
	s_add_i32 m0, s52, 0x2000
	s_add_u32 s34, s34, 0x80080
	v_lshl_add_u64 v[210:211], v[212:213], 0, s[58:59]
	s_addc_u32 s35, s35, 0
	s_add_i32 s52, s91, s47
	global_load_lds_dwordx4 v[210:211], off
	s_mov_b32 m0, s52
	v_lshl_add_u64 v[210:211], s[34:35], 0, v[190:191]
	global_load_lds_dwordx4 v[210:211], off
	s_add_i32 m0, s52, 0x2000
	v_lshl_add_u64 v[210:211], s[34:35], 0, v[200:201]
	global_load_lds_dwordx4 v[210:211], off
	s_mov_b32 m0, s61
	v_lshl_add_u64 v[210:211], v[214:215], 0, s[58:59]
	global_load_lds_dwordx4 v[210:211], off
	s_mov_b32 m0, s69
	v_lshl_add_u64 v[210:211], v[216:217], 0, s[58:59]
	global_load_lds_dwordx4 v[210:211], off
	s_waitcnt vmcnt(8) lgkmcnt(0)
	s_barrier
	s_setprio 1
	v_mfma_f32_16x16x32_bf16 v[62:65], v[130:133], v[162:165], v[62:65]
	v_mfma_f32_16x16x32_bf16 v[58:61], v[138:141], v[162:165], v[58:61]
	v_mfma_f32_16x16x32_bf16 v[46:49], v[130:133], v[170:173], v[46:49]
	v_mfma_f32_16x16x32_bf16 v[42:45], v[138:141], v[170:173], v[42:45]
	v_mfma_f32_16x16x32_bf16 v[30:33], v[130:133], v[178:181], v[30:33]
	v_mfma_f32_16x16x32_bf16 v[26:29], v[138:141], v[178:181], v[26:29]
	v_mfma_f32_16x16x32_bf16 v[14:17], v[130:133], v[196:199], v[14:17]
	v_mfma_f32_16x16x32_bf16 v[10:13], v[138:141], v[196:199], v[10:13]
	v_mfma_f32_16x16x32_bf16 v[62:65], v[134:137], v[166:169], v[62:65]
	v_mfma_f32_16x16x32_bf16 v[58:61], v[142:145], v[166:169], v[58:61]
	v_mfma_f32_16x16x32_bf16 v[46:49], v[134:137], v[174:177], v[46:49]
	v_mfma_f32_16x16x32_bf16 v[42:45], v[142:145], v[174:177], v[42:45]
	v_mfma_f32_16x16x32_bf16 v[30:33], v[134:137], v[182:185], v[30:33]
	v_mfma_f32_16x16x32_bf16 v[26:29], v[142:145], v[182:185], v[26:29]
	v_mfma_f32_16x16x32_bf16 v[14:17], v[134:137], v[206:209], v[14:17]
	v_mfma_f32_16x16x32_bf16 v[10:13], v[142:145], v[206:209], v[10:13]
	s_setprio 0
	s_setprio 1
	v_mfma_f32_16x16x32_bf16 v[54:57], v[146:149], v[162:165], v[54:57]
	v_mfma_f32_16x16x32_bf16 v[50:53], v[154:157], v[162:165], v[50:53]
	v_mfma_f32_16x16x32_bf16 v[38:41], v[146:149], v[170:173], v[38:41]
	v_mfma_f32_16x16x32_bf16 v[34:37], v[154:157], v[170:173], v[34:37]
	v_mfma_f32_16x16x32_bf16 v[22:25], v[146:149], v[178:181], v[22:25]
	v_mfma_f32_16x16x32_bf16 v[18:21], v[154:157], v[178:181], v[18:21]
	v_mfma_f32_16x16x32_bf16 v[6:9], v[146:149], v[196:199], v[6:9]
	v_mfma_f32_16x16x32_bf16 v[2:5], v[154:157], v[196:199], v[2:5]
	v_mfma_f32_16x16x32_bf16 v[54:57], v[150:153], v[166:169], v[54:57]
	v_mfma_f32_16x16x32_bf16 v[50:53], v[158:161], v[166:169], v[50:53]
	v_mfma_f32_16x16x32_bf16 v[38:41], v[150:153], v[174:177], v[38:41]
	v_mfma_f32_16x16x32_bf16 v[34:37], v[158:161], v[174:177], v[34:37]
	v_mfma_f32_16x16x32_bf16 v[22:25], v[150:153], v[182:185], v[22:25]
	v_mfma_f32_16x16x32_bf16 v[18:21], v[158:161], v[182:185], v[18:21]
	v_mfma_f32_16x16x32_bf16 v[6:9], v[150:153], v[206:209], v[6:9]
	v_mfma_f32_16x16x32_bf16 v[2:5], v[158:161], v[206:209], v[2:5]
	s_setprio 0
	s_barrier
	s_add_i32 s89, s89, 2
	s_add_u32 s30, s30, 0x100
	s_addc_u32 s31, s31, 0
	s_add_u32 s81, s81, 0x100
	s_addc_u32 s88, s88, 0
	s_cmp_gt_u32 s89, 29
	s_cbranch_scc1 .Lpeel_done_5
	s_branch .LBB0_823
.Ltrip0_strict_5:
	s_add_u32 s34, s30, 0xfff80080
	s_addc_u32 s35, s31, -1
	s_add_i32 s90, 0, 0x10000
	s_cmp_eq_u32 s89, 28
	s_cselect_b32 s53, s17, s35
	s_cselect_b32 s52, s27, s34
	s_cselect_b32 s35, s15, s88
	s_cselect_b32 s34, s29, s81
	s_add_i32 s96, 0, 0x14000
	v_add_u32_e32 v142, s90, v220
	v_add_u32_e32 v158, s96, v220
	ds_read_b128 v[130:133], v142
	ds_read_b128 v[134:137], v142 offset:1024
	ds_read_b128 v[138:141], v142 offset:2048
	ds_read_b128 v[142:145], v142 offset:3072
	ds_read_b128 v[146:149], v158
	ds_read_b128 v[150:153], v158 offset:1024
	ds_read_b128 v[154:157], v158 offset:2048
	ds_read_b128 v[158:161], v158 offset:3072
	v_lshl_add_u64 v[210:211], s[30:31], 0, v[202:203]
	s_add_i32 m0, s55, 0xc000
	ds_read_b128 v[162:165], v222
	ds_read_b128 v[166:169], v222 offset:1024
	ds_read_b128 v[170:173], v222 offset:2048
	ds_read_b128 v[174:177], v222 offset:3072
	ds_read_b128 v[178:181], v222 offset:4096
	ds_read_b128 v[182:185], v222 offset:5120
	ds_read_b128 v[196:199], v222 offset:6144
	ds_read_b128 v[206:209], v222 offset:7168
	global_load_lds_dwordx4 v[210:211], off
	s_add_i32 m0, s55, 0xe000
	v_lshl_add_u64 v[210:211], s[30:31], 0, v[204:205]
	global_load_lds_dwordx4 v[210:211], off
	s_waitcnt vmcnt(8) lgkmcnt(0)
	s_barrier
	s_setprio 1
	v_mfma_f32_16x16x32_bf16 v[126:129], v[130:133], v[162:165], 0
	v_mfma_f32_16x16x32_bf16 v[122:125], v[138:141], v[162:165], 0
	v_mfma_f32_16x16x32_bf16 v[110:113], v[130:133], v[170:173], 0
	v_mfma_f32_16x16x32_bf16 v[106:109], v[138:141], v[170:173], 0
	v_mfma_f32_16x16x32_bf16 v[94:97], v[130:133], v[178:181], 0
	v_mfma_f32_16x16x32_bf16 v[90:93], v[138:141], v[178:181], 0
	v_mfma_f32_16x16x32_bf16 v[78:81], v[130:133], v[196:199], 0
	v_mfma_f32_16x16x32_bf16 v[74:77], v[138:141], v[196:199], 0
	v_mfma_f32_16x16x32_bf16 v[126:129], v[134:137], v[166:169], v[126:129]
	v_mfma_f32_16x16x32_bf16 v[122:125], v[142:145], v[166:169], v[122:125]
	v_mfma_f32_16x16x32_bf16 v[110:113], v[134:137], v[174:177], v[110:113]
	v_mfma_f32_16x16x32_bf16 v[106:109], v[142:145], v[174:177], v[106:109]
	v_mfma_f32_16x16x32_bf16 v[94:97], v[134:137], v[182:185], v[94:97]
	v_mfma_f32_16x16x32_bf16 v[90:93], v[142:145], v[182:185], v[90:93]
	v_mfma_f32_16x16x32_bf16 v[78:81], v[134:137], v[206:209], v[78:81]
	v_mfma_f32_16x16x32_bf16 v[74:77], v[142:145], v[206:209], v[74:77]
	s_setprio 0
	s_setprio 1
	v_mfma_f32_16x16x32_bf16 v[118:121], v[146:149], v[162:165], 0
	v_mfma_f32_16x16x32_bf16 v[114:117], v[154:157], v[162:165], 0
	v_mfma_f32_16x16x32_bf16 v[102:105], v[146:149], v[170:173], 0
	v_mfma_f32_16x16x32_bf16 v[98:101], v[154:157], v[170:173], 0
	v_mfma_f32_16x16x32_bf16 v[86:89], v[146:149], v[178:181], 0
	v_mfma_f32_16x16x32_bf16 v[82:85], v[154:157], v[178:181], 0
	v_mfma_f32_16x16x32_bf16 v[70:73], v[146:149], v[196:199], 0
	v_mfma_f32_16x16x32_bf16 v[66:69], v[154:157], v[196:199], 0
	v_mfma_f32_16x16x32_bf16 v[118:121], v[150:153], v[166:169], v[118:121]
	v_mfma_f32_16x16x32_bf16 v[114:117], v[158:161], v[166:169], v[114:117]
	v_mfma_f32_16x16x32_bf16 v[102:105], v[150:153], v[174:177], v[102:105]
	v_mfma_f32_16x16x32_bf16 v[98:101], v[158:161], v[174:177], v[98:101]
	v_mfma_f32_16x16x32_bf16 v[86:89], v[150:153], v[182:185], v[86:89]
	v_mfma_f32_16x16x32_bf16 v[82:85], v[158:161], v[182:185], v[82:85]
	v_mfma_f32_16x16x32_bf16 v[70:73], v[150:153], v[206:209], v[70:73]
	v_mfma_f32_16x16x32_bf16 v[66:69], v[158:161], v[206:209], v[66:69]
	s_setprio 0
	s_barrier
	s_add_i32 s90, s90, s47
	v_lshl_add_u64 v[210:211], s[34:35], 0, v[190:191]
	s_mov_b32 m0, s90
	ds_read_b128 v[162:165], v222 offset:16384
	ds_read_b128 v[166:169], v222 offset:17408
	ds_read_b128 v[170:173], v222 offset:18432
	ds_read_b128 v[174:177], v222 offset:19456
	ds_read_b128 v[178:181], v222 offset:20480
	ds_read_b128 v[182:185], v222 offset:21504
	ds_read_b128 v[196:199], v222 offset:22528
	ds_read_b128 v[206:209], v222 offset:23552
	global_load_lds_dwordx4 v[210:211], off
	s_add_i32 m0, s90, 0x2000
	s_add_u32 s90, s34, 0x80000
	v_lshl_add_u64 v[212:213], s[34:35], 0, v[200:201]
	s_addc_u32 s91, s35, 0
	s_add_i32 s96, s96, s47
	global_load_lds_dwordx4 v[212:213], off
	v_lshl_add_u64 v[214:215], s[90:91], 0, v[190:191]
	s_mov_b32 m0, s96
	v_lshl_add_u64 v[216:217], s[52:53], 0, v[188:189]
	global_load_lds_dwordx4 v[214:215], off
	s_add_i32 m0, s96, 0x2000
	v_lshl_add_u64 v[214:215], s[90:91], 0, v[200:201]
	global_load_lds_dwordx4 v[214:215], off
	s_mov_b32 m0, s55
	v_lshl_add_u64 v[214:215], s[52:53], 0, v[186:187]
	global_load_lds_dwordx4 v[214:215], off
	s_mov_b32 m0, s56
	s_nop 0
	global_load_lds_dwordx4 v[216:217], off
	s_waitcnt vmcnt(8) lgkmcnt(0)
	s_barrier
	s_setprio 1
	v_mfma_f32_16x16x32_bf16 v[62:65], v[130:133], v[162:165], 0
	v_mfma_f32_16x16x32_bf16 v[58:61], v[138:141], v[162:165], 0
	v_mfma_f32_16x16x32_bf16 v[46:49], v[130:133], v[170:173], 0
	v_mfma_f32_16x16x32_bf16 v[42:45], v[138:141], v[170:173], 0
	v_mfma_f32_16x16x32_bf16 v[30:33], v[130:133], v[178:181], 0
	v_mfma_f32_16x16x32_bf16 v[26:29], v[138:141], v[178:181], 0
	v_mfma_f32_16x16x32_bf16 v[14:17], v[130:133], v[196:199], 0
	v_mfma_f32_16x16x32_bf16 v[10:13], v[138:141], v[196:199], 0
	v_mfma_f32_16x16x32_bf16 v[62:65], v[134:137], v[166:169], v[62:65]
	v_mfma_f32_16x16x32_bf16 v[58:61], v[142:145], v[166:169], v[58:61]
	v_mfma_f32_16x16x32_bf16 v[46:49], v[134:137], v[174:177], v[46:49]
	v_mfma_f32_16x16x32_bf16 v[42:45], v[142:145], v[174:177], v[42:45]
	v_mfma_f32_16x16x32_bf16 v[30:33], v[134:137], v[182:185], v[30:33]
	v_mfma_f32_16x16x32_bf16 v[26:29], v[142:145], v[182:185], v[26:29]
	v_mfma_f32_16x16x32_bf16 v[14:17], v[134:137], v[206:209], v[14:17]
	v_mfma_f32_16x16x32_bf16 v[10:13], v[142:145], v[206:209], v[10:13]
	s_setprio 0
	s_setprio 1
	v_mfma_f32_16x16x32_bf16 v[54:57], v[146:149], v[162:165], 0
	v_mfma_f32_16x16x32_bf16 v[50:53], v[154:157], v[162:165], 0
	v_mfma_f32_16x16x32_bf16 v[38:41], v[146:149], v[170:173], 0
	v_mfma_f32_16x16x32_bf16 v[34:37], v[154:157], v[170:173], 0
	v_mfma_f32_16x16x32_bf16 v[22:25], v[146:149], v[178:181], 0
	v_mfma_f32_16x16x32_bf16 v[18:21], v[154:157], v[178:181], 0
	v_mfma_f32_16x16x32_bf16 v[6:9], v[146:149], v[196:199], 0
	v_mfma_f32_16x16x32_bf16 v[2:5], v[154:157], v[196:199], 0
	v_mfma_f32_16x16x32_bf16 v[54:57], v[150:153], v[166:169], v[54:57]
	v_mfma_f32_16x16x32_bf16 v[50:53], v[158:161], v[166:169], v[50:53]
	v_mfma_f32_16x16x32_bf16 v[38:41], v[150:153], v[174:177], v[38:41]
	v_mfma_f32_16x16x32_bf16 v[34:37], v[158:161], v[174:177], v[34:37]
	v_mfma_f32_16x16x32_bf16 v[22:25], v[150:153], v[182:185], v[22:25]
	v_mfma_f32_16x16x32_bf16 v[18:21], v[158:161], v[182:185], v[18:21]
	v_mfma_f32_16x16x32_bf16 v[6:9], v[150:153], v[206:209], v[6:9]
	v_mfma_f32_16x16x32_bf16 v[2:5], v[158:161], v[206:209], v[2:5]
	s_setprio 0
	s_barrier
	s_add_i32 s90, 0, 0x18000
	s_add_i32 s91, 0, 0x1c000
	v_add_u32_e32 v142, s90, v220
	v_add_u32_e32 v158, s91, v220
	ds_read_b128 v[130:133], v142
	ds_read_b128 v[134:137], v142 offset:1024
	ds_read_b128 v[138:141], v142 offset:2048
	ds_read_b128 v[142:145], v142 offset:3072
	ds_read_b128 v[146:149], v158
	ds_read_b128 v[150:153], v158 offset:1024
	ds_read_b128 v[154:157], v158 offset:2048
	ds_read_b128 v[158:161], v158 offset:3072
	s_add_u32 s52, s52, 0x80000
	s_addc_u32 s53, s53, 0
	s_mov_b32 m0, s57
	v_lshl_add_u64 v[218:219], s[52:53], 0, v[186:187]
	ds_read_b128 v[162:165], v222 offset:32768
	ds_read_b128 v[166:169], v222 offset:33792
	ds_read_b128 v[170:173], v222 offset:34816
	ds_read_b128 v[174:177], v222 offset:35840
	ds_read_b128 v[178:181], v222 offset:36864
	ds_read_b128 v[182:185], v222 offset:37888
	ds_read_b128 v[196:199], v222 offset:38912
	ds_read_b128 v[206:209], v222 offset:39936
	global_load_lds_dwordx4 v[218:219], off
	s_mov_b32 m0, s60
	v_lshl_add_u64 v[218:219], s[52:53], 0, v[188:189]
	global_load_lds_dwordx4 v[218:219], off
	s_waitcnt vmcnt(8) lgkmcnt(0)
	s_barrier
	s_setprio 1
	v_mfma_f32_16x16x32_bf16 v[126:129], v[130:133], v[162:165], v[126:129]
	v_mfma_f32_16x16x32_bf16 v[122:125], v[138:141], v[162:165], v[122:125]
	v_mfma_f32_16x16x32_bf16 v[110:113], v[130:133], v[170:173], v[110:113]
	v_mfma_f32_16x16x32_bf16 v[106:109], v[138:141], v[170:173], v[106:109]
	v_mfma_f32_16x16x32_bf16 v[94:97], v[130:133], v[178:181], v[94:97]
	v_mfma_f32_16x16x32_bf16 v[90:93], v[138:141], v[178:181], v[90:93]
	v_mfma_f32_16x16x32_bf16 v[78:81], v[130:133], v[196:199], v[78:81]
	v_mfma_f32_16x16x32_bf16 v[74:77], v[138:141], v[196:199], v[74:77]
	v_mfma_f32_16x16x32_bf16 v[126:129], v[134:137], v[166:169], v[126:129]
	v_mfma_f32_16x16x32_bf16 v[122:125], v[142:145], v[166:169], v[122:125]
	v_mfma_f32_16x16x32_bf16 v[110:113], v[134:137], v[174:177], v[110:113]
	v_mfma_f32_16x16x32_bf16 v[106:109], v[142:145], v[174:177], v[106:109]
	v_mfma_f32_16x16x32_bf16 v[94:97], v[134:137], v[182:185], v[94:97]
	v_mfma_f32_16x16x32_bf16 v[90:93], v[142:145], v[182:185], v[90:93]
	v_mfma_f32_16x16x32_bf16 v[78:81], v[134:137], v[206:209], v[78:81]
	v_mfma_f32_16x16x32_bf16 v[74:77], v[142:145], v[206:209], v[74:77]
	s_setprio 0
	s_setprio 1
	v_mfma_f32_16x16x32_bf16 v[118:121], v[146:149], v[162:165], v[118:121]
	v_mfma_f32_16x16x32_bf16 v[114:117], v[154:157], v[162:165], v[114:117]
	v_mfma_f32_16x16x32_bf16 v[102:105], v[146:149], v[170:173], v[102:105]
	v_mfma_f32_16x16x32_bf16 v[98:101], v[154:157], v[170:173], v[98:101]
	v_mfma_f32_16x16x32_bf16 v[86:89], v[146:149], v[178:181], v[86:89]
	v_mfma_f32_16x16x32_bf16 v[82:85], v[154:157], v[178:181], v[82:85]
	v_mfma_f32_16x16x32_bf16 v[70:73], v[146:149], v[196:199], v[70:73]
	v_mfma_f32_16x16x32_bf16 v[66:69], v[154:157], v[196:199], v[66:69]
	v_mfma_f32_16x16x32_bf16 v[118:121], v[150:153], v[166:169], v[118:121]
	v_mfma_f32_16x16x32_bf16 v[114:117], v[158:161], v[166:169], v[114:117]
	v_mfma_f32_16x16x32_bf16 v[102:105], v[150:153], v[174:177], v[102:105]
	v_mfma_f32_16x16x32_bf16 v[98:101], v[158:161], v[174:177], v[98:101]
	v_mfma_f32_16x16x32_bf16 v[86:89], v[150:153], v[182:185], v[86:89]
	v_mfma_f32_16x16x32_bf16 v[82:85], v[158:161], v[182:185], v[82:85]
	v_mfma_f32_16x16x32_bf16 v[70:73], v[150:153], v[206:209], v[70:73]
	v_mfma_f32_16x16x32_bf16 v[66:69], v[158:161], v[206:209], v[66:69]
	s_setprio 0
	s_barrier
	s_add_i32 s52, s90, s47
	v_lshl_add_u64 v[210:211], v[210:211], 0, s[58:59]
	s_mov_b32 m0, s52
	ds_read_b128 v[162:165], v222 offset:49152
	ds_read_b128 v[166:169], v222 offset:50176
	ds_read_b128 v[170:173], v222 offset:51200
	ds_read_b128 v[174:177], v222 offset:52224
	ds_read_b128 v[178:181], v222 offset:53248
	ds_read_b128 v[182:185], v222 offset:54272
	ds_read_b128 v[196:199], v222 offset:55296
	ds_read_b128 v[206:209], v222 offset:56320
	global_load_lds_dwordx4 v[210:211], off
	s_add_i32 m0, s52, 0x2000
	s_add_u32 s34, s34, 0x80080
	v_lshl_add_u64 v[210:211], v[212:213], 0, s[58:59]
	s_addc_u32 s35, s35, 0
	s_add_i32 s52, s91, s47
	global_load_lds_dwordx4 v[210:211], off
	s_mov_b32 m0, s52
	v_lshl_add_u64 v[210:211], s[34:35], 0, v[190:191]
	global_load_lds_dwordx4 v[210:211], off
	s_add_i32 m0, s52, 0x2000
	v_lshl_add_u64 v[210:211], s[34:35], 0, v[200:201]
	global_load_lds_dwordx4 v[210:211], off
	s_mov_b32 m0, s61
	v_lshl_add_u64 v[210:211], v[214:215], 0, s[58:59]
	global_load_lds_dwordx4 v[210:211], off
	s_mov_b32 m0, s69
	v_lshl_add_u64 v[210:211], v[216:217], 0, s[58:59]
	global_load_lds_dwordx4 v[210:211], off
	s_waitcnt vmcnt(8) lgkmcnt(0)
	s_barrier
	s_setprio 1
	v_mfma_f32_16x16x32_bf16 v[62:65], v[130:133], v[162:165], v[62:65]
	v_mfma_f32_16x16x32_bf16 v[58:61], v[138:141], v[162:165], v[58:61]
	v_mfma_f32_16x16x32_bf16 v[46:49], v[130:133], v[170:173], v[46:49]
	v_mfma_f32_16x16x32_bf16 v[42:45], v[138:141], v[170:173], v[42:45]
	v_mfma_f32_16x16x32_bf16 v[30:33], v[130:133], v[178:181], v[30:33]
	v_mfma_f32_16x16x32_bf16 v[26:29], v[138:141], v[178:181], v[26:29]
	v_mfma_f32_16x16x32_bf16 v[14:17], v[130:133], v[196:199], v[14:17]
	v_mfma_f32_16x16x32_bf16 v[10:13], v[138:141], v[196:199], v[10:13]
	v_mfma_f32_16x16x32_bf16 v[62:65], v[134:137], v[166:169], v[62:65]
	v_mfma_f32_16x16x32_bf16 v[58:61], v[142:145], v[166:169], v[58:61]
	v_mfma_f32_16x16x32_bf16 v[46:49], v[134:137], v[174:177], v[46:49]
	v_mfma_f32_16x16x32_bf16 v[42:45], v[142:145], v[174:177], v[42:45]
	v_mfma_f32_16x16x32_bf16 v[30:33], v[134:137], v[182:185], v[30:33]
	v_mfma_f32_16x16x32_bf16 v[26:29], v[142:145], v[182:185], v[26:29]
	v_mfma_f32_16x16x32_bf16 v[14:17], v[134:137], v[206:209], v[14:17]
	v_mfma_f32_16x16x32_bf16 v[10:13], v[142:145], v[206:209], v[10:13]
	s_setprio 0
	s_setprio 1
	v_mfma_f32_16x16x32_bf16 v[54:57], v[146:149], v[162:165], v[54:57]
	v_mfma_f32_16x16x32_bf16 v[50:53], v[154:157], v[162:165], v[50:53]
	v_mfma_f32_16x16x32_bf16 v[38:41], v[146:149], v[170:173], v[38:41]
	v_mfma_f32_16x16x32_bf16 v[34:37], v[154:157], v[170:173], v[34:37]
	v_mfma_f32_16x16x32_bf16 v[22:25], v[146:149], v[178:181], v[22:25]
	v_mfma_f32_16x16x32_bf16 v[18:21], v[154:157], v[178:181], v[18:21]
	v_mfma_f32_16x16x32_bf16 v[6:9], v[146:149], v[196:199], v[6:9]
	v_mfma_f32_16x16x32_bf16 v[2:5], v[154:157], v[196:199], v[2:5]
	v_mfma_f32_16x16x32_bf16 v[54:57], v[150:153], v[166:169], v[54:57]
	v_mfma_f32_16x16x32_bf16 v[50:53], v[158:161], v[166:169], v[50:53]
	v_mfma_f32_16x16x32_bf16 v[38:41], v[150:153], v[174:177], v[38:41]
	v_mfma_f32_16x16x32_bf16 v[34:37], v[158:161], v[174:177], v[34:37]
	v_mfma_f32_16x16x32_bf16 v[22:25], v[150:153], v[182:185], v[22:25]
	v_mfma_f32_16x16x32_bf16 v[18:21], v[158:161], v[182:185], v[18:21]
	v_mfma_f32_16x16x32_bf16 v[6:9], v[150:153], v[206:209], v[6:9]
	v_mfma_f32_16x16x32_bf16 v[2:5], v[158:161], v[206:209], v[2:5]
	s_setprio 0
	s_barrier
	s_add_i32 s89, s89, 2
	s_add_u32 s30, s30, 0x100
	s_addc_u32 s31, s31, 0
	s_add_u32 s81, s81, 0x100
	s_addc_u32 s88, s88, 0
	s_cmp_gt_u32 s89, 29
	s_cbranch_scc1 .Lpeel_done_5
.LBB0_823:
	s_add_u32 s34, s30, 0xfff80080
	s_addc_u32 s35, s31, -1
	s_add_i32 s90, 0, 0x10000
	s_cmp_eq_u32 s89, 28
	s_cselect_b32 s53, s17, s35
	s_cselect_b32 s52, s27, s34
	s_cselect_b32 s35, s15, s88
	s_cselect_b32 s34, s29, s81
	s_add_i32 s96, 0, 0x14000
	v_add_u32_e32 v142, s90, v220
	v_add_u32_e32 v158, s96, v220
	ds_read_b128 v[130:133], v142
	ds_read_b128 v[134:137], v142 offset:1024
	ds_read_b128 v[138:141], v142 offset:2048
	ds_read_b128 v[142:145], v142 offset:3072
	ds_read_b128 v[146:149], v158
	ds_read_b128 v[150:153], v158 offset:1024
	ds_read_b128 v[154:157], v158 offset:2048
	ds_read_b128 v[158:161], v158 offset:3072
	v_lshl_add_u64 v[210:211], s[30:31], 0, v[202:203]
	s_add_i32 m0, s55, 0xc000
	ds_read_b128 v[162:165], v222
	ds_read_b128 v[166:169], v222 offset:1024
	ds_read_b128 v[170:173], v222 offset:2048
	ds_read_b128 v[174:177], v222 offset:3072
	ds_read_b128 v[178:181], v222 offset:4096
	ds_read_b128 v[182:185], v222 offset:5120
	ds_read_b128 v[196:199], v222 offset:6144
	ds_read_b128 v[206:209], v222 offset:7168
	global_load_lds_dwordx4 v[210:211], off
	s_add_i32 m0, s55, 0xe000
	v_lshl_add_u64 v[210:211], s[30:31], 0, v[204:205]
	global_load_lds_dwordx4 v[210:211], off
	s_waitcnt vmcnt(8) lgkmcnt(0)
	s_barrier
	s_setprio 1
	v_mfma_f32_16x16x32_bf16 v[126:129], v[130:133], v[162:165], v[126:129]
	v_mfma_f32_16x16x32_bf16 v[122:125], v[138:141], v[162:165], v[122:125]
	v_mfma_f32_16x16x32_bf16 v[110:113], v[130:133], v[170:173], v[110:113]
	v_mfma_f32_16x16x32_bf16 v[106:109], v[138:141], v[170:173], v[106:109]
	v_mfma_f32_16x16x32_bf16 v[94:97], v[130:133], v[178:181], v[94:97]
	v_mfma_f32_16x16x32_bf16 v[90:93], v[138:141], v[178:181], v[90:93]
	v_mfma_f32_16x16x32_bf16 v[78:81], v[130:133], v[196:199], v[78:81]
	v_mfma_f32_16x16x32_bf16 v[74:77], v[138:141], v[196:199], v[74:77]
	v_mfma_f32_16x16x32_bf16 v[126:129], v[134:137], v[166:169], v[126:129]
	v_mfma_f32_16x16x32_bf16 v[122:125], v[142:145], v[166:169], v[122:125]
	v_mfma_f32_16x16x32_bf16 v[110:113], v[134:137], v[174:177], v[110:113]
	v_mfma_f32_16x16x32_bf16 v[106:109], v[142:145], v[174:177], v[106:109]
	v_mfma_f32_16x16x32_bf16 v[94:97], v[134:137], v[182:185], v[94:97]
	v_mfma_f32_16x16x32_bf16 v[90:93], v[142:145], v[182:185], v[90:93]
	v_mfma_f32_16x16x32_bf16 v[78:81], v[134:137], v[206:209], v[78:81]
	v_mfma_f32_16x16x32_bf16 v[74:77], v[142:145], v[206:209], v[74:77]
	s_setprio 0
	s_setprio 1
	v_mfma_f32_16x16x32_bf16 v[118:121], v[146:149], v[162:165], v[118:121]
	v_mfma_f32_16x16x32_bf16 v[114:117], v[154:157], v[162:165], v[114:117]
	v_mfma_f32_16x16x32_bf16 v[102:105], v[146:149], v[170:173], v[102:105]
	v_mfma_f32_16x16x32_bf16 v[98:101], v[154:157], v[170:173], v[98:101]
	v_mfma_f32_16x16x32_bf16 v[86:89], v[146:149], v[178:181], v[86:89]
	v_mfma_f32_16x16x32_bf16 v[82:85], v[154:157], v[178:181], v[82:85]
	v_mfma_f32_16x16x32_bf16 v[70:73], v[146:149], v[196:199], v[70:73]
	v_mfma_f32_16x16x32_bf16 v[66:69], v[154:157], v[196:199], v[66:69]
	v_mfma_f32_16x16x32_bf16 v[118:121], v[150:153], v[166:169], v[118:121]
	v_mfma_f32_16x16x32_bf16 v[114:117], v[158:161], v[166:169], v[114:117]
	v_mfma_f32_16x16x32_bf16 v[102:105], v[150:153], v[174:177], v[102:105]
	v_mfma_f32_16x16x32_bf16 v[98:101], v[158:161], v[174:177], v[98:101]
	v_mfma_f32_16x16x32_bf16 v[86:89], v[150:153], v[182:185], v[86:89]
	v_mfma_f32_16x16x32_bf16 v[82:85], v[158:161], v[182:185], v[82:85]
	v_mfma_f32_16x16x32_bf16 v[70:73], v[150:153], v[206:209], v[70:73]
	v_mfma_f32_16x16x32_bf16 v[66:69], v[158:161], v[206:209], v[66:69]
	s_setprio 0
	s_barrier
	s_add_i32 s90, s90, s47
	v_lshl_add_u64 v[210:211], s[34:35], 0, v[190:191]
	s_mov_b32 m0, s90
	ds_read_b128 v[162:165], v222 offset:16384
	ds_read_b128 v[166:169], v222 offset:17408
	ds_read_b128 v[170:173], v222 offset:18432
	ds_read_b128 v[174:177], v222 offset:19456
	ds_read_b128 v[178:181], v222 offset:20480
	ds_read_b128 v[182:185], v222 offset:21504
	ds_read_b128 v[196:199], v222 offset:22528
	ds_read_b128 v[206:209], v222 offset:23552
	global_load_lds_dwordx4 v[210:211], off
	s_add_i32 m0, s90, 0x2000
	s_add_u32 s90, s34, 0x80000
	v_lshl_add_u64 v[212:213], s[34:35], 0, v[200:201]
	s_addc_u32 s91, s35, 0
	s_add_i32 s96, s96, s47
	global_load_lds_dwordx4 v[212:213], off
	v_lshl_add_u64 v[214:215], s[90:91], 0, v[190:191]
	s_mov_b32 m0, s96
	v_lshl_add_u64 v[216:217], s[52:53], 0, v[188:189]
	global_load_lds_dwordx4 v[214:215], off
	s_add_i32 m0, s96, 0x2000
	v_lshl_add_u64 v[214:215], s[90:91], 0, v[200:201]
	global_load_lds_dwordx4 v[214:215], off
	s_mov_b32 m0, s55
	v_lshl_add_u64 v[214:215], s[52:53], 0, v[186:187]
	global_load_lds_dwordx4 v[214:215], off
	s_mov_b32 m0, s56
	s_nop 0
	global_load_lds_dwordx4 v[216:217], off
	s_waitcnt vmcnt(8) lgkmcnt(0)
	s_barrier
	s_setprio 1
	v_mfma_f32_16x16x32_bf16 v[62:65], v[130:133], v[162:165], v[62:65]
	v_mfma_f32_16x16x32_bf16 v[58:61], v[138:141], v[162:165], v[58:61]
	v_mfma_f32_16x16x32_bf16 v[46:49], v[130:133], v[170:173], v[46:49]
	v_mfma_f32_16x16x32_bf16 v[42:45], v[138:141], v[170:173], v[42:45]
	v_mfma_f32_16x16x32_bf16 v[30:33], v[130:133], v[178:181], v[30:33]
	v_mfma_f32_16x16x32_bf16 v[26:29], v[138:141], v[178:181], v[26:29]
	v_mfma_f32_16x16x32_bf16 v[14:17], v[130:133], v[196:199], v[14:17]
	v_mfma_f32_16x16x32_bf16 v[10:13], v[138:141], v[196:199], v[10:13]
	v_mfma_f32_16x16x32_bf16 v[62:65], v[134:137], v[166:169], v[62:65]
	v_mfma_f32_16x16x32_bf16 v[58:61], v[142:145], v[166:169], v[58:61]
	v_mfma_f32_16x16x32_bf16 v[46:49], v[134:137], v[174:177], v[46:49]
	v_mfma_f32_16x16x32_bf16 v[42:45], v[142:145], v[174:177], v[42:45]
	v_mfma_f32_16x16x32_bf16 v[30:33], v[134:137], v[182:185], v[30:33]
	v_mfma_f32_16x16x32_bf16 v[26:29], v[142:145], v[182:185], v[26:29]
	v_mfma_f32_16x16x32_bf16 v[14:17], v[134:137], v[206:209], v[14:17]
	v_mfma_f32_16x16x32_bf16 v[10:13], v[142:145], v[206:209], v[10:13]
	s_setprio 0
	s_setprio 1
	v_mfma_f32_16x16x32_bf16 v[54:57], v[146:149], v[162:165], v[54:57]
	v_mfma_f32_16x16x32_bf16 v[50:53], v[154:157], v[162:165], v[50:53]
	v_mfma_f32_16x16x32_bf16 v[38:41], v[146:149], v[170:173], v[38:41]
	v_mfma_f32_16x16x32_bf16 v[34:37], v[154:157], v[170:173], v[34:37]
	v_mfma_f32_16x16x32_bf16 v[22:25], v[146:149], v[178:181], v[22:25]
	v_mfma_f32_16x16x32_bf16 v[18:21], v[154:157], v[178:181], v[18:21]
	v_mfma_f32_16x16x32_bf16 v[6:9], v[146:149], v[196:199], v[6:9]
	v_mfma_f32_16x16x32_bf16 v[2:5], v[154:157], v[196:199], v[2:5]
	v_mfma_f32_16x16x32_bf16 v[54:57], v[150:153], v[166:169], v[54:57]
	v_mfma_f32_16x16x32_bf16 v[50:53], v[158:161], v[166:169], v[50:53]
	v_mfma_f32_16x16x32_bf16 v[38:41], v[150:153], v[174:177], v[38:41]
	v_mfma_f32_16x16x32_bf16 v[34:37], v[158:161], v[174:177], v[34:37]
	v_mfma_f32_16x16x32_bf16 v[22:25], v[150:153], v[182:185], v[22:25]
	v_mfma_f32_16x16x32_bf16 v[18:21], v[158:161], v[182:185], v[18:21]
	v_mfma_f32_16x16x32_bf16 v[6:9], v[150:153], v[206:209], v[6:9]
	v_mfma_f32_16x16x32_bf16 v[2:5], v[158:161], v[206:209], v[2:5]
	s_setprio 0
	s_barrier
	s_add_i32 s90, 0, 0x18000
	s_add_i32 s91, 0, 0x1c000
	v_add_u32_e32 v142, s90, v220
	v_add_u32_e32 v158, s91, v220
	ds_read_b128 v[130:133], v142
	ds_read_b128 v[134:137], v142 offset:1024
	ds_read_b128 v[138:141], v142 offset:2048
	ds_read_b128 v[142:145], v142 offset:3072
	ds_read_b128 v[146:149], v158
	ds_read_b128 v[150:153], v158 offset:1024
	ds_read_b128 v[154:157], v158 offset:2048
	ds_read_b128 v[158:161], v158 offset:3072
	s_add_u32 s52, s52, 0x80000
	s_addc_u32 s53, s53, 0
	s_mov_b32 m0, s57
	v_lshl_add_u64 v[218:219], s[52:53], 0, v[186:187]
	ds_read_b128 v[162:165], v222 offset:32768
	ds_read_b128 v[166:169], v222 offset:33792
	ds_read_b128 v[170:173], v222 offset:34816
	ds_read_b128 v[174:177], v222 offset:35840
	ds_read_b128 v[178:181], v222 offset:36864
	ds_read_b128 v[182:185], v222 offset:37888
	ds_read_b128 v[196:199], v222 offset:38912
	ds_read_b128 v[206:209], v222 offset:39936
	global_load_lds_dwordx4 v[218:219], off
	s_mov_b32 m0, s60
	v_lshl_add_u64 v[218:219], s[52:53], 0, v[188:189]
	global_load_lds_dwordx4 v[218:219], off
	s_waitcnt vmcnt(8) lgkmcnt(0)
	s_barrier
	s_setprio 1
	v_mfma_f32_16x16x32_bf16 v[126:129], v[130:133], v[162:165], v[126:129]
	v_mfma_f32_16x16x32_bf16 v[122:125], v[138:141], v[162:165], v[122:125]
	v_mfma_f32_16x16x32_bf16 v[110:113], v[130:133], v[170:173], v[110:113]
	v_mfma_f32_16x16x32_bf16 v[106:109], v[138:141], v[170:173], v[106:109]
	v_mfma_f32_16x16x32_bf16 v[94:97], v[130:133], v[178:181], v[94:97]
	v_mfma_f32_16x16x32_bf16 v[90:93], v[138:141], v[178:181], v[90:93]
	v_mfma_f32_16x16x32_bf16 v[78:81], v[130:133], v[196:199], v[78:81]
	v_mfma_f32_16x16x32_bf16 v[74:77], v[138:141], v[196:199], v[74:77]
	v_mfma_f32_16x16x32_bf16 v[126:129], v[134:137], v[166:169], v[126:129]
	v_mfma_f32_16x16x32_bf16 v[122:125], v[142:145], v[166:169], v[122:125]
	v_mfma_f32_16x16x32_bf16 v[110:113], v[134:137], v[174:177], v[110:113]
	v_mfma_f32_16x16x32_bf16 v[106:109], v[142:145], v[174:177], v[106:109]
	v_mfma_f32_16x16x32_bf16 v[94:97], v[134:137], v[182:185], v[94:97]
	v_mfma_f32_16x16x32_bf16 v[90:93], v[142:145], v[182:185], v[90:93]
	v_mfma_f32_16x16x32_bf16 v[78:81], v[134:137], v[206:209], v[78:81]
	v_mfma_f32_16x16x32_bf16 v[74:77], v[142:145], v[206:209], v[74:77]
	s_setprio 0
	s_setprio 1
	v_mfma_f32_16x16x32_bf16 v[118:121], v[146:149], v[162:165], v[118:121]
	v_mfma_f32_16x16x32_bf16 v[114:117], v[154:157], v[162:165], v[114:117]
	v_mfma_f32_16x16x32_bf16 v[102:105], v[146:149], v[170:173], v[102:105]
	v_mfma_f32_16x16x32_bf16 v[98:101], v[154:157], v[170:173], v[98:101]
	v_mfma_f32_16x16x32_bf16 v[86:89], v[146:149], v[178:181], v[86:89]
	v_mfma_f32_16x16x32_bf16 v[82:85], v[154:157], v[178:181], v[82:85]
	v_mfma_f32_16x16x32_bf16 v[70:73], v[146:149], v[196:199], v[70:73]
	v_mfma_f32_16x16x32_bf16 v[66:69], v[154:157], v[196:199], v[66:69]
	v_mfma_f32_16x16x32_bf16 v[118:121], v[150:153], v[166:169], v[118:121]
	v_mfma_f32_16x16x32_bf16 v[114:117], v[158:161], v[166:169], v[114:117]
	v_mfma_f32_16x16x32_bf16 v[102:105], v[150:153], v[174:177], v[102:105]
	v_mfma_f32_16x16x32_bf16 v[98:101], v[158:161], v[174:177], v[98:101]
	v_mfma_f32_16x16x32_bf16 v[86:89], v[150:153], v[182:185], v[86:89]
	v_mfma_f32_16x16x32_bf16 v[82:85], v[158:161], v[182:185], v[82:85]
	v_mfma_f32_16x16x32_bf16 v[70:73], v[150:153], v[206:209], v[70:73]
	v_mfma_f32_16x16x32_bf16 v[66:69], v[158:161], v[206:209], v[66:69]
	s_setprio 0
	s_barrier
	s_add_i32 s52, s90, s47
	v_lshl_add_u64 v[210:211], v[210:211], 0, s[58:59]
	s_mov_b32 m0, s52
	ds_read_b128 v[162:165], v222 offset:49152
	ds_read_b128 v[166:169], v222 offset:50176
	ds_read_b128 v[170:173], v222 offset:51200
	ds_read_b128 v[174:177], v222 offset:52224
	ds_read_b128 v[178:181], v222 offset:53248
	ds_read_b128 v[182:185], v222 offset:54272
	ds_read_b128 v[196:199], v222 offset:55296
	ds_read_b128 v[206:209], v222 offset:56320
	global_load_lds_dwordx4 v[210:211], off
	s_add_i32 m0, s52, 0x2000
	s_add_u32 s34, s34, 0x80080
	v_lshl_add_u64 v[210:211], v[212:213], 0, s[58:59]
	s_addc_u32 s35, s35, 0
	s_add_i32 s52, s91, s47
	global_load_lds_dwordx4 v[210:211], off
	s_mov_b32 m0, s52
	v_lshl_add_u64 v[210:211], s[34:35], 0, v[190:191]
	global_load_lds_dwordx4 v[210:211], off
	s_add_i32 m0, s52, 0x2000
	v_lshl_add_u64 v[210:211], s[34:35], 0, v[200:201]
	global_load_lds_dwordx4 v[210:211], off
	s_mov_b32 m0, s61
	v_lshl_add_u64 v[210:211], v[214:215], 0, s[58:59]
	global_load_lds_dwordx4 v[210:211], off
	s_mov_b32 m0, s69
	v_lshl_add_u64 v[210:211], v[216:217], 0, s[58:59]
	global_load_lds_dwordx4 v[210:211], off
	s_waitcnt vmcnt(8) lgkmcnt(0)
	s_barrier
	s_setprio 1
	v_mfma_f32_16x16x32_bf16 v[62:65], v[130:133], v[162:165], v[62:65]
	v_mfma_f32_16x16x32_bf16 v[58:61], v[138:141], v[162:165], v[58:61]
	v_mfma_f32_16x16x32_bf16 v[46:49], v[130:133], v[170:173], v[46:49]
	v_mfma_f32_16x16x32_bf16 v[42:45], v[138:141], v[170:173], v[42:45]
	v_mfma_f32_16x16x32_bf16 v[30:33], v[130:133], v[178:181], v[30:33]
	v_mfma_f32_16x16x32_bf16 v[26:29], v[138:141], v[178:181], v[26:29]
	v_mfma_f32_16x16x32_bf16 v[14:17], v[130:133], v[196:199], v[14:17]
	v_mfma_f32_16x16x32_bf16 v[10:13], v[138:141], v[196:199], v[10:13]
	v_mfma_f32_16x16x32_bf16 v[62:65], v[134:137], v[166:169], v[62:65]
	v_mfma_f32_16x16x32_bf16 v[58:61], v[142:145], v[166:169], v[58:61]
	v_mfma_f32_16x16x32_bf16 v[46:49], v[134:137], v[174:177], v[46:49]
	v_mfma_f32_16x16x32_bf16 v[42:45], v[142:145], v[174:177], v[42:45]
	v_mfma_f32_16x16x32_bf16 v[30:33], v[134:137], v[182:185], v[30:33]
	v_mfma_f32_16x16x32_bf16 v[26:29], v[142:145], v[182:185], v[26:29]
	v_mfma_f32_16x16x32_bf16 v[14:17], v[134:137], v[206:209], v[14:17]
	v_mfma_f32_16x16x32_bf16 v[10:13], v[142:145], v[206:209], v[10:13]
	s_setprio 0
	s_setprio 1
	v_mfma_f32_16x16x32_bf16 v[54:57], v[146:149], v[162:165], v[54:57]
	v_mfma_f32_16x16x32_bf16 v[50:53], v[154:157], v[162:165], v[50:53]
	v_mfma_f32_16x16x32_bf16 v[38:41], v[146:149], v[170:173], v[38:41]
	v_mfma_f32_16x16x32_bf16 v[34:37], v[154:157], v[170:173], v[34:37]
	v_mfma_f32_16x16x32_bf16 v[22:25], v[146:149], v[178:181], v[22:25]
	v_mfma_f32_16x16x32_bf16 v[18:21], v[154:157], v[178:181], v[18:21]
	v_mfma_f32_16x16x32_bf16 v[6:9], v[146:149], v[196:199], v[6:9]
	v_mfma_f32_16x16x32_bf16 v[2:5], v[154:157], v[196:199], v[2:5]
	v_mfma_f32_16x16x32_bf16 v[54:57], v[150:153], v[166:169], v[54:57]
	v_mfma_f32_16x16x32_bf16 v[50:53], v[158:161], v[166:169], v[50:53]
	v_mfma_f32_16x16x32_bf16 v[38:41], v[150:153], v[174:177], v[38:41]
	v_mfma_f32_16x16x32_bf16 v[34:37], v[158:161], v[174:177], v[34:37]
	v_mfma_f32_16x16x32_bf16 v[22:25], v[150:153], v[182:185], v[22:25]
	v_mfma_f32_16x16x32_bf16 v[18:21], v[158:161], v[182:185], v[18:21]
	v_mfma_f32_16x16x32_bf16 v[6:9], v[150:153], v[206:209], v[6:9]
	v_mfma_f32_16x16x32_bf16 v[2:5], v[158:161], v[206:209], v[2:5]
	s_setprio 0
	s_barrier
	s_add_i32 s89, s89, 2
	s_add_u32 s30, s30, 0x100
	s_addc_u32 s31, s31, 0
	s_add_u32 s81, s81, 0x100
	s_addc_u32 s88, s88, 0
	s_cmp_gt_u32 s89, 29
	s_cbranch_scc0 .LBB0_823

.LBB0_937:
	s_ashr_i32 s23, s22, 31
	s_lshl_b64 s[4:5], s[22:23], 20
	s_add_u32 s4, s86, s4
	s_addc_u32 s5, s87, s5
	s_and_b64 s[26:27], s[24:25], exec
	s_cselect_b32 s11, s5, s29
	s_cselect_b32 s23, s4, s28
	s_ashr_i32 s21, s20, 31
	s_lshl_b64 s[26:27], s[20:21], 20
	v_readlane_b32 s0, v254, 38
	v_readlane_b32 s1, v254, 39
	s_add_u32 s26, s0, s26
	s_addc_u32 s27, s1, s27
	s_and_b64 s[34:35], s[24:25], exec
	s_cselect_b32 s21, s27, s31
	s_cselect_b32 s53, s26, s30
	s_add_u32 s28, s28, 0x80080
	s_addc_u32 s29, s29, 0
	s_add_u32 s55, s30, 0x100
	s_addc_u32 s56, s31, 0
	s_mov_b32 s57, -2
	v_readlane_b32 s60, v255, 49
	s_nop 3
	s_cmp_eq_u32 s60, 7
	v_writelane_b32 v255, 7, 49
	s_cbranch_scc0 .Ltrip0_strict_6
	s_add_u32 s30, s28, 0xfff80080
	s_addc_u32 s31, s29, -1
	s_add_i32 s60, 0, 0x10000
	s_cmp_eq_u32 s57, 28
	s_cselect_b32 s35, s11, s31
	s_cselect_b32 s34, s23, s30
	s_cselect_b32 s31, s21, s56
	s_cselect_b32 s30, s53, s55
	s_add_i32 s66, 0, 0x14000
	v_add_u32_e32 v154, s60, v139
	v_add_u32_e32 v170, s66, v139
	ds_read_b128 v[142:145], v154
	ds_read_b128 v[146:149], v154 offset:1024
	ds_read_b128 v[150:153], v154 offset:2048
	ds_read_b128 v[154:157], v154 offset:3072
	ds_read_b128 v[158:161], v170
	ds_read_b128 v[162:165], v170 offset:1024
	ds_read_b128 v[166:169], v170 offset:2048
	ds_read_b128 v[170:173], v170 offset:3072
	v_lshl_add_u64 v[186:187], s[28:29], 0, v[134:135]
	s_add_i32 m0, s13, 0xc000
	ds_read_b128 v[174:177], v141
	ds_read_b128 v[178:181], v141 offset:1024
	ds_read_b128 v[182:185], v141 offset:2048
	ds_read_b128 v[196:199], v141 offset:3072
	ds_read_b128 v[200:203], v141 offset:4096
	ds_read_b128 v[204:207], v141 offset:5120
	ds_read_b128 v[208:211], v141 offset:6144
	ds_read_b128 v[212:215], v141 offset:7168
	global_load_lds_dwordx4 v[186:187], off
	s_add_i32 m0, s13, 0xe000
	v_lshl_add_u64 v[186:187], s[28:29], 0, v[136:137]
	global_load_lds_dwordx4 v[186:187], off
	s_waitcnt vmcnt(24) lgkmcnt(0)
	s_barrier
	s_setprio 1
	v_mfma_f32_16x16x32_bf16 v[124:127], v[142:145], v[174:177], 0
	v_mfma_f32_16x16x32_bf16 v[120:123], v[150:153], v[174:177], 0
	v_mfma_f32_16x16x32_bf16 v[116:119], v[142:145], v[182:185], 0
	v_mfma_f32_16x16x32_bf16 v[112:115], v[150:153], v[182:185], 0
	v_mfma_f32_16x16x32_bf16 v[100:103], v[142:145], v[200:203], 0
	v_mfma_f32_16x16x32_bf16 v[96:99], v[150:153], v[200:203], 0
	v_mfma_f32_16x16x32_bf16 v[84:87], v[142:145], v[208:211], 0
	v_mfma_f32_16x16x32_bf16 v[80:83], v[150:153], v[208:211], 0
	v_mfma_f32_16x16x32_bf16 v[124:127], v[146:149], v[178:181], v[124:127]
	v_mfma_f32_16x16x32_bf16 v[120:123], v[154:157], v[178:181], v[120:123]
	v_mfma_f32_16x16x32_bf16 v[116:119], v[146:149], v[196:199], v[116:119]
	v_mfma_f32_16x16x32_bf16 v[112:115], v[154:157], v[196:199], v[112:115]
	v_mfma_f32_16x16x32_bf16 v[100:103], v[146:149], v[204:207], v[100:103]
	v_mfma_f32_16x16x32_bf16 v[96:99], v[154:157], v[204:207], v[96:99]
	v_mfma_f32_16x16x32_bf16 v[84:87], v[146:149], v[212:215], v[84:87]
	v_mfma_f32_16x16x32_bf16 v[80:83], v[154:157], v[212:215], v[80:83]
	s_setprio 0
	s_setprio 1
	v_mfma_f32_16x16x32_bf16 v[108:111], v[158:161], v[174:177], 0
	v_mfma_f32_16x16x32_bf16 v[104:107], v[166:169], v[174:177], 0
	v_mfma_f32_16x16x32_bf16 v[92:95], v[158:161], v[182:185], 0
	v_mfma_f32_16x16x32_bf16 v[88:91], v[166:169], v[182:185], 0
	v_mfma_f32_16x16x32_bf16 v[76:79], v[158:161], v[200:203], 0
	v_mfma_f32_16x16x32_bf16 v[72:75], v[166:169], v[200:203], 0
	v_mfma_f32_16x16x32_bf16 v[68:71], v[158:161], v[208:211], 0
	v_mfma_f32_16x16x32_bf16 v[64:67], v[166:169], v[208:211], 0
	v_mfma_f32_16x16x32_bf16 v[108:111], v[162:165], v[178:181], v[108:111]
	v_mfma_f32_16x16x32_bf16 v[104:107], v[170:173], v[178:181], v[104:107]
	v_mfma_f32_16x16x32_bf16 v[92:95], v[162:165], v[196:199], v[92:95]
	v_mfma_f32_16x16x32_bf16 v[88:91], v[170:173], v[196:199], v[88:91]
	v_mfma_f32_16x16x32_bf16 v[76:79], v[162:165], v[204:207], v[76:79]
	v_mfma_f32_16x16x32_bf16 v[72:75], v[170:173], v[204:207], v[72:75]
	v_mfma_f32_16x16x32_bf16 v[68:71], v[162:165], v[212:215], v[68:71]
	v_mfma_f32_16x16x32_bf16 v[64:67], v[170:173], v[212:215], v[64:67]
	s_setprio 0
	s_barrier
	s_add_i32 s60, s60, s38
	v_lshl_add_u64 v[186:187], s[30:31], 0, v[190:191]
	s_mov_b32 m0, s60
	ds_read_b128 v[174:177], v141 offset:16384
	ds_read_b128 v[178:181], v141 offset:17408
	ds_read_b128 v[182:185], v141 offset:18432
	ds_read_b128 v[196:199], v141 offset:19456
	ds_read_b128 v[200:203], v141 offset:20480
	ds_read_b128 v[204:207], v141 offset:21504
	ds_read_b128 v[208:211], v141 offset:22528
	ds_read_b128 v[212:215], v141 offset:23552
	global_load_lds_dwordx4 v[186:187], off
	s_add_i32 m0, s60, 0x2000
	s_add_u32 s60, s30, 0x80000
	v_lshl_add_u64 v[216:217], s[30:31], 0, v[132:133]
	s_addc_u32 s61, s31, 0
	s_add_i32 s66, s66, s38
	global_load_lds_dwordx4 v[216:217], off
	v_lshl_add_u64 v[218:219], s[60:61], 0, v[190:191]
	s_mov_b32 m0, s66
	v_lshl_add_u64 v[220:221], s[34:35], 0, v[130:131]
	global_load_lds_dwordx4 v[218:219], off
	s_add_i32 m0, s66, 0x2000
	v_lshl_add_u64 v[218:219], s[60:61], 0, v[132:133]
	global_load_lds_dwordx4 v[218:219], off
	s_mov_b32 m0, s13
	v_lshl_add_u64 v[218:219], s[34:35], 0, v[128:129]
	global_load_lds_dwordx4 v[218:219], off
	s_mov_b32 m0, s39
	s_nop 0
	global_load_lds_dwordx4 v[220:221], off
	s_waitcnt vmcnt(24) lgkmcnt(0)
	s_barrier
	s_setprio 1
	v_mfma_f32_16x16x32_bf16 v[60:63], v[142:145], v[174:177], 0
	v_mfma_f32_16x16x32_bf16 v[56:59], v[150:153], v[174:177], 0
	v_mfma_f32_16x16x32_bf16 v[52:55], v[142:145], v[182:185], 0
	v_mfma_f32_16x16x32_bf16 v[48:51], v[150:153], v[182:185], 0
	v_mfma_f32_16x16x32_bf16 v[36:39], v[142:145], v[200:203], 0
	v_mfma_f32_16x16x32_bf16 v[32:35], v[150:153], v[200:203], 0
	v_mfma_f32_16x16x32_bf16 v[20:23], v[142:145], v[208:211], 0
	v_mfma_f32_16x16x32_bf16 v[16:19], v[150:153], v[208:211], 0
	v_mfma_f32_16x16x32_bf16 v[60:63], v[146:149], v[178:181], v[60:63]
	v_mfma_f32_16x16x32_bf16 v[56:59], v[154:157], v[178:181], v[56:59]
	v_mfma_f32_16x16x32_bf16 v[52:55], v[146:149], v[196:199], v[52:55]
	v_mfma_f32_16x16x32_bf16 v[48:51], v[154:157], v[196:199], v[48:51]
	v_mfma_f32_16x16x32_bf16 v[36:39], v[146:149], v[204:207], v[36:39]
	v_mfma_f32_16x16x32_bf16 v[32:35], v[154:157], v[204:207], v[32:35]
	v_mfma_f32_16x16x32_bf16 v[20:23], v[146:149], v[212:215], v[20:23]
	v_mfma_f32_16x16x32_bf16 v[16:19], v[154:157], v[212:215], v[16:19]
	s_setprio 0
	s_setprio 1
	v_mfma_f32_16x16x32_bf16 v[44:47], v[158:161], v[174:177], 0
	v_mfma_f32_16x16x32_bf16 v[40:43], v[166:169], v[174:177], 0
	v_mfma_f32_16x16x32_bf16 v[28:31], v[158:161], v[182:185], 0
	v_mfma_f32_16x16x32_bf16 v[24:27], v[166:169], v[182:185], 0
	v_mfma_f32_16x16x32_bf16 v[12:15], v[158:161], v[200:203], 0
	v_mfma_f32_16x16x32_bf16 v[8:11], v[166:169], v[200:203], 0
	v_mfma_f32_16x16x32_bf16 v[4:7], v[158:161], v[208:211], 0
	v_mfma_f32_16x16x32_bf16 v[0:3], v[166:169], v[208:211], 0
	v_mfma_f32_16x16x32_bf16 v[44:47], v[162:165], v[178:181], v[44:47]
	v_mfma_f32_16x16x32_bf16 v[40:43], v[170:173], v[178:181], v[40:43]
	v_mfma_f32_16x16x32_bf16 v[28:31], v[162:165], v[196:199], v[28:31]
	v_mfma_f32_16x16x32_bf16 v[24:27], v[170:173], v[196:199], v[24:27]
	v_mfma_f32_16x16x32_bf16 v[12:15], v[162:165], v[204:207], v[12:15]
	v_mfma_f32_16x16x32_bf16 v[8:11], v[170:173], v[204:207], v[8:11]
	v_mfma_f32_16x16x32_bf16 v[4:7], v[162:165], v[212:215], v[4:7]
	v_mfma_f32_16x16x32_bf16 v[0:3], v[170:173], v[212:215], v[0:3]
	s_setprio 0
	s_barrier
	s_add_i32 s60, 0, 0x18000
	s_add_i32 s61, 0, 0x1c000
	v_add_u32_e32 v154, s60, v139
	v_add_u32_e32 v170, s61, v139
	ds_read_b128 v[142:145], v154
	ds_read_b128 v[146:149], v154 offset:1024
	ds_read_b128 v[150:153], v154 offset:2048
	ds_read_b128 v[154:157], v154 offset:3072
	ds_read_b128 v[158:161], v170
	ds_read_b128 v[162:165], v170 offset:1024
	ds_read_b128 v[166:169], v170 offset:2048
	ds_read_b128 v[170:173], v170 offset:3072
	s_add_u32 s34, s34, 0x80000
	s_addc_u32 s35, s35, 0
	s_mov_b32 m0, s41
	v_lshl_add_u64 v[222:223], s[34:35], 0, v[128:129]
	ds_read_b128 v[174:177], v141 offset:32768
	ds_read_b128 v[178:181], v141 offset:33792
	ds_read_b128 v[182:185], v141 offset:34816
	ds_read_b128 v[196:199], v141 offset:35840
	ds_read_b128 v[200:203], v141 offset:36864
	ds_read_b128 v[204:207], v141 offset:37888
	ds_read_b128 v[208:211], v141 offset:38912
	ds_read_b128 v[212:215], v141 offset:39936
	global_load_lds_dwordx4 v[222:223], off
	s_mov_b32 m0, s42
	v_lshl_add_u64 v[222:223], s[34:35], 0, v[130:131]
	global_load_lds_dwordx4 v[222:223], off
	s_waitcnt vmcnt(8) lgkmcnt(0)
	s_barrier
	s_setprio 1
	v_mfma_f32_16x16x32_bf16 v[124:127], v[142:145], v[174:177], v[124:127]
	v_mfma_f32_16x16x32_bf16 v[120:123], v[150:153], v[174:177], v[120:123]
	v_mfma_f32_16x16x32_bf16 v[116:119], v[142:145], v[182:185], v[116:119]
	v_mfma_f32_16x16x32_bf16 v[112:115], v[150:153], v[182:185], v[112:115]
	v_mfma_f32_16x16x32_bf16 v[100:103], v[142:145], v[200:203], v[100:103]
	v_mfma_f32_16x16x32_bf16 v[96:99], v[150:153], v[200:203], v[96:99]
	v_mfma_f32_16x16x32_bf16 v[84:87], v[142:145], v[208:211], v[84:87]
	v_mfma_f32_16x16x32_bf16 v[80:83], v[150:153], v[208:211], v[80:83]
	v_mfma_f32_16x16x32_bf16 v[124:127], v[146:149], v[178:181], v[124:127]
	v_mfma_f32_16x16x32_bf16 v[120:123], v[154:157], v[178:181], v[120:123]
	v_mfma_f32_16x16x32_bf16 v[116:119], v[146:149], v[196:199], v[116:119]
	v_mfma_f32_16x16x32_bf16 v[112:115], v[154:157], v[196:199], v[112:115]
	v_mfma_f32_16x16x32_bf16 v[100:103], v[146:149], v[204:207], v[100:103]
	v_mfma_f32_16x16x32_bf16 v[96:99], v[154:157], v[204:207], v[96:99]
	v_mfma_f32_16x16x32_bf16 v[84:87], v[146:149], v[212:215], v[84:87]
	v_mfma_f32_16x16x32_bf16 v[80:83], v[154:157], v[212:215], v[80:83]
	s_setprio 0
	s_setprio 1
	v_mfma_f32_16x16x32_bf16 v[108:111], v[158:161], v[174:177], v[108:111]
	v_mfma_f32_16x16x32_bf16 v[104:107], v[166:169], v[174:177], v[104:107]
	v_mfma_f32_16x16x32_bf16 v[92:95], v[158:161], v[182:185], v[92:95]
	v_mfma_f32_16x16x32_bf16 v[88:91], v[166:169], v[182:185], v[88:91]
	v_mfma_f32_16x16x32_bf16 v[76:79], v[158:161], v[200:203], v[76:79]
	v_mfma_f32_16x16x32_bf16 v[72:75], v[166:169], v[200:203], v[72:75]
	v_mfma_f32_16x16x32_bf16 v[68:71], v[158:161], v[208:211], v[68:71]
	v_mfma_f32_16x16x32_bf16 v[64:67], v[166:169], v[208:211], v[64:67]
	v_mfma_f32_16x16x32_bf16 v[108:111], v[162:165], v[178:181], v[108:111]
	v_mfma_f32_16x16x32_bf16 v[104:107], v[170:173], v[178:181], v[104:107]
	v_mfma_f32_16x16x32_bf16 v[92:95], v[162:165], v[196:199], v[92:95]
	v_mfma_f32_16x16x32_bf16 v[88:91], v[170:173], v[196:199], v[88:91]
	v_mfma_f32_16x16x32_bf16 v[76:79], v[162:165], v[204:207], v[76:79]
	v_mfma_f32_16x16x32_bf16 v[72:75], v[170:173], v[204:207], v[72:75]
	v_mfma_f32_16x16x32_bf16 v[68:71], v[162:165], v[212:215], v[68:71]
	v_mfma_f32_16x16x32_bf16 v[64:67], v[170:173], v[212:215], v[64:67]
	s_setprio 0
	s_barrier
	s_add_i32 s34, s60, s38
	v_lshl_add_u64 v[186:187], v[186:187], 0, s[58:59]
	s_mov_b32 m0, s34
	ds_read_b128 v[174:177], v141 offset:49152
	ds_read_b128 v[178:181], v141 offset:50176
	ds_read_b128 v[182:185], v141 offset:51200
	ds_read_b128 v[196:199], v141 offset:52224
	ds_read_b128 v[200:203], v141 offset:53248
	ds_read_b128 v[204:207], v141 offset:54272
	ds_read_b128 v[208:211], v141 offset:55296
	ds_read_b128 v[212:215], v141 offset:56320
	global_load_lds_dwordx4 v[186:187], off
	s_add_i32 m0, s34, 0x2000
	s_add_u32 s30, s30, 0x80080
	v_lshl_add_u64 v[186:187], v[216:217], 0, s[58:59]
	s_addc_u32 s31, s31, 0
	s_add_i32 s34, s61, s38
	global_load_lds_dwordx4 v[186:187], off
	s_mov_b32 m0, s34
	v_lshl_add_u64 v[186:187], s[30:31], 0, v[190:191]
	global_load_lds_dwordx4 v[186:187], off
	s_add_i32 m0, s34, 0x2000
	v_lshl_add_u64 v[186:187], s[30:31], 0, v[132:133]
	global_load_lds_dwordx4 v[186:187], off
	s_mov_b32 m0, s43
	v_lshl_add_u64 v[186:187], v[218:219], 0, s[58:59]
	global_load_lds_dwordx4 v[186:187], off
	s_mov_b32 m0, s47
	v_lshl_add_u64 v[186:187], v[220:221], 0, s[58:59]
	global_load_lds_dwordx4 v[186:187], off
	s_waitcnt vmcnt(8) lgkmcnt(0)
	s_barrier
	s_setprio 1
	v_mfma_f32_16x16x32_bf16 v[60:63], v[142:145], v[174:177], v[60:63]
	v_mfma_f32_16x16x32_bf16 v[56:59], v[150:153], v[174:177], v[56:59]
	v_mfma_f32_16x16x32_bf16 v[52:55], v[142:145], v[182:185], v[52:55]
	v_mfma_f32_16x16x32_bf16 v[48:51], v[150:153], v[182:185], v[48:51]
	v_mfma_f32_16x16x32_bf16 v[36:39], v[142:145], v[200:203], v[36:39]
	v_mfma_f32_16x16x32_bf16 v[32:35], v[150:153], v[200:203], v[32:35]
	v_mfma_f32_16x16x32_bf16 v[20:23], v[142:145], v[208:211], v[20:23]
	v_mfma_f32_16x16x32_bf16 v[16:19], v[150:153], v[208:211], v[16:19]
	v_mfma_f32_16x16x32_bf16 v[60:63], v[146:149], v[178:181], v[60:63]
	v_mfma_f32_16x16x32_bf16 v[56:59], v[154:157], v[178:181], v[56:59]
	v_mfma_f32_16x16x32_bf16 v[52:55], v[146:149], v[196:199], v[52:55]
	v_mfma_f32_16x16x32_bf16 v[48:51], v[154:157], v[196:199], v[48:51]
	v_mfma_f32_16x16x32_bf16 v[36:39], v[146:149], v[204:207], v[36:39]
	v_mfma_f32_16x16x32_bf16 v[32:35], v[154:157], v[204:207], v[32:35]
	v_mfma_f32_16x16x32_bf16 v[20:23], v[146:149], v[212:215], v[20:23]
	v_mfma_f32_16x16x32_bf16 v[16:19], v[154:157], v[212:215], v[16:19]
	s_setprio 0
	s_setprio 1
	v_mfma_f32_16x16x32_bf16 v[44:47], v[158:161], v[174:177], v[44:47]
	v_mfma_f32_16x16x32_bf16 v[40:43], v[166:169], v[174:177], v[40:43]
	v_mfma_f32_16x16x32_bf16 v[28:31], v[158:161], v[182:185], v[28:31]
	v_mfma_f32_16x16x32_bf16 v[24:27], v[166:169], v[182:185], v[24:27]
	v_mfma_f32_16x16x32_bf16 v[12:15], v[158:161], v[200:203], v[12:15]
	v_mfma_f32_16x16x32_bf16 v[8:11], v[166:169], v[200:203], v[8:11]
	v_mfma_f32_16x16x32_bf16 v[4:7], v[158:161], v[208:211], v[4:7]
	v_mfma_f32_16x16x32_bf16 v[0:3], v[166:169], v[208:211], v[0:3]
	v_mfma_f32_16x16x32_bf16 v[44:47], v[162:165], v[178:181], v[44:47]
	v_mfma_f32_16x16x32_bf16 v[40:43], v[170:173], v[178:181], v[40:43]
	v_mfma_f32_16x16x32_bf16 v[28:31], v[162:165], v[196:199], v[28:31]
	v_mfma_f32_16x16x32_bf16 v[24:27], v[170:173], v[196:199], v[24:27]
	v_mfma_f32_16x16x32_bf16 v[12:15], v[162:165], v[204:207], v[12:15]
	v_mfma_f32_16x16x32_bf16 v[8:11], v[170:173], v[204:207], v[8:11]
	v_mfma_f32_16x16x32_bf16 v[4:7], v[162:165], v[212:215], v[4:7]
	v_mfma_f32_16x16x32_bf16 v[0:3], v[170:173], v[212:215], v[0:3]
	s_setprio 0
	s_barrier
	s_add_i32 s57, s57, 2
	s_add_u32 s28, s28, 0x100
	s_addc_u32 s29, s29, 0
	s_add_u32 s55, s55, 0x100
	s_addc_u32 s56, s56, 0
	s_cmp_gt_u32 s57, 29
	s_cbranch_scc1 .Lpeel_done_6
	s_branch .LBB0_938
.Ltrip0_strict_6:
	s_add_u32 s30, s28, 0xfff80080
	s_addc_u32 s31, s29, -1
	s_add_i32 s60, 0, 0x10000
	s_cmp_eq_u32 s57, 28
	s_cselect_b32 s35, s11, s31
	s_cselect_b32 s34, s23, s30
	s_cselect_b32 s31, s21, s56
	s_cselect_b32 s30, s53, s55
	s_add_i32 s66, 0, 0x14000
	v_add_u32_e32 v154, s60, v139
	v_add_u32_e32 v170, s66, v139
	ds_read_b128 v[142:145], v154
	ds_read_b128 v[146:149], v154 offset:1024
	ds_read_b128 v[150:153], v154 offset:2048
	ds_read_b128 v[154:157], v154 offset:3072
	ds_read_b128 v[158:161], v170
	ds_read_b128 v[162:165], v170 offset:1024
	ds_read_b128 v[166:169], v170 offset:2048
	ds_read_b128 v[170:173], v170 offset:3072
	v_lshl_add_u64 v[186:187], s[28:29], 0, v[134:135]
	s_add_i32 m0, s13, 0xc000
	ds_read_b128 v[174:177], v141
	ds_read_b128 v[178:181], v141 offset:1024
	ds_read_b128 v[182:185], v141 offset:2048
	ds_read_b128 v[196:199], v141 offset:3072
	ds_read_b128 v[200:203], v141 offset:4096
	ds_read_b128 v[204:207], v141 offset:5120
	ds_read_b128 v[208:211], v141 offset:6144
	ds_read_b128 v[212:215], v141 offset:7168
	global_load_lds_dwordx4 v[186:187], off
	s_add_i32 m0, s13, 0xe000
	v_lshl_add_u64 v[186:187], s[28:29], 0, v[136:137]
	global_load_lds_dwordx4 v[186:187], off
	s_waitcnt vmcnt(8) lgkmcnt(0)
	s_barrier
	s_setprio 1
	v_mfma_f32_16x16x32_bf16 v[124:127], v[142:145], v[174:177], 0
	v_mfma_f32_16x16x32_bf16 v[120:123], v[150:153], v[174:177], 0
	v_mfma_f32_16x16x32_bf16 v[116:119], v[142:145], v[182:185], 0
	v_mfma_f32_16x16x32_bf16 v[112:115], v[150:153], v[182:185], 0
	v_mfma_f32_16x16x32_bf16 v[100:103], v[142:145], v[200:203], 0
	v_mfma_f32_16x16x32_bf16 v[96:99], v[150:153], v[200:203], 0
	v_mfma_f32_16x16x32_bf16 v[84:87], v[142:145], v[208:211], 0
	v_mfma_f32_16x16x32_bf16 v[80:83], v[150:153], v[208:211], 0
	v_mfma_f32_16x16x32_bf16 v[124:127], v[146:149], v[178:181], v[124:127]
	v_mfma_f32_16x16x32_bf16 v[120:123], v[154:157], v[178:181], v[120:123]
	v_mfma_f32_16x16x32_bf16 v[116:119], v[146:149], v[196:199], v[116:119]
	v_mfma_f32_16x16x32_bf16 v[112:115], v[154:157], v[196:199], v[112:115]
	v_mfma_f32_16x16x32_bf16 v[100:103], v[146:149], v[204:207], v[100:103]
	v_mfma_f32_16x16x32_bf16 v[96:99], v[154:157], v[204:207], v[96:99]
	v_mfma_f32_16x16x32_bf16 v[84:87], v[146:149], v[212:215], v[84:87]
	v_mfma_f32_16x16x32_bf16 v[80:83], v[154:157], v[212:215], v[80:83]
	s_setprio 0
	s_setprio 1
	v_mfma_f32_16x16x32_bf16 v[108:111], v[158:161], v[174:177], 0
	v_mfma_f32_16x16x32_bf16 v[104:107], v[166:169], v[174:177], 0
	v_mfma_f32_16x16x32_bf16 v[92:95], v[158:161], v[182:185], 0
	v_mfma_f32_16x16x32_bf16 v[88:91], v[166:169], v[182:185], 0
	v_mfma_f32_16x16x32_bf16 v[76:79], v[158:161], v[200:203], 0
	v_mfma_f32_16x16x32_bf16 v[72:75], v[166:169], v[200:203], 0
	v_mfma_f32_16x16x32_bf16 v[68:71], v[158:161], v[208:211], 0
	v_mfma_f32_16x16x32_bf16 v[64:67], v[166:169], v[208:211], 0
	v_mfma_f32_16x16x32_bf16 v[108:111], v[162:165], v[178:181], v[108:111]
	v_mfma_f32_16x16x32_bf16 v[104:107], v[170:173], v[178:181], v[104:107]
	v_mfma_f32_16x16x32_bf16 v[92:95], v[162:165], v[196:199], v[92:95]
	v_mfma_f32_16x16x32_bf16 v[88:91], v[170:173], v[196:199], v[88:91]
	v_mfma_f32_16x16x32_bf16 v[76:79], v[162:165], v[204:207], v[76:79]
	v_mfma_f32_16x16x32_bf16 v[72:75], v[170:173], v[204:207], v[72:75]
	v_mfma_f32_16x16x32_bf16 v[68:71], v[162:165], v[212:215], v[68:71]
	v_mfma_f32_16x16x32_bf16 v[64:67], v[170:173], v[212:215], v[64:67]
	s_setprio 0
	s_barrier
	s_add_i32 s60, s60, s38
	v_lshl_add_u64 v[186:187], s[30:31], 0, v[190:191]
	s_mov_b32 m0, s60
	ds_read_b128 v[174:177], v141 offset:16384
	ds_read_b128 v[178:181], v141 offset:17408
	ds_read_b128 v[182:185], v141 offset:18432
	ds_read_b128 v[196:199], v141 offset:19456
	ds_read_b128 v[200:203], v141 offset:20480
	ds_read_b128 v[204:207], v141 offset:21504
	ds_read_b128 v[208:211], v141 offset:22528
	ds_read_b128 v[212:215], v141 offset:23552
	global_load_lds_dwordx4 v[186:187], off
	s_add_i32 m0, s60, 0x2000
	s_add_u32 s60, s30, 0x80000
	v_lshl_add_u64 v[216:217], s[30:31], 0, v[132:133]
	s_addc_u32 s61, s31, 0
	s_add_i32 s66, s66, s38
	global_load_lds_dwordx4 v[216:217], off
	v_lshl_add_u64 v[218:219], s[60:61], 0, v[190:191]
	s_mov_b32 m0, s66
	v_lshl_add_u64 v[220:221], s[34:35], 0, v[130:131]
	global_load_lds_dwordx4 v[218:219], off
	s_add_i32 m0, s66, 0x2000
	v_lshl_add_u64 v[218:219], s[60:61], 0, v[132:133]
	global_load_lds_dwordx4 v[218:219], off
	s_mov_b32 m0, s13
	v_lshl_add_u64 v[218:219], s[34:35], 0, v[128:129]
	global_load_lds_dwordx4 v[218:219], off
	s_mov_b32 m0, s39
	s_nop 0
	global_load_lds_dwordx4 v[220:221], off
	s_waitcnt vmcnt(8) lgkmcnt(0)
	s_barrier
	s_setprio 1
	v_mfma_f32_16x16x32_bf16 v[60:63], v[142:145], v[174:177], 0
	v_mfma_f32_16x16x32_bf16 v[56:59], v[150:153], v[174:177], 0
	v_mfma_f32_16x16x32_bf16 v[52:55], v[142:145], v[182:185], 0
	v_mfma_f32_16x16x32_bf16 v[48:51], v[150:153], v[182:185], 0
	v_mfma_f32_16x16x32_bf16 v[36:39], v[142:145], v[200:203], 0
	v_mfma_f32_16x16x32_bf16 v[32:35], v[150:153], v[200:203], 0
	v_mfma_f32_16x16x32_bf16 v[20:23], v[142:145], v[208:211], 0
	v_mfma_f32_16x16x32_bf16 v[16:19], v[150:153], v[208:211], 0
	v_mfma_f32_16x16x32_bf16 v[60:63], v[146:149], v[178:181], v[60:63]
	v_mfma_f32_16x16x32_bf16 v[56:59], v[154:157], v[178:181], v[56:59]
	v_mfma_f32_16x16x32_bf16 v[52:55], v[146:149], v[196:199], v[52:55]
	v_mfma_f32_16x16x32_bf16 v[48:51], v[154:157], v[196:199], v[48:51]
	v_mfma_f32_16x16x32_bf16 v[36:39], v[146:149], v[204:207], v[36:39]
	v_mfma_f32_16x16x32_bf16 v[32:35], v[154:157], v[204:207], v[32:35]
	v_mfma_f32_16x16x32_bf16 v[20:23], v[146:149], v[212:215], v[20:23]
	v_mfma_f32_16x16x32_bf16 v[16:19], v[154:157], v[212:215], v[16:19]
	s_setprio 0
	s_setprio 1
	v_mfma_f32_16x16x32_bf16 v[44:47], v[158:161], v[174:177], 0
	v_mfma_f32_16x16x32_bf16 v[40:43], v[166:169], v[174:177], 0
	v_mfma_f32_16x16x32_bf16 v[28:31], v[158:161], v[182:185], 0
	v_mfma_f32_16x16x32_bf16 v[24:27], v[166:169], v[182:185], 0
	v_mfma_f32_16x16x32_bf16 v[12:15], v[158:161], v[200:203], 0
	v_mfma_f32_16x16x32_bf16 v[8:11], v[166:169], v[200:203], 0
	v_mfma_f32_16x16x32_bf16 v[4:7], v[158:161], v[208:211], 0
	v_mfma_f32_16x16x32_bf16 v[0:3], v[166:169], v[208:211], 0
	v_mfma_f32_16x16x32_bf16 v[44:47], v[162:165], v[178:181], v[44:47]
	v_mfma_f32_16x16x32_bf16 v[40:43], v[170:173], v[178:181], v[40:43]
	v_mfma_f32_16x16x32_bf16 v[28:31], v[162:165], v[196:199], v[28:31]
	v_mfma_f32_16x16x32_bf16 v[24:27], v[170:173], v[196:199], v[24:27]
	v_mfma_f32_16x16x32_bf16 v[12:15], v[162:165], v[204:207], v[12:15]
	v_mfma_f32_16x16x32_bf16 v[8:11], v[170:173], v[204:207], v[8:11]
	v_mfma_f32_16x16x32_bf16 v[4:7], v[162:165], v[212:215], v[4:7]
	v_mfma_f32_16x16x32_bf16 v[0:3], v[170:173], v[212:215], v[0:3]
	s_setprio 0
	s_barrier
	s_add_i32 s60, 0, 0x18000
	s_add_i32 s61, 0, 0x1c000
	v_add_u32_e32 v154, s60, v139
	v_add_u32_e32 v170, s61, v139
	ds_read_b128 v[142:145], v154
	ds_read_b128 v[146:149], v154 offset:1024
	ds_read_b128 v[150:153], v154 offset:2048
	ds_read_b128 v[154:157], v154 offset:3072
	ds_read_b128 v[158:161], v170
	ds_read_b128 v[162:165], v170 offset:1024
	ds_read_b128 v[166:169], v170 offset:2048
	ds_read_b128 v[170:173], v170 offset:3072
	s_add_u32 s34, s34, 0x80000
	s_addc_u32 s35, s35, 0
	s_mov_b32 m0, s41
	v_lshl_add_u64 v[222:223], s[34:35], 0, v[128:129]
	ds_read_b128 v[174:177], v141 offset:32768
	ds_read_b128 v[178:181], v141 offset:33792
	ds_read_b128 v[182:185], v141 offset:34816
	ds_read_b128 v[196:199], v141 offset:35840
	ds_read_b128 v[200:203], v141 offset:36864
	ds_read_b128 v[204:207], v141 offset:37888
	ds_read_b128 v[208:211], v141 offset:38912
	ds_read_b128 v[212:215], v141 offset:39936
	global_load_lds_dwordx4 v[222:223], off
	s_mov_b32 m0, s42
	v_lshl_add_u64 v[222:223], s[34:35], 0, v[130:131]
	global_load_lds_dwordx4 v[222:223], off
	s_waitcnt vmcnt(8) lgkmcnt(0)
	s_barrier
	s_setprio 1
	v_mfma_f32_16x16x32_bf16 v[124:127], v[142:145], v[174:177], v[124:127]
	v_mfma_f32_16x16x32_bf16 v[120:123], v[150:153], v[174:177], v[120:123]
	v_mfma_f32_16x16x32_bf16 v[116:119], v[142:145], v[182:185], v[116:119]
	v_mfma_f32_16x16x32_bf16 v[112:115], v[150:153], v[182:185], v[112:115]
	v_mfma_f32_16x16x32_bf16 v[100:103], v[142:145], v[200:203], v[100:103]
	v_mfma_f32_16x16x32_bf16 v[96:99], v[150:153], v[200:203], v[96:99]
	v_mfma_f32_16x16x32_bf16 v[84:87], v[142:145], v[208:211], v[84:87]
	v_mfma_f32_16x16x32_bf16 v[80:83], v[150:153], v[208:211], v[80:83]
	v_mfma_f32_16x16x32_bf16 v[124:127], v[146:149], v[178:181], v[124:127]
	v_mfma_f32_16x16x32_bf16 v[120:123], v[154:157], v[178:181], v[120:123]
	v_mfma_f32_16x16x32_bf16 v[116:119], v[146:149], v[196:199], v[116:119]
	v_mfma_f32_16x16x32_bf16 v[112:115], v[154:157], v[196:199], v[112:115]
	v_mfma_f32_16x16x32_bf16 v[100:103], v[146:149], v[204:207], v[100:103]
	v_mfma_f32_16x16x32_bf16 v[96:99], v[154:157], v[204:207], v[96:99]
	v_mfma_f32_16x16x32_bf16 v[84:87], v[146:149], v[212:215], v[84:87]
	v_mfma_f32_16x16x32_bf16 v[80:83], v[154:157], v[212:215], v[80:83]
	s_setprio 0
	s_setprio 1
	v_mfma_f32_16x16x32_bf16 v[108:111], v[158:161], v[174:177], v[108:111]
	v_mfma_f32_16x16x32_bf16 v[104:107], v[166:169], v[174:177], v[104:107]
	v_mfma_f32_16x16x32_bf16 v[92:95], v[158:161], v[182:185], v[92:95]
	v_mfma_f32_16x16x32_bf16 v[88:91], v[166:169], v[182:185], v[88:91]
	v_mfma_f32_16x16x32_bf16 v[76:79], v[158:161], v[200:203], v[76:79]
	v_mfma_f32_16x16x32_bf16 v[72:75], v[166:169], v[200:203], v[72:75]
	v_mfma_f32_16x16x32_bf16 v[68:71], v[158:161], v[208:211], v[68:71]
	v_mfma_f32_16x16x32_bf16 v[64:67], v[166:169], v[208:211], v[64:67]
	v_mfma_f32_16x16x32_bf16 v[108:111], v[162:165], v[178:181], v[108:111]
	v_mfma_f32_16x16x32_bf16 v[104:107], v[170:173], v[178:181], v[104:107]
	v_mfma_f32_16x16x32_bf16 v[92:95], v[162:165], v[196:199], v[92:95]
	v_mfma_f32_16x16x32_bf16 v[88:91], v[170:173], v[196:199], v[88:91]
	v_mfma_f32_16x16x32_bf16 v[76:79], v[162:165], v[204:207], v[76:79]
	v_mfma_f32_16x16x32_bf16 v[72:75], v[170:173], v[204:207], v[72:75]
	v_mfma_f32_16x16x32_bf16 v[68:71], v[162:165], v[212:215], v[68:71]
	v_mfma_f32_16x16x32_bf16 v[64:67], v[170:173], v[212:215], v[64:67]
	s_setprio 0
	s_barrier
	s_add_i32 s34, s60, s38
	v_lshl_add_u64 v[186:187], v[186:187], 0, s[58:59]
	s_mov_b32 m0, s34
	ds_read_b128 v[174:177], v141 offset:49152
	ds_read_b128 v[178:181], v141 offset:50176
	ds_read_b128 v[182:185], v141 offset:51200
	ds_read_b128 v[196:199], v141 offset:52224
	ds_read_b128 v[200:203], v141 offset:53248
	ds_read_b128 v[204:207], v141 offset:54272
	ds_read_b128 v[208:211], v141 offset:55296
	ds_read_b128 v[212:215], v141 offset:56320
	global_load_lds_dwordx4 v[186:187], off
	s_add_i32 m0, s34, 0x2000
	s_add_u32 s30, s30, 0x80080
	v_lshl_add_u64 v[186:187], v[216:217], 0, s[58:59]
	s_addc_u32 s31, s31, 0
	s_add_i32 s34, s61, s38
	global_load_lds_dwordx4 v[186:187], off
	s_mov_b32 m0, s34
	v_lshl_add_u64 v[186:187], s[30:31], 0, v[190:191]
	global_load_lds_dwordx4 v[186:187], off
	s_add_i32 m0, s34, 0x2000
	v_lshl_add_u64 v[186:187], s[30:31], 0, v[132:133]
	global_load_lds_dwordx4 v[186:187], off
	s_mov_b32 m0, s43
	v_lshl_add_u64 v[186:187], v[218:219], 0, s[58:59]
	global_load_lds_dwordx4 v[186:187], off
	s_mov_b32 m0, s47
	v_lshl_add_u64 v[186:187], v[220:221], 0, s[58:59]
	global_load_lds_dwordx4 v[186:187], off
	s_waitcnt vmcnt(8) lgkmcnt(0)
	s_barrier
	s_setprio 1
	v_mfma_f32_16x16x32_bf16 v[60:63], v[142:145], v[174:177], v[60:63]
	v_mfma_f32_16x16x32_bf16 v[56:59], v[150:153], v[174:177], v[56:59]
	v_mfma_f32_16x16x32_bf16 v[52:55], v[142:145], v[182:185], v[52:55]
	v_mfma_f32_16x16x32_bf16 v[48:51], v[150:153], v[182:185], v[48:51]
	v_mfma_f32_16x16x32_bf16 v[36:39], v[142:145], v[200:203], v[36:39]
	v_mfma_f32_16x16x32_bf16 v[32:35], v[150:153], v[200:203], v[32:35]
	v_mfma_f32_16x16x32_bf16 v[20:23], v[142:145], v[208:211], v[20:23]
	v_mfma_f32_16x16x32_bf16 v[16:19], v[150:153], v[208:211], v[16:19]
	v_mfma_f32_16x16x32_bf16 v[60:63], v[146:149], v[178:181], v[60:63]
	v_mfma_f32_16x16x32_bf16 v[56:59], v[154:157], v[178:181], v[56:59]
	v_mfma_f32_16x16x32_bf16 v[52:55], v[146:149], v[196:199], v[52:55]
	v_mfma_f32_16x16x32_bf16 v[48:51], v[154:157], v[196:199], v[48:51]
	v_mfma_f32_16x16x32_bf16 v[36:39], v[146:149], v[204:207], v[36:39]
	v_mfma_f32_16x16x32_bf16 v[32:35], v[154:157], v[204:207], v[32:35]
	v_mfma_f32_16x16x32_bf16 v[20:23], v[146:149], v[212:215], v[20:23]
	v_mfma_f32_16x16x32_bf16 v[16:19], v[154:157], v[212:215], v[16:19]
	s_setprio 0
	s_setprio 1
	v_mfma_f32_16x16x32_bf16 v[44:47], v[158:161], v[174:177], v[44:47]
	v_mfma_f32_16x16x32_bf16 v[40:43], v[166:169], v[174:177], v[40:43]
	v_mfma_f32_16x16x32_bf16 v[28:31], v[158:161], v[182:185], v[28:31]
	v_mfma_f32_16x16x32_bf16 v[24:27], v[166:169], v[182:185], v[24:27]
	v_mfma_f32_16x16x32_bf16 v[12:15], v[158:161], v[200:203], v[12:15]
	v_mfma_f32_16x16x32_bf16 v[8:11], v[166:169], v[200:203], v[8:11]
	v_mfma_f32_16x16x32_bf16 v[4:7], v[158:161], v[208:211], v[4:7]
	v_mfma_f32_16x16x32_bf16 v[0:3], v[166:169], v[208:211], v[0:3]
	v_mfma_f32_16x16x32_bf16 v[44:47], v[162:165], v[178:181], v[44:47]
	v_mfma_f32_16x16x32_bf16 v[40:43], v[170:173], v[178:181], v[40:43]
	v_mfma_f32_16x16x32_bf16 v[28:31], v[162:165], v[196:199], v[28:31]
	v_mfma_f32_16x16x32_bf16 v[24:27], v[170:173], v[196:199], v[24:27]
	v_mfma_f32_16x16x32_bf16 v[12:15], v[162:165], v[204:207], v[12:15]
	v_mfma_f32_16x16x32_bf16 v[8:11], v[170:173], v[204:207], v[8:11]
	v_mfma_f32_16x16x32_bf16 v[4:7], v[162:165], v[212:215], v[4:7]
	v_mfma_f32_16x16x32_bf16 v[0:3], v[170:173], v[212:215], v[0:3]
	s_setprio 0
	s_barrier
	s_add_i32 s57, s57, 2
	s_add_u32 s28, s28, 0x100
	s_addc_u32 s29, s29, 0
	s_add_u32 s55, s55, 0x100
	s_addc_u32 s56, s56, 0
	s_cmp_gt_u32 s57, 29
	s_cbranch_scc1 .Lpeel_done_6
.LBB0_938:
	s_add_u32 s30, s28, 0xfff80080
	s_addc_u32 s31, s29, -1
	s_add_i32 s60, 0, 0x10000
	s_cmp_eq_u32 s57, 28
	s_cselect_b32 s35, s11, s31
	s_cselect_b32 s34, s23, s30
	s_cselect_b32 s31, s21, s56
	s_cselect_b32 s30, s53, s55
	s_add_i32 s66, 0, 0x14000
	v_add_u32_e32 v154, s60, v139
	v_add_u32_e32 v170, s66, v139
	ds_read_b128 v[142:145], v154
	ds_read_b128 v[146:149], v154 offset:1024
	ds_read_b128 v[150:153], v154 offset:2048
	ds_read_b128 v[154:157], v154 offset:3072
	ds_read_b128 v[158:161], v170
	ds_read_b128 v[162:165], v170 offset:1024
	ds_read_b128 v[166:169], v170 offset:2048
	ds_read_b128 v[170:173], v170 offset:3072
	v_lshl_add_u64 v[186:187], s[28:29], 0, v[134:135]
	s_add_i32 m0, s13, 0xc000
	ds_read_b128 v[174:177], v141
	ds_read_b128 v[178:181], v141 offset:1024
	ds_read_b128 v[182:185], v141 offset:2048
	ds_read_b128 v[196:199], v141 offset:3072
	ds_read_b128 v[200:203], v141 offset:4096
	ds_read_b128 v[204:207], v141 offset:5120
	ds_read_b128 v[208:211], v141 offset:6144
	ds_read_b128 v[212:215], v141 offset:7168
	global_load_lds_dwordx4 v[186:187], off
	s_add_i32 m0, s13, 0xe000
	v_lshl_add_u64 v[186:187], s[28:29], 0, v[136:137]
	global_load_lds_dwordx4 v[186:187], off
	s_waitcnt vmcnt(8) lgkmcnt(0)
	s_barrier
	s_setprio 1
	v_mfma_f32_16x16x32_bf16 v[124:127], v[142:145], v[174:177], v[124:127]
	v_mfma_f32_16x16x32_bf16 v[120:123], v[150:153], v[174:177], v[120:123]
	v_mfma_f32_16x16x32_bf16 v[116:119], v[142:145], v[182:185], v[116:119]
	v_mfma_f32_16x16x32_bf16 v[112:115], v[150:153], v[182:185], v[112:115]
	v_mfma_f32_16x16x32_bf16 v[100:103], v[142:145], v[200:203], v[100:103]
	v_mfma_f32_16x16x32_bf16 v[96:99], v[150:153], v[200:203], v[96:99]
	v_mfma_f32_16x16x32_bf16 v[84:87], v[142:145], v[208:211], v[84:87]
	v_mfma_f32_16x16x32_bf16 v[80:83], v[150:153], v[208:211], v[80:83]
	v_mfma_f32_16x16x32_bf16 v[124:127], v[146:149], v[178:181], v[124:127]
	v_mfma_f32_16x16x32_bf16 v[120:123], v[154:157], v[178:181], v[120:123]
	v_mfma_f32_16x16x32_bf16 v[116:119], v[146:149], v[196:199], v[116:119]
	v_mfma_f32_16x16x32_bf16 v[112:115], v[154:157], v[196:199], v[112:115]
	v_mfma_f32_16x16x32_bf16 v[100:103], v[146:149], v[204:207], v[100:103]
	v_mfma_f32_16x16x32_bf16 v[96:99], v[154:157], v[204:207], v[96:99]
	v_mfma_f32_16x16x32_bf16 v[84:87], v[146:149], v[212:215], v[84:87]
	v_mfma_f32_16x16x32_bf16 v[80:83], v[154:157], v[212:215], v[80:83]
	s_setprio 0
	s_setprio 1
	v_mfma_f32_16x16x32_bf16 v[108:111], v[158:161], v[174:177], v[108:111]
	v_mfma_f32_16x16x32_bf16 v[104:107], v[166:169], v[174:177], v[104:107]
	v_mfma_f32_16x16x32_bf16 v[92:95], v[158:161], v[182:185], v[92:95]
	v_mfma_f32_16x16x32_bf16 v[88:91], v[166:169], v[182:185], v[88:91]
	v_mfma_f32_16x16x32_bf16 v[76:79], v[158:161], v[200:203], v[76:79]
	v_mfma_f32_16x16x32_bf16 v[72:75], v[166:169], v[200:203], v[72:75]
	v_mfma_f32_16x16x32_bf16 v[68:71], v[158:161], v[208:211], v[68:71]
	v_mfma_f32_16x16x32_bf16 v[64:67], v[166:169], v[208:211], v[64:67]
	v_mfma_f32_16x16x32_bf16 v[108:111], v[162:165], v[178:181], v[108:111]
	v_mfma_f32_16x16x32_bf16 v[104:107], v[170:173], v[178:181], v[104:107]
	v_mfma_f32_16x16x32_bf16 v[92:95], v[162:165], v[196:199], v[92:95]
	v_mfma_f32_16x16x32_bf16 v[88:91], v[170:173], v[196:199], v[88:91]
	v_mfma_f32_16x16x32_bf16 v[76:79], v[162:165], v[204:207], v[76:79]
	v_mfma_f32_16x16x32_bf16 v[72:75], v[170:173], v[204:207], v[72:75]
	v_mfma_f32_16x16x32_bf16 v[68:71], v[162:165], v[212:215], v[68:71]
	v_mfma_f32_16x16x32_bf16 v[64:67], v[170:173], v[212:215], v[64:67]
	s_setprio 0
	s_barrier
	s_add_i32 s60, s60, s38
	v_lshl_add_u64 v[186:187], s[30:31], 0, v[190:191]
	s_mov_b32 m0, s60
	ds_read_b128 v[174:177], v141 offset:16384
	ds_read_b128 v[178:181], v141 offset:17408
	ds_read_b128 v[182:185], v141 offset:18432
	ds_read_b128 v[196:199], v141 offset:19456
	ds_read_b128 v[200:203], v141 offset:20480
	ds_read_b128 v[204:207], v141 offset:21504
	ds_read_b128 v[208:211], v141 offset:22528
	ds_read_b128 v[212:215], v141 offset:23552
	global_load_lds_dwordx4 v[186:187], off
	s_add_i32 m0, s60, 0x2000
	s_add_u32 s60, s30, 0x80000
	v_lshl_add_u64 v[216:217], s[30:31], 0, v[132:133]
	s_addc_u32 s61, s31, 0
	s_add_i32 s66, s66, s38
	global_load_lds_dwordx4 v[216:217], off
	v_lshl_add_u64 v[218:219], s[60:61], 0, v[190:191]
	s_mov_b32 m0, s66
	v_lshl_add_u64 v[220:221], s[34:35], 0, v[130:131]
	global_load_lds_dwordx4 v[218:219], off
	s_add_i32 m0, s66, 0x2000
	v_lshl_add_u64 v[218:219], s[60:61], 0, v[132:133]
	global_load_lds_dwordx4 v[218:219], off
	s_mov_b32 m0, s13
	v_lshl_add_u64 v[218:219], s[34:35], 0, v[128:129]
	global_load_lds_dwordx4 v[218:219], off
	s_mov_b32 m0, s39
	s_nop 0
	global_load_lds_dwordx4 v[220:221], off
	s_waitcnt vmcnt(8) lgkmcnt(0)
	s_barrier
	s_setprio 1
	v_mfma_f32_16x16x32_bf16 v[60:63], v[142:145], v[174:177], v[60:63]
	v_mfma_f32_16x16x32_bf16 v[56:59], v[150:153], v[174:177], v[56:59]
	v_mfma_f32_16x16x32_bf16 v[52:55], v[142:145], v[182:185], v[52:55]
	v_mfma_f32_16x16x32_bf16 v[48:51], v[150:153], v[182:185], v[48:51]
	v_mfma_f32_16x16x32_bf16 v[36:39], v[142:145], v[200:203], v[36:39]
	v_mfma_f32_16x16x32_bf16 v[32:35], v[150:153], v[200:203], v[32:35]
	v_mfma_f32_16x16x32_bf16 v[20:23], v[142:145], v[208:211], v[20:23]
	v_mfma_f32_16x16x32_bf16 v[16:19], v[150:153], v[208:211], v[16:19]
	v_mfma_f32_16x16x32_bf16 v[60:63], v[146:149], v[178:181], v[60:63]
	v_mfma_f32_16x16x32_bf16 v[56:59], v[154:157], v[178:181], v[56:59]
	v_mfma_f32_16x16x32_bf16 v[52:55], v[146:149], v[196:199], v[52:55]
	v_mfma_f32_16x16x32_bf16 v[48:51], v[154:157], v[196:199], v[48:51]
	v_mfma_f32_16x16x32_bf16 v[36:39], v[146:149], v[204:207], v[36:39]
	v_mfma_f32_16x16x32_bf16 v[32:35], v[154:157], v[204:207], v[32:35]
	v_mfma_f32_16x16x32_bf16 v[20:23], v[146:149], v[212:215], v[20:23]
	v_mfma_f32_16x16x32_bf16 v[16:19], v[154:157], v[212:215], v[16:19]
	s_setprio 0
	s_setprio 1
	v_mfma_f32_16x16x32_bf16 v[44:47], v[158:161], v[174:177], v[44:47]
	v_mfma_f32_16x16x32_bf16 v[40:43], v[166:169], v[174:177], v[40:43]
	v_mfma_f32_16x16x32_bf16 v[28:31], v[158:161], v[182:185], v[28:31]
	v_mfma_f32_16x16x32_bf16 v[24:27], v[166:169], v[182:185], v[24:27]
	v_mfma_f32_16x16x32_bf16 v[12:15], v[158:161], v[200:203], v[12:15]
	v_mfma_f32_16x16x32_bf16 v[8:11], v[166:169], v[200:203], v[8:11]
	v_mfma_f32_16x16x32_bf16 v[4:7], v[158:161], v[208:211], v[4:7]
	v_mfma_f32_16x16x32_bf16 v[0:3], v[166:169], v[208:211], v[0:3]
	v_mfma_f32_16x16x32_bf16 v[44:47], v[162:165], v[178:181], v[44:47]
	v_mfma_f32_16x16x32_bf16 v[40:43], v[170:173], v[178:181], v[40:43]
	v_mfma_f32_16x16x32_bf16 v[28:31], v[162:165], v[196:199], v[28:31]
	v_mfma_f32_16x16x32_bf16 v[24:27], v[170:173], v[196:199], v[24:27]
	v_mfma_f32_16x16x32_bf16 v[12:15], v[162:165], v[204:207], v[12:15]
	v_mfma_f32_16x16x32_bf16 v[8:11], v[170:173], v[204:207], v[8:11]
	v_mfma_f32_16x16x32_bf16 v[4:7], v[162:165], v[212:215], v[4:7]
	v_mfma_f32_16x16x32_bf16 v[0:3], v[170:173], v[212:215], v[0:3]
	s_setprio 0
	s_barrier
	s_add_i32 s60, 0, 0x18000
	s_add_i32 s61, 0, 0x1c000
	v_add_u32_e32 v154, s60, v139
	v_add_u32_e32 v170, s61, v139
	ds_read_b128 v[142:145], v154
	ds_read_b128 v[146:149], v154 offset:1024
	ds_read_b128 v[150:153], v154 offset:2048
	ds_read_b128 v[154:157], v154 offset:3072
	ds_read_b128 v[158:161], v170
	ds_read_b128 v[162:165], v170 offset:1024
	ds_read_b128 v[166:169], v170 offset:2048
	ds_read_b128 v[170:173], v170 offset:3072
	s_add_u32 s34, s34, 0x80000
	s_addc_u32 s35, s35, 0
	s_mov_b32 m0, s41
	v_lshl_add_u64 v[222:223], s[34:35], 0, v[128:129]
	ds_read_b128 v[174:177], v141 offset:32768
	ds_read_b128 v[178:181], v141 offset:33792
	ds_read_b128 v[182:185], v141 offset:34816
	ds_read_b128 v[196:199], v141 offset:35840
	ds_read_b128 v[200:203], v141 offset:36864
	ds_read_b128 v[204:207], v141 offset:37888
	ds_read_b128 v[208:211], v141 offset:38912
	ds_read_b128 v[212:215], v141 offset:39936
	global_load_lds_dwordx4 v[222:223], off
	s_mov_b32 m0, s42
	v_lshl_add_u64 v[222:223], s[34:35], 0, v[130:131]
	global_load_lds_dwordx4 v[222:223], off
	s_waitcnt vmcnt(8) lgkmcnt(0)
	s_barrier
	s_setprio 1
	v_mfma_f32_16x16x32_bf16 v[124:127], v[142:145], v[174:177], v[124:127]
	v_mfma_f32_16x16x32_bf16 v[120:123], v[150:153], v[174:177], v[120:123]
	v_mfma_f32_16x16x32_bf16 v[116:119], v[142:145], v[182:185], v[116:119]
	v_mfma_f32_16x16x32_bf16 v[112:115], v[150:153], v[182:185], v[112:115]
	v_mfma_f32_16x16x32_bf16 v[100:103], v[142:145], v[200:203], v[100:103]
	v_mfma_f32_16x16x32_bf16 v[96:99], v[150:153], v[200:203], v[96:99]
	v_mfma_f32_16x16x32_bf16 v[84:87], v[142:145], v[208:211], v[84:87]
	v_mfma_f32_16x16x32_bf16 v[80:83], v[150:153], v[208:211], v[80:83]
	v_mfma_f32_16x16x32_bf16 v[124:127], v[146:149], v[178:181], v[124:127]
	v_mfma_f32_16x16x32_bf16 v[120:123], v[154:157], v[178:181], v[120:123]
	v_mfma_f32_16x16x32_bf16 v[116:119], v[146:149], v[196:199], v[116:119]
	v_mfma_f32_16x16x32_bf16 v[112:115], v[154:157], v[196:199], v[112:115]
	v_mfma_f32_16x16x32_bf16 v[100:103], v[146:149], v[204:207], v[100:103]
	v_mfma_f32_16x16x32_bf16 v[96:99], v[154:157], v[204:207], v[96:99]
	v_mfma_f32_16x16x32_bf16 v[84:87], v[146:149], v[212:215], v[84:87]
	v_mfma_f32_16x16x32_bf16 v[80:83], v[154:157], v[212:215], v[80:83]
	s_setprio 0
	s_setprio 1
	v_mfma_f32_16x16x32_bf16 v[108:111], v[158:161], v[174:177], v[108:111]
	v_mfma_f32_16x16x32_bf16 v[104:107], v[166:169], v[174:177], v[104:107]
	v_mfma_f32_16x16x32_bf16 v[92:95], v[158:161], v[182:185], v[92:95]
	v_mfma_f32_16x16x32_bf16 v[88:91], v[166:169], v[182:185], v[88:91]
	v_mfma_f32_16x16x32_bf16 v[76:79], v[158:161], v[200:203], v[76:79]
	v_mfma_f32_16x16x32_bf16 v[72:75], v[166:169], v[200:203], v[72:75]
	v_mfma_f32_16x16x32_bf16 v[68:71], v[158:161], v[208:211], v[68:71]
	v_mfma_f32_16x16x32_bf16 v[64:67], v[166:169], v[208:211], v[64:67]
	v_mfma_f32_16x16x32_bf16 v[108:111], v[162:165], v[178:181], v[108:111]
	v_mfma_f32_16x16x32_bf16 v[104:107], v[170:173], v[178:181], v[104:107]
	v_mfma_f32_16x16x32_bf16 v[92:95], v[162:165], v[196:199], v[92:95]
	v_mfma_f32_16x16x32_bf16 v[88:91], v[170:173], v[196:199], v[88:91]
	v_mfma_f32_16x16x32_bf16 v[76:79], v[162:165], v[204:207], v[76:79]
	v_mfma_f32_16x16x32_bf16 v[72:75], v[170:173], v[204:207], v[72:75]
	v_mfma_f32_16x16x32_bf16 v[68:71], v[162:165], v[212:215], v[68:71]
	v_mfma_f32_16x16x32_bf16 v[64:67], v[170:173], v[212:215], v[64:67]
	s_setprio 0
	s_barrier
	s_add_i32 s34, s60, s38
	v_lshl_add_u64 v[186:187], v[186:187], 0, s[58:59]
	s_mov_b32 m0, s34
	ds_read_b128 v[174:177], v141 offset:49152
	ds_read_b128 v[178:181], v141 offset:50176
	ds_read_b128 v[182:185], v141 offset:51200
	ds_read_b128 v[196:199], v141 offset:52224
	ds_read_b128 v[200:203], v141 offset:53248
	ds_read_b128 v[204:207], v141 offset:54272
	ds_read_b128 v[208:211], v141 offset:55296
	ds_read_b128 v[212:215], v141 offset:56320
	global_load_lds_dwordx4 v[186:187], off
	s_add_i32 m0, s34, 0x2000
	s_add_u32 s30, s30, 0x80080
	v_lshl_add_u64 v[186:187], v[216:217], 0, s[58:59]
	s_addc_u32 s31, s31, 0
	s_add_i32 s34, s61, s38
	global_load_lds_dwordx4 v[186:187], off
	s_mov_b32 m0, s34
	v_lshl_add_u64 v[186:187], s[30:31], 0, v[190:191]
	global_load_lds_dwordx4 v[186:187], off
	s_add_i32 m0, s34, 0x2000
	v_lshl_add_u64 v[186:187], s[30:31], 0, v[132:133]
	global_load_lds_dwordx4 v[186:187], off
	s_mov_b32 m0, s43
	v_lshl_add_u64 v[186:187], v[218:219], 0, s[58:59]
	global_load_lds_dwordx4 v[186:187], off
	s_mov_b32 m0, s47
	v_lshl_add_u64 v[186:187], v[220:221], 0, s[58:59]
	global_load_lds_dwordx4 v[186:187], off
	s_waitcnt vmcnt(8) lgkmcnt(0)
	s_barrier
	s_setprio 1
	v_mfma_f32_16x16x32_bf16 v[60:63], v[142:145], v[174:177], v[60:63]
	v_mfma_f32_16x16x32_bf16 v[56:59], v[150:153], v[174:177], v[56:59]
	v_mfma_f32_16x16x32_bf16 v[52:55], v[142:145], v[182:185], v[52:55]
	v_mfma_f32_16x16x32_bf16 v[48:51], v[150:153], v[182:185], v[48:51]
	v_mfma_f32_16x16x32_bf16 v[36:39], v[142:145], v[200:203], v[36:39]
	v_mfma_f32_16x16x32_bf16 v[32:35], v[150:153], v[200:203], v[32:35]
	v_mfma_f32_16x16x32_bf16 v[20:23], v[142:145], v[208:211], v[20:23]
	v_mfma_f32_16x16x32_bf16 v[16:19], v[150:153], v[208:211], v[16:19]
	v_mfma_f32_16x16x32_bf16 v[60:63], v[146:149], v[178:181], v[60:63]
	v_mfma_f32_16x16x32_bf16 v[56:59], v[154:157], v[178:181], v[56:59]
	v_mfma_f32_16x16x32_bf16 v[52:55], v[146:149], v[196:199], v[52:55]
	v_mfma_f32_16x16x32_bf16 v[48:51], v[154:157], v[196:199], v[48:51]
	v_mfma_f32_16x16x32_bf16 v[36:39], v[146:149], v[204:207], v[36:39]
	v_mfma_f32_16x16x32_bf16 v[32:35], v[154:157], v[204:207], v[32:35]
	v_mfma_f32_16x16x32_bf16 v[20:23], v[146:149], v[212:215], v[20:23]
	v_mfma_f32_16x16x32_bf16 v[16:19], v[154:157], v[212:215], v[16:19]
	s_setprio 0
	s_setprio 1
	v_mfma_f32_16x16x32_bf16 v[44:47], v[158:161], v[174:177], v[44:47]
	v_mfma_f32_16x16x32_bf16 v[40:43], v[166:169], v[174:177], v[40:43]
	v_mfma_f32_16x16x32_bf16 v[28:31], v[158:161], v[182:185], v[28:31]
	v_mfma_f32_16x16x32_bf16 v[24:27], v[166:169], v[182:185], v[24:27]
	v_mfma_f32_16x16x32_bf16 v[12:15], v[158:161], v[200:203], v[12:15]
	v_mfma_f32_16x16x32_bf16 v[8:11], v[166:169], v[200:203], v[8:11]
	v_mfma_f32_16x16x32_bf16 v[4:7], v[158:161], v[208:211], v[4:7]
	v_mfma_f32_16x16x32_bf16 v[0:3], v[166:169], v[208:211], v[0:3]
	v_mfma_f32_16x16x32_bf16 v[44:47], v[162:165], v[178:181], v[44:47]
	v_mfma_f32_16x16x32_bf16 v[40:43], v[170:173], v[178:181], v[40:43]
	v_mfma_f32_16x16x32_bf16 v[28:31], v[162:165], v[196:199], v[28:31]
	v_mfma_f32_16x16x32_bf16 v[24:27], v[170:173], v[196:199], v[24:27]
	v_mfma_f32_16x16x32_bf16 v[12:15], v[162:165], v[204:207], v[12:15]
	v_mfma_f32_16x16x32_bf16 v[8:11], v[170:173], v[204:207], v[8:11]
	v_mfma_f32_16x16x32_bf16 v[4:7], v[162:165], v[212:215], v[4:7]
	v_mfma_f32_16x16x32_bf16 v[0:3], v[170:173], v[212:215], v[0:3]
	s_setprio 0
	s_barrier
	s_add_i32 s57, s57, 2
	s_add_u32 s28, s28, 0x100
	s_addc_u32 s29, s29, 0
	s_add_u32 s55, s55, 0x100
	s_addc_u32 s56, s56, 0
	s_cmp_gt_u32 s57, 29
	s_cbranch_scc0 .LBB0_938

.LBB0_1104:
	s_ashr_i32 s61, s60, 31
	s_lshl_b64 s[52:53], s[60:61], 20
	v_readlane_b32 s0, v254, 17
	v_readlane_b32 s1, v254, 18
	s_add_u32 s88, s0, s52
	s_addc_u32 s89, s1, s53
	s_and_b64 s[52:53], s[8:9], exec
	s_cselect_b32 s13, s89, s11
	s_cselect_b32 s15, s88, s10
	s_ashr_i32 s57, s56, 31
	s_lshl_b64 s[52:53], s[56:57], 20
	v_readlane_b32 s0, v254, 36
	v_readlane_b32 s1, v254, 37
	s_add_u32 s90, s0, s52
	s_addc_u32 s91, s1, s53
	s_and_b64 s[52:53], s[8:9], exec
	s_cselect_b32 s57, s91, s17
	s_cselect_b32 s61, s90, s16
	s_add_u32 s66, s16, 0x100
	s_addc_u32 s67, s17, 0
	s_mov_b32 vcc_lo, -2
	v_readlane_b32 s0, v255, 49
	s_nop 3
	s_cmp_eq_u32 s0, 8
	v_writelane_b32 v255, 8, 49
	s_cbranch_scc0 .Ltrip0_strict_7
	s_add_u32 s16, s10, 0x100
	s_addc_u32 s17, s11, 0
	s_add_i32 vcc_hi, 0, 0x10000
	s_cmp_eq_u32 vcc_lo, 28
	s_cselect_b32 s69, s13, s17
	s_cselect_b32 s68, s15, s16
	s_cselect_b32 s53, s57, s67
	s_cselect_b32 s52, s61, s66
	s_add_i32 s0, 0, 0x14000
	v_add_u32_e32 v140, vcc_hi, v200
	v_add_u32_e32 v156, s0, v200
	ds_read_b128 v[128:131], v140
	ds_read_b128 v[132:135], v140 offset:1024
	ds_read_b128 v[136:139], v140 offset:2048
	ds_read_b128 v[140:143], v140 offset:3072
	ds_read_b128 v[144:147], v156
	ds_read_b128 v[148:151], v156 offset:1024
	ds_read_b128 v[152:155], v156 offset:2048
	ds_read_b128 v[156:159], v156 offset:3072
	v_lshl_add_u64 v[186:187], s[10:11], 0, v[182:183]
	s_add_i32 m0, s40, 0xc000
	ds_read_b128 v[160:163], v206
	ds_read_b128 v[164:167], v206 offset:1024
	ds_read_b128 v[168:171], v206 offset:2048
	ds_read_b128 v[172:175], v206 offset:3072
	ds_read_b128 v[196:199], v206 offset:4096
	ds_read_b128 v[208:211], v206 offset:5120
	ds_read_b128 v[212:215], v206 offset:6144
	ds_read_b128 v[216:219], v206 offset:7168
	global_load_lds_dwordx4 v[186:187], off
	s_add_i32 m0, s40, 0xe000
	v_lshl_add_u64 v[186:187], s[10:11], 0, v[184:185]
	global_load_lds_dwordx4 v[186:187], off
	s_waitcnt vmcnt(24) lgkmcnt(0)
	s_barrier
	s_setprio 1
	v_mfma_f32_16x16x32_bf16 v[120:123], v[128:131], v[160:163], 0
	v_mfma_f32_16x16x32_bf16 v[48:51], v[136:139], v[160:163], 0
	v_mfma_f32_16x16x32_bf16 v[124:127], v[128:131], v[168:171], 0
	v_mfma_f32_16x16x32_bf16 v[60:63], v[136:139], v[168:171], 0
	v_mfma_f32_16x16x32_bf16 v[112:115], v[128:131], v[196:199], 0
	v_mfma_f32_16x16x32_bf16 v[52:55], v[136:139], v[196:199], 0
	v_mfma_f32_16x16x32_bf16 v[108:111], v[128:131], v[212:215], 0
	v_mfma_f32_16x16x32_bf16 v[36:39], v[136:139], v[212:215], 0
	v_mfma_f32_16x16x32_bf16 v[120:123], v[132:135], v[164:167], v[120:123]
	v_mfma_f32_16x16x32_bf16 v[48:51], v[140:143], v[164:167], v[48:51]
	v_mfma_f32_16x16x32_bf16 v[124:127], v[132:135], v[172:175], v[124:127]
	v_mfma_f32_16x16x32_bf16 v[60:63], v[140:143], v[172:175], v[60:63]
	v_mfma_f32_16x16x32_bf16 v[112:115], v[132:135], v[208:211], v[112:115]
	v_mfma_f32_16x16x32_bf16 v[52:55], v[140:143], v[208:211], v[52:55]
	v_mfma_f32_16x16x32_bf16 v[108:111], v[132:135], v[216:219], v[108:111]
	v_mfma_f32_16x16x32_bf16 v[36:39], v[140:143], v[216:219], v[36:39]
	s_setprio 0
	s_setprio 1
	v_mfma_f32_16x16x32_bf16 v[100:103], v[144:147], v[160:163], 0
	v_mfma_f32_16x16x32_bf16 v[40:43], v[152:155], v[160:163], 0
	v_mfma_f32_16x16x32_bf16 v[116:119], v[144:147], v[168:171], 0
	v_mfma_f32_16x16x32_bf16 v[56:59], v[152:155], v[168:171], 0
	v_mfma_f32_16x16x32_bf16 v[104:107], v[144:147], v[196:199], 0
	v_mfma_f32_16x16x32_bf16 v[44:47], v[152:155], v[196:199], 0
	v_mfma_f32_16x16x32_bf16 v[96:99], v[144:147], v[212:215], 0
	v_mfma_f32_16x16x32_bf16 v[32:35], v[152:155], v[212:215], 0
	v_mfma_f32_16x16x32_bf16 v[100:103], v[148:151], v[164:167], v[100:103]
	v_mfma_f32_16x16x32_bf16 v[40:43], v[156:159], v[164:167], v[40:43]
	v_mfma_f32_16x16x32_bf16 v[116:119], v[148:151], v[172:175], v[116:119]
	v_mfma_f32_16x16x32_bf16 v[56:59], v[156:159], v[172:175], v[56:59]
	v_mfma_f32_16x16x32_bf16 v[104:107], v[148:151], v[208:211], v[104:107]
	v_mfma_f32_16x16x32_bf16 v[44:47], v[156:159], v[208:211], v[44:47]
	v_mfma_f32_16x16x32_bf16 v[96:99], v[148:151], v[216:219], v[96:99]
	v_mfma_f32_16x16x32_bf16 v[32:35], v[156:159], v[216:219], v[32:35]
	s_setprio 0
	s_barrier
	s_add_i32 s1, vcc_hi, s33
	v_lshl_add_u64 v[186:187], s[52:53], 0, v[190:191]
	s_mov_b32 m0, s1
	ds_read_b128 v[160:163], v206 offset:16384
	ds_read_b128 v[164:167], v206 offset:17408
	ds_read_b128 v[168:171], v206 offset:18432
	ds_read_b128 v[172:175], v206 offset:19456
	ds_read_b128 v[196:199], v206 offset:20480
	ds_read_b128 v[208:211], v206 offset:21504
	ds_read_b128 v[212:215], v206 offset:22528
	ds_read_b128 v[216:219], v206 offset:23552
	global_load_lds_dwordx4 v[186:187], off
	s_add_i32 m0, s1, 0x2000
	s_add_u32 s10, s52, 0x80000
	v_lshl_add_u64 v[220:221], s[52:53], 0, v[180:181]
	s_addc_u32 s11, s53, 0
	s_add_i32 s0, s0, s33
	global_load_lds_dwordx4 v[220:221], off
	v_lshl_add_u64 v[222:223], s[10:11], 0, v[190:191]
	s_mov_b32 m0, s0
	v_lshl_add_u64 v[224:225], s[68:69], 0, v[178:179]
	global_load_lds_dwordx4 v[222:223], off
	s_add_i32 m0, s0, 0x2000
	v_lshl_add_u64 v[222:223], s[10:11], 0, v[180:181]
	global_load_lds_dwordx4 v[222:223], off
	s_mov_b32 m0, s40
	v_lshl_add_u64 v[222:223], s[68:69], 0, v[176:177]
	global_load_lds_dwordx4 v[222:223], off
	s_mov_b32 m0, s41
	s_nop 0
	global_load_lds_dwordx4 v[224:225], off
	s_waitcnt vmcnt(24) lgkmcnt(0)
	s_barrier
	s_setprio 1
	v_mfma_f32_16x16x32_bf16 v[88:91], v[128:131], v[160:163], 0
	v_mfma_f32_16x16x32_bf16 v[20:23], v[136:139], v[160:163], 0
	v_mfma_f32_16x16x32_bf16 v[92:95], v[128:131], v[168:171], 0
	v_mfma_f32_16x16x32_bf16 v[28:31], v[136:139], v[168:171], 0
	v_mfma_f32_16x16x32_bf16 v[80:83], v[128:131], v[196:199], 0
	v_mfma_f32_16x16x32_bf16 v[16:19], v[136:139], v[196:199], 0
	v_mfma_f32_16x16x32_bf16 v[76:79], v[128:131], v[212:215], 0
	v_mfma_f32_16x16x32_bf16 v[12:15], v[136:139], v[212:215], 0
	v_mfma_f32_16x16x32_bf16 v[88:91], v[132:135], v[164:167], v[88:91]
	v_mfma_f32_16x16x32_bf16 v[20:23], v[140:143], v[164:167], v[20:23]
	v_mfma_f32_16x16x32_bf16 v[92:95], v[132:135], v[172:175], v[92:95]
	v_mfma_f32_16x16x32_bf16 v[28:31], v[140:143], v[172:175], v[28:31]
	v_mfma_f32_16x16x32_bf16 v[80:83], v[132:135], v[208:211], v[80:83]
	v_mfma_f32_16x16x32_bf16 v[16:19], v[140:143], v[208:211], v[16:19]
	v_mfma_f32_16x16x32_bf16 v[76:79], v[132:135], v[216:219], v[76:79]
	v_mfma_f32_16x16x32_bf16 v[12:15], v[140:143], v[216:219], v[12:15]
	s_setprio 0
	s_setprio 1
	v_mfma_f32_16x16x32_bf16 v[68:71], v[144:147], v[160:163], 0
	v_mfma_f32_16x16x32_bf16 v[4:7], v[152:155], v[160:163], 0
	v_mfma_f32_16x16x32_bf16 v[84:87], v[144:147], v[168:171], 0
	v_mfma_f32_16x16x32_bf16 v[24:27], v[152:155], v[168:171], 0
	v_mfma_f32_16x16x32_bf16 v[72:75], v[144:147], v[196:199], 0
	v_mfma_f32_16x16x32_bf16 v[8:11], v[152:155], v[196:199], 0
	v_mfma_f32_16x16x32_bf16 v[64:67], v[144:147], v[212:215], 0
	v_mfma_f32_16x16x32_bf16 v[0:3], v[152:155], v[212:215], 0
	v_mfma_f32_16x16x32_bf16 v[68:71], v[148:151], v[164:167], v[68:71]
	v_mfma_f32_16x16x32_bf16 v[4:7], v[156:159], v[164:167], v[4:7]
	v_mfma_f32_16x16x32_bf16 v[84:87], v[148:151], v[172:175], v[84:87]
	v_mfma_f32_16x16x32_bf16 v[24:27], v[156:159], v[172:175], v[24:27]
	v_mfma_f32_16x16x32_bf16 v[72:75], v[148:151], v[208:211], v[72:75]
	v_mfma_f32_16x16x32_bf16 v[8:11], v[156:159], v[208:211], v[8:11]
	v_mfma_f32_16x16x32_bf16 v[64:67], v[148:151], v[216:219], v[64:67]
	v_mfma_f32_16x16x32_bf16 v[0:3], v[156:159], v[216:219], v[0:3]
	s_setprio 0
	s_barrier
	s_add_i32 s0, 0, 0x18000
	s_add_i32 s1, 0, 0x1c000
	v_add_u32_e32 v140, s0, v200
	v_add_u32_e32 v156, s1, v200
	ds_read_b128 v[128:131], v140
	ds_read_b128 v[132:135], v140 offset:1024
	ds_read_b128 v[136:139], v140 offset:2048
	ds_read_b128 v[140:143], v140 offset:3072
	ds_read_b128 v[144:147], v156
	ds_read_b128 v[148:151], v156 offset:1024
	ds_read_b128 v[152:155], v156 offset:2048
	ds_read_b128 v[156:159], v156 offset:3072
	s_add_u32 s10, s68, 0x80000
	s_addc_u32 s11, s69, 0
	s_mov_b32 m0, s42
	v_lshl_add_u64 v[226:227], s[10:11], 0, v[176:177]
	ds_read_b128 v[160:163], v206 offset:32768
	ds_read_b128 v[164:167], v206 offset:33792
	ds_read_b128 v[168:171], v206 offset:34816
	ds_read_b128 v[172:175], v206 offset:35840
	ds_read_b128 v[196:199], v206 offset:36864
	ds_read_b128 v[208:211], v206 offset:37888
	ds_read_b128 v[212:215], v206 offset:38912
	ds_read_b128 v[216:219], v206 offset:39936
	global_load_lds_dwordx4 v[226:227], off
	s_mov_b32 m0, s43
	v_lshl_add_u64 v[226:227], s[10:11], 0, v[178:179]
	global_load_lds_dwordx4 v[226:227], off
	s_waitcnt vmcnt(8) lgkmcnt(0)
	s_barrier
	s_setprio 1
	v_mfma_f32_16x16x32_bf16 v[120:123], v[128:131], v[160:163], v[120:123]
	v_mfma_f32_16x16x32_bf16 v[48:51], v[136:139], v[160:163], v[48:51]
	v_mfma_f32_16x16x32_bf16 v[124:127], v[128:131], v[168:171], v[124:127]
	v_mfma_f32_16x16x32_bf16 v[60:63], v[136:139], v[168:171], v[60:63]
	v_mfma_f32_16x16x32_bf16 v[112:115], v[128:131], v[196:199], v[112:115]
	v_mfma_f32_16x16x32_bf16 v[52:55], v[136:139], v[196:199], v[52:55]
	v_mfma_f32_16x16x32_bf16 v[108:111], v[128:131], v[212:215], v[108:111]
	v_mfma_f32_16x16x32_bf16 v[36:39], v[136:139], v[212:215], v[36:39]
	v_mfma_f32_16x16x32_bf16 v[120:123], v[132:135], v[164:167], v[120:123]
	v_mfma_f32_16x16x32_bf16 v[48:51], v[140:143], v[164:167], v[48:51]
	v_mfma_f32_16x16x32_bf16 v[124:127], v[132:135], v[172:175], v[124:127]
	v_mfma_f32_16x16x32_bf16 v[60:63], v[140:143], v[172:175], v[60:63]
	v_mfma_f32_16x16x32_bf16 v[112:115], v[132:135], v[208:211], v[112:115]
	v_mfma_f32_16x16x32_bf16 v[52:55], v[140:143], v[208:211], v[52:55]
	v_mfma_f32_16x16x32_bf16 v[108:111], v[132:135], v[216:219], v[108:111]
	v_mfma_f32_16x16x32_bf16 v[36:39], v[140:143], v[216:219], v[36:39]
	s_setprio 0
	s_setprio 1
	v_mfma_f32_16x16x32_bf16 v[100:103], v[144:147], v[160:163], v[100:103]
	v_mfma_f32_16x16x32_bf16 v[40:43], v[152:155], v[160:163], v[40:43]
	v_mfma_f32_16x16x32_bf16 v[116:119], v[144:147], v[168:171], v[116:119]
	v_mfma_f32_16x16x32_bf16 v[56:59], v[152:155], v[168:171], v[56:59]
	v_mfma_f32_16x16x32_bf16 v[104:107], v[144:147], v[196:199], v[104:107]
	v_mfma_f32_16x16x32_bf16 v[44:47], v[152:155], v[196:199], v[44:47]
	v_mfma_f32_16x16x32_bf16 v[96:99], v[144:147], v[212:215], v[96:99]
	v_mfma_f32_16x16x32_bf16 v[32:35], v[152:155], v[212:215], v[32:35]
	v_mfma_f32_16x16x32_bf16 v[100:103], v[148:151], v[164:167], v[100:103]
	v_mfma_f32_16x16x32_bf16 v[40:43], v[156:159], v[164:167], v[40:43]
	v_mfma_f32_16x16x32_bf16 v[116:119], v[148:151], v[172:175], v[116:119]
	v_mfma_f32_16x16x32_bf16 v[56:59], v[156:159], v[172:175], v[56:59]
	v_mfma_f32_16x16x32_bf16 v[104:107], v[148:151], v[208:211], v[104:107]
	v_mfma_f32_16x16x32_bf16 v[44:47], v[156:159], v[208:211], v[44:47]
	v_mfma_f32_16x16x32_bf16 v[96:99], v[148:151], v[216:219], v[96:99]
	v_mfma_f32_16x16x32_bf16 v[32:35], v[156:159], v[216:219], v[32:35]
	s_setprio 0
	s_barrier
	s_add_i32 s0, s0, s33
	v_lshl_add_u64 v[186:187], v[186:187], 0, s[58:59]
	s_mov_b32 m0, s0
	ds_read_b128 v[160:163], v206 offset:49152
	ds_read_b128 v[164:167], v206 offset:50176
	ds_read_b128 v[168:171], v206 offset:51200
	ds_read_b128 v[172:175], v206 offset:52224
	ds_read_b128 v[196:199], v206 offset:53248
	ds_read_b128 v[208:211], v206 offset:54272
	ds_read_b128 v[212:215], v206 offset:55296
	ds_read_b128 v[216:219], v206 offset:56320
	global_load_lds_dwordx4 v[186:187], off
	s_add_i32 m0, s0, 0x2000
	s_add_u32 s10, s52, 0x80080
	v_lshl_add_u64 v[186:187], v[220:221], 0, s[58:59]
	s_addc_u32 s11, s53, 0
	s_add_i32 s0, s1, s33
	global_load_lds_dwordx4 v[186:187], off
	s_mov_b32 m0, s0
	v_lshl_add_u64 v[186:187], s[10:11], 0, v[190:191]
	global_load_lds_dwordx4 v[186:187], off
	s_add_i32 m0, s0, 0x2000
	v_lshl_add_u64 v[186:187], s[10:11], 0, v[180:181]
	global_load_lds_dwordx4 v[186:187], off
	s_mov_b32 m0, s55
	v_lshl_add_u64 v[186:187], v[222:223], 0, s[58:59]
	global_load_lds_dwordx4 v[186:187], off
	s_mov_b32 m0, s77
	v_lshl_add_u64 v[186:187], v[224:225], 0, s[58:59]
	global_load_lds_dwordx4 v[186:187], off
	s_waitcnt vmcnt(8) lgkmcnt(0)
	s_barrier
	s_setprio 1
	v_mfma_f32_16x16x32_bf16 v[88:91], v[128:131], v[160:163], v[88:91]
	v_mfma_f32_16x16x32_bf16 v[20:23], v[136:139], v[160:163], v[20:23]
	v_mfma_f32_16x16x32_bf16 v[92:95], v[128:131], v[168:171], v[92:95]
	v_mfma_f32_16x16x32_bf16 v[28:31], v[136:139], v[168:171], v[28:31]
	v_mfma_f32_16x16x32_bf16 v[80:83], v[128:131], v[196:199], v[80:83]
	v_mfma_f32_16x16x32_bf16 v[16:19], v[136:139], v[196:199], v[16:19]
	v_mfma_f32_16x16x32_bf16 v[76:79], v[128:131], v[212:215], v[76:79]
	v_mfma_f32_16x16x32_bf16 v[12:15], v[136:139], v[212:215], v[12:15]
	v_mfma_f32_16x16x32_bf16 v[88:91], v[132:135], v[164:167], v[88:91]
	v_mfma_f32_16x16x32_bf16 v[20:23], v[140:143], v[164:167], v[20:23]
	v_mfma_f32_16x16x32_bf16 v[92:95], v[132:135], v[172:175], v[92:95]
	v_mfma_f32_16x16x32_bf16 v[28:31], v[140:143], v[172:175], v[28:31]
	v_mfma_f32_16x16x32_bf16 v[80:83], v[132:135], v[208:211], v[80:83]
	v_mfma_f32_16x16x32_bf16 v[16:19], v[140:143], v[208:211], v[16:19]
	v_mfma_f32_16x16x32_bf16 v[76:79], v[132:135], v[216:219], v[76:79]
	v_mfma_f32_16x16x32_bf16 v[12:15], v[140:143], v[216:219], v[12:15]
	s_setprio 0
	s_setprio 1
	v_mfma_f32_16x16x32_bf16 v[68:71], v[144:147], v[160:163], v[68:71]
	v_mfma_f32_16x16x32_bf16 v[4:7], v[152:155], v[160:163], v[4:7]
	v_mfma_f32_16x16x32_bf16 v[84:87], v[144:147], v[168:171], v[84:87]
	v_mfma_f32_16x16x32_bf16 v[24:27], v[152:155], v[168:171], v[24:27]
	v_mfma_f32_16x16x32_bf16 v[72:75], v[144:147], v[196:199], v[72:75]
	v_mfma_f32_16x16x32_bf16 v[8:11], v[152:155], v[196:199], v[8:11]
	v_mfma_f32_16x16x32_bf16 v[64:67], v[144:147], v[212:215], v[64:67]
	v_mfma_f32_16x16x32_bf16 v[0:3], v[152:155], v[212:215], v[0:3]
	v_mfma_f32_16x16x32_bf16 v[68:71], v[148:151], v[164:167], v[68:71]
	v_mfma_f32_16x16x32_bf16 v[4:7], v[156:159], v[164:167], v[4:7]
	v_mfma_f32_16x16x32_bf16 v[84:87], v[148:151], v[172:175], v[84:87]
	v_mfma_f32_16x16x32_bf16 v[24:27], v[156:159], v[172:175], v[24:27]
	v_mfma_f32_16x16x32_bf16 v[72:75], v[148:151], v[208:211], v[72:75]
	v_mfma_f32_16x16x32_bf16 v[8:11], v[156:159], v[208:211], v[8:11]
	v_mfma_f32_16x16x32_bf16 v[64:67], v[148:151], v[216:219], v[64:67]
	v_mfma_f32_16x16x32_bf16 v[0:3], v[156:159], v[216:219], v[0:3]
	s_setprio 0
	s_barrier
	s_add_i32 vcc_lo, vcc_lo, 2
	s_add_u32 s66, s66, 0x100
	s_addc_u32 s67, s67, 0
	s_cmp_gt_u32 vcc_lo, 29
	s_mov_b64 s[10:11], s[16:17]
	s_cbranch_scc1 .Lpeel_done_7
	s_branch .LBB0_1105
.Ltrip0_strict_7:
	s_add_u32 s16, s10, 0x100
	s_addc_u32 s17, s11, 0
	s_add_i32 vcc_hi, 0, 0x10000
	s_cmp_eq_u32 vcc_lo, 28
	s_cselect_b32 s69, s13, s17
	s_cselect_b32 s68, s15, s16
	s_cselect_b32 s53, s57, s67
	s_cselect_b32 s52, s61, s66
	s_add_i32 s0, 0, 0x14000
	v_add_u32_e32 v140, vcc_hi, v200
	v_add_u32_e32 v156, s0, v200
	ds_read_b128 v[128:131], v140
	ds_read_b128 v[132:135], v140 offset:1024
	ds_read_b128 v[136:139], v140 offset:2048
	ds_read_b128 v[140:143], v140 offset:3072
	ds_read_b128 v[144:147], v156
	ds_read_b128 v[148:151], v156 offset:1024
	ds_read_b128 v[152:155], v156 offset:2048
	ds_read_b128 v[156:159], v156 offset:3072
	v_lshl_add_u64 v[186:187], s[10:11], 0, v[182:183]
	s_add_i32 m0, s40, 0xc000
	ds_read_b128 v[160:163], v206
	ds_read_b128 v[164:167], v206 offset:1024
	ds_read_b128 v[168:171], v206 offset:2048
	ds_read_b128 v[172:175], v206 offset:3072
	ds_read_b128 v[196:199], v206 offset:4096
	ds_read_b128 v[208:211], v206 offset:5120
	ds_read_b128 v[212:215], v206 offset:6144
	ds_read_b128 v[216:219], v206 offset:7168
	global_load_lds_dwordx4 v[186:187], off
	s_add_i32 m0, s40, 0xe000
	v_lshl_add_u64 v[186:187], s[10:11], 0, v[184:185]
	global_load_lds_dwordx4 v[186:187], off
	s_waitcnt vmcnt(8) lgkmcnt(0)
	s_barrier
	s_setprio 1
	v_mfma_f32_16x16x32_bf16 v[120:123], v[128:131], v[160:163], 0
	v_mfma_f32_16x16x32_bf16 v[48:51], v[136:139], v[160:163], 0
	v_mfma_f32_16x16x32_bf16 v[124:127], v[128:131], v[168:171], 0
	v_mfma_f32_16x16x32_bf16 v[60:63], v[136:139], v[168:171], 0
	v_mfma_f32_16x16x32_bf16 v[112:115], v[128:131], v[196:199], 0
	v_mfma_f32_16x16x32_bf16 v[52:55], v[136:139], v[196:199], 0
	v_mfma_f32_16x16x32_bf16 v[108:111], v[128:131], v[212:215], 0
	v_mfma_f32_16x16x32_bf16 v[36:39], v[136:139], v[212:215], 0
	v_mfma_f32_16x16x32_bf16 v[120:123], v[132:135], v[164:167], v[120:123]
	v_mfma_f32_16x16x32_bf16 v[48:51], v[140:143], v[164:167], v[48:51]
	v_mfma_f32_16x16x32_bf16 v[124:127], v[132:135], v[172:175], v[124:127]
	v_mfma_f32_16x16x32_bf16 v[60:63], v[140:143], v[172:175], v[60:63]
	v_mfma_f32_16x16x32_bf16 v[112:115], v[132:135], v[208:211], v[112:115]
	v_mfma_f32_16x16x32_bf16 v[52:55], v[140:143], v[208:211], v[52:55]
	v_mfma_f32_16x16x32_bf16 v[108:111], v[132:135], v[216:219], v[108:111]
	v_mfma_f32_16x16x32_bf16 v[36:39], v[140:143], v[216:219], v[36:39]
	s_setprio 0
	s_setprio 1
	v_mfma_f32_16x16x32_bf16 v[100:103], v[144:147], v[160:163], 0
	v_mfma_f32_16x16x32_bf16 v[40:43], v[152:155], v[160:163], 0
	v_mfma_f32_16x16x32_bf16 v[116:119], v[144:147], v[168:171], 0
	v_mfma_f32_16x16x32_bf16 v[56:59], v[152:155], v[168:171], 0
	v_mfma_f32_16x16x32_bf16 v[104:107], v[144:147], v[196:199], 0
	v_mfma_f32_16x16x32_bf16 v[44:47], v[152:155], v[196:199], 0
	v_mfma_f32_16x16x32_bf16 v[96:99], v[144:147], v[212:215], 0
	v_mfma_f32_16x16x32_bf16 v[32:35], v[152:155], v[212:215], 0
	v_mfma_f32_16x16x32_bf16 v[100:103], v[148:151], v[164:167], v[100:103]
	v_mfma_f32_16x16x32_bf16 v[40:43], v[156:159], v[164:167], v[40:43]
	v_mfma_f32_16x16x32_bf16 v[116:119], v[148:151], v[172:175], v[116:119]
	v_mfma_f32_16x16x32_bf16 v[56:59], v[156:159], v[172:175], v[56:59]
	v_mfma_f32_16x16x32_bf16 v[104:107], v[148:151], v[208:211], v[104:107]
	v_mfma_f32_16x16x32_bf16 v[44:47], v[156:159], v[208:211], v[44:47]
	v_mfma_f32_16x16x32_bf16 v[96:99], v[148:151], v[216:219], v[96:99]
	v_mfma_f32_16x16x32_bf16 v[32:35], v[156:159], v[216:219], v[32:35]
	s_setprio 0
	s_barrier
	s_add_i32 s1, vcc_hi, s33
	v_lshl_add_u64 v[186:187], s[52:53], 0, v[190:191]
	s_mov_b32 m0, s1
	ds_read_b128 v[160:163], v206 offset:16384
	ds_read_b128 v[164:167], v206 offset:17408
	ds_read_b128 v[168:171], v206 offset:18432
	ds_read_b128 v[172:175], v206 offset:19456
	ds_read_b128 v[196:199], v206 offset:20480
	ds_read_b128 v[208:211], v206 offset:21504
	ds_read_b128 v[212:215], v206 offset:22528
	ds_read_b128 v[216:219], v206 offset:23552
	global_load_lds_dwordx4 v[186:187], off
	s_add_i32 m0, s1, 0x2000
	s_add_u32 s10, s52, 0x80000
	v_lshl_add_u64 v[220:221], s[52:53], 0, v[180:181]
	s_addc_u32 s11, s53, 0
	s_add_i32 s0, s0, s33
	global_load_lds_dwordx4 v[220:221], off
	v_lshl_add_u64 v[222:223], s[10:11], 0, v[190:191]
	s_mov_b32 m0, s0
	v_lshl_add_u64 v[224:225], s[68:69], 0, v[178:179]
	global_load_lds_dwordx4 v[222:223], off
	s_add_i32 m0, s0, 0x2000
	v_lshl_add_u64 v[222:223], s[10:11], 0, v[180:181]
	global_load_lds_dwordx4 v[222:223], off
	s_mov_b32 m0, s40
	v_lshl_add_u64 v[222:223], s[68:69], 0, v[176:177]
	global_load_lds_dwordx4 v[222:223], off
	s_mov_b32 m0, s41
	s_nop 0
	global_load_lds_dwordx4 v[224:225], off
	s_waitcnt vmcnt(8) lgkmcnt(0)
	s_barrier
	s_setprio 1
	v_mfma_f32_16x16x32_bf16 v[88:91], v[128:131], v[160:163], 0
	v_mfma_f32_16x16x32_bf16 v[20:23], v[136:139], v[160:163], 0
	v_mfma_f32_16x16x32_bf16 v[92:95], v[128:131], v[168:171], 0
	v_mfma_f32_16x16x32_bf16 v[28:31], v[136:139], v[168:171], 0
	v_mfma_f32_16x16x32_bf16 v[80:83], v[128:131], v[196:199], 0
	v_mfma_f32_16x16x32_bf16 v[16:19], v[136:139], v[196:199], 0
	v_mfma_f32_16x16x32_bf16 v[76:79], v[128:131], v[212:215], 0
	v_mfma_f32_16x16x32_bf16 v[12:15], v[136:139], v[212:215], 0
	v_mfma_f32_16x16x32_bf16 v[88:91], v[132:135], v[164:167], v[88:91]
	v_mfma_f32_16x16x32_bf16 v[20:23], v[140:143], v[164:167], v[20:23]
	v_mfma_f32_16x16x32_bf16 v[92:95], v[132:135], v[172:175], v[92:95]
	v_mfma_f32_16x16x32_bf16 v[28:31], v[140:143], v[172:175], v[28:31]
	v_mfma_f32_16x16x32_bf16 v[80:83], v[132:135], v[208:211], v[80:83]
	v_mfma_f32_16x16x32_bf16 v[16:19], v[140:143], v[208:211], v[16:19]
	v_mfma_f32_16x16x32_bf16 v[76:79], v[132:135], v[216:219], v[76:79]
	v_mfma_f32_16x16x32_bf16 v[12:15], v[140:143], v[216:219], v[12:15]
	s_setprio 0
	s_setprio 1
	v_mfma_f32_16x16x32_bf16 v[68:71], v[144:147], v[160:163], 0
	v_mfma_f32_16x16x32_bf16 v[4:7], v[152:155], v[160:163], 0
	v_mfma_f32_16x16x32_bf16 v[84:87], v[144:147], v[168:171], 0
	v_mfma_f32_16x16x32_bf16 v[24:27], v[152:155], v[168:171], 0
	v_mfma_f32_16x16x32_bf16 v[72:75], v[144:147], v[196:199], 0
	v_mfma_f32_16x16x32_bf16 v[8:11], v[152:155], v[196:199], 0
	v_mfma_f32_16x16x32_bf16 v[64:67], v[144:147], v[212:215], 0
	v_mfma_f32_16x16x32_bf16 v[0:3], v[152:155], v[212:215], 0
	v_mfma_f32_16x16x32_bf16 v[68:71], v[148:151], v[164:167], v[68:71]
	v_mfma_f32_16x16x32_bf16 v[4:7], v[156:159], v[164:167], v[4:7]
	v_mfma_f32_16x16x32_bf16 v[84:87], v[148:151], v[172:175], v[84:87]
	v_mfma_f32_16x16x32_bf16 v[24:27], v[156:159], v[172:175], v[24:27]
	v_mfma_f32_16x16x32_bf16 v[72:75], v[148:151], v[208:211], v[72:75]
	v_mfma_f32_16x16x32_bf16 v[8:11], v[156:159], v[208:211], v[8:11]
	v_mfma_f32_16x16x32_bf16 v[64:67], v[148:151], v[216:219], v[64:67]
	v_mfma_f32_16x16x32_bf16 v[0:3], v[156:159], v[216:219], v[0:3]
	s_setprio 0
	s_barrier
	s_add_i32 s0, 0, 0x18000
	s_add_i32 s1, 0, 0x1c000
	v_add_u32_e32 v140, s0, v200
	v_add_u32_e32 v156, s1, v200
	ds_read_b128 v[128:131], v140
	ds_read_b128 v[132:135], v140 offset:1024
	ds_read_b128 v[136:139], v140 offset:2048
	ds_read_b128 v[140:143], v140 offset:3072
	ds_read_b128 v[144:147], v156
	ds_read_b128 v[148:151], v156 offset:1024
	ds_read_b128 v[152:155], v156 offset:2048
	ds_read_b128 v[156:159], v156 offset:3072
	s_add_u32 s10, s68, 0x80000
	s_addc_u32 s11, s69, 0
	s_mov_b32 m0, s42
	v_lshl_add_u64 v[226:227], s[10:11], 0, v[176:177]
	ds_read_b128 v[160:163], v206 offset:32768
	ds_read_b128 v[164:167], v206 offset:33792
	ds_read_b128 v[168:171], v206 offset:34816
	ds_read_b128 v[172:175], v206 offset:35840
	ds_read_b128 v[196:199], v206 offset:36864
	ds_read_b128 v[208:211], v206 offset:37888
	ds_read_b128 v[212:215], v206 offset:38912
	ds_read_b128 v[216:219], v206 offset:39936
	global_load_lds_dwordx4 v[226:227], off
	s_mov_b32 m0, s43
	v_lshl_add_u64 v[226:227], s[10:11], 0, v[178:179]
	global_load_lds_dwordx4 v[226:227], off
	s_waitcnt vmcnt(8) lgkmcnt(0)
	s_barrier
	s_setprio 1
	v_mfma_f32_16x16x32_bf16 v[120:123], v[128:131], v[160:163], v[120:123]
	v_mfma_f32_16x16x32_bf16 v[48:51], v[136:139], v[160:163], v[48:51]
	v_mfma_f32_16x16x32_bf16 v[124:127], v[128:131], v[168:171], v[124:127]
	v_mfma_f32_16x16x32_bf16 v[60:63], v[136:139], v[168:171], v[60:63]
	v_mfma_f32_16x16x32_bf16 v[112:115], v[128:131], v[196:199], v[112:115]
	v_mfma_f32_16x16x32_bf16 v[52:55], v[136:139], v[196:199], v[52:55]
	v_mfma_f32_16x16x32_bf16 v[108:111], v[128:131], v[212:215], v[108:111]
	v_mfma_f32_16x16x32_bf16 v[36:39], v[136:139], v[212:215], v[36:39]
	v_mfma_f32_16x16x32_bf16 v[120:123], v[132:135], v[164:167], v[120:123]
	v_mfma_f32_16x16x32_bf16 v[48:51], v[140:143], v[164:167], v[48:51]
	v_mfma_f32_16x16x32_bf16 v[124:127], v[132:135], v[172:175], v[124:127]
	v_mfma_f32_16x16x32_bf16 v[60:63], v[140:143], v[172:175], v[60:63]
	v_mfma_f32_16x16x32_bf16 v[112:115], v[132:135], v[208:211], v[112:115]
	v_mfma_f32_16x16x32_bf16 v[52:55], v[140:143], v[208:211], v[52:55]
	v_mfma_f32_16x16x32_bf16 v[108:111], v[132:135], v[216:219], v[108:111]
	v_mfma_f32_16x16x32_bf16 v[36:39], v[140:143], v[216:219], v[36:39]
	s_setprio 0
	s_setprio 1
	v_mfma_f32_16x16x32_bf16 v[100:103], v[144:147], v[160:163], v[100:103]
	v_mfma_f32_16x16x32_bf16 v[40:43], v[152:155], v[160:163], v[40:43]
	v_mfma_f32_16x16x32_bf16 v[116:119], v[144:147], v[168:171], v[116:119]
	v_mfma_f32_16x16x32_bf16 v[56:59], v[152:155], v[168:171], v[56:59]
	v_mfma_f32_16x16x32_bf16 v[104:107], v[144:147], v[196:199], v[104:107]
	v_mfma_f32_16x16x32_bf16 v[44:47], v[152:155], v[196:199], v[44:47]
	v_mfma_f32_16x16x32_bf16 v[96:99], v[144:147], v[212:215], v[96:99]
	v_mfma_f32_16x16x32_bf16 v[32:35], v[152:155], v[212:215], v[32:35]
	v_mfma_f32_16x16x32_bf16 v[100:103], v[148:151], v[164:167], v[100:103]
	v_mfma_f32_16x16x32_bf16 v[40:43], v[156:159], v[164:167], v[40:43]
	v_mfma_f32_16x16x32_bf16 v[116:119], v[148:151], v[172:175], v[116:119]
	v_mfma_f32_16x16x32_bf16 v[56:59], v[156:159], v[172:175], v[56:59]
	v_mfma_f32_16x16x32_bf16 v[104:107], v[148:151], v[208:211], v[104:107]
	v_mfma_f32_16x16x32_bf16 v[44:47], v[156:159], v[208:211], v[44:47]
	v_mfma_f32_16x16x32_bf16 v[96:99], v[148:151], v[216:219], v[96:99]
	v_mfma_f32_16x16x32_bf16 v[32:35], v[156:159], v[216:219], v[32:35]
	s_setprio 0
	s_barrier
	s_add_i32 s0, s0, s33
	v_lshl_add_u64 v[186:187], v[186:187], 0, s[58:59]
	s_mov_b32 m0, s0
	ds_read_b128 v[160:163], v206 offset:49152
	ds_read_b128 v[164:167], v206 offset:50176
	ds_read_b128 v[168:171], v206 offset:51200
	ds_read_b128 v[172:175], v206 offset:52224
	ds_read_b128 v[196:199], v206 offset:53248
	ds_read_b128 v[208:211], v206 offset:54272
	ds_read_b128 v[212:215], v206 offset:55296
	ds_read_b128 v[216:219], v206 offset:56320
	global_load_lds_dwordx4 v[186:187], off
	s_add_i32 m0, s0, 0x2000
	s_add_u32 s10, s52, 0x80080
	v_lshl_add_u64 v[186:187], v[220:221], 0, s[58:59]
	s_addc_u32 s11, s53, 0
	s_add_i32 s0, s1, s33
	global_load_lds_dwordx4 v[186:187], off
	s_mov_b32 m0, s0
	v_lshl_add_u64 v[186:187], s[10:11], 0, v[190:191]
	global_load_lds_dwordx4 v[186:187], off
	s_add_i32 m0, s0, 0x2000
	v_lshl_add_u64 v[186:187], s[10:11], 0, v[180:181]
	global_load_lds_dwordx4 v[186:187], off
	s_mov_b32 m0, s55
	v_lshl_add_u64 v[186:187], v[222:223], 0, s[58:59]
	global_load_lds_dwordx4 v[186:187], off
	s_mov_b32 m0, s77
	v_lshl_add_u64 v[186:187], v[224:225], 0, s[58:59]
	global_load_lds_dwordx4 v[186:187], off
	s_waitcnt vmcnt(8) lgkmcnt(0)
	s_barrier
	s_setprio 1
	v_mfma_f32_16x16x32_bf16 v[88:91], v[128:131], v[160:163], v[88:91]
	v_mfma_f32_16x16x32_bf16 v[20:23], v[136:139], v[160:163], v[20:23]
	v_mfma_f32_16x16x32_bf16 v[92:95], v[128:131], v[168:171], v[92:95]
	v_mfma_f32_16x16x32_bf16 v[28:31], v[136:139], v[168:171], v[28:31]
	v_mfma_f32_16x16x32_bf16 v[80:83], v[128:131], v[196:199], v[80:83]
	v_mfma_f32_16x16x32_bf16 v[16:19], v[136:139], v[196:199], v[16:19]
	v_mfma_f32_16x16x32_bf16 v[76:79], v[128:131], v[212:215], v[76:79]
	v_mfma_f32_16x16x32_bf16 v[12:15], v[136:139], v[212:215], v[12:15]
	v_mfma_f32_16x16x32_bf16 v[88:91], v[132:135], v[164:167], v[88:91]
	v_mfma_f32_16x16x32_bf16 v[20:23], v[140:143], v[164:167], v[20:23]
	v_mfma_f32_16x16x32_bf16 v[92:95], v[132:135], v[172:175], v[92:95]
	v_mfma_f32_16x16x32_bf16 v[28:31], v[140:143], v[172:175], v[28:31]
	v_mfma_f32_16x16x32_bf16 v[80:83], v[132:135], v[208:211], v[80:83]
	v_mfma_f32_16x16x32_bf16 v[16:19], v[140:143], v[208:211], v[16:19]
	v_mfma_f32_16x16x32_bf16 v[76:79], v[132:135], v[216:219], v[76:79]
	v_mfma_f32_16x16x32_bf16 v[12:15], v[140:143], v[216:219], v[12:15]
	s_setprio 0
	s_setprio 1
	v_mfma_f32_16x16x32_bf16 v[68:71], v[144:147], v[160:163], v[68:71]
	v_mfma_f32_16x16x32_bf16 v[4:7], v[152:155], v[160:163], v[4:7]
	v_mfma_f32_16x16x32_bf16 v[84:87], v[144:147], v[168:171], v[84:87]
	v_mfma_f32_16x16x32_bf16 v[24:27], v[152:155], v[168:171], v[24:27]
	v_mfma_f32_16x16x32_bf16 v[72:75], v[144:147], v[196:199], v[72:75]
	v_mfma_f32_16x16x32_bf16 v[8:11], v[152:155], v[196:199], v[8:11]
	v_mfma_f32_16x16x32_bf16 v[64:67], v[144:147], v[212:215], v[64:67]
	v_mfma_f32_16x16x32_bf16 v[0:3], v[152:155], v[212:215], v[0:3]
	v_mfma_f32_16x16x32_bf16 v[68:71], v[148:151], v[164:167], v[68:71]
	v_mfma_f32_16x16x32_bf16 v[4:7], v[156:159], v[164:167], v[4:7]
	v_mfma_f32_16x16x32_bf16 v[84:87], v[148:151], v[172:175], v[84:87]
	v_mfma_f32_16x16x32_bf16 v[24:27], v[156:159], v[172:175], v[24:27]
	v_mfma_f32_16x16x32_bf16 v[72:75], v[148:151], v[208:211], v[72:75]
	v_mfma_f32_16x16x32_bf16 v[8:11], v[156:159], v[208:211], v[8:11]
	v_mfma_f32_16x16x32_bf16 v[64:67], v[148:151], v[216:219], v[64:67]
	v_mfma_f32_16x16x32_bf16 v[0:3], v[156:159], v[216:219], v[0:3]
	s_setprio 0
	s_barrier
	s_add_i32 vcc_lo, vcc_lo, 2
	s_add_u32 s66, s66, 0x100
	s_addc_u32 s67, s67, 0
	s_cmp_gt_u32 vcc_lo, 29
	s_mov_b64 s[10:11], s[16:17]
	s_cbranch_scc1 .Lpeel_done_7
.LBB0_1105:
	s_add_u32 s16, s10, 0x100
	s_addc_u32 s17, s11, 0
	s_add_i32 vcc_hi, 0, 0x10000
	s_cmp_eq_u32 vcc_lo, 28
	s_cselect_b32 s69, s13, s17
	s_cselect_b32 s68, s15, s16
	s_cselect_b32 s53, s57, s67
	s_cselect_b32 s52, s61, s66
	s_add_i32 s0, 0, 0x14000
	v_add_u32_e32 v140, vcc_hi, v200
	v_add_u32_e32 v156, s0, v200
	ds_read_b128 v[128:131], v140
	ds_read_b128 v[132:135], v140 offset:1024
	ds_read_b128 v[136:139], v140 offset:2048
	ds_read_b128 v[140:143], v140 offset:3072
	ds_read_b128 v[144:147], v156
	ds_read_b128 v[148:151], v156 offset:1024
	ds_read_b128 v[152:155], v156 offset:2048
	ds_read_b128 v[156:159], v156 offset:3072
	v_lshl_add_u64 v[186:187], s[10:11], 0, v[182:183]
	s_add_i32 m0, s40, 0xc000
	ds_read_b128 v[160:163], v206
	ds_read_b128 v[164:167], v206 offset:1024
	ds_read_b128 v[168:171], v206 offset:2048
	ds_read_b128 v[172:175], v206 offset:3072
	ds_read_b128 v[196:199], v206 offset:4096
	ds_read_b128 v[208:211], v206 offset:5120
	ds_read_b128 v[212:215], v206 offset:6144
	ds_read_b128 v[216:219], v206 offset:7168
	global_load_lds_dwordx4 v[186:187], off
	s_add_i32 m0, s40, 0xe000
	v_lshl_add_u64 v[186:187], s[10:11], 0, v[184:185]
	global_load_lds_dwordx4 v[186:187], off
	s_waitcnt vmcnt(8) lgkmcnt(0)
	s_barrier
	s_setprio 1
	v_mfma_f32_16x16x32_bf16 v[120:123], v[128:131], v[160:163], v[120:123]
	v_mfma_f32_16x16x32_bf16 v[48:51], v[136:139], v[160:163], v[48:51]
	v_mfma_f32_16x16x32_bf16 v[124:127], v[128:131], v[168:171], v[124:127]
	v_mfma_f32_16x16x32_bf16 v[60:63], v[136:139], v[168:171], v[60:63]
	v_mfma_f32_16x16x32_bf16 v[112:115], v[128:131], v[196:199], v[112:115]
	v_mfma_f32_16x16x32_bf16 v[52:55], v[136:139], v[196:199], v[52:55]
	v_mfma_f32_16x16x32_bf16 v[108:111], v[128:131], v[212:215], v[108:111]
	v_mfma_f32_16x16x32_bf16 v[36:39], v[136:139], v[212:215], v[36:39]
	v_mfma_f32_16x16x32_bf16 v[120:123], v[132:135], v[164:167], v[120:123]
	v_mfma_f32_16x16x32_bf16 v[48:51], v[140:143], v[164:167], v[48:51]
	v_mfma_f32_16x16x32_bf16 v[124:127], v[132:135], v[172:175], v[124:127]
	v_mfma_f32_16x16x32_bf16 v[60:63], v[140:143], v[172:175], v[60:63]
	v_mfma_f32_16x16x32_bf16 v[112:115], v[132:135], v[208:211], v[112:115]
	v_mfma_f32_16x16x32_bf16 v[52:55], v[140:143], v[208:211], v[52:55]
	v_mfma_f32_16x16x32_bf16 v[108:111], v[132:135], v[216:219], v[108:111]
	v_mfma_f32_16x16x32_bf16 v[36:39], v[140:143], v[216:219], v[36:39]
	s_setprio 0
	s_setprio 1
	v_mfma_f32_16x16x32_bf16 v[100:103], v[144:147], v[160:163], v[100:103]
	v_mfma_f32_16x16x32_bf16 v[40:43], v[152:155], v[160:163], v[40:43]
	v_mfma_f32_16x16x32_bf16 v[116:119], v[144:147], v[168:171], v[116:119]
	v_mfma_f32_16x16x32_bf16 v[56:59], v[152:155], v[168:171], v[56:59]
	v_mfma_f32_16x16x32_bf16 v[104:107], v[144:147], v[196:199], v[104:107]
	v_mfma_f32_16x16x32_bf16 v[44:47], v[152:155], v[196:199], v[44:47]
	v_mfma_f32_16x16x32_bf16 v[96:99], v[144:147], v[212:215], v[96:99]
	v_mfma_f32_16x16x32_bf16 v[32:35], v[152:155], v[212:215], v[32:35]
	v_mfma_f32_16x16x32_bf16 v[100:103], v[148:151], v[164:167], v[100:103]
	v_mfma_f32_16x16x32_bf16 v[40:43], v[156:159], v[164:167], v[40:43]
	v_mfma_f32_16x16x32_bf16 v[116:119], v[148:151], v[172:175], v[116:119]
	v_mfma_f32_16x16x32_bf16 v[56:59], v[156:159], v[172:175], v[56:59]
	v_mfma_f32_16x16x32_bf16 v[104:107], v[148:151], v[208:211], v[104:107]
	v_mfma_f32_16x16x32_bf16 v[44:47], v[156:159], v[208:211], v[44:47]
	v_mfma_f32_16x16x32_bf16 v[96:99], v[148:151], v[216:219], v[96:99]
	v_mfma_f32_16x16x32_bf16 v[32:35], v[156:159], v[216:219], v[32:35]
	s_setprio 0
	s_barrier
	s_add_i32 s1, vcc_hi, s33
	v_lshl_add_u64 v[186:187], s[52:53], 0, v[190:191]
	s_mov_b32 m0, s1
	ds_read_b128 v[160:163], v206 offset:16384
	ds_read_b128 v[164:167], v206 offset:17408
	ds_read_b128 v[168:171], v206 offset:18432
	ds_read_b128 v[172:175], v206 offset:19456
	ds_read_b128 v[196:199], v206 offset:20480
	ds_read_b128 v[208:211], v206 offset:21504
	ds_read_b128 v[212:215], v206 offset:22528
	ds_read_b128 v[216:219], v206 offset:23552
	global_load_lds_dwordx4 v[186:187], off
	s_add_i32 m0, s1, 0x2000
	s_add_u32 s10, s52, 0x80000
	v_lshl_add_u64 v[220:221], s[52:53], 0, v[180:181]
	s_addc_u32 s11, s53, 0
	s_add_i32 s0, s0, s33
	global_load_lds_dwordx4 v[220:221], off
	v_lshl_add_u64 v[222:223], s[10:11], 0, v[190:191]
	s_mov_b32 m0, s0
	v_lshl_add_u64 v[224:225], s[68:69], 0, v[178:179]
	global_load_lds_dwordx4 v[222:223], off
	s_add_i32 m0, s0, 0x2000
	v_lshl_add_u64 v[222:223], s[10:11], 0, v[180:181]
	global_load_lds_dwordx4 v[222:223], off
	s_mov_b32 m0, s40
	v_lshl_add_u64 v[222:223], s[68:69], 0, v[176:177]
	global_load_lds_dwordx4 v[222:223], off
	s_mov_b32 m0, s41
	s_nop 0
	global_load_lds_dwordx4 v[224:225], off
	s_waitcnt vmcnt(8) lgkmcnt(0)
	s_barrier
	s_setprio 1
	v_mfma_f32_16x16x32_bf16 v[88:91], v[128:131], v[160:163], v[88:91]
	v_mfma_f32_16x16x32_bf16 v[20:23], v[136:139], v[160:163], v[20:23]
	v_mfma_f32_16x16x32_bf16 v[92:95], v[128:131], v[168:171], v[92:95]
	v_mfma_f32_16x16x32_bf16 v[28:31], v[136:139], v[168:171], v[28:31]
	v_mfma_f32_16x16x32_bf16 v[80:83], v[128:131], v[196:199], v[80:83]
	v_mfma_f32_16x16x32_bf16 v[16:19], v[136:139], v[196:199], v[16:19]
	v_mfma_f32_16x16x32_bf16 v[76:79], v[128:131], v[212:215], v[76:79]
	v_mfma_f32_16x16x32_bf16 v[12:15], v[136:139], v[212:215], v[12:15]
	v_mfma_f32_16x16x32_bf16 v[88:91], v[132:135], v[164:167], v[88:91]
	v_mfma_f32_16x16x32_bf16 v[20:23], v[140:143], v[164:167], v[20:23]
	v_mfma_f32_16x16x32_bf16 v[92:95], v[132:135], v[172:175], v[92:95]
	v_mfma_f32_16x16x32_bf16 v[28:31], v[140:143], v[172:175], v[28:31]
	v_mfma_f32_16x16x32_bf16 v[80:83], v[132:135], v[208:211], v[80:83]
	v_mfma_f32_16x16x32_bf16 v[16:19], v[140:143], v[208:211], v[16:19]
	v_mfma_f32_16x16x32_bf16 v[76:79], v[132:135], v[216:219], v[76:79]
	v_mfma_f32_16x16x32_bf16 v[12:15], v[140:143], v[216:219], v[12:15]
	s_setprio 0
	s_setprio 1
	v_mfma_f32_16x16x32_bf16 v[68:71], v[144:147], v[160:163], v[68:71]
	v_mfma_f32_16x16x32_bf16 v[4:7], v[152:155], v[160:163], v[4:7]
	v_mfma_f32_16x16x32_bf16 v[84:87], v[144:147], v[168:171], v[84:87]
	v_mfma_f32_16x16x32_bf16 v[24:27], v[152:155], v[168:171], v[24:27]
	v_mfma_f32_16x16x32_bf16 v[72:75], v[144:147], v[196:199], v[72:75]
	v_mfma_f32_16x16x32_bf16 v[8:11], v[152:155], v[196:199], v[8:11]
	v_mfma_f32_16x16x32_bf16 v[64:67], v[144:147], v[212:215], v[64:67]
	v_mfma_f32_16x16x32_bf16 v[0:3], v[152:155], v[212:215], v[0:3]
	v_mfma_f32_16x16x32_bf16 v[68:71], v[148:151], v[164:167], v[68:71]
	v_mfma_f32_16x16x32_bf16 v[4:7], v[156:159], v[164:167], v[4:7]
	v_mfma_f32_16x16x32_bf16 v[84:87], v[148:151], v[172:175], v[84:87]
	v_mfma_f32_16x16x32_bf16 v[24:27], v[156:159], v[172:175], v[24:27]
	v_mfma_f32_16x16x32_bf16 v[72:75], v[148:151], v[208:211], v[72:75]
	v_mfma_f32_16x16x32_bf16 v[8:11], v[156:159], v[208:211], v[8:11]
	v_mfma_f32_16x16x32_bf16 v[64:67], v[148:151], v[216:219], v[64:67]
	v_mfma_f32_16x16x32_bf16 v[0:3], v[156:159], v[216:219], v[0:3]
	s_setprio 0
	s_barrier
	s_add_i32 s0, 0, 0x18000
	s_add_i32 s1, 0, 0x1c000
	v_add_u32_e32 v140, s0, v200
	v_add_u32_e32 v156, s1, v200
	ds_read_b128 v[128:131], v140
	ds_read_b128 v[132:135], v140 offset:1024
	ds_read_b128 v[136:139], v140 offset:2048
	ds_read_b128 v[140:143], v140 offset:3072
	ds_read_b128 v[144:147], v156
	ds_read_b128 v[148:151], v156 offset:1024
	ds_read_b128 v[152:155], v156 offset:2048
	ds_read_b128 v[156:159], v156 offset:3072
	s_add_u32 s10, s68, 0x80000
	s_addc_u32 s11, s69, 0
	s_mov_b32 m0, s42
	v_lshl_add_u64 v[226:227], s[10:11], 0, v[176:177]
	ds_read_b128 v[160:163], v206 offset:32768
	ds_read_b128 v[164:167], v206 offset:33792
	ds_read_b128 v[168:171], v206 offset:34816
	ds_read_b128 v[172:175], v206 offset:35840
	ds_read_b128 v[196:199], v206 offset:36864
	ds_read_b128 v[208:211], v206 offset:37888
	ds_read_b128 v[212:215], v206 offset:38912
	ds_read_b128 v[216:219], v206 offset:39936
	global_load_lds_dwordx4 v[226:227], off
	s_mov_b32 m0, s43
	v_lshl_add_u64 v[226:227], s[10:11], 0, v[178:179]
	global_load_lds_dwordx4 v[226:227], off
	s_waitcnt vmcnt(8) lgkmcnt(0)
	s_barrier
	s_setprio 1
	v_mfma_f32_16x16x32_bf16 v[120:123], v[128:131], v[160:163], v[120:123]
	v_mfma_f32_16x16x32_bf16 v[48:51], v[136:139], v[160:163], v[48:51]
	v_mfma_f32_16x16x32_bf16 v[124:127], v[128:131], v[168:171], v[124:127]
	v_mfma_f32_16x16x32_bf16 v[60:63], v[136:139], v[168:171], v[60:63]
	v_mfma_f32_16x16x32_bf16 v[112:115], v[128:131], v[196:199], v[112:115]
	v_mfma_f32_16x16x32_bf16 v[52:55], v[136:139], v[196:199], v[52:55]
	v_mfma_f32_16x16x32_bf16 v[108:111], v[128:131], v[212:215], v[108:111]
	v_mfma_f32_16x16x32_bf16 v[36:39], v[136:139], v[212:215], v[36:39]
	v_mfma_f32_16x16x32_bf16 v[120:123], v[132:135], v[164:167], v[120:123]
	v_mfma_f32_16x16x32_bf16 v[48:51], v[140:143], v[164:167], v[48:51]
	v_mfma_f32_16x16x32_bf16 v[124:127], v[132:135], v[172:175], v[124:127]
	v_mfma_f32_16x16x32_bf16 v[60:63], v[140:143], v[172:175], v[60:63]
	v_mfma_f32_16x16x32_bf16 v[112:115], v[132:135], v[208:211], v[112:115]
	v_mfma_f32_16x16x32_bf16 v[52:55], v[140:143], v[208:211], v[52:55]
	v_mfma_f32_16x16x32_bf16 v[108:111], v[132:135], v[216:219], v[108:111]
	v_mfma_f32_16x16x32_bf16 v[36:39], v[140:143], v[216:219], v[36:39]
	s_setprio 0
	s_setprio 1
	v_mfma_f32_16x16x32_bf16 v[100:103], v[144:147], v[160:163], v[100:103]
	v_mfma_f32_16x16x32_bf16 v[40:43], v[152:155], v[160:163], v[40:43]
	v_mfma_f32_16x16x32_bf16 v[116:119], v[144:147], v[168:171], v[116:119]
	v_mfma_f32_16x16x32_bf16 v[56:59], v[152:155], v[168:171], v[56:59]
	v_mfma_f32_16x16x32_bf16 v[104:107], v[144:147], v[196:199], v[104:107]
	v_mfma_f32_16x16x32_bf16 v[44:47], v[152:155], v[196:199], v[44:47]
	v_mfma_f32_16x16x32_bf16 v[96:99], v[144:147], v[212:215], v[96:99]
	v_mfma_f32_16x16x32_bf16 v[32:35], v[152:155], v[212:215], v[32:35]
	v_mfma_f32_16x16x32_bf16 v[100:103], v[148:151], v[164:167], v[100:103]
	v_mfma_f32_16x16x32_bf16 v[40:43], v[156:159], v[164:167], v[40:43]
	v_mfma_f32_16x16x32_bf16 v[116:119], v[148:151], v[172:175], v[116:119]
	v_mfma_f32_16x16x32_bf16 v[56:59], v[156:159], v[172:175], v[56:59]
	v_mfma_f32_16x16x32_bf16 v[104:107], v[148:151], v[208:211], v[104:107]
	v_mfma_f32_16x16x32_bf16 v[44:47], v[156:159], v[208:211], v[44:47]
	v_mfma_f32_16x16x32_bf16 v[96:99], v[148:151], v[216:219], v[96:99]
	v_mfma_f32_16x16x32_bf16 v[32:35], v[156:159], v[216:219], v[32:35]
	s_setprio 0
	s_barrier
	s_add_i32 s0, s0, s33
	v_lshl_add_u64 v[186:187], v[186:187], 0, s[58:59]
	s_mov_b32 m0, s0
	ds_read_b128 v[160:163], v206 offset:49152
	ds_read_b128 v[164:167], v206 offset:50176
	ds_read_b128 v[168:171], v206 offset:51200
	ds_read_b128 v[172:175], v206 offset:52224
	ds_read_b128 v[196:199], v206 offset:53248
	ds_read_b128 v[208:211], v206 offset:54272
	ds_read_b128 v[212:215], v206 offset:55296
	ds_read_b128 v[216:219], v206 offset:56320
	global_load_lds_dwordx4 v[186:187], off
	s_add_i32 m0, s0, 0x2000
	s_add_u32 s10, s52, 0x80080
	v_lshl_add_u64 v[186:187], v[220:221], 0, s[58:59]
	s_addc_u32 s11, s53, 0
	s_add_i32 s0, s1, s33
	global_load_lds_dwordx4 v[186:187], off
	s_mov_b32 m0, s0
	v_lshl_add_u64 v[186:187], s[10:11], 0, v[190:191]
	global_load_lds_dwordx4 v[186:187], off
	s_add_i32 m0, s0, 0x2000
	v_lshl_add_u64 v[186:187], s[10:11], 0, v[180:181]
	global_load_lds_dwordx4 v[186:187], off
	s_mov_b32 m0, s55
	v_lshl_add_u64 v[186:187], v[222:223], 0, s[58:59]
	global_load_lds_dwordx4 v[186:187], off
	s_mov_b32 m0, s77
	v_lshl_add_u64 v[186:187], v[224:225], 0, s[58:59]
	global_load_lds_dwordx4 v[186:187], off
	s_waitcnt vmcnt(8) lgkmcnt(0)
	s_barrier
	s_setprio 1
	v_mfma_f32_16x16x32_bf16 v[88:91], v[128:131], v[160:163], v[88:91]
	v_mfma_f32_16x16x32_bf16 v[20:23], v[136:139], v[160:163], v[20:23]
	v_mfma_f32_16x16x32_bf16 v[92:95], v[128:131], v[168:171], v[92:95]
	v_mfma_f32_16x16x32_bf16 v[28:31], v[136:139], v[168:171], v[28:31]
	v_mfma_f32_16x16x32_bf16 v[80:83], v[128:131], v[196:199], v[80:83]
	v_mfma_f32_16x16x32_bf16 v[16:19], v[136:139], v[196:199], v[16:19]
	v_mfma_f32_16x16x32_bf16 v[76:79], v[128:131], v[212:215], v[76:79]
	v_mfma_f32_16x16x32_bf16 v[12:15], v[136:139], v[212:215], v[12:15]
	v_mfma_f32_16x16x32_bf16 v[88:91], v[132:135], v[164:167], v[88:91]
	v_mfma_f32_16x16x32_bf16 v[20:23], v[140:143], v[164:167], v[20:23]
	v_mfma_f32_16x16x32_bf16 v[92:95], v[132:135], v[172:175], v[92:95]
	v_mfma_f32_16x16x32_bf16 v[28:31], v[140:143], v[172:175], v[28:31]
	v_mfma_f32_16x16x32_bf16 v[80:83], v[132:135], v[208:211], v[80:83]
	v_mfma_f32_16x16x32_bf16 v[16:19], v[140:143], v[208:211], v[16:19]
	v_mfma_f32_16x16x32_bf16 v[76:79], v[132:135], v[216:219], v[76:79]
	v_mfma_f32_16x16x32_bf16 v[12:15], v[140:143], v[216:219], v[12:15]
	s_setprio 0
	s_setprio 1
	v_mfma_f32_16x16x32_bf16 v[68:71], v[144:147], v[160:163], v[68:71]
	v_mfma_f32_16x16x32_bf16 v[4:7], v[152:155], v[160:163], v[4:7]
	v_mfma_f32_16x16x32_bf16 v[84:87], v[144:147], v[168:171], v[84:87]
	v_mfma_f32_16x16x32_bf16 v[24:27], v[152:155], v[168:171], v[24:27]
	v_mfma_f32_16x16x32_bf16 v[72:75], v[144:147], v[196:199], v[72:75]
	v_mfma_f32_16x16x32_bf16 v[8:11], v[152:155], v[196:199], v[8:11]
	v_mfma_f32_16x16x32_bf16 v[64:67], v[144:147], v[212:215], v[64:67]
	v_mfma_f32_16x16x32_bf16 v[0:3], v[152:155], v[212:215], v[0:3]
	v_mfma_f32_16x16x32_bf16 v[68:71], v[148:151], v[164:167], v[68:71]
	v_mfma_f32_16x16x32_bf16 v[4:7], v[156:159], v[164:167], v[4:7]
	v_mfma_f32_16x16x32_bf16 v[84:87], v[148:151], v[172:175], v[84:87]
	v_mfma_f32_16x16x32_bf16 v[24:27], v[156:159], v[172:175], v[24:27]
	v_mfma_f32_16x16x32_bf16 v[72:75], v[148:151], v[208:211], v[72:75]
	v_mfma_f32_16x16x32_bf16 v[8:11], v[156:159], v[208:211], v[8:11]
	v_mfma_f32_16x16x32_bf16 v[64:67], v[148:151], v[216:219], v[64:67]
	v_mfma_f32_16x16x32_bf16 v[0:3], v[156:159], v[216:219], v[0:3]
	s_setprio 0
	s_barrier
	s_add_i32 vcc_lo, vcc_lo, 2
	s_add_u32 s66, s66, 0x100
	s_addc_u32 s67, s67, 0
	s_cmp_gt_u32 vcc_lo, 29
	s_mov_b64 s[10:11], s[16:17]
	s_cbranch_scc0 .LBB0_1105

.LBB0_1349:
	s_add_u32 s47, s20, 0x100
	s_addc_u32 s52, s21, 0
	s_mov_b32 s53, -2
	v_readlane_b32 s0, v255, 49
	s_nop 3
	s_cmp_eq_u32 s0, 9
	v_writelane_b32 v255, 9, 49
	s_cbranch_scc0 .Ltrip0_strict_8
	s_add_u32 s20, s16, 0x100
	s_addc_u32 s21, s17, 0
	s_add_i32 s0, 0, 0x10000
	s_cmpk_eq_i32 s53, 0x54
	s_cselect_b32 s25, s13, s21
	s_cselect_b32 s24, s12, s20
	s_cselect_b32 s23, s15, s52
	s_cselect_b32 s22, s14, s47
	s_add_i32 s1, 0, 0x14000
	v_add_u32_e32 v154, s0, v139
	v_add_u32_e32 v170, s1, v139
	ds_read_b128 v[142:145], v154
	ds_read_b128 v[146:149], v154 offset:1024
	ds_read_b128 v[150:153], v154 offset:2048
	ds_read_b128 v[154:157], v154 offset:3072
	ds_read_b128 v[158:161], v170
	ds_read_b128 v[162:165], v170 offset:1024
	ds_read_b128 v[166:169], v170 offset:2048
	ds_read_b128 v[170:173], v170 offset:3072
	v_lshl_add_u64 v[186:187], s[16:17], 0, v[134:135]
	s_add_i32 m0, s29, 0xc000
	ds_read_b128 v[174:177], v141
	ds_read_b128 v[178:181], v141 offset:1024
	ds_read_b128 v[182:185], v141 offset:2048
	ds_read_b128 v[196:199], v141 offset:3072
	ds_read_b128 v[200:203], v141 offset:4096
	ds_read_b128 v[204:207], v141 offset:5120
	ds_read_b128 v[208:211], v141 offset:6144
	ds_read_b128 v[212:215], v141 offset:7168
	global_load_lds_dwordx4 v[186:187], off
	s_add_i32 m0, s29, 0xe000
	v_lshl_add_u64 v[186:187], s[16:17], 0, v[136:137]
	global_load_lds_dwordx4 v[186:187], off
	s_waitcnt vmcnt(24) lgkmcnt(0)
	s_barrier
	s_setprio 1
	v_mfma_f32_16x16x32_bf16 v[124:127], v[142:145], v[174:177], 0
	v_mfma_f32_16x16x32_bf16 v[120:123], v[150:153], v[174:177], 0
	v_mfma_f32_16x16x32_bf16 v[116:119], v[142:145], v[182:185], 0
	v_mfma_f32_16x16x32_bf16 v[112:115], v[150:153], v[182:185], 0
	v_mfma_f32_16x16x32_bf16 v[100:103], v[142:145], v[200:203], 0
	v_mfma_f32_16x16x32_bf16 v[96:99], v[150:153], v[200:203], 0
	v_mfma_f32_16x16x32_bf16 v[84:87], v[142:145], v[208:211], 0
	v_mfma_f32_16x16x32_bf16 v[80:83], v[150:153], v[208:211], 0
	v_mfma_f32_16x16x32_bf16 v[124:127], v[146:149], v[178:181], v[124:127]
	v_mfma_f32_16x16x32_bf16 v[120:123], v[154:157], v[178:181], v[120:123]
	v_mfma_f32_16x16x32_bf16 v[116:119], v[146:149], v[196:199], v[116:119]
	v_mfma_f32_16x16x32_bf16 v[112:115], v[154:157], v[196:199], v[112:115]
	v_mfma_f32_16x16x32_bf16 v[100:103], v[146:149], v[204:207], v[100:103]
	v_mfma_f32_16x16x32_bf16 v[96:99], v[154:157], v[204:207], v[96:99]
	v_mfma_f32_16x16x32_bf16 v[84:87], v[146:149], v[212:215], v[84:87]
	v_mfma_f32_16x16x32_bf16 v[80:83], v[154:157], v[212:215], v[80:83]
	s_setprio 0
	s_setprio 1
	v_mfma_f32_16x16x32_bf16 v[108:111], v[158:161], v[174:177], 0
	v_mfma_f32_16x16x32_bf16 v[104:107], v[166:169], v[174:177], 0
	v_mfma_f32_16x16x32_bf16 v[92:95], v[158:161], v[182:185], 0
	v_mfma_f32_16x16x32_bf16 v[88:91], v[166:169], v[182:185], 0
	v_mfma_f32_16x16x32_bf16 v[76:79], v[158:161], v[200:203], 0
	v_mfma_f32_16x16x32_bf16 v[72:75], v[166:169], v[200:203], 0
	v_mfma_f32_16x16x32_bf16 v[68:71], v[158:161], v[208:211], 0
	v_mfma_f32_16x16x32_bf16 v[64:67], v[166:169], v[208:211], 0
	v_mfma_f32_16x16x32_bf16 v[108:111], v[162:165], v[178:181], v[108:111]
	v_mfma_f32_16x16x32_bf16 v[104:107], v[170:173], v[178:181], v[104:107]
	v_mfma_f32_16x16x32_bf16 v[92:95], v[162:165], v[196:199], v[92:95]
	v_mfma_f32_16x16x32_bf16 v[88:91], v[170:173], v[196:199], v[88:91]
	v_mfma_f32_16x16x32_bf16 v[76:79], v[162:165], v[204:207], v[76:79]
	v_mfma_f32_16x16x32_bf16 v[72:75], v[170:173], v[204:207], v[72:75]
	v_mfma_f32_16x16x32_bf16 v[68:71], v[162:165], v[212:215], v[68:71]
	v_mfma_f32_16x16x32_bf16 v[64:67], v[170:173], v[212:215], v[64:67]
	s_setprio 0
	s_barrier
	s_add_i32 s0, s0, s28
	v_lshl_add_u64 v[186:187], s[22:23], 0, v[190:191]
	s_mov_b32 m0, s0
	ds_read_b128 v[174:177], v141 offset:16384
	ds_read_b128 v[178:181], v141 offset:17408
	ds_read_b128 v[182:185], v141 offset:18432
	ds_read_b128 v[196:199], v141 offset:19456
	ds_read_b128 v[200:203], v141 offset:20480
	ds_read_b128 v[204:207], v141 offset:21504
	ds_read_b128 v[208:211], v141 offset:22528
	ds_read_b128 v[212:215], v141 offset:23552
	global_load_lds_dwordx4 v[186:187], off
	s_add_i32 m0, s0, 0x2000
	s_add_u32 s16, s22, 0x160000
	v_lshl_add_u64 v[216:217], s[22:23], 0, v[132:133]
	s_addc_u32 s17, s23, 0
	s_add_i32 s0, s1, s28
	global_load_lds_dwordx4 v[216:217], off
	v_lshl_add_u64 v[218:219], s[16:17], 0, v[190:191]
	s_mov_b32 m0, s0
	v_lshl_add_u64 v[220:221], s[24:25], 0, v[130:131]
	global_load_lds_dwordx4 v[218:219], off
	s_add_i32 m0, s0, 0x2000
	v_lshl_add_u64 v[218:219], s[16:17], 0, v[132:133]
	global_load_lds_dwordx4 v[218:219], off
	s_mov_b32 m0, s29
	v_lshl_add_u64 v[218:219], s[24:25], 0, v[128:129]
	global_load_lds_dwordx4 v[218:219], off
	s_mov_b32 m0, s30
	s_nop 0
	global_load_lds_dwordx4 v[220:221], off
	s_waitcnt vmcnt(24) lgkmcnt(0)
	s_barrier
	s_setprio 1
	v_mfma_f32_16x16x32_bf16 v[60:63], v[142:145], v[174:177], 0
	v_mfma_f32_16x16x32_bf16 v[56:59], v[150:153], v[174:177], 0
	v_mfma_f32_16x16x32_bf16 v[52:55], v[142:145], v[182:185], 0
	v_mfma_f32_16x16x32_bf16 v[48:51], v[150:153], v[182:185], 0
	v_mfma_f32_16x16x32_bf16 v[36:39], v[142:145], v[200:203], 0
	v_mfma_f32_16x16x32_bf16 v[32:35], v[150:153], v[200:203], 0
	v_mfma_f32_16x16x32_bf16 v[20:23], v[142:145], v[208:211], 0
	v_mfma_f32_16x16x32_bf16 v[16:19], v[150:153], v[208:211], 0
	v_mfma_f32_16x16x32_bf16 v[60:63], v[146:149], v[178:181], v[60:63]
	v_mfma_f32_16x16x32_bf16 v[56:59], v[154:157], v[178:181], v[56:59]
	v_mfma_f32_16x16x32_bf16 v[52:55], v[146:149], v[196:199], v[52:55]
	v_mfma_f32_16x16x32_bf16 v[48:51], v[154:157], v[196:199], v[48:51]
	v_mfma_f32_16x16x32_bf16 v[36:39], v[146:149], v[204:207], v[36:39]
	v_mfma_f32_16x16x32_bf16 v[32:35], v[154:157], v[204:207], v[32:35]
	v_mfma_f32_16x16x32_bf16 v[20:23], v[146:149], v[212:215], v[20:23]
	v_mfma_f32_16x16x32_bf16 v[16:19], v[154:157], v[212:215], v[16:19]
	s_setprio 0
	s_setprio 1
	v_mfma_f32_16x16x32_bf16 v[44:47], v[158:161], v[174:177], 0
	v_mfma_f32_16x16x32_bf16 v[40:43], v[166:169], v[174:177], 0
	v_mfma_f32_16x16x32_bf16 v[28:31], v[158:161], v[182:185], 0
	v_mfma_f32_16x16x32_bf16 v[24:27], v[166:169], v[182:185], 0
	v_mfma_f32_16x16x32_bf16 v[12:15], v[158:161], v[200:203], 0
	v_mfma_f32_16x16x32_bf16 v[8:11], v[166:169], v[200:203], 0
	v_mfma_f32_16x16x32_bf16 v[4:7], v[158:161], v[208:211], 0
	v_mfma_f32_16x16x32_bf16 v[0:3], v[166:169], v[208:211], 0
	v_mfma_f32_16x16x32_bf16 v[44:47], v[162:165], v[178:181], v[44:47]
	v_mfma_f32_16x16x32_bf16 v[40:43], v[170:173], v[178:181], v[40:43]
	v_mfma_f32_16x16x32_bf16 v[28:31], v[162:165], v[196:199], v[28:31]
	v_mfma_f32_16x16x32_bf16 v[24:27], v[170:173], v[196:199], v[24:27]
	v_mfma_f32_16x16x32_bf16 v[12:15], v[162:165], v[204:207], v[12:15]
	v_mfma_f32_16x16x32_bf16 v[8:11], v[170:173], v[204:207], v[8:11]
	v_mfma_f32_16x16x32_bf16 v[4:7], v[162:165], v[212:215], v[4:7]
	v_mfma_f32_16x16x32_bf16 v[0:3], v[170:173], v[212:215], v[0:3]
	s_setprio 0
	s_barrier
	s_add_i32 s0, 0, 0x18000
	s_add_i32 s1, 0, 0x1c000
	v_add_u32_e32 v154, s0, v139
	v_add_u32_e32 v170, s1, v139
	ds_read_b128 v[142:145], v154
	ds_read_b128 v[146:149], v154 offset:1024
	ds_read_b128 v[150:153], v154 offset:2048
	ds_read_b128 v[154:157], v154 offset:3072
	ds_read_b128 v[158:161], v170
	ds_read_b128 v[162:165], v170 offset:1024
	ds_read_b128 v[166:169], v170 offset:2048
	ds_read_b128 v[170:173], v170 offset:3072
	s_add_u32 s16, s24, 0x160000
	s_addc_u32 s17, s25, 0
	s_mov_b32 m0, s31
	v_lshl_add_u64 v[222:223], s[16:17], 0, v[128:129]
	ds_read_b128 v[174:177], v141 offset:32768
	ds_read_b128 v[178:181], v141 offset:33792
	ds_read_b128 v[182:185], v141 offset:34816
	ds_read_b128 v[196:199], v141 offset:35840
	ds_read_b128 v[200:203], v141 offset:36864
	ds_read_b128 v[204:207], v141 offset:37888
	ds_read_b128 v[208:211], v141 offset:38912
	ds_read_b128 v[212:215], v141 offset:39936
	global_load_lds_dwordx4 v[222:223], off
	s_mov_b32 m0, s33
	v_lshl_add_u64 v[222:223], s[16:17], 0, v[130:131]
	global_load_lds_dwordx4 v[222:223], off
	s_waitcnt vmcnt(8) lgkmcnt(0)
	s_barrier
	s_setprio 1
	v_mfma_f32_16x16x32_bf16 v[124:127], v[142:145], v[174:177], v[124:127]
	v_mfma_f32_16x16x32_bf16 v[120:123], v[150:153], v[174:177], v[120:123]
	v_mfma_f32_16x16x32_bf16 v[116:119], v[142:145], v[182:185], v[116:119]
	v_mfma_f32_16x16x32_bf16 v[112:115], v[150:153], v[182:185], v[112:115]
	v_mfma_f32_16x16x32_bf16 v[100:103], v[142:145], v[200:203], v[100:103]
	v_mfma_f32_16x16x32_bf16 v[96:99], v[150:153], v[200:203], v[96:99]
	v_mfma_f32_16x16x32_bf16 v[84:87], v[142:145], v[208:211], v[84:87]
	v_mfma_f32_16x16x32_bf16 v[80:83], v[150:153], v[208:211], v[80:83]
	v_mfma_f32_16x16x32_bf16 v[124:127], v[146:149], v[178:181], v[124:127]
	v_mfma_f32_16x16x32_bf16 v[120:123], v[154:157], v[178:181], v[120:123]
	v_mfma_f32_16x16x32_bf16 v[116:119], v[146:149], v[196:199], v[116:119]
	v_mfma_f32_16x16x32_bf16 v[112:115], v[154:157], v[196:199], v[112:115]
	v_mfma_f32_16x16x32_bf16 v[100:103], v[146:149], v[204:207], v[100:103]
	v_mfma_f32_16x16x32_bf16 v[96:99], v[154:157], v[204:207], v[96:99]
	v_mfma_f32_16x16x32_bf16 v[84:87], v[146:149], v[212:215], v[84:87]
	v_mfma_f32_16x16x32_bf16 v[80:83], v[154:157], v[212:215], v[80:83]
	s_setprio 0
	s_setprio 1
	v_mfma_f32_16x16x32_bf16 v[108:111], v[158:161], v[174:177], v[108:111]
	v_mfma_f32_16x16x32_bf16 v[104:107], v[166:169], v[174:177], v[104:107]
	v_mfma_f32_16x16x32_bf16 v[92:95], v[158:161], v[182:185], v[92:95]
	v_mfma_f32_16x16x32_bf16 v[88:91], v[166:169], v[182:185], v[88:91]
	v_mfma_f32_16x16x32_bf16 v[76:79], v[158:161], v[200:203], v[76:79]
	v_mfma_f32_16x16x32_bf16 v[72:75], v[166:169], v[200:203], v[72:75]
	v_mfma_f32_16x16x32_bf16 v[68:71], v[158:161], v[208:211], v[68:71]
	v_mfma_f32_16x16x32_bf16 v[64:67], v[166:169], v[208:211], v[64:67]
	v_mfma_f32_16x16x32_bf16 v[108:111], v[162:165], v[178:181], v[108:111]
	v_mfma_f32_16x16x32_bf16 v[104:107], v[170:173], v[178:181], v[104:107]
	v_mfma_f32_16x16x32_bf16 v[92:95], v[162:165], v[196:199], v[92:95]
	v_mfma_f32_16x16x32_bf16 v[88:91], v[170:173], v[196:199], v[88:91]
	v_mfma_f32_16x16x32_bf16 v[76:79], v[162:165], v[204:207], v[76:79]
	v_mfma_f32_16x16x32_bf16 v[72:75], v[170:173], v[204:207], v[72:75]
	v_mfma_f32_16x16x32_bf16 v[68:71], v[162:165], v[212:215], v[68:71]
	v_mfma_f32_16x16x32_bf16 v[64:67], v[170:173], v[212:215], v[64:67]
	s_setprio 0
	s_barrier
	s_add_i32 s0, s0, s28
	v_lshl_add_u64 v[186:187], v[186:187], 0, s[58:59]
	s_mov_b32 m0, s0
	ds_read_b128 v[174:177], v141 offset:49152
	ds_read_b128 v[178:181], v141 offset:50176
	ds_read_b128 v[182:185], v141 offset:51200
	ds_read_b128 v[196:199], v141 offset:52224
	ds_read_b128 v[200:203], v141 offset:53248
	ds_read_b128 v[204:207], v141 offset:54272
	ds_read_b128 v[208:211], v141 offset:55296
	ds_read_b128 v[212:215], v141 offset:56320
	global_load_lds_dwordx4 v[186:187], off
	s_add_i32 m0, s0, 0x2000
	s_add_u32 s16, s22, 0x160080
	v_lshl_add_u64 v[186:187], v[216:217], 0, s[58:59]
	s_addc_u32 s17, s23, 0
	s_add_i32 s0, s1, s28
	global_load_lds_dwordx4 v[186:187], off
	s_mov_b32 m0, s0
	v_lshl_add_u64 v[186:187], s[16:17], 0, v[190:191]
	global_load_lds_dwordx4 v[186:187], off
	s_add_i32 m0, s0, 0x2000
	v_lshl_add_u64 v[186:187], s[16:17], 0, v[132:133]
	global_load_lds_dwordx4 v[186:187], off
	s_mov_b32 m0, s37
	v_lshl_add_u64 v[186:187], v[218:219], 0, s[58:59]
	global_load_lds_dwordx4 v[186:187], off
	s_mov_b32 m0, s38
	v_lshl_add_u64 v[186:187], v[220:221], 0, s[58:59]
	global_load_lds_dwordx4 v[186:187], off
	s_waitcnt vmcnt(8) lgkmcnt(0)
	s_barrier
	s_setprio 1
	v_mfma_f32_16x16x32_bf16 v[60:63], v[142:145], v[174:177], v[60:63]
	v_mfma_f32_16x16x32_bf16 v[56:59], v[150:153], v[174:177], v[56:59]
	v_mfma_f32_16x16x32_bf16 v[52:55], v[142:145], v[182:185], v[52:55]
	v_mfma_f32_16x16x32_bf16 v[48:51], v[150:153], v[182:185], v[48:51]
	v_mfma_f32_16x16x32_bf16 v[36:39], v[142:145], v[200:203], v[36:39]
	v_mfma_f32_16x16x32_bf16 v[32:35], v[150:153], v[200:203], v[32:35]
	v_mfma_f32_16x16x32_bf16 v[20:23], v[142:145], v[208:211], v[20:23]
	v_mfma_f32_16x16x32_bf16 v[16:19], v[150:153], v[208:211], v[16:19]
	v_mfma_f32_16x16x32_bf16 v[60:63], v[146:149], v[178:181], v[60:63]
	v_mfma_f32_16x16x32_bf16 v[56:59], v[154:157], v[178:181], v[56:59]
	v_mfma_f32_16x16x32_bf16 v[52:55], v[146:149], v[196:199], v[52:55]
	v_mfma_f32_16x16x32_bf16 v[48:51], v[154:157], v[196:199], v[48:51]
	v_mfma_f32_16x16x32_bf16 v[36:39], v[146:149], v[204:207], v[36:39]
	v_mfma_f32_16x16x32_bf16 v[32:35], v[154:157], v[204:207], v[32:35]
	v_mfma_f32_16x16x32_bf16 v[20:23], v[146:149], v[212:215], v[20:23]
	v_mfma_f32_16x16x32_bf16 v[16:19], v[154:157], v[212:215], v[16:19]
	s_setprio 0
	s_setprio 1
	v_mfma_f32_16x16x32_bf16 v[44:47], v[158:161], v[174:177], v[44:47]
	v_mfma_f32_16x16x32_bf16 v[40:43], v[166:169], v[174:177], v[40:43]
	v_mfma_f32_16x16x32_bf16 v[28:31], v[158:161], v[182:185], v[28:31]
	v_mfma_f32_16x16x32_bf16 v[24:27], v[166:169], v[182:185], v[24:27]
	v_mfma_f32_16x16x32_bf16 v[12:15], v[158:161], v[200:203], v[12:15]
	v_mfma_f32_16x16x32_bf16 v[8:11], v[166:169], v[200:203], v[8:11]
	v_mfma_f32_16x16x32_bf16 v[4:7], v[158:161], v[208:211], v[4:7]
	v_mfma_f32_16x16x32_bf16 v[0:3], v[166:169], v[208:211], v[0:3]
	v_mfma_f32_16x16x32_bf16 v[44:47], v[162:165], v[178:181], v[44:47]
	v_mfma_f32_16x16x32_bf16 v[40:43], v[170:173], v[178:181], v[40:43]
	v_mfma_f32_16x16x32_bf16 v[28:31], v[162:165], v[196:199], v[28:31]
	v_mfma_f32_16x16x32_bf16 v[24:27], v[170:173], v[196:199], v[24:27]
	v_mfma_f32_16x16x32_bf16 v[12:15], v[162:165], v[204:207], v[12:15]
	v_mfma_f32_16x16x32_bf16 v[8:11], v[170:173], v[204:207], v[8:11]
	v_mfma_f32_16x16x32_bf16 v[4:7], v[162:165], v[212:215], v[4:7]
	v_mfma_f32_16x16x32_bf16 v[0:3], v[170:173], v[212:215], v[0:3]
	s_setprio 0
	s_barrier
	s_add_i32 s53, s53, 2
	s_add_u32 s47, s47, 0x100
	s_addc_u32 s52, s52, 0
	s_cmpk_gt_u32 s53, 0x55
	s_mov_b64 s[16:17], s[20:21]
	s_cbranch_scc1 .Lpeel_done_8
	s_branch .LBB0_1350
.Ltrip0_strict_8:
	s_add_u32 s20, s16, 0x100
	s_addc_u32 s21, s17, 0
	s_add_i32 s0, 0, 0x10000
	s_cmpk_eq_i32 s53, 0x54
	s_cselect_b32 s25, s13, s21
	s_cselect_b32 s24, s12, s20
	s_cselect_b32 s23, s15, s52
	s_cselect_b32 s22, s14, s47
	s_add_i32 s1, 0, 0x14000
	v_add_u32_e32 v154, s0, v139
	v_add_u32_e32 v170, s1, v139
	ds_read_b128 v[142:145], v154
	ds_read_b128 v[146:149], v154 offset:1024
	ds_read_b128 v[150:153], v154 offset:2048
	ds_read_b128 v[154:157], v154 offset:3072
	ds_read_b128 v[158:161], v170
	ds_read_b128 v[162:165], v170 offset:1024
	ds_read_b128 v[166:169], v170 offset:2048
	ds_read_b128 v[170:173], v170 offset:3072
	v_lshl_add_u64 v[186:187], s[16:17], 0, v[134:135]
	s_add_i32 m0, s29, 0xc000
	ds_read_b128 v[174:177], v141
	ds_read_b128 v[178:181], v141 offset:1024
	ds_read_b128 v[182:185], v141 offset:2048
	ds_read_b128 v[196:199], v141 offset:3072
	ds_read_b128 v[200:203], v141 offset:4096
	ds_read_b128 v[204:207], v141 offset:5120
	ds_read_b128 v[208:211], v141 offset:6144
	ds_read_b128 v[212:215], v141 offset:7168
	global_load_lds_dwordx4 v[186:187], off
	s_add_i32 m0, s29, 0xe000
	v_lshl_add_u64 v[186:187], s[16:17], 0, v[136:137]
	global_load_lds_dwordx4 v[186:187], off
	s_waitcnt vmcnt(8) lgkmcnt(0)
	s_barrier
	s_setprio 1
	v_mfma_f32_16x16x32_bf16 v[124:127], v[142:145], v[174:177], 0
	v_mfma_f32_16x16x32_bf16 v[120:123], v[150:153], v[174:177], 0
	v_mfma_f32_16x16x32_bf16 v[116:119], v[142:145], v[182:185], 0
	v_mfma_f32_16x16x32_bf16 v[112:115], v[150:153], v[182:185], 0
	v_mfma_f32_16x16x32_bf16 v[100:103], v[142:145], v[200:203], 0
	v_mfma_f32_16x16x32_bf16 v[96:99], v[150:153], v[200:203], 0
	v_mfma_f32_16x16x32_bf16 v[84:87], v[142:145], v[208:211], 0
	v_mfma_f32_16x16x32_bf16 v[80:83], v[150:153], v[208:211], 0
	v_mfma_f32_16x16x32_bf16 v[124:127], v[146:149], v[178:181], v[124:127]
	v_mfma_f32_16x16x32_bf16 v[120:123], v[154:157], v[178:181], v[120:123]
	v_mfma_f32_16x16x32_bf16 v[116:119], v[146:149], v[196:199], v[116:119]
	v_mfma_f32_16x16x32_bf16 v[112:115], v[154:157], v[196:199], v[112:115]
	v_mfma_f32_16x16x32_bf16 v[100:103], v[146:149], v[204:207], v[100:103]
	v_mfma_f32_16x16x32_bf16 v[96:99], v[154:157], v[204:207], v[96:99]
	v_mfma_f32_16x16x32_bf16 v[84:87], v[146:149], v[212:215], v[84:87]
	v_mfma_f32_16x16x32_bf16 v[80:83], v[154:157], v[212:215], v[80:83]
	s_setprio 0
	s_setprio 1
	v_mfma_f32_16x16x32_bf16 v[108:111], v[158:161], v[174:177], 0
	v_mfma_f32_16x16x32_bf16 v[104:107], v[166:169], v[174:177], 0
	v_mfma_f32_16x16x32_bf16 v[92:95], v[158:161], v[182:185], 0
	v_mfma_f32_16x16x32_bf16 v[88:91], v[166:169], v[182:185], 0
	v_mfma_f32_16x16x32_bf16 v[76:79], v[158:161], v[200:203], 0
	v_mfma_f32_16x16x32_bf16 v[72:75], v[166:169], v[200:203], 0
	v_mfma_f32_16x16x32_bf16 v[68:71], v[158:161], v[208:211], 0
	v_mfma_f32_16x16x32_bf16 v[64:67], v[166:169], v[208:211], 0
	v_mfma_f32_16x16x32_bf16 v[108:111], v[162:165], v[178:181], v[108:111]
	v_mfma_f32_16x16x32_bf16 v[104:107], v[170:173], v[178:181], v[104:107]
	v_mfma_f32_16x16x32_bf16 v[92:95], v[162:165], v[196:199], v[92:95]
	v_mfma_f32_16x16x32_bf16 v[88:91], v[170:173], v[196:199], v[88:91]
	v_mfma_f32_16x16x32_bf16 v[76:79], v[162:165], v[204:207], v[76:79]
	v_mfma_f32_16x16x32_bf16 v[72:75], v[170:173], v[204:207], v[72:75]
	v_mfma_f32_16x16x32_bf16 v[68:71], v[162:165], v[212:215], v[68:71]
	v_mfma_f32_16x16x32_bf16 v[64:67], v[170:173], v[212:215], v[64:67]
	s_setprio 0
	s_barrier
	s_add_i32 s0, s0, s28
	v_lshl_add_u64 v[186:187], s[22:23], 0, v[190:191]
	s_mov_b32 m0, s0
	ds_read_b128 v[174:177], v141 offset:16384
	ds_read_b128 v[178:181], v141 offset:17408
	ds_read_b128 v[182:185], v141 offset:18432
	ds_read_b128 v[196:199], v141 offset:19456
	ds_read_b128 v[200:203], v141 offset:20480
	ds_read_b128 v[204:207], v141 offset:21504
	ds_read_b128 v[208:211], v141 offset:22528
	ds_read_b128 v[212:215], v141 offset:23552
	global_load_lds_dwordx4 v[186:187], off
	s_add_i32 m0, s0, 0x2000
	s_add_u32 s16, s22, 0x160000
	v_lshl_add_u64 v[216:217], s[22:23], 0, v[132:133]
	s_addc_u32 s17, s23, 0
	s_add_i32 s0, s1, s28
	global_load_lds_dwordx4 v[216:217], off
	v_lshl_add_u64 v[218:219], s[16:17], 0, v[190:191]
	s_mov_b32 m0, s0
	v_lshl_add_u64 v[220:221], s[24:25], 0, v[130:131]
	global_load_lds_dwordx4 v[218:219], off
	s_add_i32 m0, s0, 0x2000
	v_lshl_add_u64 v[218:219], s[16:17], 0, v[132:133]
	global_load_lds_dwordx4 v[218:219], off
	s_mov_b32 m0, s29
	v_lshl_add_u64 v[218:219], s[24:25], 0, v[128:129]
	global_load_lds_dwordx4 v[218:219], off
	s_mov_b32 m0, s30
	s_nop 0
	global_load_lds_dwordx4 v[220:221], off
	s_waitcnt vmcnt(8) lgkmcnt(0)
	s_barrier
	s_setprio 1
	v_mfma_f32_16x16x32_bf16 v[60:63], v[142:145], v[174:177], 0
	v_mfma_f32_16x16x32_bf16 v[56:59], v[150:153], v[174:177], 0
	v_mfma_f32_16x16x32_bf16 v[52:55], v[142:145], v[182:185], 0
	v_mfma_f32_16x16x32_bf16 v[48:51], v[150:153], v[182:185], 0
	v_mfma_f32_16x16x32_bf16 v[36:39], v[142:145], v[200:203], 0
	v_mfma_f32_16x16x32_bf16 v[32:35], v[150:153], v[200:203], 0
	v_mfma_f32_16x16x32_bf16 v[20:23], v[142:145], v[208:211], 0
	v_mfma_f32_16x16x32_bf16 v[16:19], v[150:153], v[208:211], 0
	v_mfma_f32_16x16x32_bf16 v[60:63], v[146:149], v[178:181], v[60:63]
	v_mfma_f32_16x16x32_bf16 v[56:59], v[154:157], v[178:181], v[56:59]
	v_mfma_f32_16x16x32_bf16 v[52:55], v[146:149], v[196:199], v[52:55]
	v_mfma_f32_16x16x32_bf16 v[48:51], v[154:157], v[196:199], v[48:51]
	v_mfma_f32_16x16x32_bf16 v[36:39], v[146:149], v[204:207], v[36:39]
	v_mfma_f32_16x16x32_bf16 v[32:35], v[154:157], v[204:207], v[32:35]
	v_mfma_f32_16x16x32_bf16 v[20:23], v[146:149], v[212:215], v[20:23]
	v_mfma_f32_16x16x32_bf16 v[16:19], v[154:157], v[212:215], v[16:19]
	s_setprio 0
	s_setprio 1
	v_mfma_f32_16x16x32_bf16 v[44:47], v[158:161], v[174:177], 0
	v_mfma_f32_16x16x32_bf16 v[40:43], v[166:169], v[174:177], 0
	v_mfma_f32_16x16x32_bf16 v[28:31], v[158:161], v[182:185], 0
	v_mfma_f32_16x16x32_bf16 v[24:27], v[166:169], v[182:185], 0
	v_mfma_f32_16x16x32_bf16 v[12:15], v[158:161], v[200:203], 0
	v_mfma_f32_16x16x32_bf16 v[8:11], v[166:169], v[200:203], 0
	v_mfma_f32_16x16x32_bf16 v[4:7], v[158:161], v[208:211], 0
	v_mfma_f32_16x16x32_bf16 v[0:3], v[166:169], v[208:211], 0
	v_mfma_f32_16x16x32_bf16 v[44:47], v[162:165], v[178:181], v[44:47]
	v_mfma_f32_16x16x32_bf16 v[40:43], v[170:173], v[178:181], v[40:43]
	v_mfma_f32_16x16x32_bf16 v[28:31], v[162:165], v[196:199], v[28:31]
	v_mfma_f32_16x16x32_bf16 v[24:27], v[170:173], v[196:199], v[24:27]
	v_mfma_f32_16x16x32_bf16 v[12:15], v[162:165], v[204:207], v[12:15]
	v_mfma_f32_16x16x32_bf16 v[8:11], v[170:173], v[204:207], v[8:11]
	v_mfma_f32_16x16x32_bf16 v[4:7], v[162:165], v[212:215], v[4:7]
	v_mfma_f32_16x16x32_bf16 v[0:3], v[170:173], v[212:215], v[0:3]
	s_setprio 0
	s_barrier
	s_add_i32 s0, 0, 0x18000
	s_add_i32 s1, 0, 0x1c000
	v_add_u32_e32 v154, s0, v139
	v_add_u32_e32 v170, s1, v139
	ds_read_b128 v[142:145], v154
	ds_read_b128 v[146:149], v154 offset:1024
	ds_read_b128 v[150:153], v154 offset:2048
	ds_read_b128 v[154:157], v154 offset:3072
	ds_read_b128 v[158:161], v170
	ds_read_b128 v[162:165], v170 offset:1024
	ds_read_b128 v[166:169], v170 offset:2048
	ds_read_b128 v[170:173], v170 offset:3072
	s_add_u32 s16, s24, 0x160000
	s_addc_u32 s17, s25, 0
	s_mov_b32 m0, s31
	v_lshl_add_u64 v[222:223], s[16:17], 0, v[128:129]
	ds_read_b128 v[174:177], v141 offset:32768
	ds_read_b128 v[178:181], v141 offset:33792
	ds_read_b128 v[182:185], v141 offset:34816
	ds_read_b128 v[196:199], v141 offset:35840
	ds_read_b128 v[200:203], v141 offset:36864
	ds_read_b128 v[204:207], v141 offset:37888
	ds_read_b128 v[208:211], v141 offset:38912
	ds_read_b128 v[212:215], v141 offset:39936
	global_load_lds_dwordx4 v[222:223], off
	s_mov_b32 m0, s33
	v_lshl_add_u64 v[222:223], s[16:17], 0, v[130:131]
	global_load_lds_dwordx4 v[222:223], off
	s_waitcnt vmcnt(8) lgkmcnt(0)
	s_barrier
	s_setprio 1
	v_mfma_f32_16x16x32_bf16 v[124:127], v[142:145], v[174:177], v[124:127]
	v_mfma_f32_16x16x32_bf16 v[120:123], v[150:153], v[174:177], v[120:123]
	v_mfma_f32_16x16x32_bf16 v[116:119], v[142:145], v[182:185], v[116:119]
	v_mfma_f32_16x16x32_bf16 v[112:115], v[150:153], v[182:185], v[112:115]
	v_mfma_f32_16x16x32_bf16 v[100:103], v[142:145], v[200:203], v[100:103]
	v_mfma_f32_16x16x32_bf16 v[96:99], v[150:153], v[200:203], v[96:99]
	v_mfma_f32_16x16x32_bf16 v[84:87], v[142:145], v[208:211], v[84:87]
	v_mfma_f32_16x16x32_bf16 v[80:83], v[150:153], v[208:211], v[80:83]
	v_mfma_f32_16x16x32_bf16 v[124:127], v[146:149], v[178:181], v[124:127]
	v_mfma_f32_16x16x32_bf16 v[120:123], v[154:157], v[178:181], v[120:123]
	v_mfma_f32_16x16x32_bf16 v[116:119], v[146:149], v[196:199], v[116:119]
	v_mfma_f32_16x16x32_bf16 v[112:115], v[154:157], v[196:199], v[112:115]
	v_mfma_f32_16x16x32_bf16 v[100:103], v[146:149], v[204:207], v[100:103]
	v_mfma_f32_16x16x32_bf16 v[96:99], v[154:157], v[204:207], v[96:99]
	v_mfma_f32_16x16x32_bf16 v[84:87], v[146:149], v[212:215], v[84:87]
	v_mfma_f32_16x16x32_bf16 v[80:83], v[154:157], v[212:215], v[80:83]
	s_setprio 0
	s_setprio 1
	v_mfma_f32_16x16x32_bf16 v[108:111], v[158:161], v[174:177], v[108:111]
	v_mfma_f32_16x16x32_bf16 v[104:107], v[166:169], v[174:177], v[104:107]
	v_mfma_f32_16x16x32_bf16 v[92:95], v[158:161], v[182:185], v[92:95]
	v_mfma_f32_16x16x32_bf16 v[88:91], v[166:169], v[182:185], v[88:91]
	v_mfma_f32_16x16x32_bf16 v[76:79], v[158:161], v[200:203], v[76:79]
	v_mfma_f32_16x16x32_bf16 v[72:75], v[166:169], v[200:203], v[72:75]
	v_mfma_f32_16x16x32_bf16 v[68:71], v[158:161], v[208:211], v[68:71]
	v_mfma_f32_16x16x32_bf16 v[64:67], v[166:169], v[208:211], v[64:67]
	v_mfma_f32_16x16x32_bf16 v[108:111], v[162:165], v[178:181], v[108:111]
	v_mfma_f32_16x16x32_bf16 v[104:107], v[170:173], v[178:181], v[104:107]
	v_mfma_f32_16x16x32_bf16 v[92:95], v[162:165], v[196:199], v[92:95]
	v_mfma_f32_16x16x32_bf16 v[88:91], v[170:173], v[196:199], v[88:91]
	v_mfma_f32_16x16x32_bf16 v[76:79], v[162:165], v[204:207], v[76:79]
	v_mfma_f32_16x16x32_bf16 v[72:75], v[170:173], v[204:207], v[72:75]
	v_mfma_f32_16x16x32_bf16 v[68:71], v[162:165], v[212:215], v[68:71]
	v_mfma_f32_16x16x32_bf16 v[64:67], v[170:173], v[212:215], v[64:67]
	s_setprio 0
	s_barrier
	s_add_i32 s0, s0, s28
	v_lshl_add_u64 v[186:187], v[186:187], 0, s[58:59]
	s_mov_b32 m0, s0
	ds_read_b128 v[174:177], v141 offset:49152
	ds_read_b128 v[178:181], v141 offset:50176
	ds_read_b128 v[182:185], v141 offset:51200
	ds_read_b128 v[196:199], v141 offset:52224
	ds_read_b128 v[200:203], v141 offset:53248
	ds_read_b128 v[204:207], v141 offset:54272
	ds_read_b128 v[208:211], v141 offset:55296
	ds_read_b128 v[212:215], v141 offset:56320
	global_load_lds_dwordx4 v[186:187], off
	s_add_i32 m0, s0, 0x2000
	s_add_u32 s16, s22, 0x160080
	v_lshl_add_u64 v[186:187], v[216:217], 0, s[58:59]
	s_addc_u32 s17, s23, 0
	s_add_i32 s0, s1, s28
	global_load_lds_dwordx4 v[186:187], off
	s_mov_b32 m0, s0
	v_lshl_add_u64 v[186:187], s[16:17], 0, v[190:191]
	global_load_lds_dwordx4 v[186:187], off
	s_add_i32 m0, s0, 0x2000
	v_lshl_add_u64 v[186:187], s[16:17], 0, v[132:133]
	global_load_lds_dwordx4 v[186:187], off
	s_mov_b32 m0, s37
	v_lshl_add_u64 v[186:187], v[218:219], 0, s[58:59]
	global_load_lds_dwordx4 v[186:187], off
	s_mov_b32 m0, s38
	v_lshl_add_u64 v[186:187], v[220:221], 0, s[58:59]
	global_load_lds_dwordx4 v[186:187], off
	s_waitcnt vmcnt(8) lgkmcnt(0)
	s_barrier
	s_setprio 1
	v_mfma_f32_16x16x32_bf16 v[60:63], v[142:145], v[174:177], v[60:63]
	v_mfma_f32_16x16x32_bf16 v[56:59], v[150:153], v[174:177], v[56:59]
	v_mfma_f32_16x16x32_bf16 v[52:55], v[142:145], v[182:185], v[52:55]
	v_mfma_f32_16x16x32_bf16 v[48:51], v[150:153], v[182:185], v[48:51]
	v_mfma_f32_16x16x32_bf16 v[36:39], v[142:145], v[200:203], v[36:39]
	v_mfma_f32_16x16x32_bf16 v[32:35], v[150:153], v[200:203], v[32:35]
	v_mfma_f32_16x16x32_bf16 v[20:23], v[142:145], v[208:211], v[20:23]
	v_mfma_f32_16x16x32_bf16 v[16:19], v[150:153], v[208:211], v[16:19]
	v_mfma_f32_16x16x32_bf16 v[60:63], v[146:149], v[178:181], v[60:63]
	v_mfma_f32_16x16x32_bf16 v[56:59], v[154:157], v[178:181], v[56:59]
	v_mfma_f32_16x16x32_bf16 v[52:55], v[146:149], v[196:199], v[52:55]
	v_mfma_f32_16x16x32_bf16 v[48:51], v[154:157], v[196:199], v[48:51]
	v_mfma_f32_16x16x32_bf16 v[36:39], v[146:149], v[204:207], v[36:39]
	v_mfma_f32_16x16x32_bf16 v[32:35], v[154:157], v[204:207], v[32:35]
	v_mfma_f32_16x16x32_bf16 v[20:23], v[146:149], v[212:215], v[20:23]
	v_mfma_f32_16x16x32_bf16 v[16:19], v[154:157], v[212:215], v[16:19]
	s_setprio 0
	s_setprio 1
	v_mfma_f32_16x16x32_bf16 v[44:47], v[158:161], v[174:177], v[44:47]
	v_mfma_f32_16x16x32_bf16 v[40:43], v[166:169], v[174:177], v[40:43]
	v_mfma_f32_16x16x32_bf16 v[28:31], v[158:161], v[182:185], v[28:31]
	v_mfma_f32_16x16x32_bf16 v[24:27], v[166:169], v[182:185], v[24:27]
	v_mfma_f32_16x16x32_bf16 v[12:15], v[158:161], v[200:203], v[12:15]
	v_mfma_f32_16x16x32_bf16 v[8:11], v[166:169], v[200:203], v[8:11]
	v_mfma_f32_16x16x32_bf16 v[4:7], v[158:161], v[208:211], v[4:7]
	v_mfma_f32_16x16x32_bf16 v[0:3], v[166:169], v[208:211], v[0:3]
	v_mfma_f32_16x16x32_bf16 v[44:47], v[162:165], v[178:181], v[44:47]
	v_mfma_f32_16x16x32_bf16 v[40:43], v[170:173], v[178:181], v[40:43]
	v_mfma_f32_16x16x32_bf16 v[28:31], v[162:165], v[196:199], v[28:31]
	v_mfma_f32_16x16x32_bf16 v[24:27], v[170:173], v[196:199], v[24:27]
	v_mfma_f32_16x16x32_bf16 v[12:15], v[162:165], v[204:207], v[12:15]
	v_mfma_f32_16x16x32_bf16 v[8:11], v[170:173], v[204:207], v[8:11]
	v_mfma_f32_16x16x32_bf16 v[4:7], v[162:165], v[212:215], v[4:7]
	v_mfma_f32_16x16x32_bf16 v[0:3], v[170:173], v[212:215], v[0:3]
	s_setprio 0
	s_barrier
	s_add_i32 s53, s53, 2
	s_add_u32 s47, s47, 0x100
	s_addc_u32 s52, s52, 0
	s_cmpk_gt_u32 s53, 0x55
	s_mov_b64 s[16:17], s[20:21]
	s_cbranch_scc1 .Lpeel_done_8
.LBB0_1350:
	s_add_u32 s20, s16, 0x100
	s_addc_u32 s21, s17, 0
	s_add_i32 s0, 0, 0x10000
	s_cmpk_eq_i32 s53, 0x54
	s_cselect_b32 s25, s13, s21
	s_cselect_b32 s24, s12, s20
	s_cselect_b32 s23, s15, s52
	s_cselect_b32 s22, s14, s47
	s_add_i32 s1, 0, 0x14000
	v_add_u32_e32 v154, s0, v139
	v_add_u32_e32 v170, s1, v139
	ds_read_b128 v[142:145], v154
	ds_read_b128 v[146:149], v154 offset:1024
	ds_read_b128 v[150:153], v154 offset:2048
	ds_read_b128 v[154:157], v154 offset:3072
	ds_read_b128 v[158:161], v170
	ds_read_b128 v[162:165], v170 offset:1024
	ds_read_b128 v[166:169], v170 offset:2048
	ds_read_b128 v[170:173], v170 offset:3072
	v_lshl_add_u64 v[186:187], s[16:17], 0, v[134:135]
	s_add_i32 m0, s29, 0xc000
	ds_read_b128 v[174:177], v141
	ds_read_b128 v[178:181], v141 offset:1024
	ds_read_b128 v[182:185], v141 offset:2048
	ds_read_b128 v[196:199], v141 offset:3072
	ds_read_b128 v[200:203], v141 offset:4096
	ds_read_b128 v[204:207], v141 offset:5120
	ds_read_b128 v[208:211], v141 offset:6144
	ds_read_b128 v[212:215], v141 offset:7168
	global_load_lds_dwordx4 v[186:187], off
	s_add_i32 m0, s29, 0xe000
	v_lshl_add_u64 v[186:187], s[16:17], 0, v[136:137]
	global_load_lds_dwordx4 v[186:187], off
	s_waitcnt vmcnt(8) lgkmcnt(0)
	s_barrier
	s_setprio 1
	v_mfma_f32_16x16x32_bf16 v[124:127], v[142:145], v[174:177], v[124:127]
	v_mfma_f32_16x16x32_bf16 v[120:123], v[150:153], v[174:177], v[120:123]
	v_mfma_f32_16x16x32_bf16 v[116:119], v[142:145], v[182:185], v[116:119]
	v_mfma_f32_16x16x32_bf16 v[112:115], v[150:153], v[182:185], v[112:115]
	v_mfma_f32_16x16x32_bf16 v[100:103], v[142:145], v[200:203], v[100:103]
	v_mfma_f32_16x16x32_bf16 v[96:99], v[150:153], v[200:203], v[96:99]
	v_mfma_f32_16x16x32_bf16 v[84:87], v[142:145], v[208:211], v[84:87]
	v_mfma_f32_16x16x32_bf16 v[80:83], v[150:153], v[208:211], v[80:83]
	v_mfma_f32_16x16x32_bf16 v[124:127], v[146:149], v[178:181], v[124:127]
	v_mfma_f32_16x16x32_bf16 v[120:123], v[154:157], v[178:181], v[120:123]
	v_mfma_f32_16x16x32_bf16 v[116:119], v[146:149], v[196:199], v[116:119]
	v_mfma_f32_16x16x32_bf16 v[112:115], v[154:157], v[196:199], v[112:115]
	v_mfma_f32_16x16x32_bf16 v[100:103], v[146:149], v[204:207], v[100:103]
	v_mfma_f32_16x16x32_bf16 v[96:99], v[154:157], v[204:207], v[96:99]
	v_mfma_f32_16x16x32_bf16 v[84:87], v[146:149], v[212:215], v[84:87]
	v_mfma_f32_16x16x32_bf16 v[80:83], v[154:157], v[212:215], v[80:83]
	s_setprio 0
	s_setprio 1
	v_mfma_f32_16x16x32_bf16 v[108:111], v[158:161], v[174:177], v[108:111]
	v_mfma_f32_16x16x32_bf16 v[104:107], v[166:169], v[174:177], v[104:107]
	v_mfma_f32_16x16x32_bf16 v[92:95], v[158:161], v[182:185], v[92:95]
	v_mfma_f32_16x16x32_bf16 v[88:91], v[166:169], v[182:185], v[88:91]
	v_mfma_f32_16x16x32_bf16 v[76:79], v[158:161], v[200:203], v[76:79]
	v_mfma_f32_16x16x32_bf16 v[72:75], v[166:169], v[200:203], v[72:75]
	v_mfma_f32_16x16x32_bf16 v[68:71], v[158:161], v[208:211], v[68:71]
	v_mfma_f32_16x16x32_bf16 v[64:67], v[166:169], v[208:211], v[64:67]
	v_mfma_f32_16x16x32_bf16 v[108:111], v[162:165], v[178:181], v[108:111]
	v_mfma_f32_16x16x32_bf16 v[104:107], v[170:173], v[178:181], v[104:107]
	v_mfma_f32_16x16x32_bf16 v[92:95], v[162:165], v[196:199], v[92:95]
	v_mfma_f32_16x16x32_bf16 v[88:91], v[170:173], v[196:199], v[88:91]
	v_mfma_f32_16x16x32_bf16 v[76:79], v[162:165], v[204:207], v[76:79]
	v_mfma_f32_16x16x32_bf16 v[72:75], v[170:173], v[204:207], v[72:75]
	v_mfma_f32_16x16x32_bf16 v[68:71], v[162:165], v[212:215], v[68:71]
	v_mfma_f32_16x16x32_bf16 v[64:67], v[170:173], v[212:215], v[64:67]
	s_setprio 0
	s_barrier
	s_add_i32 s0, s0, s28
	v_lshl_add_u64 v[186:187], s[22:23], 0, v[190:191]
	s_mov_b32 m0, s0
	ds_read_b128 v[174:177], v141 offset:16384
	ds_read_b128 v[178:181], v141 offset:17408
	ds_read_b128 v[182:185], v141 offset:18432
	ds_read_b128 v[196:199], v141 offset:19456
	ds_read_b128 v[200:203], v141 offset:20480
	ds_read_b128 v[204:207], v141 offset:21504
	ds_read_b128 v[208:211], v141 offset:22528
	ds_read_b128 v[212:215], v141 offset:23552
	global_load_lds_dwordx4 v[186:187], off
	s_add_i32 m0, s0, 0x2000
	s_add_u32 s16, s22, 0x160000
	v_lshl_add_u64 v[216:217], s[22:23], 0, v[132:133]
	s_addc_u32 s17, s23, 0
	s_add_i32 s0, s1, s28
	global_load_lds_dwordx4 v[216:217], off
	v_lshl_add_u64 v[218:219], s[16:17], 0, v[190:191]
	s_mov_b32 m0, s0
	v_lshl_add_u64 v[220:221], s[24:25], 0, v[130:131]
	global_load_lds_dwordx4 v[218:219], off
	s_add_i32 m0, s0, 0x2000
	v_lshl_add_u64 v[218:219], s[16:17], 0, v[132:133]
	global_load_lds_dwordx4 v[218:219], off
	s_mov_b32 m0, s29
	v_lshl_add_u64 v[218:219], s[24:25], 0, v[128:129]
	global_load_lds_dwordx4 v[218:219], off
	s_mov_b32 m0, s30
	s_nop 0
	global_load_lds_dwordx4 v[220:221], off
	s_waitcnt vmcnt(8) lgkmcnt(0)
	s_barrier
	s_setprio 1
	v_mfma_f32_16x16x32_bf16 v[60:63], v[142:145], v[174:177], v[60:63]
	v_mfma_f32_16x16x32_bf16 v[56:59], v[150:153], v[174:177], v[56:59]
	v_mfma_f32_16x16x32_bf16 v[52:55], v[142:145], v[182:185], v[52:55]
	v_mfma_f32_16x16x32_bf16 v[48:51], v[150:153], v[182:185], v[48:51]
	v_mfma_f32_16x16x32_bf16 v[36:39], v[142:145], v[200:203], v[36:39]
	v_mfma_f32_16x16x32_bf16 v[32:35], v[150:153], v[200:203], v[32:35]
	v_mfma_f32_16x16x32_bf16 v[20:23], v[142:145], v[208:211], v[20:23]
	v_mfma_f32_16x16x32_bf16 v[16:19], v[150:153], v[208:211], v[16:19]
	v_mfma_f32_16x16x32_bf16 v[60:63], v[146:149], v[178:181], v[60:63]
	v_mfma_f32_16x16x32_bf16 v[56:59], v[154:157], v[178:181], v[56:59]
	v_mfma_f32_16x16x32_bf16 v[52:55], v[146:149], v[196:199], v[52:55]
	v_mfma_f32_16x16x32_bf16 v[48:51], v[154:157], v[196:199], v[48:51]
	v_mfma_f32_16x16x32_bf16 v[36:39], v[146:149], v[204:207], v[36:39]
	v_mfma_f32_16x16x32_bf16 v[32:35], v[154:157], v[204:207], v[32:35]
	v_mfma_f32_16x16x32_bf16 v[20:23], v[146:149], v[212:215], v[20:23]
	v_mfma_f32_16x16x32_bf16 v[16:19], v[154:157], v[212:215], v[16:19]
	s_setprio 0
	s_setprio 1
	v_mfma_f32_16x16x32_bf16 v[44:47], v[158:161], v[174:177], v[44:47]
	v_mfma_f32_16x16x32_bf16 v[40:43], v[166:169], v[174:177], v[40:43]
	v_mfma_f32_16x16x32_bf16 v[28:31], v[158:161], v[182:185], v[28:31]
	v_mfma_f32_16x16x32_bf16 v[24:27], v[166:169], v[182:185], v[24:27]
	v_mfma_f32_16x16x32_bf16 v[12:15], v[158:161], v[200:203], v[12:15]
	v_mfma_f32_16x16x32_bf16 v[8:11], v[166:169], v[200:203], v[8:11]
	v_mfma_f32_16x16x32_bf16 v[4:7], v[158:161], v[208:211], v[4:7]
	v_mfma_f32_16x16x32_bf16 v[0:3], v[166:169], v[208:211], v[0:3]
	v_mfma_f32_16x16x32_bf16 v[44:47], v[162:165], v[178:181], v[44:47]
	v_mfma_f32_16x16x32_bf16 v[40:43], v[170:173], v[178:181], v[40:43]
	v_mfma_f32_16x16x32_bf16 v[28:31], v[162:165], v[196:199], v[28:31]
	v_mfma_f32_16x16x32_bf16 v[24:27], v[170:173], v[196:199], v[24:27]
	v_mfma_f32_16x16x32_bf16 v[12:15], v[162:165], v[204:207], v[12:15]
	v_mfma_f32_16x16x32_bf16 v[8:11], v[170:173], v[204:207], v[8:11]
	v_mfma_f32_16x16x32_bf16 v[4:7], v[162:165], v[212:215], v[4:7]
	v_mfma_f32_16x16x32_bf16 v[0:3], v[170:173], v[212:215], v[0:3]
	s_setprio 0
	s_barrier
	s_add_i32 s0, 0, 0x18000
	s_add_i32 s1, 0, 0x1c000
	v_add_u32_e32 v154, s0, v139
	v_add_u32_e32 v170, s1, v139
	ds_read_b128 v[142:145], v154
	ds_read_b128 v[146:149], v154 offset:1024
	ds_read_b128 v[150:153], v154 offset:2048
	ds_read_b128 v[154:157], v154 offset:3072
	ds_read_b128 v[158:161], v170
	ds_read_b128 v[162:165], v170 offset:1024
	ds_read_b128 v[166:169], v170 offset:2048
	ds_read_b128 v[170:173], v170 offset:3072
	s_add_u32 s16, s24, 0x160000
	s_addc_u32 s17, s25, 0
	s_mov_b32 m0, s31
	v_lshl_add_u64 v[222:223], s[16:17], 0, v[128:129]
	ds_read_b128 v[174:177], v141 offset:32768
	ds_read_b128 v[178:181], v141 offset:33792
	ds_read_b128 v[182:185], v141 offset:34816
	ds_read_b128 v[196:199], v141 offset:35840
	ds_read_b128 v[200:203], v141 offset:36864
	ds_read_b128 v[204:207], v141 offset:37888
	ds_read_b128 v[208:211], v141 offset:38912
	ds_read_b128 v[212:215], v141 offset:39936
	global_load_lds_dwordx4 v[222:223], off
	s_mov_b32 m0, s33
	v_lshl_add_u64 v[222:223], s[16:17], 0, v[130:131]
	global_load_lds_dwordx4 v[222:223], off
	s_waitcnt vmcnt(8) lgkmcnt(0)
	s_barrier
	s_setprio 1
	v_mfma_f32_16x16x32_bf16 v[124:127], v[142:145], v[174:177], v[124:127]
	v_mfma_f32_16x16x32_bf16 v[120:123], v[150:153], v[174:177], v[120:123]
	v_mfma_f32_16x16x32_bf16 v[116:119], v[142:145], v[182:185], v[116:119]
	v_mfma_f32_16x16x32_bf16 v[112:115], v[150:153], v[182:185], v[112:115]
	v_mfma_f32_16x16x32_bf16 v[100:103], v[142:145], v[200:203], v[100:103]
	v_mfma_f32_16x16x32_bf16 v[96:99], v[150:153], v[200:203], v[96:99]
	v_mfma_f32_16x16x32_bf16 v[84:87], v[142:145], v[208:211], v[84:87]
	v_mfma_f32_16x16x32_bf16 v[80:83], v[150:153], v[208:211], v[80:83]
	v_mfma_f32_16x16x32_bf16 v[124:127], v[146:149], v[178:181], v[124:127]
	v_mfma_f32_16x16x32_bf16 v[120:123], v[154:157], v[178:181], v[120:123]
	v_mfma_f32_16x16x32_bf16 v[116:119], v[146:149], v[196:199], v[116:119]
	v_mfma_f32_16x16x32_bf16 v[112:115], v[154:157], v[196:199], v[112:115]
	v_mfma_f32_16x16x32_bf16 v[100:103], v[146:149], v[204:207], v[100:103]
	v_mfma_f32_16x16x32_bf16 v[96:99], v[154:157], v[204:207], v[96:99]
	v_mfma_f32_16x16x32_bf16 v[84:87], v[146:149], v[212:215], v[84:87]
	v_mfma_f32_16x16x32_bf16 v[80:83], v[154:157], v[212:215], v[80:83]
	s_setprio 0
	s_setprio 1
	v_mfma_f32_16x16x32_bf16 v[108:111], v[158:161], v[174:177], v[108:111]
	v_mfma_f32_16x16x32_bf16 v[104:107], v[166:169], v[174:177], v[104:107]
	v_mfma_f32_16x16x32_bf16 v[92:95], v[158:161], v[182:185], v[92:95]
	v_mfma_f32_16x16x32_bf16 v[88:91], v[166:169], v[182:185], v[88:91]
	v_mfma_f32_16x16x32_bf16 v[76:79], v[158:161], v[200:203], v[76:79]
	v_mfma_f32_16x16x32_bf16 v[72:75], v[166:169], v[200:203], v[72:75]
	v_mfma_f32_16x16x32_bf16 v[68:71], v[158:161], v[208:211], v[68:71]
	v_mfma_f32_16x16x32_bf16 v[64:67], v[166:169], v[208:211], v[64:67]
	v_mfma_f32_16x16x32_bf16 v[108:111], v[162:165], v[178:181], v[108:111]
	v_mfma_f32_16x16x32_bf16 v[104:107], v[170:173], v[178:181], v[104:107]
	v_mfma_f32_16x16x32_bf16 v[92:95], v[162:165], v[196:199], v[92:95]
	v_mfma_f32_16x16x32_bf16 v[88:91], v[170:173], v[196:199], v[88:91]
	v_mfma_f32_16x16x32_bf16 v[76:79], v[162:165], v[204:207], v[76:79]
	v_mfma_f32_16x16x32_bf16 v[72:75], v[170:173], v[204:207], v[72:75]
	v_mfma_f32_16x16x32_bf16 v[68:71], v[162:165], v[212:215], v[68:71]
	v_mfma_f32_16x16x32_bf16 v[64:67], v[170:173], v[212:215], v[64:67]
	s_setprio 0
	s_barrier
	s_add_i32 s0, s0, s28
	v_lshl_add_u64 v[186:187], v[186:187], 0, s[58:59]
	s_mov_b32 m0, s0
	ds_read_b128 v[174:177], v141 offset:49152
	ds_read_b128 v[178:181], v141 offset:50176
	ds_read_b128 v[182:185], v141 offset:51200
	ds_read_b128 v[196:199], v141 offset:52224
	ds_read_b128 v[200:203], v141 offset:53248
	ds_read_b128 v[204:207], v141 offset:54272
	ds_read_b128 v[208:211], v141 offset:55296
	ds_read_b128 v[212:215], v141 offset:56320
	global_load_lds_dwordx4 v[186:187], off
	s_add_i32 m0, s0, 0x2000
	s_add_u32 s16, s22, 0x160080
	v_lshl_add_u64 v[186:187], v[216:217], 0, s[58:59]
	s_addc_u32 s17, s23, 0
	s_add_i32 s0, s1, s28
	global_load_lds_dwordx4 v[186:187], off
	s_mov_b32 m0, s0
	v_lshl_add_u64 v[186:187], s[16:17], 0, v[190:191]
	global_load_lds_dwordx4 v[186:187], off
	s_add_i32 m0, s0, 0x2000
	v_lshl_add_u64 v[186:187], s[16:17], 0, v[132:133]
	global_load_lds_dwordx4 v[186:187], off
	s_mov_b32 m0, s37
	v_lshl_add_u64 v[186:187], v[218:219], 0, s[58:59]
	global_load_lds_dwordx4 v[186:187], off
	s_mov_b32 m0, s38
	v_lshl_add_u64 v[186:187], v[220:221], 0, s[58:59]
	global_load_lds_dwordx4 v[186:187], off
	s_waitcnt vmcnt(8) lgkmcnt(0)
	s_barrier
	s_setprio 1
	v_mfma_f32_16x16x32_bf16 v[60:63], v[142:145], v[174:177], v[60:63]
	v_mfma_f32_16x16x32_bf16 v[56:59], v[150:153], v[174:177], v[56:59]
	v_mfma_f32_16x16x32_bf16 v[52:55], v[142:145], v[182:185], v[52:55]
	v_mfma_f32_16x16x32_bf16 v[48:51], v[150:153], v[182:185], v[48:51]
	v_mfma_f32_16x16x32_bf16 v[36:39], v[142:145], v[200:203], v[36:39]
	v_mfma_f32_16x16x32_bf16 v[32:35], v[150:153], v[200:203], v[32:35]
	v_mfma_f32_16x16x32_bf16 v[20:23], v[142:145], v[208:211], v[20:23]
	v_mfma_f32_16x16x32_bf16 v[16:19], v[150:153], v[208:211], v[16:19]
	v_mfma_f32_16x16x32_bf16 v[60:63], v[146:149], v[178:181], v[60:63]
	v_mfma_f32_16x16x32_bf16 v[56:59], v[154:157], v[178:181], v[56:59]
	v_mfma_f32_16x16x32_bf16 v[52:55], v[146:149], v[196:199], v[52:55]
	v_mfma_f32_16x16x32_bf16 v[48:51], v[154:157], v[196:199], v[48:51]
	v_mfma_f32_16x16x32_bf16 v[36:39], v[146:149], v[204:207], v[36:39]
	v_mfma_f32_16x16x32_bf16 v[32:35], v[154:157], v[204:207], v[32:35]
	v_mfma_f32_16x16x32_bf16 v[20:23], v[146:149], v[212:215], v[20:23]
	v_mfma_f32_16x16x32_bf16 v[16:19], v[154:157], v[212:215], v[16:19]
	s_setprio 0
	s_setprio 1
	v_mfma_f32_16x16x32_bf16 v[44:47], v[158:161], v[174:177], v[44:47]
	v_mfma_f32_16x16x32_bf16 v[40:43], v[166:169], v[174:177], v[40:43]
	v_mfma_f32_16x16x32_bf16 v[28:31], v[158:161], v[182:185], v[28:31]
	v_mfma_f32_16x16x32_bf16 v[24:27], v[166:169], v[182:185], v[24:27]
	v_mfma_f32_16x16x32_bf16 v[12:15], v[158:161], v[200:203], v[12:15]
	v_mfma_f32_16x16x32_bf16 v[8:11], v[166:169], v[200:203], v[8:11]
	v_mfma_f32_16x16x32_bf16 v[4:7], v[158:161], v[208:211], v[4:7]
	v_mfma_f32_16x16x32_bf16 v[0:3], v[166:169], v[208:211], v[0:3]
	v_mfma_f32_16x16x32_bf16 v[44:47], v[162:165], v[178:181], v[44:47]
	v_mfma_f32_16x16x32_bf16 v[40:43], v[170:173], v[178:181], v[40:43]
	v_mfma_f32_16x16x32_bf16 v[28:31], v[162:165], v[196:199], v[28:31]
	v_mfma_f32_16x16x32_bf16 v[24:27], v[170:173], v[196:199], v[24:27]
	v_mfma_f32_16x16x32_bf16 v[12:15], v[162:165], v[204:207], v[12:15]
	v_mfma_f32_16x16x32_bf16 v[8:11], v[170:173], v[204:207], v[8:11]
	v_mfma_f32_16x16x32_bf16 v[4:7], v[162:165], v[212:215], v[4:7]
	v_mfma_f32_16x16x32_bf16 v[0:3], v[170:173], v[212:215], v[0:3]
	s_setprio 0
	s_barrier
	s_add_i32 s53, s53, 2
	s_add_u32 s47, s47, 0x100
	s_addc_u32 s52, s52, 0
	s_cmpk_gt_u32 s53, 0x55
	s_mov_b64 s[16:17], s[20:21]
	s_cbranch_scc0 .LBB0_1350
